# GEMM K-loops: also drop the flips in the K=256 loop and the duplicated lgkmcnt(0) before each MFMA burst
# speedup vs baseline: 1.0266x; 1.0057x over previous
; #define PG8_STAGE(bufoff, gbase, voff) do { _Pragma("unroll") for (int _i = 0; _i < 2; ++_i) \
;         __builtin_amdgcn_global_load_lds((const unsigned*)((const char*)(gbase) + (voff)[_i]), (LAS unsigned*)(lds + (bufoff) + ldsw + _i * 8192), 16, 0, 0); } while (0)
; #define PG8_LDA(dst, b, h) do { _Pragma("unroll") for (int m = 0; m < 4; ++m) _Pragma("unroll") for (int k = 0; k < 2; ++k) dst[m][k] = *(const LAS bf16x8*)(lds + PG8_SA(b, h) + aoff + m * 2048 + k * 1024); } while (0)
; #define PG8_LDB(dst, b, h) do { _Pragma("unroll") for (int n = 0; n < 2; ++n) _Pragma("unroll") for (int k = 0; k < 2; ++k) dst[n][k] = *(const LAS bf16x8*)(lds + PG8_SB(b, h) + boff + n * 2048 + k * 1024); } while (0)
; #define PG8_MMA(ai, bj, At, Bt) do { __builtin_amdgcn_s_setprio(1); _Pragma("unroll") for (int m = 0; m < 4; ++m) _Pragma("unroll") for (int n = 0; n < 2; ++n) _Pragma("unroll") for (int k = 0; k < 2; ++k) \
;         acc[ai][bj][m][n] = __builtin_amdgcn_mfma_f32_16x16x32_bf16(Bt[n][k], At[m][k], acc[ai][bj][m][n], 0, 0, 0); __builtin_amdgcn_s_setprio(0); } while (0)
; #define PG8_WAIT_V(n) asm volatile("s_waitcnt vmcnt(" #n ")" ::: "memory")
; #define PG8_WAIT_L(n) asm volatile("s_waitcnt lgkmcnt(" #n ")" ::: "memory")
; template <class Epi>
; __device__ __forceinline__ void gemm_phase(LAS unsigned char* lds, const Gemm g, const StaticOrder& S, const Epi& E) {
;     ...
;         for (int t = 0; t < nt; t += 2) {
;             const bool last = (t == nt - 2);
;             const char* a1 = cA + (size_t)(t + 1) * kstep;
;             const char* a2 = last ? nA : cA + (size_t)(t + 2) * kstep; const char* b2 = last ? nB : cB + (size_t)(t + 2) * kstep;
;             const char* a3 = a2 + kstep; const char* b3 = b2 + kstep;
;             PG8_LDB(B0, 0, 0); PG8_SCHED; PG8_LDA(At, 0, 0); PG8_STAGE(PG8_SA(1, 1), a1 + hstep, voffA);
;             PG8_WAIT_L(8); PG8_BAR; PG8_WAIT_L(0); PG8_MMA(0, 0, At, B0); PG8_BAR; PG8_SCHED;
;             PG8_LDB(B1, 0, 1); PG8_STAGE(PG8_SB(0, 0), b2, voffB);
;             PG8_BAR; PG8_WAIT_L(0); PG8_MMA(0, 1, At, B1); PG8_BAR;
;             PG8_LDA(At, 0, 1); PG8_STAGE(PG8_SA(0, 0), a2, voffA);
;             PG8_BAR; PG8_WAIT_L(0); PG8_MMA(1, 0, At, B0); PG8_BAR; PG8_SCHED;
;             PG8_STAGE(PG8_SB(0, 1), b2 + hstep, voffB);
;             PG8_WAIT_V(6); PG8_BAR; PG8_MMA(1, 1, At, B1); PG8_BAR;
.LBB0_203:
	ds_read_b128 v[144:147], v153
	ds_read_b128 v[160:163], v153 offset:1024
	ds_read_b128 v[164:167], v153 offset:2048
	ds_read_b128 v[168:171], v153 offset:3072
	s_add_u32 s44, s42, 0xfff80080
	s_addc_u32 s45, s43, -1
	s_cmp_eq_u32 s54, 28
	s_cselect_b32 s47, s25, s45
	s_cselect_b32 s46, s50, s44
	s_cselect_b32 s45, s23, s53
	s_cselect_b32 s44, s51, s52
	s_add_i32 m0, s11, 0xc000
	ds_read_b128 v[172:175], v154
	ds_read_b128 v[176:179], v154 offset:1024
	ds_read_b128 v[180:183], v154 offset:2048
	ds_read_b128 v[184:187], v154 offset:3072
	ds_read_b128 v[188:191], v154 offset:4096
	ds_read_b128 v[192:195], v154 offset:5120
	ds_read_b128 v[196:199], v154 offset:6144
	ds_read_b128 v[200:203], v154 offset:7168
	global_load_lds_dwordx4 v136, s[42:43]
	s_add_i32 m0, s11, 0xe000
	s_nop 0
	global_load_lds_dwordx4 v138, s[42:43]
	s_waitcnt lgkmcnt(8)
	s_barrier
	s_waitcnt lgkmcnt(0)
	v_mfma_f32_16x16x32_bf16 v[124:127], v[144:147], v[172:175], v[124:127]
	v_mfma_f32_16x16x32_bf16 v[120:123], v[164:167], v[172:175], v[120:123]
	v_mfma_f32_16x16x32_bf16 v[108:111], v[144:147], v[180:183], v[108:111]
	v_mfma_f32_16x16x32_bf16 v[104:107], v[164:167], v[180:183], v[104:107]
	v_mfma_f32_16x16x32_bf16 v[92:95], v[144:147], v[188:191], v[92:95]
	v_mfma_f32_16x16x32_bf16 v[88:91], v[164:167], v[188:191], v[88:91]
	v_mfma_f32_16x16x32_bf16 v[76:79], v[144:147], v[196:199], v[76:79]
	v_mfma_f32_16x16x32_bf16 v[72:75], v[164:167], v[196:199], v[72:75]
	v_mfma_f32_16x16x32_bf16 v[124:127], v[160:163], v[176:179], v[124:127]
	v_mfma_f32_16x16x32_bf16 v[120:123], v[168:171], v[176:179], v[120:123]
	v_mfma_f32_16x16x32_bf16 v[108:111], v[160:163], v[184:187], v[108:111]
	v_mfma_f32_16x16x32_bf16 v[104:107], v[168:171], v[184:187], v[104:107]
	v_mfma_f32_16x16x32_bf16 v[92:95], v[160:163], v[192:195], v[92:95]
	v_mfma_f32_16x16x32_bf16 v[88:91], v[168:171], v[192:195], v[88:91]
	v_mfma_f32_16x16x32_bf16 v[76:79], v[160:163], v[200:203], v[76:79]
	v_mfma_f32_16x16x32_bf16 v[72:75], v[168:171], v[200:203], v[72:75]
	s_barrier
	s_add_i32 s55, s41, s10
	s_add_u32 s98, s44, s8
	s_addc_u32 s99, s45, s9
	s_mov_b32 m0, s55
	ds_read_b128 v[204:207], v155
	ds_read_b128 v[208:211], v155 offset:1024
	ds_read_b128 v[212:215], v155 offset:2048
	ds_read_b128 v[216:219], v155 offset:3072
	global_load_lds_dwordx4 v132, s[44:45]
	s_add_i32 m0, s55, 0x2000
	s_nop 0
	global_load_lds_dwordx4 v128, s[44:45]
	s_barrier
	s_waitcnt lgkmcnt(0)
	v_mfma_f32_16x16x32_bf16 v[116:119], v[204:207], v[172:175], v[116:119]
	v_mfma_f32_16x16x32_bf16 v[112:115], v[212:215], v[172:175], v[112:115]
	v_mfma_f32_16x16x32_bf16 v[100:103], v[204:207], v[180:183], v[100:103]
	v_mfma_f32_16x16x32_bf16 v[96:99], v[212:215], v[180:183], v[96:99]
	v_mfma_f32_16x16x32_bf16 v[84:87], v[204:207], v[188:191], v[84:87]
	v_mfma_f32_16x16x32_bf16 v[80:83], v[212:215], v[188:191], v[80:83]
	v_mfma_f32_16x16x32_bf16 v[68:71], v[204:207], v[196:199], v[68:71]
	v_mfma_f32_16x16x32_bf16 v[64:67], v[212:215], v[196:199], v[64:67]
	v_mfma_f32_16x16x32_bf16 v[116:119], v[208:211], v[176:179], v[116:119]
	v_mfma_f32_16x16x32_bf16 v[112:115], v[216:219], v[176:179], v[112:115]
	v_mfma_f32_16x16x32_bf16 v[100:103], v[208:211], v[184:187], v[100:103]
	v_mfma_f32_16x16x32_bf16 v[96:99], v[216:219], v[184:187], v[96:99]
	v_mfma_f32_16x16x32_bf16 v[84:87], v[208:211], v[192:195], v[84:87]
	v_mfma_f32_16x16x32_bf16 v[80:83], v[216:219], v[192:195], v[80:83]
	v_mfma_f32_16x16x32_bf16 v[68:71], v[208:211], v[200:203], v[68:71]
	v_mfma_f32_16x16x32_bf16 v[64:67], v[216:219], v[200:203], v[64:67]
	s_mov_b32 m0, s11
	s_add_u32 s100, s46, s8
	s_addc_u32 s101, s47, s9
	s_barrier
	ds_read_b128 v[172:175], v154 offset:16384
	ds_read_b128 v[176:179], v154 offset:17408
	ds_read_b128 v[180:183], v154 offset:18432
	ds_read_b128 v[184:187], v154 offset:19456
	ds_read_b128 v[188:191], v154 offset:20480
	ds_read_b128 v[192:195], v154 offset:21504
	ds_read_b128 v[196:199], v154 offset:22528
	ds_read_b128 v[200:203], v154 offset:23552
	global_load_lds_dwordx4 v134, s[46:47]
	s_mov_b32 m0, s13
	s_nop 0
	global_load_lds_dwordx4 v130, s[46:47]
	s_barrier
	s_waitcnt lgkmcnt(0)
	v_mfma_f32_16x16x32_bf16 v[60:63], v[144:147], v[172:175], v[60:63]
	v_mfma_f32_16x16x32_bf16 v[56:59], v[164:167], v[172:175], v[56:59]
	v_mfma_f32_16x16x32_bf16 v[44:47], v[144:147], v[180:183], v[44:47]
	v_mfma_f32_16x16x32_bf16 v[40:43], v[164:167], v[180:183], v[40:43]
	v_mfma_f32_16x16x32_bf16 v[28:31], v[144:147], v[188:191], v[28:31]
	v_mfma_f32_16x16x32_bf16 v[24:27], v[164:167], v[188:191], v[24:27]
	v_mfma_f32_16x16x32_bf16 v[12:15], v[144:147], v[196:199], v[12:15]
	v_mfma_f32_16x16x32_bf16 v[8:11], v[164:167], v[196:199], v[8:11]
	v_mfma_f32_16x16x32_bf16 v[60:63], v[160:163], v[176:179], v[60:63]
	v_mfma_f32_16x16x32_bf16 v[56:59], v[168:171], v[176:179], v[56:59]
	v_mfma_f32_16x16x32_bf16 v[44:47], v[160:163], v[184:187], v[44:47]
	v_mfma_f32_16x16x32_bf16 v[40:43], v[168:171], v[184:187], v[40:43]
	v_mfma_f32_16x16x32_bf16 v[28:31], v[160:163], v[192:195], v[28:31]
	v_mfma_f32_16x16x32_bf16 v[24:27], v[168:171], v[192:195], v[24:27]
	v_mfma_f32_16x16x32_bf16 v[12:15], v[160:163], v[200:203], v[12:15]
	v_mfma_f32_16x16x32_bf16 v[8:11], v[168:171], v[200:203], v[8:11]
	s_barrier
	s_add_u32 s56, s44, 0x80000
	s_addc_u32 s57, s45, 0
	s_add_i32 s55, s48, s10
	s_mov_b32 m0, s55
	s_nop 0
	global_load_lds_dwordx4 v132, s[56:57]
	s_add_i32 m0, s55, 0x2000
	s_nop 0
	global_load_lds_dwordx4 v128, s[56:57]
	s_waitcnt vmcnt(6)
	s_barrier
; #define PG8_STAGE(bufoff, gbase, voff) do { _Pragma("unroll") for (int _i = 0; _i < 2; ++_i) \
;         __builtin_amdgcn_global_load_lds((const unsigned*)((const char*)(gbase) + (voff)[_i]), (LAS unsigned*)(lds + (bufoff) + ldsw + _i * 8192), 16, 0, 0); } while (0)
; #define PG8_LDA(dst, b, h) do { _Pragma("unroll") for (int m = 0; m < 4; ++m) _Pragma("unroll") for (int k = 0; k < 2; ++k) dst[m][k] = *(const LAS bf16x8*)(lds + PG8_SA(b, h) + aoff + m * 2048 + k * 1024); } while (0)
; #define PG8_LDB(dst, b, h) do { _Pragma("unroll") for (int n = 0; n < 2; ++n) _Pragma("unroll") for (int k = 0; k < 2; ++k) dst[n][k] = *(const LAS bf16x8*)(lds + PG8_SB(b, h) + boff + n * 2048 + k * 1024); } while (0)
; #define PG8_MMA(ai, bj, At, Bt) do { __builtin_amdgcn_s_setprio(1); _Pragma("unroll") for (int m = 0; m < 4; ++m) _Pragma("unroll") for (int n = 0; n < 2; ++n) _Pragma("unroll") for (int k = 0; k < 2; ++k) \
;         acc[ai][bj][m][n] = __builtin_amdgcn_mfma_f32_16x16x32_bf16(Bt[n][k], At[m][k], acc[ai][bj][m][n], 0, 0, 0); __builtin_amdgcn_s_setprio(0); } while (0)
; #define PG8_WAIT_V(n) asm volatile("s_waitcnt vmcnt(" #n ")" ::: "memory")
; #define PG8_WAIT_L(n) asm volatile("s_waitcnt lgkmcnt(" #n ")" ::: "memory")
; #define PG8_BAR __builtin_amdgcn_s_barrier()
; #define PG8_SCHED __builtin_amdgcn_sched_barrier(0)
; template <class Epi>
; __device__ __forceinline__ void gemm_phase(LAS unsigned char* lds, const Gemm g, const StaticOrder& S, const Epi& E) {
;     ...
;             PG8_WAIT_V(6); PG8_BAR; PG8_MMA(1, 1, At, B1); PG8_BAR;
;             PG8_LDB(B0, 1, 0); PG8_SCHED; PG8_LDA(At, 1, 0); PG8_STAGE(PG8_SA(0, 1), a2 + hstep, voffA);
;             PG8_WAIT_L(8); PG8_BAR; PG8_WAIT_L(0); PG8_MMA(0, 0, At, B0); PG8_BAR; PG8_SCHED;
;             PG8_LDB(B1, 1, 1); PG8_STAGE(PG8_SB(1, 0), b3, voffB);
;             PG8_BAR; PG8_WAIT_L(0); PG8_MMA(0, 1, At, B1); PG8_BAR;
;             PG8_LDA(At, 1, 1); PG8_STAGE(PG8_SA(1, 0), a3, voffA);
	v_mfma_f32_16x16x32_bf16 v[52:55], v[204:207], v[172:175], v[52:55]
	v_mfma_f32_16x16x32_bf16 v[48:51], v[212:215], v[172:175], v[48:51]
	v_mfma_f32_16x16x32_bf16 v[36:39], v[204:207], v[180:183], v[36:39]
	v_mfma_f32_16x16x32_bf16 v[32:35], v[212:215], v[180:183], v[32:35]
	v_mfma_f32_16x16x32_bf16 v[20:23], v[204:207], v[188:191], v[20:23]
	v_mfma_f32_16x16x32_bf16 v[16:19], v[212:215], v[188:191], v[16:19]
	v_mfma_f32_16x16x32_bf16 v[4:7], v[204:207], v[196:199], v[4:7]
	v_mfma_f32_16x16x32_bf16 v[0:3], v[212:215], v[196:199], v[0:3]
	v_mfma_f32_16x16x32_bf16 v[52:55], v[208:211], v[176:179], v[52:55]
	v_mfma_f32_16x16x32_bf16 v[48:51], v[216:219], v[176:179], v[48:51]
	v_mfma_f32_16x16x32_bf16 v[36:39], v[208:211], v[184:187], v[36:39]
	v_mfma_f32_16x16x32_bf16 v[32:35], v[216:219], v[184:187], v[32:35]
	v_mfma_f32_16x16x32_bf16 v[20:23], v[208:211], v[192:195], v[20:23]
	v_mfma_f32_16x16x32_bf16 v[16:19], v[216:219], v[192:195], v[16:19]
	v_mfma_f32_16x16x32_bf16 v[4:7], v[208:211], v[200:203], v[4:7]
	v_mfma_f32_16x16x32_bf16 v[0:3], v[216:219], v[200:203], v[0:3]
	s_add_i32 s55, 0, 0x18000
	v_add_u32_e32 v168, s55, v151
	s_barrier
	ds_read_b128 v[144:147], v168
	ds_read_b128 v[160:163], v168 offset:1024
	ds_read_b128 v[164:167], v168 offset:2048
	ds_read_b128 v[168:171], v168 offset:3072
	s_add_u32 s46, s46, 0x80000
	s_addc_u32 s47, s47, 0
	s_mov_b32 m0, s30
	ds_read_b128 v[172:175], v154 offset:32768
	ds_read_b128 v[176:179], v154 offset:33792
	ds_read_b128 v[180:183], v154 offset:34816
	ds_read_b128 v[184:187], v154 offset:35840
	ds_read_b128 v[188:191], v154 offset:36864
	ds_read_b128 v[192:195], v154 offset:37888
	ds_read_b128 v[196:199], v154 offset:38912
	ds_read_b128 v[200:203], v154 offset:39936
	global_load_lds_dwordx4 v134, s[46:47]
	s_mov_b32 m0, s31
	s_nop 0
	global_load_lds_dwordx4 v130, s[46:47]
	s_waitcnt lgkmcnt(8)
	s_barrier
	s_waitcnt lgkmcnt(0)
	v_mfma_f32_16x16x32_bf16 v[124:127], v[144:147], v[172:175], v[124:127]
	v_mfma_f32_16x16x32_bf16 v[120:123], v[164:167], v[172:175], v[120:123]
	v_mfma_f32_16x16x32_bf16 v[108:111], v[144:147], v[180:183], v[108:111]
	v_mfma_f32_16x16x32_bf16 v[104:107], v[164:167], v[180:183], v[104:107]
	v_mfma_f32_16x16x32_bf16 v[92:95], v[144:147], v[188:191], v[92:95]
	v_mfma_f32_16x16x32_bf16 v[88:91], v[164:167], v[188:191], v[88:91]
	v_mfma_f32_16x16x32_bf16 v[76:79], v[144:147], v[196:199], v[76:79]
	v_mfma_f32_16x16x32_bf16 v[72:75], v[164:167], v[196:199], v[72:75]
	v_mfma_f32_16x16x32_bf16 v[124:127], v[160:163], v[176:179], v[124:127]
	v_mfma_f32_16x16x32_bf16 v[120:123], v[168:171], v[176:179], v[120:123]
	v_mfma_f32_16x16x32_bf16 v[108:111], v[160:163], v[184:187], v[108:111]
	v_mfma_f32_16x16x32_bf16 v[104:107], v[168:171], v[184:187], v[104:107]
	v_mfma_f32_16x16x32_bf16 v[92:95], v[160:163], v[192:195], v[92:95]
	v_mfma_f32_16x16x32_bf16 v[88:91], v[168:171], v[192:195], v[88:91]
	v_mfma_f32_16x16x32_bf16 v[76:79], v[160:163], v[200:203], v[76:79]
	v_mfma_f32_16x16x32_bf16 v[72:75], v[168:171], v[200:203], v[72:75]
	s_barrier
	s_add_i32 s46, 0, 0x1c000
	s_add_i32 s47, s55, s10
	v_add_u32_e32 v216, s46, v151
	s_mov_b32 m0, s47
	ds_read_b128 v[204:207], v216
	ds_read_b128 v[208:211], v216 offset:1024
	ds_read_b128 v[212:215], v216 offset:2048
	ds_read_b128 v[216:219], v216 offset:3072
	global_load_lds_dwordx4 v132, s[98:99]
	s_add_i32 m0, s47, 0x2000
	s_nop 0
	global_load_lds_dwordx4 v128, s[98:99]
	s_barrier
	s_waitcnt lgkmcnt(0)
	v_mfma_f32_16x16x32_bf16 v[116:119], v[204:207], v[172:175], v[116:119]
	v_mfma_f32_16x16x32_bf16 v[112:115], v[212:215], v[172:175], v[112:115]
	v_mfma_f32_16x16x32_bf16 v[100:103], v[204:207], v[180:183], v[100:103]
	v_mfma_f32_16x16x32_bf16 v[96:99], v[212:215], v[180:183], v[96:99]
	v_mfma_f32_16x16x32_bf16 v[84:87], v[204:207], v[188:191], v[84:87]
	v_mfma_f32_16x16x32_bf16 v[80:83], v[212:215], v[188:191], v[80:83]
	v_mfma_f32_16x16x32_bf16 v[68:71], v[204:207], v[196:199], v[68:71]
	v_mfma_f32_16x16x32_bf16 v[64:67], v[212:215], v[196:199], v[64:67]
	v_mfma_f32_16x16x32_bf16 v[116:119], v[208:211], v[176:179], v[116:119]
	v_mfma_f32_16x16x32_bf16 v[112:115], v[216:219], v[176:179], v[112:115]
	v_mfma_f32_16x16x32_bf16 v[100:103], v[208:211], v[184:187], v[100:103]
	v_mfma_f32_16x16x32_bf16 v[96:99], v[216:219], v[184:187], v[96:99]
	v_mfma_f32_16x16x32_bf16 v[84:87], v[208:211], v[192:195], v[84:87]
	v_mfma_f32_16x16x32_bf16 v[80:83], v[216:219], v[192:195], v[80:83]
	v_mfma_f32_16x16x32_bf16 v[68:71], v[208:211], v[200:203], v[68:71]
	v_mfma_f32_16x16x32_bf16 v[64:67], v[216:219], v[200:203], v[64:67]
	s_mov_b32 m0, s36
	s_barrier
	ds_read_b128 v[172:175], v154 offset:49152
	ds_read_b128 v[176:179], v154 offset:50176
	ds_read_b128 v[180:183], v154 offset:51200
	ds_read_b128 v[184:187], v154 offset:52224
	ds_read_b128 v[188:191], v154 offset:53248
	ds_read_b128 v[192:195], v154 offset:54272
	ds_read_b128 v[196:199], v154 offset:55296
	ds_read_b128 v[200:203], v154 offset:56320
	global_load_lds_dwordx4 v134, s[100:101]
	s_mov_b32 m0, s37
	s_nop 0
	global_load_lds_dwordx4 v130, s[100:101]
	s_barrier
; __device__ __forceinline__ float fast_rcp(float x) { return __builtin_amdgcn_rcpf(x); }
; __device__ __forceinline__ float fast_exp2(float x) { return __builtin_amdgcn_exp2f(x); }
; #define PG8_STAGE(bufoff, gbase, voff) do { _Pragma("unroll") for (int _i = 0; _i < 2; ++_i) \
;         __builtin_amdgcn_global_load_lds((const unsigned*)((const char*)(gbase) + (voff)[_i]), (LAS unsigned*)(lds + (bufoff) + ldsw + _i * 8192), 16, 0, 0); } while (0)
; #define PG8_MMA(ai, bj, At, Bt) do { __builtin_amdgcn_s_setprio(1); _Pragma("unroll") for (int m = 0; m < 4; ++m) _Pragma("unroll") for (int n = 0; n < 2; ++n) _Pragma("unroll") for (int k = 0; k < 2; ++k) \
;         acc[ai][bj][m][n] = __builtin_amdgcn_mfma_f32_16x16x32_bf16(Bt[n][k], At[m][k], acc[ai][bj][m][n], 0, 0, 0); __builtin_amdgcn_s_setprio(0); } while (0)
; #define PG8_WAIT_V(n) asm volatile("s_waitcnt vmcnt(" #n ")" ::: "memory")
; #define PG8_WAIT_L(n) asm volatile("s_waitcnt lgkmcnt(" #n ")" ::: "memory")
; #define PG8_BAR __builtin_amdgcn_s_barrier()
; #define PG8_SCHED __builtin_amdgcn_sched_barrier(0)
; template <class Epi>
; __device__ __forceinline__ void gemm_phase(LAS unsigned char* lds, const Gemm g, const StaticOrder& S, const Epi& E) {
;     ...
;             PG8_BAR; PG8_WAIT_L(0); PG8_MMA(1, 0, At, B0); PG8_BAR; PG8_SCHED;
;             PG8_STAGE(PG8_SB(1, 1), b3 + hstep, voffB);
;             PG8_WAIT_V(6); PG8_BAR; PG8_MMA(1, 1, At, B1); PG8_BAR;
;     __device__ __forceinline__ void operator()(const f32x4 (&acc)[2][2][4][2], const Unit& u, int wr, int wc, int fr, int fq) const {
;         const int row0 = u.pm * BM + wr * 64 + fr, col0 = u.pn * HALF + wc * 32 + 8 * fq;
; #pragma unroll
;         for (int ai = 0; ai < 2; ++ai)
; #pragma unroll
;             for (int m = 0; m < 4; ++m) { bf16_t* rowp = O + (size_t)(row0 + ai * HALF + m * 16) * DFF + col0;
;                 const float r = rs[row0 + ai * HALF + m * 16], r2 = r * r;
;                 f32x4 h0, h1;
; #pragma unroll
;                 for (int j = 0; j < 4; ++j) {
;                     const float g0 = acc[ai][0][m][0][j], g1 = acc[ai][0][m][1][j];
;                     h0[j] = g0 * r2 * fast_rcp(1.0f + fast_exp2(g0 * (-LOG2E * r))) * acc[ai][1][m][0][j];
;                     h1[j] = g1 * r2 * fast_rcp(1.0f + fast_exp2(g1 * (-LOG2E * r))) * acc[ai][1][m][1][j]; }
;                 *(u32x4*)rowp = pack8(h0, h1); }
	s_waitcnt lgkmcnt(0)
	v_mfma_f32_16x16x32_bf16 v[60:63], v[144:147], v[172:175], v[60:63]
	v_mfma_f32_16x16x32_bf16 v[56:59], v[164:167], v[172:175], v[56:59]
	v_mfma_f32_16x16x32_bf16 v[44:47], v[144:147], v[180:183], v[44:47]
	v_mfma_f32_16x16x32_bf16 v[40:43], v[164:167], v[180:183], v[40:43]
	v_mfma_f32_16x16x32_bf16 v[28:31], v[144:147], v[188:191], v[28:31]
	v_mfma_f32_16x16x32_bf16 v[24:27], v[164:167], v[188:191], v[24:27]
	v_mfma_f32_16x16x32_bf16 v[12:15], v[144:147], v[196:199], v[12:15]
	v_mfma_f32_16x16x32_bf16 v[8:11], v[164:167], v[196:199], v[8:11]
	v_mfma_f32_16x16x32_bf16 v[60:63], v[160:163], v[176:179], v[60:63]
	v_mfma_f32_16x16x32_bf16 v[56:59], v[168:171], v[176:179], v[56:59]
	v_mfma_f32_16x16x32_bf16 v[44:47], v[160:163], v[184:187], v[44:47]
	v_mfma_f32_16x16x32_bf16 v[40:43], v[168:171], v[184:187], v[40:43]
	v_mfma_f32_16x16x32_bf16 v[28:31], v[160:163], v[192:195], v[28:31]
	v_mfma_f32_16x16x32_bf16 v[24:27], v[168:171], v[192:195], v[24:27]
	v_mfma_f32_16x16x32_bf16 v[12:15], v[160:163], v[200:203], v[12:15]
	v_mfma_f32_16x16x32_bf16 v[8:11], v[168:171], v[200:203], v[8:11]
	s_barrier
	s_add_u32 s44, s44, 0x80080
	s_addc_u32 s45, s45, 0
	s_add_i32 s46, s46, s10
	s_mov_b32 m0, s46
	s_nop 0
	global_load_lds_dwordx4 v132, s[44:45]
	s_add_i32 m0, s46, 0x2000
	s_nop 0
	global_load_lds_dwordx4 v128, s[44:45]
	s_waitcnt vmcnt(6)
	s_barrier
	v_mfma_f32_16x16x32_bf16 v[52:55], v[204:207], v[172:175], v[52:55]
	v_mfma_f32_16x16x32_bf16 v[48:51], v[212:215], v[172:175], v[48:51]
	v_mfma_f32_16x16x32_bf16 v[36:39], v[204:207], v[180:183], v[36:39]
	v_mfma_f32_16x16x32_bf16 v[32:35], v[212:215], v[180:183], v[32:35]
	v_mfma_f32_16x16x32_bf16 v[20:23], v[204:207], v[188:191], v[20:23]
	v_mfma_f32_16x16x32_bf16 v[16:19], v[212:215], v[188:191], v[16:19]
	v_mfma_f32_16x16x32_bf16 v[4:7], v[204:207], v[196:199], v[4:7]
	v_mfma_f32_16x16x32_bf16 v[0:3], v[212:215], v[196:199], v[0:3]
	v_mfma_f32_16x16x32_bf16 v[52:55], v[208:211], v[176:179], v[52:55]
	v_mfma_f32_16x16x32_bf16 v[48:51], v[216:219], v[176:179], v[48:51]
	v_mfma_f32_16x16x32_bf16 v[36:39], v[208:211], v[184:187], v[36:39]
	v_mfma_f32_16x16x32_bf16 v[32:35], v[216:219], v[184:187], v[32:35]
	v_mfma_f32_16x16x32_bf16 v[20:23], v[208:211], v[192:195], v[20:23]
	v_mfma_f32_16x16x32_bf16 v[16:19], v[216:219], v[192:195], v[16:19]
	v_mfma_f32_16x16x32_bf16 v[4:7], v[208:211], v[200:203], v[4:7]
	v_mfma_f32_16x16x32_bf16 v[0:3], v[216:219], v[200:203], v[0:3]
	s_add_i32 s54, s54, 2
	s_add_u32 s42, s42, 0x100
	s_addc_u32 s43, s43, 0
	s_add_u32 s52, s52, 0x100
	s_addc_u32 s53, s53, 0
	s_cmp_gt_u32 s54, 29
	s_barrier
	s_cbranch_scc0 .LBB0_203
	v_lshl_add_u32 v144, s40, 8, v150
	v_ashrrev_i32_e32 v145, 31, v144
	v_lshl_add_u64 v[148:149], v[144:145], 2, s[14:15]
	v_mov_b32_e32 v145, v224
	v_mov_b32_e32 v204, v225
	v_mov_b32_e32 v205, v226
	v_mov_b32_e32 v206, v227
	v_mov_b32_e32 v207, v228
	v_mov_b32_e32 v208, v229
	v_mov_b32_e32 v209, v230
	v_mov_b32_e32 v210, v231
	v_lshl_or_b32 v156, s34, 7, v152
	v_ashrrev_i32_e32 v157, 31, v156
	v_mov_b64_e32 v[146:147], s[20:21]
	v_mad_i64_i32 v[160:161], s[42:43], v144, s49, v[146:147]
	s_and_b64 vcc, exec, s[4:5]
	s_mov_b32 s34, s22
	s_mov_b32 s40, s24
	s_mov_b64 s[44:45], s[28:29]
	v_mul_f32_e32 v162, v145, v145
	v_mul_f32_e32 v145, 0xbfb8aa3b, v145
	v_mul_f32_e32 v163, v124, v162
	v_mul_f32_e32 v124, v124, v145
	v_exp_f32_e32 v124, v124
	s_nop 0
	v_add_f32_e32 v124, 1.0, v124
	v_rcp_f32_e32 v124, v124
	s_nop 0
	v_mul_f32_e32 v124, v163, v124
	v_mul_f32_e32 v116, v116, v124
	v_mul_f32_e32 v124, v120, v162
	v_mul_f32_e32 v120, v120, v145
	v_exp_f32_e32 v120, v120
	s_nop 0
	v_add_f32_e32 v120, 1.0, v120
	v_rcp_f32_e32 v120, v120
	s_nop 0
	v_mul_f32_e32 v120, v124, v120
	v_mul_f32_e32 v124, v125, v145
	v_exp_f32_e32 v124, v124
	v_mul_f32_e32 v120, v112, v120
	v_mul_f32_e32 v112, v125, v162
	v_add_f32_e32 v124, 1.0, v124
	v_rcp_f32_e32 v124, v124
	s_nop 0
	v_mul_f32_e32 v112, v112, v124
	v_mul_f32_e32 v117, v117, v112
	v_mul_f32_e32 v112, v121, v162
	v_mul_f32_e32 v121, v121, v145
	v_exp_f32_e32 v121, v121
	s_nop 0
	v_add_f32_e32 v121, 1.0, v121
	v_rcp_f32_e32 v121, v121
	s_nop 0
	v_mul_f32_e32 v112, v112, v121
	v_mul_f32_e32 v121, v113, v112
	v_mul_f32_e32 v113, v126, v145
	v_exp_f32_e32 v113, v113
	v_mul_f32_e32 v112, v126, v162
	v_add_f32_e32 v113, 1.0, v113
	v_rcp_f32_e32 v113, v113
	s_nop 0
	v_mul_f32_e32 v112, v112, v113
	v_mul_f32_e32 v113, v122, v145
	v_exp_f32_e32 v113, v113
	v_mul_f32_e32 v124, v118, v112
	v_mul_f32_e32 v112, v122, v162
	v_add_f32_e32 v113, 1.0, v113
	v_rcp_f32_e32 v113, v113
	s_nop 0
	v_mul_f32_e32 v112, v112, v113
	v_mul_f32_e32 v113, v127, v145
	v_exp_f32_e32 v113, v113
	v_mul_f32_e32 v122, v114, v112
	v_mul_f32_e32 v112, v127, v162
	v_cvt_pk_bf16_f32 v114, v116, v117
	v_add_f32_e32 v113, 1.0, v113
	v_rcp_f32_e32 v113, v113
	s_nop 0
	v_mul_f32_e32 v112, v112, v113
	v_mul_f32_e32 v113, v123, v145
	v_exp_f32_e32 v113, v113
	v_mul_f32_e32 v125, v119, v112
	v_mul_f32_e32 v112, v123, v162
	v_add_f32_e32 v113, 1.0, v113
	v_rcp_f32_e32 v113, v113
	s_nop 0
	v_mul_f32_e32 v112, v112, v113
	v_mul_f32_e32 v123, v115, v112
	v_lshlrev_b64 v[112:113], 1, v[156:157]
	v_lshl_add_u64 v[118:119], v[160:161], 0, v[112:113]
	v_cvt_pk_bf16_f32 v115, v124, v125
	v_cvt_pk_bf16_f32 v116, v120, v121
	v_cvt_pk_bf16_f32 v117, v122, v123
	global_store_dwordx4 v[118:119], v[114:117], off
	s_nop 1
	v_mov_b32_e32 v116, v204
	s_nop 0
	v_or_b32_e32 v114, 16, v144
	v_mad_i64_i32 v[114:115], s[42:43], v114, s49, v[146:147]
	v_mul_f32_e32 v117, v116, v116
	v_mul_f32_e32 v116, 0xbfb8aa3b, v116
	v_mul_f32_e32 v118, v108, v117
; __device__ __forceinline__ float fast_rcp(float x) { return __builtin_amdgcn_rcpf(x); }
; __device__ __forceinline__ float fast_exp2(float x) { return __builtin_amdgcn_exp2f(x); }
; __device__ __forceinline__ u32x4 pack8(f32x4 v0, f32x4 v1) { u32x4 w; w.x = cvt_pk_bf16(v0[0], v0[1]); w.y = cvt_pk_bf16(v0[2], v0[3]); w.z = cvt_pk_bf16(v1[0], v1[1]); w.w = cvt_pk_bf16(v1[2], v1[3]); return w; }
;     __device__ __forceinline__ void operator()(const f32x4 (&acc)[2][2][4][2], const Unit& u, int wr, int wc, int fr, int fq) const {
;         const int row0 = u.pm * BM + wr * 64 + fr, col0 = u.pn * HALF + wc * 32 + 8 * fq;
; #pragma unroll
;         for (int ai = 0; ai < 2; ++ai)
; #pragma unroll
;             for (int m = 0; m < 4; ++m) { bf16_t* rowp = O + (size_t)(row0 + ai * HALF + m * 16) * DFF + col0;
;                 const float r = rs[row0 + ai * HALF + m * 16], r2 = r * r;
;                 f32x4 h0, h1;
; #pragma unroll
;                 for (int j = 0; j < 4; ++j) {
;                     const float g0 = acc[ai][0][m][0][j], g1 = acc[ai][0][m][1][j];
;                     h0[j] = g0 * r2 * fast_rcp(1.0f + fast_exp2(g0 * (-LOG2E * r))) * acc[ai][1][m][0][j];
;                     h1[j] = g1 * r2 * fast_rcp(1.0f + fast_exp2(g1 * (-LOG2E * r))) * acc[ai][1][m][1][j]; }
;                 *(u32x4*)rowp = pack8(h0, h1); }
	v_mul_f32_e32 v108, v108, v116
	v_exp_f32_e32 v108, v108
	s_nop 0
	v_add_f32_e32 v108, 1.0, v108
	v_rcp_f32_e32 v108, v108
	s_nop 0
	v_mul_f32_e32 v108, v118, v108
	v_mul_f32_e32 v108, v100, v108
	v_mul_f32_e32 v100, v104, v117
	v_mul_f32_e32 v104, v104, v116
	v_exp_f32_e32 v104, v104
	s_nop 0
	v_add_f32_e32 v104, 1.0, v104
	v_rcp_f32_e32 v104, v104
	s_nop 0
	v_mul_f32_e32 v100, v100, v104
	v_mul_f32_e32 v104, v96, v100
	v_mul_f32_e32 v100, v109, v116
	v_exp_f32_e32 v100, v100
	v_mul_f32_e32 v96, v109, v117
	v_add_f32_e32 v100, 1.0, v100
	v_rcp_f32_e32 v100, v100
	s_nop 0
	v_mul_f32_e32 v96, v96, v100
	v_mul_f32_e32 v96, v101, v96
	v_mul_f32_e32 v101, v105, v116
	v_exp_f32_e32 v101, v101
	v_mul_f32_e32 v100, v105, v117
	v_cvt_pk_bf16_f32 v96, v108, v96
	v_add_f32_e32 v101, 1.0, v101
	v_rcp_f32_e32 v101, v101
	s_nop 0
	v_mul_f32_e32 v100, v100, v101
	v_mul_f32_e32 v105, v97, v100
	v_mul_f32_e32 v100, v110, v116
	v_exp_f32_e32 v100, v100
	v_mul_f32_e32 v101, v106, v116
	v_exp_f32_e32 v101, v101
	v_mul_f32_e32 v97, v110, v117
	v_add_f32_e32 v100, 1.0, v100
	v_rcp_f32_e32 v100, v100
	v_add_f32_e32 v101, 1.0, v101
	v_rcp_f32_e32 v101, v101
	v_mul_f32_e32 v97, v97, v100
	v_mul_f32_e32 v100, v106, v117
	v_mul_f32_e32 v100, v100, v101
	v_mul_f32_e32 v97, v102, v97
	v_mul_f32_e32 v102, v98, v100
	v_mul_f32_e32 v100, v111, v116
	v_exp_f32_e32 v100, v100
	v_mul_f32_e32 v101, v107, v116
	v_exp_f32_e32 v101, v101
	v_mul_f32_e32 v98, v111, v117
	v_add_f32_e32 v100, 1.0, v100
	v_rcp_f32_e32 v100, v100
	v_add_f32_e32 v101, 1.0, v101
	v_rcp_f32_e32 v101, v101
	v_mul_f32_e32 v98, v98, v100
	v_mul_f32_e32 v100, v107, v117
	v_mul_f32_e32 v100, v100, v101
	v_mul_f32_e32 v98, v103, v98
	v_mul_f32_e32 v99, v99, v100
	v_lshl_add_u64 v[100:101], v[114:115], 0, v[112:113]
	v_cvt_pk_bf16_f32 v97, v97, v98
	v_cvt_pk_bf16_f32 v98, v104, v105
	v_cvt_pk_bf16_f32 v99, v102, v99
	global_store_dwordx4 v[100:101], v[96:99], off
	s_nop 1
	v_mov_b32_e32 v98, v205
	s_nop 0
	v_or_b32_e32 v96, 32, v144
	v_mad_i64_i32 v[96:97], s[42:43], v96, s49, v[146:147]
	v_mul_f32_e32 v99, v98, v98
	v_mul_f32_e32 v98, 0xbfb8aa3b, v98
	v_mul_f32_e32 v100, v92, v99
	v_mul_f32_e32 v92, v92, v98
	v_exp_f32_e32 v92, v92
	s_nop 0
	v_add_f32_e32 v92, 1.0, v92
	v_rcp_f32_e32 v92, v92
	s_nop 0
	v_mul_f32_e32 v92, v100, v92
	v_mul_f32_e32 v92, v84, v92
	v_mul_f32_e32 v84, v88, v99
	v_mul_f32_e32 v88, v88, v98
	v_exp_f32_e32 v88, v88
	s_nop 0
	v_add_f32_e32 v88, 1.0, v88
	v_rcp_f32_e32 v88, v88
	s_nop 0
	v_mul_f32_e32 v84, v84, v88
	v_mul_f32_e32 v88, v80, v84
	v_mul_f32_e32 v84, v93, v98
	v_exp_f32_e32 v84, v84
	v_mul_f32_e32 v80, v93, v99
	v_add_f32_e32 v84, 1.0, v84
	v_rcp_f32_e32 v84, v84
	s_nop 0
	v_mul_f32_e32 v80, v80, v84
	v_mul_f32_e32 v80, v85, v80
	v_mul_f32_e32 v85, v89, v98
	v_exp_f32_e32 v85, v85
	v_mul_f32_e32 v84, v89, v99
	v_cvt_pk_bf16_f32 v80, v92, v80
	v_add_f32_e32 v85, 1.0, v85
	v_rcp_f32_e32 v85, v85
	s_nop 0
	v_mul_f32_e32 v84, v84, v85
	v_mul_f32_e32 v89, v81, v84
	v_mul_f32_e32 v84, v94, v98
	v_exp_f32_e32 v84, v84
	v_mul_f32_e32 v85, v90, v98
	v_exp_f32_e32 v85, v85
	v_mul_f32_e32 v81, v94, v99
	v_add_f32_e32 v84, 1.0, v84
	v_rcp_f32_e32 v84, v84
	v_add_f32_e32 v85, 1.0, v85
	v_rcp_f32_e32 v85, v85
	v_mul_f32_e32 v81, v81, v84
	v_mul_f32_e32 v84, v90, v99
	v_mul_f32_e32 v84, v84, v85
	v_mul_f32_e32 v81, v86, v81
	v_mul_f32_e32 v86, v82, v84
	v_mul_f32_e32 v84, v95, v98
	v_exp_f32_e32 v84, v84
	v_mul_f32_e32 v85, v91, v98
	v_exp_f32_e32 v85, v85
	v_mul_f32_e32 v82, v95, v99
	v_add_f32_e32 v84, 1.0, v84
	v_rcp_f32_e32 v84, v84
	v_add_f32_e32 v85, 1.0, v85
	v_rcp_f32_e32 v85, v85
	v_mul_f32_e32 v82, v82, v84
	v_mul_f32_e32 v84, v91, v99
	v_mul_f32_e32 v84, v84, v85
	v_mul_f32_e32 v82, v87, v82
	v_mul_f32_e32 v83, v83, v84
	v_lshl_add_u64 v[84:85], v[96:97], 0, v[112:113]
	v_cvt_pk_bf16_f32 v81, v81, v82
	v_cvt_pk_bf16_f32 v82, v88, v89
	v_cvt_pk_bf16_f32 v83, v86, v83
	global_store_dwordx4 v[84:85], v[80:83], off
	s_nop 1
	v_mov_b32_e32 v82, v206
	s_nop 0
	v_or_b32_e32 v80, 48, v144
	v_mad_i64_i32 v[80:81], s[42:43], v80, s49, v[146:147]
	v_mul_f32_e32 v83, v82, v82
	v_mul_f32_e32 v82, 0xbfb8aa3b, v82
	v_mul_f32_e32 v84, v76, v83
	v_mul_f32_e32 v76, v76, v82
	v_exp_f32_e32 v76, v76
	s_nop 0
	v_add_f32_e32 v76, 1.0, v76
	v_rcp_f32_e32 v76, v76
	s_nop 0
	v_mul_f32_e32 v76, v84, v76
	v_mul_f32_e32 v76, v68, v76
	v_mul_f32_e32 v68, v72, v83
	v_mul_f32_e32 v72, v72, v82
	v_exp_f32_e32 v72, v72
	s_nop 0
	v_add_f32_e32 v72, 1.0, v72
	v_rcp_f32_e32 v72, v72
	s_nop 0
	v_mul_f32_e32 v68, v68, v72
	v_mul_f32_e32 v72, v64, v68
	v_mul_f32_e32 v68, v77, v82
	v_exp_f32_e32 v68, v68
	v_mul_f32_e32 v64, v77, v83
	v_add_f32_e32 v68, 1.0, v68
	v_rcp_f32_e32 v68, v68
	s_nop 0
	v_mul_f32_e32 v64, v64, v68
	v_mul_f32_e32 v64, v69, v64
	v_mul_f32_e32 v69, v73, v82
	v_exp_f32_e32 v69, v69
	v_mul_f32_e32 v68, v73, v83
	v_cvt_pk_bf16_f32 v64, v76, v64
	v_add_f32_e32 v69, 1.0, v69
	v_rcp_f32_e32 v69, v69
	s_nop 0
	v_mul_f32_e32 v68, v68, v69
	v_mul_f32_e32 v73, v65, v68
	v_mul_f32_e32 v68, v78, v82
	v_exp_f32_e32 v68, v68
	v_mul_f32_e32 v69, v74, v82
	v_exp_f32_e32 v69, v69
	v_mul_f32_e32 v65, v78, v83
	v_add_f32_e32 v68, 1.0, v68
	v_rcp_f32_e32 v68, v68
	v_add_f32_e32 v69, 1.0, v69
	v_rcp_f32_e32 v69, v69
	v_mul_f32_e32 v65, v65, v68
	v_mul_f32_e32 v68, v74, v83
	v_mul_f32_e32 v68, v68, v69
	v_mul_f32_e32 v65, v70, v65
	v_mul_f32_e32 v70, v66, v68
	v_mul_f32_e32 v68, v79, v82
	v_exp_f32_e32 v68, v68
	v_mul_f32_e32 v69, v75, v82
	v_exp_f32_e32 v69, v69
	v_mul_f32_e32 v66, v79, v83
	v_add_f32_e32 v68, 1.0, v68
	v_rcp_f32_e32 v68, v68
	v_add_f32_e32 v69, 1.0, v69
	v_rcp_f32_e32 v69, v69
; __device__ __forceinline__ float fast_rcp(float x) { return __builtin_amdgcn_rcpf(x); }
; __device__ __forceinline__ float fast_exp2(float x) { return __builtin_amdgcn_exp2f(x); }
; __device__ __forceinline__ u32x4 pack8(f32x4 v0, f32x4 v1) { u32x4 w; w.x = cvt_pk_bf16(v0[0], v0[1]); w.y = cvt_pk_bf16(v0[2], v0[3]); w.z = cvt_pk_bf16(v1[0], v1[1]); w.w = cvt_pk_bf16(v1[2], v1[3]); return w; }
;     __device__ __forceinline__ void operator()(const f32x4 (&acc)[2][2][4][2], const Unit& u, int wr, int wc, int fr, int fq) const {
;         const int row0 = u.pm * BM + wr * 64 + fr, col0 = u.pn * HALF + wc * 32 + 8 * fq;
; #pragma unroll
;         for (int ai = 0; ai < 2; ++ai)
; #pragma unroll
;             for (int m = 0; m < 4; ++m) { bf16_t* rowp = O + (size_t)(row0 + ai * HALF + m * 16) * DFF + col0;
;                 const float r = rs[row0 + ai * HALF + m * 16], r2 = r * r;
;                 f32x4 h0, h1;
; #pragma unroll
;                 for (int j = 0; j < 4; ++j) {
;                     const float g0 = acc[ai][0][m][0][j], g1 = acc[ai][0][m][1][j];
;                     h0[j] = g0 * r2 * fast_rcp(1.0f + fast_exp2(g0 * (-LOG2E * r))) * acc[ai][1][m][0][j];
;                     h1[j] = g1 * r2 * fast_rcp(1.0f + fast_exp2(g1 * (-LOG2E * r))) * acc[ai][1][m][1][j]; }
;                 *(u32x4*)rowp = pack8(h0, h1); }
	v_mul_f32_e32 v66, v66, v68
	v_mul_f32_e32 v68, v75, v83
	v_mul_f32_e32 v68, v68, v69
	v_mul_f32_e32 v66, v71, v66
	v_mul_f32_e32 v67, v67, v68
	v_lshl_add_u64 v[68:69], v[80:81], 0, v[112:113]
	v_cvt_pk_bf16_f32 v65, v65, v66
	v_cvt_pk_bf16_f32 v66, v72, v73
	v_cvt_pk_bf16_f32 v67, v70, v67
	global_store_dwordx4 v[68:69], v[64:67], off
	s_nop 1
	v_mov_b32_e32 v66, v207
	s_nop 0
	v_add_u32_e32 v64, 0x80, v144
	v_mad_i64_i32 v[64:65], s[42:43], v64, s49, v[146:147]
	v_mul_f32_e32 v67, v66, v66
	v_mul_f32_e32 v66, 0xbfb8aa3b, v66
	v_mul_f32_e32 v68, v60, v67
	v_mul_f32_e32 v60, v60, v66
	v_exp_f32_e32 v60, v60
	s_nop 0
	v_add_f32_e32 v60, 1.0, v60
	v_rcp_f32_e32 v60, v60
	s_nop 0
	v_mul_f32_e32 v60, v68, v60
	v_mul_f32_e32 v60, v52, v60
	v_mul_f32_e32 v52, v56, v67
	v_mul_f32_e32 v56, v56, v66
	v_exp_f32_e32 v56, v56
	s_nop 0
	v_add_f32_e32 v56, 1.0, v56
	v_rcp_f32_e32 v56, v56
	s_nop 0
	v_mul_f32_e32 v52, v52, v56
	v_mul_f32_e32 v56, v48, v52
	v_mul_f32_e32 v52, v61, v66
	v_exp_f32_e32 v52, v52
	v_mul_f32_e32 v48, v61, v67
	v_add_f32_e32 v52, 1.0, v52
	v_rcp_f32_e32 v52, v52
	s_nop 0
	v_mul_f32_e32 v48, v48, v52
	v_mul_f32_e32 v48, v53, v48
	v_mul_f32_e32 v53, v57, v66
	v_exp_f32_e32 v53, v53
	v_mul_f32_e32 v52, v57, v67
	v_cvt_pk_bf16_f32 v48, v60, v48
	v_add_f32_e32 v53, 1.0, v53
	v_rcp_f32_e32 v53, v53
	s_nop 0
	v_mul_f32_e32 v52, v52, v53
	v_mul_f32_e32 v57, v49, v52
	v_mul_f32_e32 v52, v62, v66
	v_exp_f32_e32 v52, v52
	v_mul_f32_e32 v53, v58, v66
	v_exp_f32_e32 v53, v53
	v_mul_f32_e32 v49, v62, v67
	v_add_f32_e32 v52, 1.0, v52
	v_rcp_f32_e32 v52, v52
	v_add_f32_e32 v53, 1.0, v53
	v_rcp_f32_e32 v53, v53
	v_mul_f32_e32 v49, v49, v52
	v_mul_f32_e32 v52, v58, v67
	v_mul_f32_e32 v52, v52, v53
	v_mul_f32_e32 v49, v54, v49
	v_mul_f32_e32 v54, v50, v52
	v_mul_f32_e32 v52, v63, v66
	v_exp_f32_e32 v52, v52
	v_mul_f32_e32 v53, v59, v66
	v_exp_f32_e32 v53, v53
	v_mul_f32_e32 v50, v63, v67
	v_add_f32_e32 v52, 1.0, v52
	v_rcp_f32_e32 v52, v52
	v_add_f32_e32 v53, 1.0, v53
	v_rcp_f32_e32 v53, v53
	v_mul_f32_e32 v50, v50, v52
	v_mul_f32_e32 v52, v59, v67
	v_mul_f32_e32 v52, v52, v53
	v_mul_f32_e32 v50, v55, v50
	v_mul_f32_e32 v51, v51, v52
	v_lshl_add_u64 v[52:53], v[64:65], 0, v[112:113]
	v_cvt_pk_bf16_f32 v49, v49, v50
	v_cvt_pk_bf16_f32 v50, v56, v57
	v_cvt_pk_bf16_f32 v51, v54, v51
	global_store_dwordx4 v[52:53], v[48:51], off
	s_nop 1
	v_mov_b32_e32 v50, v208
	s_nop 0
	v_add_u32_e32 v48, 0x90, v144
	v_mad_i64_i32 v[48:49], s[42:43], v48, s49, v[146:147]
	v_mul_f32_e32 v51, v50, v50
	v_mul_f32_e32 v50, 0xbfb8aa3b, v50
	v_mul_f32_e32 v52, v44, v51
	v_mul_f32_e32 v44, v44, v50
	v_exp_f32_e32 v44, v44
	s_nop 0
	v_add_f32_e32 v44, 1.0, v44
	v_rcp_f32_e32 v44, v44
	s_nop 0
	v_mul_f32_e32 v44, v52, v44
	v_mul_f32_e32 v44, v36, v44
	v_mul_f32_e32 v36, v40, v51
	v_mul_f32_e32 v40, v40, v50
	v_exp_f32_e32 v40, v40
	s_nop 0
	v_add_f32_e32 v40, 1.0, v40
	v_rcp_f32_e32 v40, v40
	s_nop 0
	v_mul_f32_e32 v36, v36, v40
	v_mul_f32_e32 v40, v32, v36
	v_mul_f32_e32 v36, v45, v50
	v_exp_f32_e32 v36, v36
	v_mul_f32_e32 v32, v45, v51
	v_add_f32_e32 v36, 1.0, v36
	v_rcp_f32_e32 v36, v36
	s_nop 0
	v_mul_f32_e32 v32, v32, v36
	v_mul_f32_e32 v32, v37, v32
	v_mul_f32_e32 v37, v41, v50
	v_exp_f32_e32 v37, v37
	v_mul_f32_e32 v36, v41, v51
	v_cvt_pk_bf16_f32 v32, v44, v32
	v_add_f32_e32 v37, 1.0, v37
	v_rcp_f32_e32 v37, v37
	s_nop 0
	v_mul_f32_e32 v36, v36, v37
	v_mul_f32_e32 v41, v33, v36
	v_mul_f32_e32 v36, v46, v50
	v_exp_f32_e32 v36, v36
	v_mul_f32_e32 v37, v42, v50
	v_exp_f32_e32 v37, v37
	v_mul_f32_e32 v33, v46, v51
	v_add_f32_e32 v36, 1.0, v36
	v_rcp_f32_e32 v36, v36
	v_add_f32_e32 v37, 1.0, v37
	v_rcp_f32_e32 v37, v37
	v_mul_f32_e32 v33, v33, v36
	v_mul_f32_e32 v36, v42, v51
	v_mul_f32_e32 v36, v36, v37
	v_mul_f32_e32 v33, v38, v33
	v_mul_f32_e32 v38, v34, v36
	v_mul_f32_e32 v36, v47, v50
	v_exp_f32_e32 v36, v36
	v_mul_f32_e32 v37, v43, v50
	v_exp_f32_e32 v37, v37
	v_mul_f32_e32 v34, v47, v51
	v_add_f32_e32 v36, 1.0, v36
	v_rcp_f32_e32 v36, v36
	v_add_f32_e32 v37, 1.0, v37
	v_rcp_f32_e32 v37, v37
	v_mul_f32_e32 v34, v34, v36
	v_mul_f32_e32 v36, v43, v51
	v_mul_f32_e32 v36, v36, v37
	v_mul_f32_e32 v34, v39, v34
	v_mul_f32_e32 v35, v35, v36
	v_lshl_add_u64 v[36:37], v[48:49], 0, v[112:113]
; __device__ __forceinline__ float fast_rcp(float x) { return __builtin_amdgcn_rcpf(x); }
; __device__ __forceinline__ float fast_exp2(float x) { return __builtin_amdgcn_exp2f(x); }
; #define PG8_WAIT_V(n) asm volatile("s_waitcnt vmcnt(" #n ")" ::: "memory")
; #define PG8_BAR __builtin_amdgcn_s_barrier()
; __device__ __forceinline__ u32x4 pack8(f32x4 v0, f32x4 v1) { u32x4 w; w.x = cvt_pk_bf16(v0[0], v0[1]); w.y = cvt_pk_bf16(v0[2], v0[3]); w.z = cvt_pk_bf16(v1[0], v1[1]); w.w = cvt_pk_bf16(v1[2], v1[3]); return w; }
; template <class Epi>
; __device__ __forceinline__ void gemm_phase(LAS unsigned char* lds, const Gemm g, const StaticOrder& S, const Epi& E) {
;     ...
;         if (!has_next) break;
; #pragma unroll
;         for (int a = 0; a < 2; ++a)
; #pragma unroll
;             for (int b = 0; b < 2; ++b)
; #pragma unroll
;                 for (int m = 0; m < 4; ++m)
; #pragma unroll
;                     for (int n = 0; n < 2; ++n) acc[a][b][m][n] = (f32x4){0.f, 0.f, 0.f, 0.f};
;         cur = nxt; cA = nA; cB = nB; ++ui;
;     }
;     PG8_WAIT_V(0);
;     if (wr == 0) PG8_BAR;
;     PG8_BAR;
;     __device__ __forceinline__ void operator()(const f32x4 (&acc)[2][2][4][2], const Unit& u, int wr, int wc, int fr, int fq) const {
;         const int row0 = u.pm * BM + wr * 64 + fr, col0 = u.pn * HALF + wc * 32 + 8 * fq;
; #pragma unroll
;         for (int ai = 0; ai < 2; ++ai)
; #pragma unroll
;             for (int m = 0; m < 4; ++m) { bf16_t* rowp = O + (size_t)(row0 + ai * HALF + m * 16) * DFF + col0;
;                 const float r = rs[row0 + ai * HALF + m * 16], r2 = r * r;
;                 f32x4 h0, h1;
; #pragma unroll
;                 for (int j = 0; j < 4; ++j) {
;                     const float g0 = acc[ai][0][m][0][j], g1 = acc[ai][0][m][1][j];
;                     h0[j] = g0 * r2 * fast_rcp(1.0f + fast_exp2(g0 * (-LOG2E * r))) * acc[ai][1][m][0][j];
;                     h1[j] = g1 * r2 * fast_rcp(1.0f + fast_exp2(g1 * (-LOG2E * r))) * acc[ai][1][m][1][j]; }
;                 *(u32x4*)rowp = pack8(h0, h1); }
	v_cvt_pk_bf16_f32 v33, v33, v34
	v_cvt_pk_bf16_f32 v34, v40, v41
	v_cvt_pk_bf16_f32 v35, v38, v35
	global_store_dwordx4 v[36:37], v[32:35], off
	s_nop 1
	v_mov_b32_e32 v34, v209
	s_nop 0
	v_add_u32_e32 v32, 0xa0, v144
	v_mad_i64_i32 v[32:33], s[42:43], v32, s49, v[146:147]
	v_mul_f32_e32 v35, v34, v34
	v_mul_f32_e32 v34, 0xbfb8aa3b, v34
	v_mul_f32_e32 v36, v28, v35
	v_mul_f32_e32 v28, v28, v34
	v_exp_f32_e32 v28, v28
	s_nop 0
	v_add_f32_e32 v28, 1.0, v28
	v_rcp_f32_e32 v28, v28
	s_nop 0
	v_mul_f32_e32 v28, v36, v28
	v_mul_f32_e32 v28, v20, v28
	v_mul_f32_e32 v20, v24, v35
	v_mul_f32_e32 v24, v24, v34
	v_exp_f32_e32 v24, v24
	s_nop 0
	v_add_f32_e32 v24, 1.0, v24
	v_rcp_f32_e32 v24, v24
	s_nop 0
	v_mul_f32_e32 v20, v20, v24
	v_mul_f32_e32 v24, v16, v20
	v_mul_f32_e32 v20, v29, v34
	v_exp_f32_e32 v20, v20
	v_mul_f32_e32 v16, v29, v35
	v_add_f32_e32 v20, 1.0, v20
	v_rcp_f32_e32 v20, v20
	s_nop 0
	v_mul_f32_e32 v16, v16, v20
	v_mul_f32_e32 v16, v21, v16
	v_mul_f32_e32 v21, v25, v34
	v_exp_f32_e32 v21, v21
	v_mul_f32_e32 v20, v25, v35
	v_cvt_pk_bf16_f32 v16, v28, v16
	v_add_f32_e32 v21, 1.0, v21
	v_rcp_f32_e32 v21, v21
	s_nop 0
	v_mul_f32_e32 v20, v20, v21
	v_mul_f32_e32 v25, v17, v20
	v_mul_f32_e32 v20, v30, v34
	v_exp_f32_e32 v20, v20
	v_mul_f32_e32 v21, v26, v34
	v_exp_f32_e32 v21, v21
	v_mul_f32_e32 v17, v30, v35
	v_add_f32_e32 v20, 1.0, v20
	v_rcp_f32_e32 v20, v20
	v_add_f32_e32 v21, 1.0, v21
	v_rcp_f32_e32 v21, v21
	v_mul_f32_e32 v17, v17, v20
	v_mul_f32_e32 v20, v26, v35
	v_mul_f32_e32 v20, v20, v21
	v_mul_f32_e32 v17, v22, v17
	v_mul_f32_e32 v22, v18, v20
	v_mul_f32_e32 v20, v31, v34
	v_exp_f32_e32 v20, v20
	v_mul_f32_e32 v21, v27, v34
	v_exp_f32_e32 v21, v21
	v_mul_f32_e32 v18, v31, v35
	v_add_f32_e32 v20, 1.0, v20
	v_rcp_f32_e32 v20, v20
	v_add_f32_e32 v21, 1.0, v21
	v_rcp_f32_e32 v21, v21
	v_mul_f32_e32 v18, v18, v20
	v_mul_f32_e32 v20, v27, v35
	v_mul_f32_e32 v20, v20, v21
	v_mul_f32_e32 v18, v23, v18
	v_mul_f32_e32 v19, v19, v20
	v_lshl_add_u64 v[20:21], v[32:33], 0, v[112:113]
	v_cvt_pk_bf16_f32 v17, v17, v18
	v_cvt_pk_bf16_f32 v18, v24, v25
	v_cvt_pk_bf16_f32 v19, v22, v19
	global_store_dwordx4 v[20:21], v[16:19], off
	s_nop 1
	v_mov_b32_e32 v18, v210
	s_nop 0
	v_add_u32_e32 v16, 0xb0, v144
	v_mad_i64_i32 v[16:17], s[42:43], v16, s49, v[146:147]
	s_mov_b64 s[42:43], s[26:27]
	v_mul_f32_e32 v19, v18, v18
	v_mul_f32_e32 v18, 0xbfb8aa3b, v18
	v_mul_f32_e32 v20, v12, v19
	v_mul_f32_e32 v12, v12, v18
	v_exp_f32_e32 v12, v12
	s_nop 0
	v_add_f32_e32 v12, 1.0, v12
	v_rcp_f32_e32 v12, v12
	s_nop 0
	v_mul_f32_e32 v12, v20, v12
	v_mul_f32_e32 v12, v4, v12
	v_mul_f32_e32 v4, v8, v19
	v_mul_f32_e32 v8, v8, v18
	v_exp_f32_e32 v8, v8
	s_nop 0
	v_add_f32_e32 v8, 1.0, v8
	v_rcp_f32_e32 v8, v8
	s_nop 0
	v_mul_f32_e32 v4, v4, v8
	v_mul_f32_e32 v8, v0, v4
	v_mul_f32_e32 v4, v13, v18
	v_exp_f32_e32 v4, v4
	v_mul_f32_e32 v0, v13, v19
	v_add_f32_e32 v4, 1.0, v4
	v_rcp_f32_e32 v4, v4
	s_nop 0
	v_mul_f32_e32 v0, v0, v4
	v_mul_f32_e32 v0, v5, v0
	v_mul_f32_e32 v5, v9, v18
	v_exp_f32_e32 v5, v5
	v_mul_f32_e32 v4, v9, v19
	v_cvt_pk_bf16_f32 v0, v12, v0
	v_add_f32_e32 v5, 1.0, v5
	v_rcp_f32_e32 v5, v5
	s_nop 0
	v_mul_f32_e32 v4, v4, v5
	v_mul_f32_e32 v9, v1, v4
	v_mul_f32_e32 v4, v14, v18
	v_exp_f32_e32 v4, v4
	v_mul_f32_e32 v5, v10, v18
	v_exp_f32_e32 v5, v5
	v_mul_f32_e32 v1, v14, v19
	v_add_f32_e32 v4, 1.0, v4
	v_rcp_f32_e32 v4, v4
	v_add_f32_e32 v5, 1.0, v5
	v_rcp_f32_e32 v5, v5
	v_mul_f32_e32 v1, v1, v4
	v_mul_f32_e32 v4, v10, v19
	v_mul_f32_e32 v4, v4, v5
	v_mul_f32_e32 v1, v6, v1
	v_mul_f32_e32 v6, v2, v4
	v_mul_f32_e32 v4, v15, v18
	v_exp_f32_e32 v4, v4
	v_mul_f32_e32 v5, v11, v18
	v_exp_f32_e32 v5, v5
	v_mul_f32_e32 v2, v15, v19
	v_add_f32_e32 v4, 1.0, v4
	v_rcp_f32_e32 v4, v4
	v_add_f32_e32 v5, 1.0, v5
	v_rcp_f32_e32 v5, v5
	v_mul_f32_e32 v2, v2, v4
	v_mul_f32_e32 v4, v11, v19
	v_mul_f32_e32 v4, v4, v5
	v_mul_f32_e32 v2, v7, v2
	v_mul_f32_e32 v3, v3, v4
	v_lshl_add_u64 v[4:5], v[16:17], 0, v[112:113]
	v_cvt_pk_bf16_f32 v1, v1, v2
	v_cvt_pk_bf16_f32 v2, v8, v9
	v_cvt_pk_bf16_f32 v3, v6, v3
	global_store_dwordx4 v[4:5], v[0:3], off
	s_cbranch_vccz .LBB0_200
	s_waitcnt vmcnt(0)
	s_cmpk_gt_u32 s3, 0xff
	s_cbranch_scc1 .LBB0_207
	s_barrier

; #define PG8_STAGE(bufoff, gbase, voff) do { _Pragma("unroll") for (int _i = 0; _i < 2; ++_i) \
;         __builtin_amdgcn_global_load_lds((const unsigned*)((const char*)(gbase) + (voff)[_i]), (LAS unsigned*)(lds + (bufoff) + ldsw + _i * 8192), 16, 0, 0); } while (0)
; #define PG8_LDA(dst, b, h) do { _Pragma("unroll") for (int m = 0; m < 4; ++m) _Pragma("unroll") for (int k = 0; k < 2; ++k) dst[m][k] = *(const LAS bf16x8*)(lds + PG8_SA(b, h) + aoff + m * 2048 + k * 1024); } while (0)
; #define PG8_LDB(dst, b, h) do { _Pragma("unroll") for (int n = 0; n < 2; ++n) _Pragma("unroll") for (int k = 0; k < 2; ++k) dst[n][k] = *(const LAS bf16x8*)(lds + PG8_SB(b, h) + boff + n * 2048 + k * 1024); } while (0)
; #define PG8_MMA(ai, bj, At, Bt) do { __builtin_amdgcn_s_setprio(1); _Pragma("unroll") for (int m = 0; m < 4; ++m) _Pragma("unroll") for (int n = 0; n < 2; ++n) _Pragma("unroll") for (int k = 0; k < 2; ++k) \
;         acc[ai][bj][m][n] = __builtin_amdgcn_mfma_f32_16x16x32_bf16(Bt[n][k], At[m][k], acc[ai][bj][m][n], 0, 0, 0); __builtin_amdgcn_s_setprio(0); } while (0)
; #define PG8_WAIT_V(n) asm volatile("s_waitcnt vmcnt(" #n ")" ::: "memory")
; #define PG8_WAIT_L(n) asm volatile("s_waitcnt lgkmcnt(" #n ")" ::: "memory")
; template <class Epi>
; __device__ __forceinline__ void gemm_phase(LAS unsigned char* lds, const Gemm g, const StaticOrder& S, const Epi& E) {
;     ...
;         for (int t = 0; t < nt; t += 2) {
;             const bool last = (t == nt - 2);
;             const char* a1 = cA + (size_t)(t + 1) * kstep;
;             const char* a2 = last ? nA : cA + (size_t)(t + 2) * kstep; const char* b2 = last ? nB : cB + (size_t)(t + 2) * kstep;
;             const char* a3 = a2 + kstep; const char* b3 = b2 + kstep;
;             PG8_LDB(B0, 0, 0); PG8_SCHED; PG8_LDA(At, 0, 0); PG8_STAGE(PG8_SA(1, 1), a1 + hstep, voffA);
;             PG8_WAIT_L(8); PG8_BAR; PG8_WAIT_L(0); PG8_MMA(0, 0, At, B0); PG8_BAR; PG8_SCHED;
;             PG8_LDB(B1, 0, 1); PG8_STAGE(PG8_SB(0, 0), b2, voffB);
;             PG8_BAR; PG8_WAIT_L(0); PG8_MMA(0, 1, At, B1); PG8_BAR;
;             PG8_LDA(At, 0, 1); PG8_STAGE(PG8_SA(0, 0), a2, voffA);
;             PG8_BAR; PG8_WAIT_L(0); PG8_MMA(1, 0, At, B0); PG8_BAR; PG8_SCHED;
;             PG8_STAGE(PG8_SB(0, 1), b2 + hstep, voffB);
;             PG8_WAIT_V(6); PG8_BAR; PG8_MMA(1, 1, At, B1); PG8_BAR;
.LBB0_283:
	ds_read_b128 v[148:151], v145
	ds_read_b128 v[152:155], v145 offset:1024
	ds_read_b128 v[160:163], v145 offset:2048
	ds_read_b128 v[164:167], v145 offset:3072
	s_add_u32 s50, s48, 0x100
	s_addc_u32 s51, s49, 0
	s_cmpk_eq_i32 s65, 0x54
	s_cselect_b32 s55, s47, s51
	s_cselect_b32 s54, s46, s50
	s_cselect_b32 s53, s5, s64
	s_cselect_b32 s52, s4, s63
	s_add_i32 m0, s23, 0xc000
	ds_read_b128 v[168:171], v146
	ds_read_b128 v[172:175], v146 offset:1024
	ds_read_b128 v[176:179], v146 offset:2048
	ds_read_b128 v[180:183], v146 offset:3072
	ds_read_b128 v[184:187], v146 offset:4096
	ds_read_b128 v[188:191], v146 offset:5120
	ds_read_b128 v[192:195], v146 offset:6144
	ds_read_b128 v[196:199], v146 offset:7168
	global_load_lds_dwordx4 v136, s[48:49]
	s_add_i32 m0, s23, 0xe000
	s_nop 0
	global_load_lds_dwordx4 v138, s[48:49]
	s_waitcnt lgkmcnt(8)
	s_barrier
	s_waitcnt lgkmcnt(0)
	v_mfma_f32_16x16x32_bf16 v[124:127], v[148:151], v[168:171], v[124:127]
	v_mfma_f32_16x16x32_bf16 v[120:123], v[160:163], v[168:171], v[120:123]
	v_mfma_f32_16x16x32_bf16 v[112:115], v[148:151], v[176:179], v[112:115]
	v_mfma_f32_16x16x32_bf16 v[104:107], v[160:163], v[176:179], v[104:107]
	v_mfma_f32_16x16x32_bf16 v[96:99], v[148:151], v[184:187], v[96:99]
	v_mfma_f32_16x16x32_bf16 v[88:91], v[160:163], v[184:187], v[88:91]
	v_mfma_f32_16x16x32_bf16 v[80:83], v[148:151], v[192:195], v[80:83]
	v_mfma_f32_16x16x32_bf16 v[72:75], v[160:163], v[192:195], v[72:75]
	v_mfma_f32_16x16x32_bf16 v[124:127], v[152:155], v[172:175], v[124:127]
	v_mfma_f32_16x16x32_bf16 v[120:123], v[164:167], v[172:175], v[120:123]
	v_mfma_f32_16x16x32_bf16 v[112:115], v[152:155], v[180:183], v[112:115]
	v_mfma_f32_16x16x32_bf16 v[104:107], v[164:167], v[180:183], v[104:107]
	v_mfma_f32_16x16x32_bf16 v[96:99], v[152:155], v[188:191], v[96:99]
	v_mfma_f32_16x16x32_bf16 v[88:91], v[164:167], v[188:191], v[88:91]
	v_mfma_f32_16x16x32_bf16 v[80:83], v[152:155], v[196:199], v[80:83]
	v_mfma_f32_16x16x32_bf16 v[72:75], v[164:167], v[196:199], v[72:75]
	s_barrier
	s_add_i32 s48, s39, s13
	s_add_u32 s98, s52, s6
	s_addc_u32 s99, s53, s7
	s_mov_b32 m0, s48
	ds_read_b128 v[200:203], v147
	ds_read_b128 v[204:207], v147 offset:1024
	ds_read_b128 v[208:211], v147 offset:2048
	ds_read_b128 v[212:215], v147 offset:3072
	global_load_lds_dwordx4 v132, s[52:53]
	s_add_i32 m0, s48, 0x2000
	s_nop 0
	global_load_lds_dwordx4 v128, s[52:53]
	s_barrier
	s_waitcnt lgkmcnt(0)
	v_mfma_f32_16x16x32_bf16 v[116:119], v[200:203], v[168:171], v[116:119]
	v_mfma_f32_16x16x32_bf16 v[108:111], v[208:211], v[168:171], v[108:111]
	v_mfma_f32_16x16x32_bf16 v[100:103], v[200:203], v[176:179], v[100:103]
	v_mfma_f32_16x16x32_bf16 v[92:95], v[208:211], v[176:179], v[92:95]
	v_mfma_f32_16x16x32_bf16 v[84:87], v[200:203], v[184:187], v[84:87]
	v_mfma_f32_16x16x32_bf16 v[76:79], v[208:211], v[184:187], v[76:79]
	v_mfma_f32_16x16x32_bf16 v[68:71], v[200:203], v[192:195], v[68:71]
	v_mfma_f32_16x16x32_bf16 v[64:67], v[208:211], v[192:195], v[64:67]
	v_mfma_f32_16x16x32_bf16 v[116:119], v[204:207], v[172:175], v[116:119]
	v_mfma_f32_16x16x32_bf16 v[108:111], v[212:215], v[172:175], v[108:111]
	v_mfma_f32_16x16x32_bf16 v[100:103], v[204:207], v[180:183], v[100:103]
	v_mfma_f32_16x16x32_bf16 v[92:95], v[212:215], v[180:183], v[92:95]
	v_mfma_f32_16x16x32_bf16 v[84:87], v[204:207], v[188:191], v[84:87]
	v_mfma_f32_16x16x32_bf16 v[76:79], v[212:215], v[188:191], v[76:79]
	v_mfma_f32_16x16x32_bf16 v[68:71], v[204:207], v[196:199], v[68:71]
	v_mfma_f32_16x16x32_bf16 v[64:67], v[212:215], v[196:199], v[64:67]
	s_mov_b32 m0, s23
	s_add_u32 s100, s54, s6
	s_addc_u32 s101, s55, s7
	s_barrier
	ds_read_b128 v[168:171], v146 offset:16384
	ds_read_b128 v[172:175], v146 offset:17408
	ds_read_b128 v[176:179], v146 offset:18432
	ds_read_b128 v[180:183], v146 offset:19456
	ds_read_b128 v[184:187], v146 offset:20480
	ds_read_b128 v[188:191], v146 offset:21504
	ds_read_b128 v[192:195], v146 offset:22528
	ds_read_b128 v[196:199], v146 offset:23552
	global_load_lds_dwordx4 v134, s[54:55]
	s_mov_b32 m0, s30
	s_nop 0
	global_load_lds_dwordx4 v130, s[54:55]
	s_barrier
	s_waitcnt lgkmcnt(0)
	v_mfma_f32_16x16x32_bf16 v[60:63], v[148:151], v[168:171], v[60:63]
	v_mfma_f32_16x16x32_bf16 v[56:59], v[160:163], v[168:171], v[56:59]
	v_mfma_f32_16x16x32_bf16 v[52:55], v[148:151], v[176:179], v[52:55]
	v_mfma_f32_16x16x32_bf16 v[44:47], v[160:163], v[176:179], v[44:47]
	v_mfma_f32_16x16x32_bf16 v[36:39], v[148:151], v[184:187], v[36:39]
	v_mfma_f32_16x16x32_bf16 v[28:31], v[160:163], v[184:187], v[28:31]
	v_mfma_f32_16x16x32_bf16 v[20:23], v[148:151], v[192:195], v[20:23]
	v_mfma_f32_16x16x32_bf16 v[12:15], v[160:163], v[192:195], v[12:15]
	v_mfma_f32_16x16x32_bf16 v[60:63], v[152:155], v[172:175], v[60:63]
	v_mfma_f32_16x16x32_bf16 v[56:59], v[164:167], v[172:175], v[56:59]
	v_mfma_f32_16x16x32_bf16 v[52:55], v[152:155], v[180:183], v[52:55]
	v_mfma_f32_16x16x32_bf16 v[44:47], v[164:167], v[180:183], v[44:47]
	v_mfma_f32_16x16x32_bf16 v[36:39], v[152:155], v[188:191], v[36:39]
	v_mfma_f32_16x16x32_bf16 v[28:31], v[164:167], v[188:191], v[28:31]
	v_mfma_f32_16x16x32_bf16 v[20:23], v[152:155], v[196:199], v[20:23]
	v_mfma_f32_16x16x32_bf16 v[12:15], v[164:167], v[196:199], v[12:15]
	s_barrier
	s_add_u32 s48, s52, 0x160000
	s_addc_u32 s49, s53, 0
	s_add_i32 s66, s40, s13
	s_mov_b32 m0, s66
	s_nop 0
	global_load_lds_dwordx4 v132, s[48:49]
	s_add_i32 m0, s66, 0x2000
	s_nop 0
	global_load_lds_dwordx4 v128, s[48:49]
	s_waitcnt vmcnt(6)
	s_barrier
; #define PG8_STAGE(bufoff, gbase, voff) do { _Pragma("unroll") for (int _i = 0; _i < 2; ++_i) \
;         __builtin_amdgcn_global_load_lds((const unsigned*)((const char*)(gbase) + (voff)[_i]), (LAS unsigned*)(lds + (bufoff) + ldsw + _i * 8192), 16, 0, 0); } while (0)
; #define PG8_LDA(dst, b, h) do { _Pragma("unroll") for (int m = 0; m < 4; ++m) _Pragma("unroll") for (int k = 0; k < 2; ++k) dst[m][k] = *(const LAS bf16x8*)(lds + PG8_SA(b, h) + aoff + m * 2048 + k * 1024); } while (0)
; #define PG8_LDB(dst, b, h) do { _Pragma("unroll") for (int n = 0; n < 2; ++n) _Pragma("unroll") for (int k = 0; k < 2; ++k) dst[n][k] = *(const LAS bf16x8*)(lds + PG8_SB(b, h) + boff + n * 2048 + k * 1024); } while (0)
; #define PG8_MMA(ai, bj, At, Bt) do { __builtin_amdgcn_s_setprio(1); _Pragma("unroll") for (int m = 0; m < 4; ++m) _Pragma("unroll") for (int n = 0; n < 2; ++n) _Pragma("unroll") for (int k = 0; k < 2; ++k) \
;         acc[ai][bj][m][n] = __builtin_amdgcn_mfma_f32_16x16x32_bf16(Bt[n][k], At[m][k], acc[ai][bj][m][n], 0, 0, 0); __builtin_amdgcn_s_setprio(0); } while (0)
; #define PG8_WAIT_V(n) asm volatile("s_waitcnt vmcnt(" #n ")" ::: "memory")
; #define PG8_WAIT_L(n) asm volatile("s_waitcnt lgkmcnt(" #n ")" ::: "memory")
; #define PG8_BAR __builtin_amdgcn_s_barrier()
; #define PG8_SCHED __builtin_amdgcn_sched_barrier(0)
; template <class Epi>
; __device__ __forceinline__ void gemm_phase(LAS unsigned char* lds, const Gemm g, const StaticOrder& S, const Epi& E) {
;     ...
;             PG8_WAIT_V(6); PG8_BAR; PG8_MMA(1, 1, At, B1); PG8_BAR;
;             PG8_LDB(B0, 1, 0); PG8_SCHED; PG8_LDA(At, 1, 0); PG8_STAGE(PG8_SA(0, 1), a2 + hstep, voffA);
;             PG8_WAIT_L(8); PG8_BAR; PG8_WAIT_L(0); PG8_MMA(0, 0, At, B0); PG8_BAR; PG8_SCHED;
;             PG8_LDB(B1, 1, 1); PG8_STAGE(PG8_SB(1, 0), b3, voffB);
;             PG8_BAR; PG8_WAIT_L(0); PG8_MMA(0, 1, At, B1); PG8_BAR;
;             PG8_LDA(At, 1, 1); PG8_STAGE(PG8_SA(1, 0), a3, voffA);
	v_mfma_f32_16x16x32_bf16 v[48:51], v[200:203], v[168:171], v[48:51]
	v_mfma_f32_16x16x32_bf16 v[40:43], v[208:211], v[168:171], v[40:43]
	v_mfma_f32_16x16x32_bf16 v[32:35], v[200:203], v[176:179], v[32:35]
	v_mfma_f32_16x16x32_bf16 v[24:27], v[208:211], v[176:179], v[24:27]
	v_mfma_f32_16x16x32_bf16 v[16:19], v[200:203], v[184:187], v[16:19]
	v_mfma_f32_16x16x32_bf16 v[8:11], v[208:211], v[184:187], v[8:11]
	v_mfma_f32_16x16x32_bf16 v[4:7], v[200:203], v[192:195], v[4:7]
	v_mfma_f32_16x16x32_bf16 v[0:3], v[208:211], v[192:195], v[0:3]
	v_mfma_f32_16x16x32_bf16 v[48:51], v[204:207], v[172:175], v[48:51]
	v_mfma_f32_16x16x32_bf16 v[40:43], v[212:215], v[172:175], v[40:43]
	v_mfma_f32_16x16x32_bf16 v[32:35], v[204:207], v[180:183], v[32:35]
	v_mfma_f32_16x16x32_bf16 v[24:27], v[212:215], v[180:183], v[24:27]
	v_mfma_f32_16x16x32_bf16 v[16:19], v[204:207], v[188:191], v[16:19]
	v_mfma_f32_16x16x32_bf16 v[8:11], v[212:215], v[188:191], v[8:11]
	v_mfma_f32_16x16x32_bf16 v[4:7], v[204:207], v[196:199], v[4:7]
	v_mfma_f32_16x16x32_bf16 v[0:3], v[212:215], v[196:199], v[0:3]
	s_add_i32 s66, 0, 0x18000
	v_add_u32_e32 v164, s66, v143
	s_barrier
	ds_read_b128 v[148:151], v164
	ds_read_b128 v[152:155], v164 offset:1024
	ds_read_b128 v[160:163], v164 offset:2048
	ds_read_b128 v[164:167], v164 offset:3072
	s_add_u32 s48, s54, 0x160000
	s_addc_u32 s49, s55, 0
	s_mov_b32 m0, s31
	ds_read_b128 v[168:171], v146 offset:32768
	ds_read_b128 v[172:175], v146 offset:33792
	ds_read_b128 v[176:179], v146 offset:34816
	ds_read_b128 v[180:183], v146 offset:35840
	ds_read_b128 v[184:187], v146 offset:36864
	ds_read_b128 v[188:191], v146 offset:37888
	ds_read_b128 v[192:195], v146 offset:38912
	ds_read_b128 v[196:199], v146 offset:39936
	global_load_lds_dwordx4 v134, s[48:49]
	s_mov_b32 m0, s33
	s_nop 0
	global_load_lds_dwordx4 v130, s[48:49]
	s_waitcnt lgkmcnt(8)
	s_barrier
	s_waitcnt lgkmcnt(0)
	v_mfma_f32_16x16x32_bf16 v[124:127], v[148:151], v[168:171], v[124:127]
	v_mfma_f32_16x16x32_bf16 v[120:123], v[160:163], v[168:171], v[120:123]
	v_mfma_f32_16x16x32_bf16 v[112:115], v[148:151], v[176:179], v[112:115]
	v_mfma_f32_16x16x32_bf16 v[104:107], v[160:163], v[176:179], v[104:107]
	v_mfma_f32_16x16x32_bf16 v[96:99], v[148:151], v[184:187], v[96:99]
	v_mfma_f32_16x16x32_bf16 v[88:91], v[160:163], v[184:187], v[88:91]
	v_mfma_f32_16x16x32_bf16 v[80:83], v[148:151], v[192:195], v[80:83]
	v_mfma_f32_16x16x32_bf16 v[72:75], v[160:163], v[192:195], v[72:75]
	v_mfma_f32_16x16x32_bf16 v[124:127], v[152:155], v[172:175], v[124:127]
	v_mfma_f32_16x16x32_bf16 v[120:123], v[164:167], v[172:175], v[120:123]
	v_mfma_f32_16x16x32_bf16 v[112:115], v[152:155], v[180:183], v[112:115]
	v_mfma_f32_16x16x32_bf16 v[104:107], v[164:167], v[180:183], v[104:107]
	v_mfma_f32_16x16x32_bf16 v[96:99], v[152:155], v[188:191], v[96:99]
	v_mfma_f32_16x16x32_bf16 v[88:91], v[164:167], v[188:191], v[88:91]
	v_mfma_f32_16x16x32_bf16 v[80:83], v[152:155], v[196:199], v[80:83]
	v_mfma_f32_16x16x32_bf16 v[72:75], v[164:167], v[196:199], v[72:75]
	s_barrier
	s_add_i32 s54, 0, 0x1c000
	s_add_i32 s48, s66, s13
	v_add_u32_e32 v212, s54, v143
	s_mov_b32 m0, s48
	ds_read_b128 v[200:203], v212
	ds_read_b128 v[204:207], v212 offset:1024
	ds_read_b128 v[208:211], v212 offset:2048
	ds_read_b128 v[212:215], v212 offset:3072
	global_load_lds_dwordx4 v132, s[98:99]
	s_add_i32 m0, s48, 0x2000
	s_nop 0
	global_load_lds_dwordx4 v128, s[98:99]
	s_barrier
	s_waitcnt lgkmcnt(0)
	v_mfma_f32_16x16x32_bf16 v[116:119], v[200:203], v[168:171], v[116:119]
	v_mfma_f32_16x16x32_bf16 v[108:111], v[208:211], v[168:171], v[108:111]
	v_mfma_f32_16x16x32_bf16 v[100:103], v[200:203], v[176:179], v[100:103]
	v_mfma_f32_16x16x32_bf16 v[92:95], v[208:211], v[176:179], v[92:95]
	v_mfma_f32_16x16x32_bf16 v[84:87], v[200:203], v[184:187], v[84:87]
	v_mfma_f32_16x16x32_bf16 v[76:79], v[208:211], v[184:187], v[76:79]
	v_mfma_f32_16x16x32_bf16 v[68:71], v[200:203], v[192:195], v[68:71]
	v_mfma_f32_16x16x32_bf16 v[64:67], v[208:211], v[192:195], v[64:67]
	v_mfma_f32_16x16x32_bf16 v[116:119], v[204:207], v[172:175], v[116:119]
	v_mfma_f32_16x16x32_bf16 v[108:111], v[212:215], v[172:175], v[108:111]
	v_mfma_f32_16x16x32_bf16 v[100:103], v[204:207], v[180:183], v[100:103]
	v_mfma_f32_16x16x32_bf16 v[92:95], v[212:215], v[180:183], v[92:95]
	v_mfma_f32_16x16x32_bf16 v[84:87], v[204:207], v[188:191], v[84:87]
	v_mfma_f32_16x16x32_bf16 v[76:79], v[212:215], v[188:191], v[76:79]
	v_mfma_f32_16x16x32_bf16 v[68:71], v[204:207], v[196:199], v[68:71]
	v_mfma_f32_16x16x32_bf16 v[64:67], v[212:215], v[196:199], v[64:67]
	s_mov_b32 m0, s34
	s_barrier
	ds_read_b128 v[168:171], v146 offset:49152
	ds_read_b128 v[172:175], v146 offset:50176
	ds_read_b128 v[176:179], v146 offset:51200
	ds_read_b128 v[180:183], v146 offset:52224
	ds_read_b128 v[184:187], v146 offset:53248
	ds_read_b128 v[188:191], v146 offset:54272
	ds_read_b128 v[192:195], v146 offset:55296
	ds_read_b128 v[196:199], v146 offset:56320
	global_load_lds_dwordx4 v134, s[100:101]
	s_mov_b32 m0, s36
	s_nop 0
	global_load_lds_dwordx4 v130, s[100:101]
	s_barrier
; #define PG8_STAGE(bufoff, gbase, voff) do { _Pragma("unroll") for (int _i = 0; _i < 2; ++_i) \
;         __builtin_amdgcn_global_load_lds((const unsigned*)((const char*)(gbase) + (voff)[_i]), (LAS unsigned*)(lds + (bufoff) + ldsw + _i * 8192), 16, 0, 0); } while (0)
; #define PG8_MMA(ai, bj, At, Bt) do { __builtin_amdgcn_s_setprio(1); _Pragma("unroll") for (int m = 0; m < 4; ++m) _Pragma("unroll") for (int n = 0; n < 2; ++n) _Pragma("unroll") for (int k = 0; k < 2; ++k) \
;         acc[ai][bj][m][n] = __builtin_amdgcn_mfma_f32_16x16x32_bf16(Bt[n][k], At[m][k], acc[ai][bj][m][n], 0, 0, 0); __builtin_amdgcn_s_setprio(0); } while (0)
; #define PG8_WAIT_V(n) asm volatile("s_waitcnt vmcnt(" #n ")" ::: "memory")
; #define PG8_WAIT_L(n) asm volatile("s_waitcnt lgkmcnt(" #n ")" ::: "memory")
; #define PG8_BAR __builtin_amdgcn_s_barrier()
; #define PG8_SCHED __builtin_amdgcn_sched_barrier(0)
; template <class Epi>
; __device__ __forceinline__ void gemm_phase(LAS unsigned char* lds, const Gemm g, const StaticOrder& S, const Epi& E) {
;     ...
;             PG8_BAR; PG8_WAIT_L(0); PG8_MMA(1, 0, At, B0); PG8_BAR; PG8_SCHED;
;             PG8_STAGE(PG8_SB(1, 1), b3 + hstep, voffB);
;             PG8_WAIT_V(6); PG8_BAR; PG8_MMA(1, 1, At, B1); PG8_BAR;
;         }
	s_waitcnt lgkmcnt(0)
	v_mfma_f32_16x16x32_bf16 v[60:63], v[148:151], v[168:171], v[60:63]
	v_mfma_f32_16x16x32_bf16 v[56:59], v[160:163], v[168:171], v[56:59]
	v_mfma_f32_16x16x32_bf16 v[52:55], v[148:151], v[176:179], v[52:55]
	v_mfma_f32_16x16x32_bf16 v[44:47], v[160:163], v[176:179], v[44:47]
	v_mfma_f32_16x16x32_bf16 v[36:39], v[148:151], v[184:187], v[36:39]
	v_mfma_f32_16x16x32_bf16 v[28:31], v[160:163], v[184:187], v[28:31]
	v_mfma_f32_16x16x32_bf16 v[20:23], v[148:151], v[192:195], v[20:23]
	v_mfma_f32_16x16x32_bf16 v[12:15], v[160:163], v[192:195], v[12:15]
	v_mfma_f32_16x16x32_bf16 v[60:63], v[152:155], v[172:175], v[60:63]
	v_mfma_f32_16x16x32_bf16 v[56:59], v[164:167], v[172:175], v[56:59]
	v_mfma_f32_16x16x32_bf16 v[52:55], v[152:155], v[180:183], v[52:55]
	v_mfma_f32_16x16x32_bf16 v[44:47], v[164:167], v[180:183], v[44:47]
	v_mfma_f32_16x16x32_bf16 v[36:39], v[152:155], v[188:191], v[36:39]
	v_mfma_f32_16x16x32_bf16 v[28:31], v[164:167], v[188:191], v[28:31]
	v_mfma_f32_16x16x32_bf16 v[20:23], v[152:155], v[196:199], v[20:23]
	v_mfma_f32_16x16x32_bf16 v[12:15], v[164:167], v[196:199], v[12:15]
	s_barrier
	s_add_u32 s48, s52, 0x160080
	s_addc_u32 s49, s53, 0
	s_add_i32 s52, s54, s13
	s_mov_b32 m0, s52
	s_nop 0
	global_load_lds_dwordx4 v132, s[48:49]
	s_add_i32 m0, s52, 0x2000
	s_nop 0
	global_load_lds_dwordx4 v128, s[48:49]
	s_waitcnt vmcnt(6)
	s_barrier
	v_mfma_f32_16x16x32_bf16 v[48:51], v[200:203], v[168:171], v[48:51]
	v_mfma_f32_16x16x32_bf16 v[40:43], v[208:211], v[168:171], v[40:43]
	v_mfma_f32_16x16x32_bf16 v[32:35], v[200:203], v[176:179], v[32:35]
	v_mfma_f32_16x16x32_bf16 v[24:27], v[208:211], v[176:179], v[24:27]
	v_mfma_f32_16x16x32_bf16 v[16:19], v[200:203], v[184:187], v[16:19]
	v_mfma_f32_16x16x32_bf16 v[8:11], v[208:211], v[184:187], v[8:11]
	v_mfma_f32_16x16x32_bf16 v[4:7], v[200:203], v[192:195], v[4:7]
	v_mfma_f32_16x16x32_bf16 v[0:3], v[208:211], v[192:195], v[0:3]
	v_mfma_f32_16x16x32_bf16 v[48:51], v[204:207], v[172:175], v[48:51]
	v_mfma_f32_16x16x32_bf16 v[40:43], v[212:215], v[172:175], v[40:43]
	v_mfma_f32_16x16x32_bf16 v[32:35], v[204:207], v[180:183], v[32:35]
	v_mfma_f32_16x16x32_bf16 v[24:27], v[212:215], v[180:183], v[24:27]
	v_mfma_f32_16x16x32_bf16 v[16:19], v[204:207], v[188:191], v[16:19]
	v_mfma_f32_16x16x32_bf16 v[8:11], v[212:215], v[188:191], v[8:11]
	v_mfma_f32_16x16x32_bf16 v[4:7], v[204:207], v[196:199], v[4:7]
	v_mfma_f32_16x16x32_bf16 v[0:3], v[212:215], v[196:199], v[0:3]
	s_add_i32 s65, s65, 2
	s_add_u32 s63, s63, 0x100
	s_addc_u32 s64, s64, 0
	s_cmpk_gt_u32 s65, 0x55
	s_mov_b64 s[48:49], s[50:51]
	s_barrier
	s_cbranch_scc0 .LBB0_283
; __device__ __forceinline__ u32x4 pack8(f32x4 v0, f32x4 v1) { u32x4 w; w.x = cvt_pk_bf16(v0[0], v0[1]); w.y = cvt_pk_bf16(v0[2], v0[3]); w.z = cvt_pk_bf16(v1[0], v1[1]); w.w = cvt_pk_bf16(v1[2], v1[3]); return w; }
; template <class Epi>
; __device__ __forceinline__ void gemm_phase(LAS unsigned char* lds, const Gemm g, const StaticOrder& S, const Epi& E) {
;     ...
;         E(acc, cur, wr, wc, fr, fq);
;         if (!has_next) break;
; #pragma unroll
;         for (int a = 0; a < 2; ++a)
; #pragma unroll
;             for (int b = 0; b < 2; ++b)
; #pragma unroll
;                 for (int m = 0; m < 4; ++m)
; #pragma unroll
;                     for (int n = 0; n < 2; ++n) acc[a][b][m][n] = (f32x4){0.f, 0.f, 0.f, 0.f};
;         cur = nxt; cA = nA; cB = nB; ++ui;
;     }
;     __device__ __forceinline__ void operator()(const f32x4 (&acc)[2][2][4][2], const Unit& u, int wr, int wc, int fr, int fq) const {
;         const int row0 = u.pm * BM + wr * 64 + fr, col0 = u.pn * BM + wc * 32 + 8 * fq;
; #pragma unroll
;         for (int ai = 0; ai < 2; ++ai)
; #pragma unroll
;             for (int m = 0; m < 4; ++m) { bf16_t* rowp = O + (size_t)(row0 + ai * HALF + m * 16) * ldc + col0;
; #pragma unroll
;                 for (int bj = 0; bj < 2; ++bj) *(u32x4*)(rowp + bj * HALF) = pack8(acc[ai][bj][m][0], acc[ai][bj][m][1]); }
	v_lshl_add_u32 v148, s61, 8, v142
	v_lshl_or_b32 v140, s62, 8, v144
	v_ashrrev_i32_e32 v149, 31, v148
	v_ashrrev_i32_e32 v141, 31, v140
	v_lshlrev_b64 v[150:151], 12, v[148:149]
	v_lshl_add_u64 v[150:151], s[24:25], 0, v[150:151]
	v_lshlrev_b64 v[152:153], 1, v[140:141]
	v_lshl_add_u64 v[140:141], v[150:151], 0, v[152:153]
	v_cvt_pk_bf16_f32 v124, v124, v125
	v_cvt_pk_bf16_f32 v125, v126, v127
	v_cvt_pk_bf16_f32 v126, v120, v121
	v_cvt_pk_bf16_f32 v127, v122, v123
	global_store_dwordx4 v[140:141], v[124:127], off
	v_cvt_pk_bf16_f32 v116, v116, v117
	v_cvt_pk_bf16_f32 v117, v118, v119
	v_cvt_pk_bf16_f32 v118, v108, v109
	v_or_b32_e32 v108, 16, v148
	v_ashrrev_i32_e32 v109, 31, v108
	v_lshlrev_b64 v[108:109], 12, v[108:109]
	v_lshl_add_u64 v[108:109], s[24:25], 0, v[108:109]
	v_cvt_pk_bf16_f32 v119, v110, v111
	global_store_dwordx4 v[140:141], v[116:119], off offset:256
	s_mov_b32 s62, s59
	s_mov_b32 s61, s60
	v_lshl_add_u64 v[116:117], v[108:109], 0, v[152:153]
	v_cvt_pk_bf16_f32 v108, v112, v113
	v_cvt_pk_bf16_f32 v109, v114, v115
	v_cvt_pk_bf16_f32 v110, v104, v105
	v_cvt_pk_bf16_f32 v111, v106, v107
	global_store_dwordx4 v[116:117], v[108:111], off
	v_cvt_pk_bf16_f32 v100, v100, v101
	v_cvt_pk_bf16_f32 v101, v102, v103
	v_cvt_pk_bf16_f32 v102, v92, v93
	v_or_b32_e32 v92, 32, v148
	v_ashrrev_i32_e32 v93, 31, v92
	v_lshlrev_b64 v[92:93], 12, v[92:93]
	v_lshl_add_u64 v[92:93], s[24:25], 0, v[92:93]
	v_cvt_pk_bf16_f32 v103, v94, v95
	global_store_dwordx4 v[116:117], v[100:103], off offset:256
	s_mov_b64 s[50:51], s[4:5]
	s_mov_b64 s[48:49], s[46:47]
	v_lshl_add_u64 v[100:101], v[92:93], 0, v[152:153]
	v_cvt_pk_bf16_f32 v92, v96, v97
	v_cvt_pk_bf16_f32 v93, v98, v99
	v_cvt_pk_bf16_f32 v94, v88, v89
	v_cvt_pk_bf16_f32 v95, v90, v91
	global_store_dwordx4 v[100:101], v[92:95], off
	v_cvt_pk_bf16_f32 v84, v84, v85
	v_cvt_pk_bf16_f32 v85, v86, v87
	v_cvt_pk_bf16_f32 v86, v76, v77
	v_or_b32_e32 v76, 48, v148
	v_ashrrev_i32_e32 v77, 31, v76
	v_lshlrev_b64 v[76:77], 12, v[76:77]
	v_lshl_add_u64 v[76:77], s[24:25], 0, v[76:77]
	v_cvt_pk_bf16_f32 v87, v78, v79
	global_store_dwordx4 v[100:101], v[84:87], off offset:256
	s_nop 1
	v_lshl_add_u64 v[84:85], v[76:77], 0, v[152:153]
	v_cvt_pk_bf16_f32 v76, v80, v81
	v_cvt_pk_bf16_f32 v77, v82, v83
	v_cvt_pk_bf16_f32 v78, v72, v73
	v_cvt_pk_bf16_f32 v79, v74, v75
	global_store_dwordx4 v[84:85], v[76:79], off
	v_cvt_pk_bf16_f32 v68, v68, v69
	v_cvt_pk_bf16_f32 v69, v70, v71
	v_cvt_pk_bf16_f32 v70, v64, v65
	v_cvt_pk_bf16_f32 v71, v66, v67
	global_store_dwordx4 v[84:85], v[68:71], off offset:256
	v_cvt_pk_bf16_f32 v60, v60, v61
	v_cvt_pk_bf16_f32 v61, v62, v63
	v_cvt_pk_bf16_f32 v62, v56, v57
	v_add_co_u32_e32 v56, vcc, s41, v140
	v_lshl_add_u64 v[64:65], v[140:141], 0, s[8:9]
	s_nop 0
	v_addc_co_u32_e32 v57, vcc, 0, v141, vcc
	v_cvt_pk_bf16_f32 v63, v58, v59
	global_store_dwordx4 v[56:57], v[60:63], off
	v_cvt_pk_bf16_f32 v48, v48, v49
	v_cvt_pk_bf16_f32 v49, v50, v51
	v_cvt_pk_bf16_f32 v50, v40, v41
	v_cvt_pk_bf16_f32 v51, v42, v43
	global_store_dwordx4 v[64:65], v[48:51], off offset:256
	v_cvt_pk_bf16_f32 v40, v52, v53
	v_cvt_pk_bf16_f32 v41, v54, v55
	v_cvt_pk_bf16_f32 v42, v44, v45
	v_add_co_u32_e32 v44, vcc, s56, v140
	s_nop 0
	v_lshl_add_u64 v[48:49], v[140:141], 0, s[26:27]
	v_addc_co_u32_e32 v45, vcc, 0, v141, vcc
	v_cvt_pk_bf16_f32 v43, v46, v47
	global_store_dwordx4 v[44:45], v[40:43], off
	v_cvt_pk_bf16_f32 v32, v32, v33
	v_cvt_pk_bf16_f32 v33, v34, v35
	v_cvt_pk_bf16_f32 v34, v24, v25
	v_cvt_pk_bf16_f32 v35, v26, v27
	global_store_dwordx4 v[48:49], v[32:35], off offset:256
	v_cvt_pk_bf16_f32 v24, v36, v37
	v_cvt_pk_bf16_f32 v25, v38, v39
	v_cvt_pk_bf16_f32 v26, v28, v29
	v_add_co_u32_e32 v28, vcc, s57, v140
	s_nop 0
	v_lshl_add_u64 v[32:33], v[140:141], 0, s[28:29]
	v_addc_co_u32_e32 v29, vcc, 0, v141, vcc
	v_cvt_pk_bf16_f32 v27, v30, v31
	global_store_dwordx4 v[28:29], v[24:27], off
	v_cvt_pk_bf16_f32 v16, v16, v17
	v_cvt_pk_bf16_f32 v17, v18, v19
	v_cvt_pk_bf16_f32 v18, v8, v9
	v_cvt_pk_bf16_f32 v19, v10, v11
	global_store_dwordx4 v[32:33], v[16:19], off offset:256
	v_cvt_pk_bf16_f32 v8, v20, v21
	v_cvt_pk_bf16_f32 v9, v22, v23
	v_cvt_pk_bf16_f32 v10, v12, v13
	v_add_co_u32_e32 v12, vcc, s58, v140
	s_nop 0
	v_lshl_add_u64 v[16:17], v[140:141], 0, s[42:43]
	v_addc_co_u32_e32 v13, vcc, 0, v141, vcc
	s_and_b64 vcc, exec, s[44:45]
	v_cvt_pk_bf16_f32 v11, v14, v15
	global_store_dwordx4 v[12:13], v[8:11], off
	v_cvt_pk_bf16_f32 v4, v4, v5
	v_cvt_pk_bf16_f32 v5, v6, v7
	v_cvt_pk_bf16_f32 v6, v0, v1
	v_cvt_pk_bf16_f32 v7, v2, v3
	global_store_dwordx4 v[16:17], v[4:7], off offset:256
	s_cbranch_vccz .LBB0_276
	s_waitcnt vmcnt(0)
	s_cmpk_gt_u32 s3, 0xff
	v_readlane_b32 s62, v232, 20
	s_cbranch_scc1 .LBB0_287
	s_barrier

; #define PG8_STAGE(bufoff, gbase, voff) do { _Pragma("unroll") for (int _i = 0; _i < 2; ++_i) \
;         __builtin_amdgcn_global_load_lds((const unsigned*)((const char*)(gbase) + (voff)[_i]), (LAS unsigned*)(lds + (bufoff) + ldsw + _i * 8192), 16, 0, 0); } while (0)
; #define PG8_LDA(dst, b, h) do { _Pragma("unroll") for (int m = 0; m < 4; ++m) _Pragma("unroll") for (int k = 0; k < 2; ++k) dst[m][k] = *(const LAS bf16x8*)(lds + PG8_SA(b, h) + aoff + m * 2048 + k * 1024); } while (0)
; #define PG8_LDB(dst, b, h) do { _Pragma("unroll") for (int n = 0; n < 2; ++n) _Pragma("unroll") for (int k = 0; k < 2; ++k) dst[n][k] = *(const LAS bf16x8*)(lds + PG8_SB(b, h) + boff + n * 2048 + k * 1024); } while (0)
; #define PG8_MMA(ai, bj, At, Bt) do { __builtin_amdgcn_s_setprio(1); _Pragma("unroll") for (int m = 0; m < 4; ++m) _Pragma("unroll") for (int n = 0; n < 2; ++n) _Pragma("unroll") for (int k = 0; k < 2; ++k) \
;         acc[ai][bj][m][n] = __builtin_amdgcn_mfma_f32_16x16x32_bf16(Bt[n][k], At[m][k], acc[ai][bj][m][n], 0, 0, 0); __builtin_amdgcn_s_setprio(0); } while (0)
; #define PG8_WAIT_V(n) asm volatile("s_waitcnt vmcnt(" #n ")" ::: "memory")
; #define PG8_WAIT_L(n) asm volatile("s_waitcnt lgkmcnt(" #n ")" ::: "memory")
; template <class Epi>
; __device__ __forceinline__ void gemm_phase(LAS unsigned char* lds, const Gemm g, const StaticOrder& S, const Epi& E) {
;     ...
;         for (int t = 0; t < nt; t += 2) {
;             const bool last = (t == nt - 2);
;             const char* a1 = cA + (size_t)(t + 1) * kstep;
;             const char* a2 = last ? nA : cA + (size_t)(t + 2) * kstep; const char* b2 = last ? nB : cB + (size_t)(t + 2) * kstep;
;             const char* a3 = a2 + kstep; const char* b3 = b2 + kstep;
;             PG8_LDB(B0, 0, 0); PG8_SCHED; PG8_LDA(At, 0, 0); PG8_STAGE(PG8_SA(1, 1), a1 + hstep, voffA);
;             PG8_WAIT_L(8); PG8_BAR; PG8_WAIT_L(0); PG8_MMA(0, 0, At, B0); PG8_BAR; PG8_SCHED;
;             PG8_LDB(B1, 0, 1); PG8_STAGE(PG8_SB(0, 0), b2, voffB);
;             PG8_BAR; PG8_WAIT_L(0); PG8_MMA(0, 1, At, B1); PG8_BAR;
;             PG8_LDA(At, 0, 1); PG8_STAGE(PG8_SA(0, 0), a2, voffA);
;             PG8_BAR; PG8_WAIT_L(0); PG8_MMA(1, 0, At, B0); PG8_BAR; PG8_SCHED;
;             PG8_STAGE(PG8_SB(0, 1), b2 + hstep, voffB);
;             PG8_WAIT_V(6); PG8_BAR; PG8_MMA(1, 1, At, B1); PG8_BAR;
.LBB0_407:
	ds_read_b128 v[150:153], v164
	ds_read_b128 v[154:157], v164 offset:1024
	ds_read_b128 v[168:171], v164 offset:2048
	ds_read_b128 v[172:175], v164 offset:3072
	s_add_u32 s48, s46, 0xfff80080
	s_addc_u32 s49, s47, -1
	s_cmp_eq_u32 s57, 28
	s_cselect_b32 s51, s9, s49
	s_cselect_b32 s50, s45, s48
	s_cselect_b32 s49, s7, s56
	s_cselect_b32 s48, s54, s55
	s_add_i32 m0, s27, 0xc000
	ds_read_b128 v[176:179], v165
	ds_read_b128 v[180:183], v165 offset:1024
	ds_read_b128 v[184:187], v165 offset:2048
	ds_read_b128 v[188:191], v165 offset:3072
	ds_read_b128 v[192:195], v165 offset:4096
	ds_read_b128 v[196:199], v165 offset:5120
	ds_read_b128 v[200:203], v165 offset:6144
	ds_read_b128 v[204:207], v165 offset:7168
	global_load_lds_dwordx4 v142, s[46:47]
	s_add_i32 m0, s27, 0xe000
	s_nop 0
	global_load_lds_dwordx4 v144, s[46:47]
	s_waitcnt lgkmcnt(8)
	s_barrier
	s_waitcnt lgkmcnt(0)
	v_mfma_f32_16x16x32_bf16 v[124:127], v[150:153], v[176:179], v[124:127]
	v_mfma_f32_16x16x32_bf16 v[120:123], v[168:171], v[176:179], v[120:123]
	v_mfma_f32_16x16x32_bf16 v[108:111], v[150:153], v[184:187], v[108:111]
	v_mfma_f32_16x16x32_bf16 v[104:107], v[168:171], v[184:187], v[104:107]
	v_mfma_f32_16x16x32_bf16 v[92:95], v[150:153], v[192:195], v[92:95]
	v_mfma_f32_16x16x32_bf16 v[88:91], v[168:171], v[192:195], v[88:91]
	v_mfma_f32_16x16x32_bf16 v[76:79], v[150:153], v[200:203], v[76:79]
	v_mfma_f32_16x16x32_bf16 v[72:75], v[168:171], v[200:203], v[72:75]
	v_mfma_f32_16x16x32_bf16 v[124:127], v[154:157], v[180:183], v[124:127]
	v_mfma_f32_16x16x32_bf16 v[120:123], v[172:175], v[180:183], v[120:123]
	v_mfma_f32_16x16x32_bf16 v[108:111], v[154:157], v[188:191], v[108:111]
	v_mfma_f32_16x16x32_bf16 v[104:107], v[172:175], v[188:191], v[104:107]
	v_mfma_f32_16x16x32_bf16 v[92:95], v[154:157], v[196:199], v[92:95]
	v_mfma_f32_16x16x32_bf16 v[88:91], v[172:175], v[196:199], v[88:91]
	v_mfma_f32_16x16x32_bf16 v[76:79], v[154:157], v[204:207], v[76:79]
	v_mfma_f32_16x16x32_bf16 v[72:75], v[172:175], v[204:207], v[72:75]
	s_barrier
	s_add_i32 s58, s41, s23
	s_add_u32 s98, s48, s2
	s_addc_u32 s99, s49, s3
	s_mov_b32 m0, s58
	ds_read_b128 v[208:211], v166
	ds_read_b128 v[212:215], v166 offset:1024
	ds_read_b128 v[216:219], v166 offset:2048
	ds_read_b128 v[220:223], v166 offset:3072
	global_load_lds_dwordx4 v132, s[48:49]
	s_add_i32 m0, s58, 0x2000
	s_nop 0
	global_load_lds_dwordx4 v128, s[48:49]
	s_barrier
	s_waitcnt lgkmcnt(0)
	v_mfma_f32_16x16x32_bf16 v[116:119], v[208:211], v[176:179], v[116:119]
	v_mfma_f32_16x16x32_bf16 v[112:115], v[216:219], v[176:179], v[112:115]
	v_mfma_f32_16x16x32_bf16 v[100:103], v[208:211], v[184:187], v[100:103]
	v_mfma_f32_16x16x32_bf16 v[96:99], v[216:219], v[184:187], v[96:99]
	v_mfma_f32_16x16x32_bf16 v[84:87], v[208:211], v[192:195], v[84:87]
	v_mfma_f32_16x16x32_bf16 v[80:83], v[216:219], v[192:195], v[80:83]
	v_mfma_f32_16x16x32_bf16 v[68:71], v[208:211], v[200:203], v[68:71]
	v_mfma_f32_16x16x32_bf16 v[64:67], v[216:219], v[200:203], v[64:67]
	v_mfma_f32_16x16x32_bf16 v[116:119], v[212:215], v[180:183], v[116:119]
	v_mfma_f32_16x16x32_bf16 v[112:115], v[220:223], v[180:183], v[112:115]
	v_mfma_f32_16x16x32_bf16 v[100:103], v[212:215], v[188:191], v[100:103]
	v_mfma_f32_16x16x32_bf16 v[96:99], v[220:223], v[188:191], v[96:99]
	v_mfma_f32_16x16x32_bf16 v[84:87], v[212:215], v[196:199], v[84:87]
	v_mfma_f32_16x16x32_bf16 v[80:83], v[220:223], v[196:199], v[80:83]
	v_mfma_f32_16x16x32_bf16 v[68:71], v[212:215], v[204:207], v[68:71]
	v_mfma_f32_16x16x32_bf16 v[64:67], v[220:223], v[204:207], v[64:67]
	s_mov_b32 m0, s27
	s_add_u32 s100, s50, s2
	s_addc_u32 s101, s51, s3
	s_barrier
	ds_read_b128 v[176:179], v165 offset:16384
	ds_read_b128 v[180:183], v165 offset:17408
	ds_read_b128 v[184:187], v165 offset:18432
	ds_read_b128 v[188:191], v165 offset:19456
	ds_read_b128 v[192:195], v165 offset:20480
	ds_read_b128 v[196:199], v165 offset:21504
	ds_read_b128 v[200:203], v165 offset:22528
	ds_read_b128 v[204:207], v165 offset:23552
	global_load_lds_dwordx4 v134, s[50:51]
	s_mov_b32 m0, s30
	s_nop 0
	global_load_lds_dwordx4 v130, s[50:51]
	s_barrier
	s_waitcnt lgkmcnt(0)
	v_mfma_f32_16x16x32_bf16 v[60:63], v[150:153], v[176:179], v[60:63]
	v_mfma_f32_16x16x32_bf16 v[56:59], v[168:171], v[176:179], v[56:59]
	v_mfma_f32_16x16x32_bf16 v[44:47], v[150:153], v[184:187], v[44:47]
	v_mfma_f32_16x16x32_bf16 v[40:43], v[168:171], v[184:187], v[40:43]
	v_mfma_f32_16x16x32_bf16 v[28:31], v[150:153], v[192:195], v[28:31]
	v_mfma_f32_16x16x32_bf16 v[24:27], v[168:171], v[192:195], v[24:27]
	v_mfma_f32_16x16x32_bf16 v[12:15], v[150:153], v[200:203], v[12:15]
	v_mfma_f32_16x16x32_bf16 v[8:11], v[168:171], v[200:203], v[8:11]
	v_mfma_f32_16x16x32_bf16 v[60:63], v[154:157], v[180:183], v[60:63]
	v_mfma_f32_16x16x32_bf16 v[56:59], v[172:175], v[180:183], v[56:59]
	v_mfma_f32_16x16x32_bf16 v[44:47], v[154:157], v[188:191], v[44:47]
	v_mfma_f32_16x16x32_bf16 v[40:43], v[172:175], v[188:191], v[40:43]
	v_mfma_f32_16x16x32_bf16 v[28:31], v[154:157], v[196:199], v[28:31]
	v_mfma_f32_16x16x32_bf16 v[24:27], v[172:175], v[196:199], v[24:27]
	v_mfma_f32_16x16x32_bf16 v[12:15], v[154:157], v[204:207], v[12:15]
	v_mfma_f32_16x16x32_bf16 v[8:11], v[172:175], v[204:207], v[8:11]
	s_barrier
	s_add_u32 s58, s48, 0x80000
	s_addc_u32 s59, s49, 0
	s_add_i32 s60, s52, s23
	s_mov_b32 m0, s60
	s_nop 0
	global_load_lds_dwordx4 v132, s[58:59]
	s_add_i32 m0, s60, 0x2000
	s_nop 0
	global_load_lds_dwordx4 v128, s[58:59]
	s_waitcnt vmcnt(6)
	s_barrier
; #define PG8_STAGE(bufoff, gbase, voff) do { _Pragma("unroll") for (int _i = 0; _i < 2; ++_i) \
;         __builtin_amdgcn_global_load_lds((const unsigned*)((const char*)(gbase) + (voff)[_i]), (LAS unsigned*)(lds + (bufoff) + ldsw + _i * 8192), 16, 0, 0); } while (0)
; #define PG8_LDA(dst, b, h) do { _Pragma("unroll") for (int m = 0; m < 4; ++m) _Pragma("unroll") for (int k = 0; k < 2; ++k) dst[m][k] = *(const LAS bf16x8*)(lds + PG8_SA(b, h) + aoff + m * 2048 + k * 1024); } while (0)
; #define PG8_LDB(dst, b, h) do { _Pragma("unroll") for (int n = 0; n < 2; ++n) _Pragma("unroll") for (int k = 0; k < 2; ++k) dst[n][k] = *(const LAS bf16x8*)(lds + PG8_SB(b, h) + boff + n * 2048 + k * 1024); } while (0)
; #define PG8_MMA(ai, bj, At, Bt) do { __builtin_amdgcn_s_setprio(1); _Pragma("unroll") for (int m = 0; m < 4; ++m) _Pragma("unroll") for (int n = 0; n < 2; ++n) _Pragma("unroll") for (int k = 0; k < 2; ++k) \
;         acc[ai][bj][m][n] = __builtin_amdgcn_mfma_f32_16x16x32_bf16(Bt[n][k], At[m][k], acc[ai][bj][m][n], 0, 0, 0); __builtin_amdgcn_s_setprio(0); } while (0)
; #define PG8_WAIT_V(n) asm volatile("s_waitcnt vmcnt(" #n ")" ::: "memory")
; #define PG8_WAIT_L(n) asm volatile("s_waitcnt lgkmcnt(" #n ")" ::: "memory")
; #define PG8_BAR __builtin_amdgcn_s_barrier()
; #define PG8_SCHED __builtin_amdgcn_sched_barrier(0)
; template <class Epi>
; __device__ __forceinline__ void gemm_phase(LAS unsigned char* lds, const Gemm g, const StaticOrder& S, const Epi& E) {
;     ...
;             PG8_WAIT_V(6); PG8_BAR; PG8_MMA(1, 1, At, B1); PG8_BAR;
;             PG8_LDB(B0, 1, 0); PG8_SCHED; PG8_LDA(At, 1, 0); PG8_STAGE(PG8_SA(0, 1), a2 + hstep, voffA);
;             PG8_WAIT_L(8); PG8_BAR; PG8_WAIT_L(0); PG8_MMA(0, 0, At, B0); PG8_BAR; PG8_SCHED;
;             PG8_LDB(B1, 1, 1); PG8_STAGE(PG8_SB(1, 0), b3, voffB);
;             PG8_BAR; PG8_WAIT_L(0); PG8_MMA(0, 1, At, B1); PG8_BAR;
;             PG8_LDA(At, 1, 1); PG8_STAGE(PG8_SA(1, 0), a3, voffA);
	v_mfma_f32_16x16x32_bf16 v[52:55], v[208:211], v[176:179], v[52:55]
	v_mfma_f32_16x16x32_bf16 v[48:51], v[216:219], v[176:179], v[48:51]
	v_mfma_f32_16x16x32_bf16 v[36:39], v[208:211], v[184:187], v[36:39]
	v_mfma_f32_16x16x32_bf16 v[32:35], v[216:219], v[184:187], v[32:35]
	v_mfma_f32_16x16x32_bf16 v[20:23], v[208:211], v[192:195], v[20:23]
	v_mfma_f32_16x16x32_bf16 v[16:19], v[216:219], v[192:195], v[16:19]
	v_mfma_f32_16x16x32_bf16 v[4:7], v[208:211], v[200:203], v[4:7]
	v_mfma_f32_16x16x32_bf16 v[0:3], v[216:219], v[200:203], v[0:3]
	v_mfma_f32_16x16x32_bf16 v[52:55], v[212:215], v[180:183], v[52:55]
	v_mfma_f32_16x16x32_bf16 v[48:51], v[220:223], v[180:183], v[48:51]
	v_mfma_f32_16x16x32_bf16 v[36:39], v[212:215], v[188:191], v[36:39]
	v_mfma_f32_16x16x32_bf16 v[32:35], v[220:223], v[188:191], v[32:35]
	v_mfma_f32_16x16x32_bf16 v[20:23], v[212:215], v[196:199], v[20:23]
	v_mfma_f32_16x16x32_bf16 v[16:19], v[220:223], v[196:199], v[16:19]
	v_mfma_f32_16x16x32_bf16 v[4:7], v[212:215], v[204:207], v[4:7]
	v_mfma_f32_16x16x32_bf16 v[0:3], v[220:223], v[204:207], v[0:3]
	s_add_i32 s58, 0, 0x18000
	v_add_u32_e32 v136, s58, v161
	s_barrier
	ds_read_b128 v[150:153], v136
	ds_read_b128 v[154:157], v136 offset:1024
	ds_read_b128 v[168:171], v136 offset:2048
	ds_read_b128 v[172:175], v136 offset:3072
	s_add_u32 s50, s50, 0x80000
	s_addc_u32 s51, s51, 0
	s_mov_b32 m0, s31
	ds_read_b128 v[176:179], v165 offset:32768
	ds_read_b128 v[180:183], v165 offset:33792
	ds_read_b128 v[184:187], v165 offset:34816
	ds_read_b128 v[188:191], v165 offset:35840
	ds_read_b128 v[192:195], v165 offset:36864
	ds_read_b128 v[196:199], v165 offset:37888
	ds_read_b128 v[200:203], v165 offset:38912
	ds_read_b128 v[204:207], v165 offset:39936
	global_load_lds_dwordx4 v134, s[50:51]
	s_mov_b32 m0, s33
	s_nop 0
	global_load_lds_dwordx4 v130, s[50:51]
	s_waitcnt lgkmcnt(8)
	s_barrier
	s_waitcnt lgkmcnt(0)
	v_mfma_f32_16x16x32_bf16 v[124:127], v[150:153], v[176:179], v[124:127]
	v_mfma_f32_16x16x32_bf16 v[120:123], v[168:171], v[176:179], v[120:123]
	v_mfma_f32_16x16x32_bf16 v[108:111], v[150:153], v[184:187], v[108:111]
	v_mfma_f32_16x16x32_bf16 v[104:107], v[168:171], v[184:187], v[104:107]
	v_mfma_f32_16x16x32_bf16 v[92:95], v[150:153], v[192:195], v[92:95]
	v_mfma_f32_16x16x32_bf16 v[88:91], v[168:171], v[192:195], v[88:91]
	v_mfma_f32_16x16x32_bf16 v[76:79], v[150:153], v[200:203], v[76:79]
	v_mfma_f32_16x16x32_bf16 v[72:75], v[168:171], v[200:203], v[72:75]
	v_mfma_f32_16x16x32_bf16 v[124:127], v[154:157], v[180:183], v[124:127]
	v_mfma_f32_16x16x32_bf16 v[120:123], v[172:175], v[180:183], v[120:123]
	v_mfma_f32_16x16x32_bf16 v[108:111], v[154:157], v[188:191], v[108:111]
	v_mfma_f32_16x16x32_bf16 v[104:107], v[172:175], v[188:191], v[104:107]
	v_mfma_f32_16x16x32_bf16 v[92:95], v[154:157], v[196:199], v[92:95]
	v_mfma_f32_16x16x32_bf16 v[88:91], v[172:175], v[196:199], v[88:91]
	v_mfma_f32_16x16x32_bf16 v[76:79], v[154:157], v[204:207], v[76:79]
	v_mfma_f32_16x16x32_bf16 v[72:75], v[172:175], v[204:207], v[72:75]
	s_barrier
	s_add_i32 s50, 0, 0x1c000
	s_add_i32 s51, s58, s23
	v_add_u32_e32 v136, s50, v161
	s_mov_b32 m0, s51
	ds_read_b128 v[208:211], v136
	ds_read_b128 v[212:215], v136 offset:1024
	ds_read_b128 v[216:219], v136 offset:2048
	ds_read_b128 v[220:223], v136 offset:3072
	global_load_lds_dwordx4 v132, s[98:99]
	s_add_i32 m0, s51, 0x2000
	s_nop 0
	global_load_lds_dwordx4 v128, s[98:99]
	s_barrier
	s_waitcnt lgkmcnt(0)
	v_mfma_f32_16x16x32_bf16 v[116:119], v[208:211], v[176:179], v[116:119]
	v_mfma_f32_16x16x32_bf16 v[112:115], v[216:219], v[176:179], v[112:115]
	v_mfma_f32_16x16x32_bf16 v[100:103], v[208:211], v[184:187], v[100:103]
	v_mfma_f32_16x16x32_bf16 v[96:99], v[216:219], v[184:187], v[96:99]
	v_mfma_f32_16x16x32_bf16 v[84:87], v[208:211], v[192:195], v[84:87]
	v_mfma_f32_16x16x32_bf16 v[80:83], v[216:219], v[192:195], v[80:83]
	v_mfma_f32_16x16x32_bf16 v[68:71], v[208:211], v[200:203], v[68:71]
	v_mfma_f32_16x16x32_bf16 v[64:67], v[216:219], v[200:203], v[64:67]
	v_mfma_f32_16x16x32_bf16 v[116:119], v[212:215], v[180:183], v[116:119]
	v_mfma_f32_16x16x32_bf16 v[112:115], v[220:223], v[180:183], v[112:115]
	v_mfma_f32_16x16x32_bf16 v[100:103], v[212:215], v[188:191], v[100:103]
	v_mfma_f32_16x16x32_bf16 v[96:99], v[220:223], v[188:191], v[96:99]
	v_mfma_f32_16x16x32_bf16 v[84:87], v[212:215], v[196:199], v[84:87]
	v_mfma_f32_16x16x32_bf16 v[80:83], v[220:223], v[196:199], v[80:83]
	v_mfma_f32_16x16x32_bf16 v[68:71], v[212:215], v[204:207], v[68:71]
	v_mfma_f32_16x16x32_bf16 v[64:67], v[220:223], v[204:207], v[64:67]
	s_mov_b32 m0, s37
	s_barrier
	ds_read_b128 v[176:179], v165 offset:49152
	ds_read_b128 v[180:183], v165 offset:50176
	ds_read_b128 v[184:187], v165 offset:51200
	ds_read_b128 v[188:191], v165 offset:52224
	ds_read_b128 v[192:195], v165 offset:53248
	ds_read_b128 v[196:199], v165 offset:54272
	ds_read_b128 v[200:203], v165 offset:55296
	ds_read_b128 v[204:207], v165 offset:56320
	global_load_lds_dwordx4 v134, s[100:101]
	s_mov_b32 m0, s38
	s_nop 0
	global_load_lds_dwordx4 v130, s[100:101]
	s_barrier
; #define PG8_STAGE(bufoff, gbase, voff) do { _Pragma("unroll") for (int _i = 0; _i < 2; ++_i) \
;         __builtin_amdgcn_global_load_lds((const unsigned*)((const char*)(gbase) + (voff)[_i]), (LAS unsigned*)(lds + (bufoff) + ldsw + _i * 8192), 16, 0, 0); } while (0)
; #define PG8_MMA(ai, bj, At, Bt) do { __builtin_amdgcn_s_setprio(1); _Pragma("unroll") for (int m = 0; m < 4; ++m) _Pragma("unroll") for (int n = 0; n < 2; ++n) _Pragma("unroll") for (int k = 0; k < 2; ++k) \
;         acc[ai][bj][m][n] = __builtin_amdgcn_mfma_f32_16x16x32_bf16(Bt[n][k], At[m][k], acc[ai][bj][m][n], 0, 0, 0); __builtin_amdgcn_s_setprio(0); } while (0)
; #define PG8_WAIT_V(n) asm volatile("s_waitcnt vmcnt(" #n ")" ::: "memory")
; #define PG8_WAIT_L(n) asm volatile("s_waitcnt lgkmcnt(" #n ")" ::: "memory")
; #define PG8_BAR __builtin_amdgcn_s_barrier()
; #define PG8_SCHED __builtin_amdgcn_sched_barrier(0)
; __device__ __forceinline__ u32x4 pack8(f32x4 v0, f32x4 v1) { u32x4 w; w.x = cvt_pk_bf16(v0[0], v0[1]); w.y = cvt_pk_bf16(v0[2], v0[3]); w.z = cvt_pk_bf16(v1[0], v1[1]); w.w = cvt_pk_bf16(v1[2], v1[3]); return w; }
; template <class Epi>
; __device__ __forceinline__ void gemm_phase(LAS unsigned char* lds, const Gemm g, const StaticOrder& S, const Epi& E) {
;     ...
;             PG8_BAR; PG8_WAIT_L(0); PG8_MMA(1, 0, At, B0); PG8_BAR; PG8_SCHED;
;             PG8_STAGE(PG8_SB(1, 1), b3 + hstep, voffB);
;             PG8_WAIT_V(6); PG8_BAR; PG8_MMA(1, 1, At, B1); PG8_BAR;
;     __device__ __forceinline__ void operator()(const f32x4 (&acc)[2][2][4][2], const Unit& u, int wr, int wc, int fr, int fq) const {
;     ...
;             const int col0 = u.pn * BM + wc * 32 + 8 * fq; const float sc = (u.pn < 2) ? QSCALE : 1.0f;
; #pragma unroll
;             for (int ai = 0; ai < 2; ++ai)
; #pragma unroll
;                 for (int m = 0; m < 4; ++m) { bf16_t* rowp = O + (size_t)(row0 + ai * HALF + m * 16) * NQKV + col0; const float scr_ = sc * rowsc[row0 + ai * HALF + m * 16];
; #pragma unroll
;                     for (int bj = 0; bj < 2; ++bj) *(u32x4*)(rowp + bj * HALF) = pack8(acc[ai][bj][m][0] * scr_, acc[ai][bj][m][1] * scr_); }
	s_waitcnt lgkmcnt(0)
	v_mfma_f32_16x16x32_bf16 v[60:63], v[150:153], v[176:179], v[60:63]
	v_mfma_f32_16x16x32_bf16 v[56:59], v[168:171], v[176:179], v[56:59]
	v_mfma_f32_16x16x32_bf16 v[44:47], v[150:153], v[184:187], v[44:47]
	v_mfma_f32_16x16x32_bf16 v[40:43], v[168:171], v[184:187], v[40:43]
	v_mfma_f32_16x16x32_bf16 v[28:31], v[150:153], v[192:195], v[28:31]
	v_mfma_f32_16x16x32_bf16 v[24:27], v[168:171], v[192:195], v[24:27]
	v_mfma_f32_16x16x32_bf16 v[12:15], v[150:153], v[200:203], v[12:15]
	v_mfma_f32_16x16x32_bf16 v[8:11], v[168:171], v[200:203], v[8:11]
	v_mfma_f32_16x16x32_bf16 v[60:63], v[154:157], v[180:183], v[60:63]
	v_mfma_f32_16x16x32_bf16 v[56:59], v[172:175], v[180:183], v[56:59]
	v_mfma_f32_16x16x32_bf16 v[44:47], v[154:157], v[188:191], v[44:47]
	v_mfma_f32_16x16x32_bf16 v[40:43], v[172:175], v[188:191], v[40:43]
	v_mfma_f32_16x16x32_bf16 v[28:31], v[154:157], v[196:199], v[28:31]
	v_mfma_f32_16x16x32_bf16 v[24:27], v[172:175], v[196:199], v[24:27]
	v_mfma_f32_16x16x32_bf16 v[12:15], v[154:157], v[204:207], v[12:15]
	v_mfma_f32_16x16x32_bf16 v[8:11], v[172:175], v[204:207], v[8:11]
	s_barrier
	s_add_u32 s48, s48, 0x80080
	s_addc_u32 s49, s49, 0
	s_add_i32 s50, s50, s23
	s_mov_b32 m0, s50
	s_nop 0
	global_load_lds_dwordx4 v132, s[48:49]
	s_add_i32 m0, s50, 0x2000
	s_nop 0
	global_load_lds_dwordx4 v128, s[48:49]
	s_waitcnt vmcnt(6)
	s_barrier
	v_mfma_f32_16x16x32_bf16 v[52:55], v[208:211], v[176:179], v[52:55]
	v_mfma_f32_16x16x32_bf16 v[48:51], v[216:219], v[176:179], v[48:51]
	v_mfma_f32_16x16x32_bf16 v[36:39], v[208:211], v[184:187], v[36:39]
	v_mfma_f32_16x16x32_bf16 v[32:35], v[216:219], v[184:187], v[32:35]
	v_mfma_f32_16x16x32_bf16 v[20:23], v[208:211], v[192:195], v[20:23]
	v_mfma_f32_16x16x32_bf16 v[16:19], v[216:219], v[192:195], v[16:19]
	v_mfma_f32_16x16x32_bf16 v[4:7], v[208:211], v[200:203], v[4:7]
	v_mfma_f32_16x16x32_bf16 v[0:3], v[216:219], v[200:203], v[0:3]
	v_mfma_f32_16x16x32_bf16 v[52:55], v[212:215], v[180:183], v[52:55]
	v_mfma_f32_16x16x32_bf16 v[48:51], v[220:223], v[180:183], v[48:51]
	v_mfma_f32_16x16x32_bf16 v[36:39], v[212:215], v[188:191], v[36:39]
	v_mfma_f32_16x16x32_bf16 v[32:35], v[220:223], v[188:191], v[32:35]
	v_mfma_f32_16x16x32_bf16 v[20:23], v[212:215], v[196:199], v[20:23]
	v_mfma_f32_16x16x32_bf16 v[16:19], v[220:223], v[196:199], v[16:19]
	v_mfma_f32_16x16x32_bf16 v[4:7], v[212:215], v[204:207], v[4:7]
	v_mfma_f32_16x16x32_bf16 v[0:3], v[220:223], v[204:207], v[0:3]
	s_add_i32 s57, s57, 2
	s_add_u32 s46, s46, 0x100
	s_addc_u32 s47, s47, 0
	s_add_u32 s55, s55, 0x100
	s_addc_u32 s56, s56, 0
	s_cmp_gt_u32 s57, 29
	s_barrier
	s_cbranch_scc0 .LBB0_407
	v_lshl_add_u32 v154, s44, 8, v160
	s_add_i32 s9, s34, -6
	s_lshl_b32 s7, s34, 8
	s_cmp_gt_u32 s9, 11
	s_mov_b64 s[44:45], -1
	v_ashrrev_i32_e32 v155, 31, v154
	v_or_b32_e32 v174, 16, v154
	v_or_b32_e32 v173, 32, v154
	v_or_b32_e32 v172, 48, v154
	v_add_u32_e32 v171, 0x80, v154
	v_add_u32_e32 v170, 0x90, v154
	v_add_u32_e32 v169, 0xa0, v154
	v_add_u32_e32 v168, 0xb0, v154
	s_cbranch_scc0 .LBB0_410
	v_lshl_add_u64 v[150:151], v[154:155], 2, s[14:15]
	global_load_dword v136, v[150:151], off
	global_load_dword v204, v[150:151], off offset:64
	global_load_dword v205, v[150:151], off offset:128
	global_load_dword v206, v[150:151], off offset:192
	global_load_dword v207, v[150:151], off offset:512
	global_load_dword v208, v[150:151], off offset:576
	global_load_dword v209, v[150:151], off offset:640
	global_load_dword v210, v[150:151], off offset:704
	s_cmp_lt_i32 s34, 2
	v_or_b32_e32 v156, s7, v162
	s_cselect_b64 vcc, -1, 0
	v_mov_b64_e32 v[152:153], s[20:21]
	v_cndmask_b32_e32 v175, 1.0, v167, vcc
	v_ashrrev_i32_e32 v157, 31, v156
	v_mad_i64_i32 v[176:177], s[44:45], v154, s53, v[152:153]
	v_lshlrev_b64 v[156:157], 1, v[156:157]
	v_lshl_add_u64 v[180:181], v[176:177], 0, v[156:157]
	s_waitcnt vmcnt(0)
	v_mul_f32_e32 v136, v175, v136
	v_pk_mul_f32 v[178:179], v[126:127], v[136:137] op_sel_hi:[1,0]
	v_pk_mul_f32 v[176:177], v[124:125], v[136:137] op_sel_hi:[1,0]
	v_pk_mul_f32 v[182:183], v[122:123], v[136:137] op_sel_hi:[1,0]
	v_pk_mul_f32 v[184:185], v[120:121], v[136:137] op_sel_hi:[1,0]
	v_cvt_pk_bf16_f32 v176, v176, v177
	v_cvt_pk_bf16_f32 v177, v178, v179
	v_pk_mul_f32 v[186:187], v[118:119], v[136:137] op_sel_hi:[1,0]
	v_cvt_pk_bf16_f32 v178, v184, v185
	v_cvt_pk_bf16_f32 v179, v182, v183
	v_pk_mul_f32 v[188:189], v[116:117], v[136:137] op_sel_hi:[1,0]
	v_pk_mul_f32 v[190:191], v[114:115], v[136:137] op_sel_hi:[1,0]
	v_pk_mul_f32 v[192:193], v[112:113], v[136:137] op_sel_hi:[1,0]
	global_store_dwordx4 v[180:181], v[176:179], off
	s_nop 1
	v_cvt_pk_bf16_f32 v176, v188, v189
	v_cvt_pk_bf16_f32 v177, v186, v187
	v_cvt_pk_bf16_f32 v178, v192, v193
	v_cvt_pk_bf16_f32 v179, v190, v191
	global_store_dwordx4 v[180:181], v[176:179], off offset:256
	s_nop 1
	v_mov_b32_e32 v136, v204
	v_mul_f32_e32 v136, v175, v136
	v_mad_i64_i32 v[176:177], s[44:45], v174, s53, v[152:153]
	v_lshl_add_u64 v[180:181], v[176:177], 0, v[156:157]
	v_pk_mul_f32 v[178:179], v[110:111], v[136:137] op_sel_hi:[1,0]
	v_pk_mul_f32 v[176:177], v[108:109], v[136:137] op_sel_hi:[1,0]
	v_pk_mul_f32 v[182:183], v[106:107], v[136:137] op_sel_hi:[1,0]
	v_pk_mul_f32 v[184:185], v[104:105], v[136:137] op_sel_hi:[1,0]
	v_cvt_pk_bf16_f32 v176, v176, v177
	v_cvt_pk_bf16_f32 v177, v178, v179
	v_pk_mul_f32 v[186:187], v[102:103], v[136:137] op_sel_hi:[1,0]
	v_cvt_pk_bf16_f32 v178, v184, v185
	v_cvt_pk_bf16_f32 v179, v182, v183
	v_pk_mul_f32 v[188:189], v[100:101], v[136:137] op_sel_hi:[1,0]
	v_pk_mul_f32 v[190:191], v[98:99], v[136:137] op_sel_hi:[1,0]
; __device__ __forceinline__ u32x4 pack8(f32x4 v0, f32x4 v1) { u32x4 w; w.x = cvt_pk_bf16(v0[0], v0[1]); w.y = cvt_pk_bf16(v0[2], v0[3]); w.z = cvt_pk_bf16(v1[0], v1[1]); w.w = cvt_pk_bf16(v1[2], v1[3]); return w; }
;     __device__ __forceinline__ void operator()(const f32x4 (&acc)[2][2][4][2], const Unit& u, int wr, int wc, int fr, int fq) const {
;     ...
;             const int col0 = u.pn * BM + wc * 32 + 8 * fq; const float sc = (u.pn < 2) ? QSCALE : 1.0f;
; #pragma unroll
;             for (int ai = 0; ai < 2; ++ai)
; #pragma unroll
;                 for (int m = 0; m < 4; ++m) { bf16_t* rowp = O + (size_t)(row0 + ai * HALF + m * 16) * NQKV + col0; const float scr_ = sc * rowsc[row0 + ai * HALF + m * 16];
; #pragma unroll
;                     for (int bj = 0; bj < 2; ++bj) *(u32x4*)(rowp + bj * HALF) = pack8(acc[ai][bj][m][0] * scr_, acc[ai][bj][m][1] * scr_); }
	v_pk_mul_f32 v[192:193], v[96:97], v[136:137] op_sel_hi:[1,0]
	global_store_dwordx4 v[180:181], v[176:179], off
	s_nop 1
	v_cvt_pk_bf16_f32 v176, v188, v189
	v_cvt_pk_bf16_f32 v177, v186, v187
	v_cvt_pk_bf16_f32 v178, v192, v193
	v_cvt_pk_bf16_f32 v179, v190, v191
	global_store_dwordx4 v[180:181], v[176:179], off offset:256
	s_nop 1
	v_mov_b32_e32 v136, v205
	v_mul_f32_e32 v136, v175, v136
	v_mad_i64_i32 v[176:177], s[44:45], v173, s53, v[152:153]
	v_lshl_add_u64 v[180:181], v[176:177], 0, v[156:157]
	v_pk_mul_f32 v[178:179], v[94:95], v[136:137] op_sel_hi:[1,0]
	v_pk_mul_f32 v[176:177], v[92:93], v[136:137] op_sel_hi:[1,0]
	v_pk_mul_f32 v[182:183], v[90:91], v[136:137] op_sel_hi:[1,0]
	v_pk_mul_f32 v[184:185], v[88:89], v[136:137] op_sel_hi:[1,0]
	v_cvt_pk_bf16_f32 v176, v176, v177
	v_cvt_pk_bf16_f32 v177, v178, v179
	v_pk_mul_f32 v[186:187], v[86:87], v[136:137] op_sel_hi:[1,0]
	v_cvt_pk_bf16_f32 v178, v184, v185
	v_cvt_pk_bf16_f32 v179, v182, v183
	v_pk_mul_f32 v[188:189], v[84:85], v[136:137] op_sel_hi:[1,0]
	v_pk_mul_f32 v[190:191], v[82:83], v[136:137] op_sel_hi:[1,0]
	v_pk_mul_f32 v[192:193], v[80:81], v[136:137] op_sel_hi:[1,0]
	global_store_dwordx4 v[180:181], v[176:179], off
	s_nop 1
	v_cvt_pk_bf16_f32 v176, v188, v189
	v_cvt_pk_bf16_f32 v177, v186, v187
	v_cvt_pk_bf16_f32 v178, v192, v193
	v_cvt_pk_bf16_f32 v179, v190, v191
	global_store_dwordx4 v[180:181], v[176:179], off offset:256
	s_nop 1
	v_mov_b32_e32 v136, v206
	v_mul_f32_e32 v136, v175, v136
	v_mad_i64_i32 v[176:177], s[44:45], v172, s53, v[152:153]
	v_lshl_add_u64 v[180:181], v[176:177], 0, v[156:157]
	v_pk_mul_f32 v[178:179], v[78:79], v[136:137] op_sel_hi:[1,0]
	v_pk_mul_f32 v[176:177], v[76:77], v[136:137] op_sel_hi:[1,0]
	v_pk_mul_f32 v[182:183], v[74:75], v[136:137] op_sel_hi:[1,0]
	v_pk_mul_f32 v[184:185], v[72:73], v[136:137] op_sel_hi:[1,0]
	v_cvt_pk_bf16_f32 v176, v176, v177
	v_cvt_pk_bf16_f32 v177, v178, v179
	v_pk_mul_f32 v[186:187], v[70:71], v[136:137] op_sel_hi:[1,0]
	v_cvt_pk_bf16_f32 v178, v184, v185
	v_cvt_pk_bf16_f32 v179, v182, v183
	v_pk_mul_f32 v[188:189], v[68:69], v[136:137] op_sel_hi:[1,0]
	v_pk_mul_f32 v[190:191], v[66:67], v[136:137] op_sel_hi:[1,0]
	v_pk_mul_f32 v[192:193], v[64:65], v[136:137] op_sel_hi:[1,0]
	global_store_dwordx4 v[180:181], v[176:179], off
	s_nop 1
	v_cvt_pk_bf16_f32 v176, v188, v189
	v_cvt_pk_bf16_f32 v177, v186, v187
	v_cvt_pk_bf16_f32 v178, v192, v193
	v_cvt_pk_bf16_f32 v179, v190, v191
	global_store_dwordx4 v[180:181], v[176:179], off offset:256
	s_nop 1
	v_mov_b32_e32 v136, v207
	v_mul_f32_e32 v136, v175, v136
	v_mad_i64_i32 v[176:177], s[44:45], v171, s53, v[152:153]
	v_lshl_add_u64 v[180:181], v[176:177], 0, v[156:157]
	v_pk_mul_f32 v[178:179], v[62:63], v[136:137] op_sel_hi:[1,0]
	v_pk_mul_f32 v[176:177], v[60:61], v[136:137] op_sel_hi:[1,0]
	v_pk_mul_f32 v[182:183], v[58:59], v[136:137] op_sel_hi:[1,0]
	v_pk_mul_f32 v[184:185], v[56:57], v[136:137] op_sel_hi:[1,0]
	v_cvt_pk_bf16_f32 v176, v176, v177
	v_cvt_pk_bf16_f32 v177, v178, v179
	v_pk_mul_f32 v[186:187], v[54:55], v[136:137] op_sel_hi:[1,0]
	v_cvt_pk_bf16_f32 v178, v184, v185
	v_cvt_pk_bf16_f32 v179, v182, v183
	v_pk_mul_f32 v[188:189], v[52:53], v[136:137] op_sel_hi:[1,0]
	v_pk_mul_f32 v[190:191], v[50:51], v[136:137] op_sel_hi:[1,0]
	v_pk_mul_f32 v[192:193], v[48:49], v[136:137] op_sel_hi:[1,0]
	global_store_dwordx4 v[180:181], v[176:179], off
	s_nop 1
	v_cvt_pk_bf16_f32 v176, v188, v189
	v_cvt_pk_bf16_f32 v177, v186, v187
	v_cvt_pk_bf16_f32 v178, v192, v193
	v_cvt_pk_bf16_f32 v179, v190, v191
	global_store_dwordx4 v[180:181], v[176:179], off offset:256
	s_nop 1
	v_mov_b32_e32 v136, v208
	v_mul_f32_e32 v136, v175, v136
	v_mad_i64_i32 v[176:177], s[44:45], v170, s53, v[152:153]
	v_lshl_add_u64 v[180:181], v[176:177], 0, v[156:157]
	v_pk_mul_f32 v[178:179], v[46:47], v[136:137] op_sel_hi:[1,0]
	v_pk_mul_f32 v[176:177], v[44:45], v[136:137] op_sel_hi:[1,0]
	v_pk_mul_f32 v[182:183], v[42:43], v[136:137] op_sel_hi:[1,0]
	v_pk_mul_f32 v[184:185], v[40:41], v[136:137] op_sel_hi:[1,0]
	v_cvt_pk_bf16_f32 v176, v176, v177
	v_cvt_pk_bf16_f32 v177, v178, v179
	v_pk_mul_f32 v[186:187], v[38:39], v[136:137] op_sel_hi:[1,0]
	v_cvt_pk_bf16_f32 v178, v184, v185
	v_cvt_pk_bf16_f32 v179, v182, v183
	v_pk_mul_f32 v[188:189], v[36:37], v[136:137] op_sel_hi:[1,0]
	v_pk_mul_f32 v[190:191], v[34:35], v[136:137] op_sel_hi:[1,0]
	v_pk_mul_f32 v[192:193], v[32:33], v[136:137] op_sel_hi:[1,0]
	global_store_dwordx4 v[180:181], v[176:179], off
	s_nop 1
	v_cvt_pk_bf16_f32 v176, v188, v189
	v_cvt_pk_bf16_f32 v177, v186, v187
	v_cvt_pk_bf16_f32 v178, v192, v193
	v_cvt_pk_bf16_f32 v179, v190, v191
	global_store_dwordx4 v[180:181], v[176:179], off offset:256
	s_nop 1
	v_mov_b32_e32 v136, v209
	v_mul_f32_e32 v136, v175, v136
	v_mad_i64_i32 v[176:177], s[44:45], v169, s53, v[152:153]
	v_lshl_add_u64 v[180:181], v[176:177], 0, v[156:157]
	v_pk_mul_f32 v[178:179], v[30:31], v[136:137] op_sel_hi:[1,0]
	v_pk_mul_f32 v[176:177], v[28:29], v[136:137] op_sel_hi:[1,0]
	v_pk_mul_f32 v[182:183], v[26:27], v[136:137] op_sel_hi:[1,0]
	v_pk_mul_f32 v[184:185], v[24:25], v[136:137] op_sel_hi:[1,0]
	v_cvt_pk_bf16_f32 v176, v176, v177
	v_cvt_pk_bf16_f32 v177, v178, v179
	v_pk_mul_f32 v[186:187], v[22:23], v[136:137] op_sel_hi:[1,0]
	v_cvt_pk_bf16_f32 v178, v184, v185
	v_cvt_pk_bf16_f32 v179, v182, v183
	v_pk_mul_f32 v[188:189], v[20:21], v[136:137] op_sel_hi:[1,0]
	v_pk_mul_f32 v[190:191], v[18:19], v[136:137] op_sel_hi:[1,0]
	v_pk_mul_f32 v[192:193], v[16:17], v[136:137] op_sel_hi:[1,0]
	global_store_dwordx4 v[180:181], v[176:179], off
	s_nop 1
	v_cvt_pk_bf16_f32 v176, v188, v189
	v_cvt_pk_bf16_f32 v177, v186, v187
	v_cvt_pk_bf16_f32 v178, v192, v193
	v_cvt_pk_bf16_f32 v179, v190, v191
	global_store_dwordx4 v[180:181], v[176:179], off offset:256
	s_nop 1
	v_mov_b32_e32 v136, v210
	v_mad_i64_i32 v[150:151], s[44:45], v168, s53, v[152:153]
	v_lshl_add_u64 v[156:157], v[150:151], 0, v[156:157]
	s_mov_b64 s[44:45], 0
	v_mul_f32_e32 v136, v175, v136
	v_pk_mul_f32 v[152:153], v[14:15], v[136:137] op_sel_hi:[1,0]
	v_pk_mul_f32 v[150:151], v[12:13], v[136:137] op_sel_hi:[1,0]
	v_pk_mul_f32 v[176:177], v[10:11], v[136:137] op_sel_hi:[1,0]
	v_pk_mul_f32 v[178:179], v[8:9], v[136:137] op_sel_hi:[1,0]
	v_cvt_pk_bf16_f32 v150, v150, v151
	v_cvt_pk_bf16_f32 v151, v152, v153
	v_pk_mul_f32 v[180:181], v[6:7], v[136:137] op_sel_hi:[1,0]
	v_cvt_pk_bf16_f32 v152, v178, v179
	v_cvt_pk_bf16_f32 v153, v176, v177
	v_pk_mul_f32 v[182:183], v[4:5], v[136:137] op_sel_hi:[1,0]
	v_pk_mul_f32 v[184:185], v[2:3], v[136:137] op_sel_hi:[1,0]
	v_pk_mul_f32 v[186:187], v[0:1], v[136:137] op_sel_hi:[1,0]
	global_store_dwordx4 v[156:157], v[150:153], off
	s_nop 1
	v_cvt_pk_bf16_f32 v150, v182, v183
	v_cvt_pk_bf16_f32 v151, v180, v181
	v_cvt_pk_bf16_f32 v152, v186, v187
	v_cvt_pk_bf16_f32 v153, v184, v185
	global_store_dwordx4 v[156:157], v[150:153], off offset:256

; #define PG8_STAGE(bufoff, gbase, voff) do { _Pragma("unroll") for (int _i = 0; _i < 2; ++_i) \
;         __builtin_amdgcn_global_load_lds((const unsigned*)((const char*)(gbase) + (voff)[_i]), (LAS unsigned*)(lds + (bufoff) + ldsw + _i * 8192), 16, 0, 0); } while (0)
; #define PG8_LDA(dst, b, h) do { _Pragma("unroll") for (int m = 0; m < 4; ++m) _Pragma("unroll") for (int k = 0; k < 2; ++k) dst[m][k] = *(const LAS bf16x8*)(lds + PG8_SA(b, h) + aoff + m * 2048 + k * 1024); } while (0)
; #define PG8_LDB(dst, b, h) do { _Pragma("unroll") for (int n = 0; n < 2; ++n) _Pragma("unroll") for (int k = 0; k < 2; ++k) dst[n][k] = *(const LAS bf16x8*)(lds + PG8_SB(b, h) + boff + n * 2048 + k * 1024); } while (0)
; #define PG8_MMA(ai, bj, At, Bt) do { __builtin_amdgcn_s_setprio(1); _Pragma("unroll") for (int m = 0; m < 4; ++m) _Pragma("unroll") for (int n = 0; n < 2; ++n) _Pragma("unroll") for (int k = 0; k < 2; ++k) \
;         acc[ai][bj][m][n] = __builtin_amdgcn_mfma_f32_16x16x32_bf16(Bt[n][k], At[m][k], acc[ai][bj][m][n], 0, 0, 0); __builtin_amdgcn_s_setprio(0); } while (0)
; #define PG8_WAIT_V(n) asm volatile("s_waitcnt vmcnt(" #n ")" ::: "memory")
; #define PG8_WAIT_L(n) asm volatile("s_waitcnt lgkmcnt(" #n ")" ::: "memory")
; template <class Epi>
; __device__ __forceinline__ void gemm_phase(LAS unsigned char* lds, const Gemm g, const StaticOrder& S, const Epi& E) {
;     ...
;         for (int t = 0; t < nt; t += 2) {
;             const bool last = (t == nt - 2);
;             const char* a1 = cA + (size_t)(t + 1) * kstep;
;             const char* a2 = last ? nA : cA + (size_t)(t + 2) * kstep; const char* b2 = last ? nB : cB + (size_t)(t + 2) * kstep;
;             const char* a3 = a2 + kstep; const char* b3 = b2 + kstep;
;             PG8_LDB(B0, 0, 0); PG8_SCHED; PG8_LDA(At, 0, 0); PG8_STAGE(PG8_SA(1, 1), a1 + hstep, voffA);
;             PG8_WAIT_L(8); PG8_BAR; PG8_WAIT_L(0); PG8_MMA(0, 0, At, B0); PG8_BAR; PG8_SCHED;
;             PG8_LDB(B1, 0, 1); PG8_STAGE(PG8_SB(0, 0), b2, voffB);
;             PG8_BAR; PG8_WAIT_L(0); PG8_MMA(0, 1, At, B1); PG8_BAR;
;             PG8_LDA(At, 0, 1); PG8_STAGE(PG8_SA(0, 0), a2, voffA);
;             PG8_BAR; PG8_WAIT_L(0); PG8_MMA(1, 0, At, B0); PG8_BAR; PG8_SCHED;
;             PG8_STAGE(PG8_SB(0, 1), b2 + hstep, voffB);
;             PG8_WAIT_V(6); PG8_BAR; PG8_MMA(1, 1, At, B1); PG8_BAR;
.LBB0_673:
	ds_read_b128 v[148:151], v145
	ds_read_b128 v[152:155], v145 offset:1024
	ds_read_b128 v[160:163], v145 offset:2048
	ds_read_b128 v[164:167], v145 offset:3072
	s_add_u32 s52, s50, 0xfff80080
	s_addc_u32 s53, s51, -1
	s_cmp_eq_u32 s69, 28
	s_cselect_b32 s55, s43, s53
	s_cselect_b32 s54, s65, s52
	s_cselect_b32 s53, s41, s68
	s_cselect_b32 s52, s66, s67
	s_add_i32 m0, s28, 0xc000
	ds_read_b128 v[168:171], v146
	ds_read_b128 v[172:175], v146 offset:1024
	ds_read_b128 v[176:179], v146 offset:2048
	ds_read_b128 v[180:183], v146 offset:3072
	ds_read_b128 v[184:187], v146 offset:4096
	ds_read_b128 v[188:191], v146 offset:5120
	ds_read_b128 v[192:195], v146 offset:6144
	ds_read_b128 v[196:199], v146 offset:7168
	global_load_lds_dwordx4 v136, s[50:51]
	s_add_i32 m0, s28, 0xe000
	s_nop 0
	global_load_lds_dwordx4 v138, s[50:51]
	s_waitcnt lgkmcnt(8)
	s_barrier
	s_waitcnt lgkmcnt(0)
	v_mfma_f32_16x16x32_bf16 v[124:127], v[148:151], v[168:171], v[124:127]
	v_mfma_f32_16x16x32_bf16 v[120:123], v[160:163], v[168:171], v[120:123]
	v_mfma_f32_16x16x32_bf16 v[112:115], v[148:151], v[176:179], v[112:115]
	v_mfma_f32_16x16x32_bf16 v[104:107], v[160:163], v[176:179], v[104:107]
	v_mfma_f32_16x16x32_bf16 v[96:99], v[148:151], v[184:187], v[96:99]
	v_mfma_f32_16x16x32_bf16 v[88:91], v[160:163], v[184:187], v[88:91]
	v_mfma_f32_16x16x32_bf16 v[80:83], v[148:151], v[192:195], v[80:83]
	v_mfma_f32_16x16x32_bf16 v[72:75], v[160:163], v[192:195], v[72:75]
	v_mfma_f32_16x16x32_bf16 v[124:127], v[152:155], v[172:175], v[124:127]
	v_mfma_f32_16x16x32_bf16 v[120:123], v[164:167], v[172:175], v[120:123]
	v_mfma_f32_16x16x32_bf16 v[112:115], v[152:155], v[180:183], v[112:115]
	v_mfma_f32_16x16x32_bf16 v[104:107], v[164:167], v[180:183], v[104:107]
	v_mfma_f32_16x16x32_bf16 v[96:99], v[152:155], v[188:191], v[96:99]
	v_mfma_f32_16x16x32_bf16 v[88:91], v[164:167], v[188:191], v[88:91]
	v_mfma_f32_16x16x32_bf16 v[80:83], v[152:155], v[196:199], v[80:83]
	v_mfma_f32_16x16x32_bf16 v[72:75], v[164:167], v[196:199], v[72:75]
	s_barrier
	s_add_i32 s70, s58, s23
	s_add_u32 s98, s52, s6
	s_addc_u32 s99, s53, s7
	s_mov_b32 m0, s70
	ds_read_b128 v[200:203], v147
	ds_read_b128 v[204:207], v147 offset:1024
	ds_read_b128 v[208:211], v147 offset:2048
	ds_read_b128 v[212:215], v147 offset:3072
	global_load_lds_dwordx4 v132, s[52:53]
	s_add_i32 m0, s70, 0x2000
	s_nop 0
	global_load_lds_dwordx4 v128, s[52:53]
	s_barrier
	s_waitcnt lgkmcnt(0)
	v_mfma_f32_16x16x32_bf16 v[116:119], v[200:203], v[168:171], v[116:119]
	v_mfma_f32_16x16x32_bf16 v[108:111], v[208:211], v[168:171], v[108:111]
	v_mfma_f32_16x16x32_bf16 v[100:103], v[200:203], v[176:179], v[100:103]
	v_mfma_f32_16x16x32_bf16 v[92:95], v[208:211], v[176:179], v[92:95]
	v_mfma_f32_16x16x32_bf16 v[84:87], v[200:203], v[184:187], v[84:87]
	v_mfma_f32_16x16x32_bf16 v[76:79], v[208:211], v[184:187], v[76:79]
	v_mfma_f32_16x16x32_bf16 v[68:71], v[200:203], v[192:195], v[68:71]
	v_mfma_f32_16x16x32_bf16 v[64:67], v[208:211], v[192:195], v[64:67]
	v_mfma_f32_16x16x32_bf16 v[116:119], v[204:207], v[172:175], v[116:119]
	v_mfma_f32_16x16x32_bf16 v[108:111], v[212:215], v[172:175], v[108:111]
	v_mfma_f32_16x16x32_bf16 v[100:103], v[204:207], v[180:183], v[100:103]
	v_mfma_f32_16x16x32_bf16 v[92:95], v[212:215], v[180:183], v[92:95]
	v_mfma_f32_16x16x32_bf16 v[84:87], v[204:207], v[188:191], v[84:87]
	v_mfma_f32_16x16x32_bf16 v[76:79], v[212:215], v[188:191], v[76:79]
	v_mfma_f32_16x16x32_bf16 v[68:71], v[204:207], v[196:199], v[68:71]
	v_mfma_f32_16x16x32_bf16 v[64:67], v[212:215], v[196:199], v[64:67]
	s_mov_b32 m0, s28
	s_add_u32 s100, s54, s6
	s_addc_u32 s101, s55, s7
	s_barrier
	ds_read_b128 v[168:171], v146 offset:16384
	ds_read_b128 v[172:175], v146 offset:17408
	ds_read_b128 v[176:179], v146 offset:18432
	ds_read_b128 v[180:183], v146 offset:19456
	ds_read_b128 v[184:187], v146 offset:20480
	ds_read_b128 v[188:191], v146 offset:21504
	ds_read_b128 v[192:195], v146 offset:22528
	ds_read_b128 v[196:199], v146 offset:23552
	global_load_lds_dwordx4 v134, s[54:55]
	s_mov_b32 m0, s29
	s_nop 0
	global_load_lds_dwordx4 v130, s[54:55]
	s_barrier
	s_waitcnt lgkmcnt(0)
	v_mfma_f32_16x16x32_bf16 v[60:63], v[148:151], v[168:171], v[60:63]
	v_mfma_f32_16x16x32_bf16 v[56:59], v[160:163], v[168:171], v[56:59]
	v_mfma_f32_16x16x32_bf16 v[52:55], v[148:151], v[176:179], v[52:55]
	v_mfma_f32_16x16x32_bf16 v[44:47], v[160:163], v[176:179], v[44:47]
	v_mfma_f32_16x16x32_bf16 v[36:39], v[148:151], v[184:187], v[36:39]
	v_mfma_f32_16x16x32_bf16 v[28:31], v[160:163], v[184:187], v[28:31]
	v_mfma_f32_16x16x32_bf16 v[20:23], v[148:151], v[192:195], v[20:23]
	v_mfma_f32_16x16x32_bf16 v[12:15], v[160:163], v[192:195], v[12:15]
	v_mfma_f32_16x16x32_bf16 v[60:63], v[152:155], v[172:175], v[60:63]
	v_mfma_f32_16x16x32_bf16 v[56:59], v[164:167], v[172:175], v[56:59]
	v_mfma_f32_16x16x32_bf16 v[52:55], v[152:155], v[180:183], v[52:55]
	v_mfma_f32_16x16x32_bf16 v[44:47], v[164:167], v[180:183], v[44:47]
	v_mfma_f32_16x16x32_bf16 v[36:39], v[152:155], v[188:191], v[36:39]
	v_mfma_f32_16x16x32_bf16 v[28:31], v[164:167], v[188:191], v[28:31]
	v_mfma_f32_16x16x32_bf16 v[20:23], v[152:155], v[196:199], v[20:23]
	v_mfma_f32_16x16x32_bf16 v[12:15], v[164:167], v[196:199], v[12:15]
	s_barrier
	s_add_u32 s70, s52, 0x80000
	s_addc_u32 s71, s53, 0
	s_add_i32 s72, s59, s23
	s_mov_b32 m0, s72
	s_nop 0
	global_load_lds_dwordx4 v132, s[70:71]
	s_add_i32 m0, s72, 0x2000
	s_nop 0
	global_load_lds_dwordx4 v128, s[70:71]
	s_waitcnt vmcnt(6)
	s_barrier
; #define PG8_STAGE(bufoff, gbase, voff) do { _Pragma("unroll") for (int _i = 0; _i < 2; ++_i) \
;         __builtin_amdgcn_global_load_lds((const unsigned*)((const char*)(gbase) + (voff)[_i]), (LAS unsigned*)(lds + (bufoff) + ldsw + _i * 8192), 16, 0, 0); } while (0)
; #define PG8_LDA(dst, b, h) do { _Pragma("unroll") for (int m = 0; m < 4; ++m) _Pragma("unroll") for (int k = 0; k < 2; ++k) dst[m][k] = *(const LAS bf16x8*)(lds + PG8_SA(b, h) + aoff + m * 2048 + k * 1024); } while (0)
; #define PG8_LDB(dst, b, h) do { _Pragma("unroll") for (int n = 0; n < 2; ++n) _Pragma("unroll") for (int k = 0; k < 2; ++k) dst[n][k] = *(const LAS bf16x8*)(lds + PG8_SB(b, h) + boff + n * 2048 + k * 1024); } while (0)
; #define PG8_MMA(ai, bj, At, Bt) do { __builtin_amdgcn_s_setprio(1); _Pragma("unroll") for (int m = 0; m < 4; ++m) _Pragma("unroll") for (int n = 0; n < 2; ++n) _Pragma("unroll") for (int k = 0; k < 2; ++k) \
;         acc[ai][bj][m][n] = __builtin_amdgcn_mfma_f32_16x16x32_bf16(Bt[n][k], At[m][k], acc[ai][bj][m][n], 0, 0, 0); __builtin_amdgcn_s_setprio(0); } while (0)
; #define PG8_WAIT_V(n) asm volatile("s_waitcnt vmcnt(" #n ")" ::: "memory")
; #define PG8_WAIT_L(n) asm volatile("s_waitcnt lgkmcnt(" #n ")" ::: "memory")
; #define PG8_BAR __builtin_amdgcn_s_barrier()
; #define PG8_SCHED __builtin_amdgcn_sched_barrier(0)
; template <class Epi>
; __device__ __forceinline__ void gemm_phase(LAS unsigned char* lds, const Gemm g, const StaticOrder& S, const Epi& E) {
;     ...
;             PG8_WAIT_V(6); PG8_BAR; PG8_MMA(1, 1, At, B1); PG8_BAR;
;             PG8_LDB(B0, 1, 0); PG8_SCHED; PG8_LDA(At, 1, 0); PG8_STAGE(PG8_SA(0, 1), a2 + hstep, voffA);
;             PG8_WAIT_L(8); PG8_BAR; PG8_WAIT_L(0); PG8_MMA(0, 0, At, B0); PG8_BAR; PG8_SCHED;
;             PG8_LDB(B1, 1, 1); PG8_STAGE(PG8_SB(1, 0), b3, voffB);
;             PG8_BAR; PG8_WAIT_L(0); PG8_MMA(0, 1, At, B1); PG8_BAR;
;             PG8_LDA(At, 1, 1); PG8_STAGE(PG8_SA(1, 0), a3, voffA);
	v_mfma_f32_16x16x32_bf16 v[48:51], v[200:203], v[168:171], v[48:51]
	v_mfma_f32_16x16x32_bf16 v[40:43], v[208:211], v[168:171], v[40:43]
	v_mfma_f32_16x16x32_bf16 v[32:35], v[200:203], v[176:179], v[32:35]
	v_mfma_f32_16x16x32_bf16 v[24:27], v[208:211], v[176:179], v[24:27]
	v_mfma_f32_16x16x32_bf16 v[16:19], v[200:203], v[184:187], v[16:19]
	v_mfma_f32_16x16x32_bf16 v[8:11], v[208:211], v[184:187], v[8:11]
	v_mfma_f32_16x16x32_bf16 v[4:7], v[200:203], v[192:195], v[4:7]
	v_mfma_f32_16x16x32_bf16 v[0:3], v[208:211], v[192:195], v[0:3]
	v_mfma_f32_16x16x32_bf16 v[48:51], v[204:207], v[172:175], v[48:51]
	v_mfma_f32_16x16x32_bf16 v[40:43], v[212:215], v[172:175], v[40:43]
	v_mfma_f32_16x16x32_bf16 v[32:35], v[204:207], v[180:183], v[32:35]
	v_mfma_f32_16x16x32_bf16 v[24:27], v[212:215], v[180:183], v[24:27]
	v_mfma_f32_16x16x32_bf16 v[16:19], v[204:207], v[188:191], v[16:19]
	v_mfma_f32_16x16x32_bf16 v[8:11], v[212:215], v[188:191], v[8:11]
	v_mfma_f32_16x16x32_bf16 v[4:7], v[204:207], v[196:199], v[4:7]
	v_mfma_f32_16x16x32_bf16 v[0:3], v[212:215], v[196:199], v[0:3]
	s_add_i32 s70, 0, 0x18000
	v_add_u32_e32 v164, s70, v143
	s_barrier
	ds_read_b128 v[148:151], v164
	ds_read_b128 v[152:155], v164 offset:1024
	ds_read_b128 v[160:163], v164 offset:2048
	ds_read_b128 v[164:167], v164 offset:3072
	s_add_u32 s54, s54, 0x80000
	s_addc_u32 s55, s55, 0
	s_mov_b32 m0, s33
	ds_read_b128 v[168:171], v146 offset:32768
	ds_read_b128 v[172:175], v146 offset:33792
	ds_read_b128 v[176:179], v146 offset:34816
	ds_read_b128 v[180:183], v146 offset:35840
	ds_read_b128 v[184:187], v146 offset:36864
	ds_read_b128 v[188:191], v146 offset:37888
	ds_read_b128 v[192:195], v146 offset:38912
	ds_read_b128 v[196:199], v146 offset:39936
	global_load_lds_dwordx4 v134, s[54:55]
	s_mov_b32 m0, s36
	s_nop 0
	global_load_lds_dwordx4 v130, s[54:55]
	s_waitcnt lgkmcnt(8)
	s_barrier
	s_waitcnt lgkmcnt(0)
	v_mfma_f32_16x16x32_bf16 v[124:127], v[148:151], v[168:171], v[124:127]
	v_mfma_f32_16x16x32_bf16 v[120:123], v[160:163], v[168:171], v[120:123]
	v_mfma_f32_16x16x32_bf16 v[112:115], v[148:151], v[176:179], v[112:115]
	v_mfma_f32_16x16x32_bf16 v[104:107], v[160:163], v[176:179], v[104:107]
	v_mfma_f32_16x16x32_bf16 v[96:99], v[148:151], v[184:187], v[96:99]
	v_mfma_f32_16x16x32_bf16 v[88:91], v[160:163], v[184:187], v[88:91]
	v_mfma_f32_16x16x32_bf16 v[80:83], v[148:151], v[192:195], v[80:83]
	v_mfma_f32_16x16x32_bf16 v[72:75], v[160:163], v[192:195], v[72:75]
	v_mfma_f32_16x16x32_bf16 v[124:127], v[152:155], v[172:175], v[124:127]
	v_mfma_f32_16x16x32_bf16 v[120:123], v[164:167], v[172:175], v[120:123]
	v_mfma_f32_16x16x32_bf16 v[112:115], v[152:155], v[180:183], v[112:115]
	v_mfma_f32_16x16x32_bf16 v[104:107], v[164:167], v[180:183], v[104:107]
	v_mfma_f32_16x16x32_bf16 v[96:99], v[152:155], v[188:191], v[96:99]
	v_mfma_f32_16x16x32_bf16 v[88:91], v[164:167], v[188:191], v[88:91]
	v_mfma_f32_16x16x32_bf16 v[80:83], v[152:155], v[196:199], v[80:83]
	v_mfma_f32_16x16x32_bf16 v[72:75], v[164:167], v[196:199], v[72:75]
	s_barrier
	s_add_i32 s54, 0, 0x1c000
	s_add_i32 s55, s70, s23
	v_add_u32_e32 v212, s54, v143
	s_mov_b32 m0, s55
	ds_read_b128 v[200:203], v212
	ds_read_b128 v[204:207], v212 offset:1024
	ds_read_b128 v[208:211], v212 offset:2048
	ds_read_b128 v[212:215], v212 offset:3072
	global_load_lds_dwordx4 v132, s[98:99]
	s_add_i32 m0, s55, 0x2000
	s_nop 0
	global_load_lds_dwordx4 v128, s[98:99]
	s_barrier
	s_waitcnt lgkmcnt(0)
	v_mfma_f32_16x16x32_bf16 v[116:119], v[200:203], v[168:171], v[116:119]
	v_mfma_f32_16x16x32_bf16 v[108:111], v[208:211], v[168:171], v[108:111]
	v_mfma_f32_16x16x32_bf16 v[100:103], v[200:203], v[176:179], v[100:103]
	v_mfma_f32_16x16x32_bf16 v[92:95], v[208:211], v[176:179], v[92:95]
	v_mfma_f32_16x16x32_bf16 v[84:87], v[200:203], v[184:187], v[84:87]
	v_mfma_f32_16x16x32_bf16 v[76:79], v[208:211], v[184:187], v[76:79]
	v_mfma_f32_16x16x32_bf16 v[68:71], v[200:203], v[192:195], v[68:71]
	v_mfma_f32_16x16x32_bf16 v[64:67], v[208:211], v[192:195], v[64:67]
	v_mfma_f32_16x16x32_bf16 v[116:119], v[204:207], v[172:175], v[116:119]
	v_mfma_f32_16x16x32_bf16 v[108:111], v[212:215], v[172:175], v[108:111]
	v_mfma_f32_16x16x32_bf16 v[100:103], v[204:207], v[180:183], v[100:103]
	v_mfma_f32_16x16x32_bf16 v[92:95], v[212:215], v[180:183], v[92:95]
	v_mfma_f32_16x16x32_bf16 v[84:87], v[204:207], v[188:191], v[84:87]
	v_mfma_f32_16x16x32_bf16 v[76:79], v[212:215], v[188:191], v[76:79]
	v_mfma_f32_16x16x32_bf16 v[68:71], v[204:207], v[196:199], v[68:71]
	v_mfma_f32_16x16x32_bf16 v[64:67], v[212:215], v[196:199], v[64:67]
	s_mov_b32 m0, s49
	s_barrier
	ds_read_b128 v[168:171], v146 offset:49152
	ds_read_b128 v[172:175], v146 offset:50176
	ds_read_b128 v[176:179], v146 offset:51200
	ds_read_b128 v[180:183], v146 offset:52224
	ds_read_b128 v[184:187], v146 offset:53248
	ds_read_b128 v[188:191], v146 offset:54272
	ds_read_b128 v[192:195], v146 offset:55296
	ds_read_b128 v[196:199], v146 offset:56320
	global_load_lds_dwordx4 v134, s[100:101]
	s_mov_b32 m0, s56
	s_nop 0
	global_load_lds_dwordx4 v130, s[100:101]
	s_barrier
; #define PG8_STAGE(bufoff, gbase, voff) do { _Pragma("unroll") for (int _i = 0; _i < 2; ++_i) \
;         __builtin_amdgcn_global_load_lds((const unsigned*)((const char*)(gbase) + (voff)[_i]), (LAS unsigned*)(lds + (bufoff) + ldsw + _i * 8192), 16, 0, 0); } while (0)
; #define PG8_MMA(ai, bj, At, Bt) do { __builtin_amdgcn_s_setprio(1); _Pragma("unroll") for (int m = 0; m < 4; ++m) _Pragma("unroll") for (int n = 0; n < 2; ++n) _Pragma("unroll") for (int k = 0; k < 2; ++k) \
;         acc[ai][bj][m][n] = __builtin_amdgcn_mfma_f32_16x16x32_bf16(Bt[n][k], At[m][k], acc[ai][bj][m][n], 0, 0, 0); __builtin_amdgcn_s_setprio(0); } while (0)
; #define PG8_WAIT_V(n) asm volatile("s_waitcnt vmcnt(" #n ")" ::: "memory")
; #define PG8_WAIT_L(n) asm volatile("s_waitcnt lgkmcnt(" #n ")" ::: "memory")
; #define PG8_BAR __builtin_amdgcn_s_barrier()
; #define PG8_SCHED __builtin_amdgcn_sched_barrier(0)
; template <class Epi>
; __device__ __forceinline__ void gemm_phase(LAS unsigned char* lds, const Gemm g, const StaticOrder& S, const Epi& E) {
;     ...
;             PG8_BAR; PG8_WAIT_L(0); PG8_MMA(1, 0, At, B0); PG8_BAR; PG8_SCHED;
;             PG8_STAGE(PG8_SB(1, 1), b3 + hstep, voffB);
;             PG8_WAIT_V(6); PG8_BAR; PG8_MMA(1, 1, At, B1); PG8_BAR;
;         }
	s_waitcnt lgkmcnt(0)
	v_mfma_f32_16x16x32_bf16 v[60:63], v[148:151], v[168:171], v[60:63]
	v_mfma_f32_16x16x32_bf16 v[56:59], v[160:163], v[168:171], v[56:59]
	v_mfma_f32_16x16x32_bf16 v[52:55], v[148:151], v[176:179], v[52:55]
	v_mfma_f32_16x16x32_bf16 v[44:47], v[160:163], v[176:179], v[44:47]
	v_mfma_f32_16x16x32_bf16 v[36:39], v[148:151], v[184:187], v[36:39]
	v_mfma_f32_16x16x32_bf16 v[28:31], v[160:163], v[184:187], v[28:31]
	v_mfma_f32_16x16x32_bf16 v[20:23], v[148:151], v[192:195], v[20:23]
	v_mfma_f32_16x16x32_bf16 v[12:15], v[160:163], v[192:195], v[12:15]
	v_mfma_f32_16x16x32_bf16 v[60:63], v[152:155], v[172:175], v[60:63]
	v_mfma_f32_16x16x32_bf16 v[56:59], v[164:167], v[172:175], v[56:59]
	v_mfma_f32_16x16x32_bf16 v[52:55], v[152:155], v[180:183], v[52:55]
	v_mfma_f32_16x16x32_bf16 v[44:47], v[164:167], v[180:183], v[44:47]
	v_mfma_f32_16x16x32_bf16 v[36:39], v[152:155], v[188:191], v[36:39]
	v_mfma_f32_16x16x32_bf16 v[28:31], v[164:167], v[188:191], v[28:31]
	v_mfma_f32_16x16x32_bf16 v[20:23], v[152:155], v[196:199], v[20:23]
	v_mfma_f32_16x16x32_bf16 v[12:15], v[164:167], v[196:199], v[12:15]
	s_barrier
	s_add_u32 s52, s52, 0x80080
	s_addc_u32 s53, s53, 0
	s_add_i32 s54, s54, s23
	s_mov_b32 m0, s54
	s_nop 0
	global_load_lds_dwordx4 v132, s[52:53]
	s_add_i32 m0, s54, 0x2000
	s_nop 0
	global_load_lds_dwordx4 v128, s[52:53]
	s_waitcnt vmcnt(6)
	s_barrier
	v_mfma_f32_16x16x32_bf16 v[48:51], v[200:203], v[168:171], v[48:51]
	v_mfma_f32_16x16x32_bf16 v[40:43], v[208:211], v[168:171], v[40:43]
	v_mfma_f32_16x16x32_bf16 v[32:35], v[200:203], v[176:179], v[32:35]
	v_mfma_f32_16x16x32_bf16 v[24:27], v[208:211], v[176:179], v[24:27]
	v_mfma_f32_16x16x32_bf16 v[16:19], v[200:203], v[184:187], v[16:19]
	v_mfma_f32_16x16x32_bf16 v[8:11], v[208:211], v[184:187], v[8:11]
	v_mfma_f32_16x16x32_bf16 v[4:7], v[200:203], v[192:195], v[4:7]
	v_mfma_f32_16x16x32_bf16 v[0:3], v[208:211], v[192:195], v[0:3]
	v_mfma_f32_16x16x32_bf16 v[48:51], v[204:207], v[172:175], v[48:51]
	v_mfma_f32_16x16x32_bf16 v[40:43], v[212:215], v[172:175], v[40:43]
	v_mfma_f32_16x16x32_bf16 v[32:35], v[204:207], v[180:183], v[32:35]
	v_mfma_f32_16x16x32_bf16 v[24:27], v[212:215], v[180:183], v[24:27]
	v_mfma_f32_16x16x32_bf16 v[16:19], v[204:207], v[188:191], v[16:19]
	v_mfma_f32_16x16x32_bf16 v[8:11], v[212:215], v[188:191], v[8:11]
	v_mfma_f32_16x16x32_bf16 v[4:7], v[204:207], v[196:199], v[4:7]
	v_mfma_f32_16x16x32_bf16 v[0:3], v[212:215], v[196:199], v[0:3]
	s_add_i32 s69, s69, 2
	s_add_u32 s50, s50, 0x100
	s_addc_u32 s51, s51, 0
	s_add_u32 s67, s67, 0x100
	s_addc_u32 s68, s68, 0
	s_cmp_gt_u32 s69, 29
	s_barrier
	s_cbranch_scc0 .LBB0_673
; #define PG8_WAIT_V(n) asm volatile("s_waitcnt vmcnt(" #n ")" ::: "memory")
; #define PG8_BAR __builtin_amdgcn_s_barrier()
; __device__ __forceinline__ u32x4 pack8(f32x4 v0, f32x4 v1) { u32x4 w; w.x = cvt_pk_bf16(v0[0], v0[1]); w.y = cvt_pk_bf16(v0[2], v0[3]); w.z = cvt_pk_bf16(v1[0], v1[1]); w.w = cvt_pk_bf16(v1[2], v1[3]); return w; }
; template <class Epi>
; __device__ __forceinline__ void gemm_phase(LAS unsigned char* lds, const Gemm g, const StaticOrder& S, const Epi& E) {
;     ...
;         E(acc, cur, wr, wc, fr, fq);
;         if (!has_next) break;
; #pragma unroll
;         for (int a = 0; a < 2; ++a)
; #pragma unroll
;             for (int b = 0; b < 2; ++b)
; #pragma unroll
;                 for (int m = 0; m < 4; ++m)
; #pragma unroll
;                     for (int n = 0; n < 2; ++n) acc[a][b][m][n] = (f32x4){0.f, 0.f, 0.f, 0.f};
;         cur = nxt; cA = nA; cB = nB; ++ui;
;     }
;     PG8_WAIT_V(0);
;     if (wr == 0) PG8_BAR;
;     __device__ __forceinline__ void operator()(const f32x4 (&acc)[2][2][4][2], const Unit& u, int wr, int wc, int fr, int fq) const {
;         const int row0 = u.pm * BM + wr * 64 + fr, col0 = u.pn * BM + wc * 32 + 8 * fq;
; #pragma unroll
;         for (int ai = 0; ai < 2; ++ai)
; #pragma unroll
;             for (int m = 0; m < 4; ++m) { bf16_t* rowp = O + (size_t)(row0 + ai * HALF + m * 16) * ldc + col0;
; #pragma unroll
;                 for (int bj = 0; bj < 2; ++bj) *(u32x4*)(rowp + bj * HALF) = pack8(acc[ai][bj][m][0], acc[ai][bj][m][1]); }
	v_lshl_add_u32 v148, s48, 8, v142
	v_lshl_or_b32 v140, s64, 8, v144
	v_ashrrev_i32_e32 v149, 31, v148
	v_ashrrev_i32_e32 v141, 31, v140
	v_lshlrev_b64 v[150:151], 12, v[148:149]
	v_lshl_add_u64 v[150:151], s[24:25], 0, v[150:151]
	v_lshlrev_b64 v[152:153], 1, v[140:141]
	v_lshl_add_u64 v[140:141], v[150:151], 0, v[152:153]
	v_cvt_pk_bf16_f32 v124, v124, v125
	v_cvt_pk_bf16_f32 v125, v126, v127
	v_cvt_pk_bf16_f32 v126, v120, v121
	v_cvt_pk_bf16_f32 v127, v122, v123
	global_store_dwordx4 v[140:141], v[124:127], off
	v_cvt_pk_bf16_f32 v116, v116, v117
	v_cvt_pk_bf16_f32 v117, v118, v119
	v_cvt_pk_bf16_f32 v118, v108, v109
	v_or_b32_e32 v108, 16, v148
	v_ashrrev_i32_e32 v109, 31, v108
	v_lshlrev_b64 v[108:109], 12, v[108:109]
	v_lshl_add_u64 v[108:109], s[24:25], 0, v[108:109]
	v_cvt_pk_bf16_f32 v119, v110, v111
	global_store_dwordx4 v[140:141], v[116:119], off offset:256
	s_mov_b32 s64, s40
	s_mov_b32 s48, s42
	v_lshl_add_u64 v[116:117], v[108:109], 0, v[152:153]
	v_cvt_pk_bf16_f32 v108, v112, v113
	v_cvt_pk_bf16_f32 v109, v114, v115
	v_cvt_pk_bf16_f32 v110, v104, v105
	v_cvt_pk_bf16_f32 v111, v106, v107
	global_store_dwordx4 v[116:117], v[108:111], off
	v_cvt_pk_bf16_f32 v100, v100, v101
	v_cvt_pk_bf16_f32 v101, v102, v103
	v_cvt_pk_bf16_f32 v102, v92, v93
	v_or_b32_e32 v92, 32, v148
	v_ashrrev_i32_e32 v93, 31, v92
	v_lshlrev_b64 v[92:93], 12, v[92:93]
	v_lshl_add_u64 v[92:93], s[24:25], 0, v[92:93]
	v_cvt_pk_bf16_f32 v103, v94, v95
	global_store_dwordx4 v[116:117], v[100:103], off offset:256
	s_mov_b64 s[52:53], s[46:47]
	s_mov_b64 s[50:51], s[44:45]
	v_lshl_add_u64 v[100:101], v[92:93], 0, v[152:153]
	v_cvt_pk_bf16_f32 v92, v96, v97
	v_cvt_pk_bf16_f32 v93, v98, v99
	v_cvt_pk_bf16_f32 v94, v88, v89
	v_cvt_pk_bf16_f32 v95, v90, v91
	global_store_dwordx4 v[100:101], v[92:95], off
	v_cvt_pk_bf16_f32 v84, v84, v85
	v_cvt_pk_bf16_f32 v85, v86, v87
	v_cvt_pk_bf16_f32 v86, v76, v77
	v_or_b32_e32 v76, 48, v148
	v_ashrrev_i32_e32 v77, 31, v76
	v_lshlrev_b64 v[76:77], 12, v[76:77]
	v_lshl_add_u64 v[76:77], s[24:25], 0, v[76:77]
	v_cvt_pk_bf16_f32 v87, v78, v79
	global_store_dwordx4 v[100:101], v[84:87], off offset:256
	s_nop 1
	v_lshl_add_u64 v[84:85], v[76:77], 0, v[152:153]
	v_cvt_pk_bf16_f32 v76, v80, v81
	v_cvt_pk_bf16_f32 v77, v82, v83
	v_cvt_pk_bf16_f32 v78, v72, v73
	v_cvt_pk_bf16_f32 v79, v74, v75
	global_store_dwordx4 v[84:85], v[76:79], off
	v_cvt_pk_bf16_f32 v68, v68, v69
	v_cvt_pk_bf16_f32 v69, v70, v71
	v_cvt_pk_bf16_f32 v70, v64, v65
	v_cvt_pk_bf16_f32 v71, v66, v67
	global_store_dwordx4 v[84:85], v[68:71], off offset:256
	v_cvt_pk_bf16_f32 v60, v60, v61
	v_cvt_pk_bf16_f32 v61, v62, v63
	v_cvt_pk_bf16_f32 v62, v56, v57
	v_add_co_u32_e32 v56, vcc, s60, v140
	v_lshl_add_u64 v[64:65], v[140:141], 0, s[2:3]
	s_nop 0
	v_addc_co_u32_e32 v57, vcc, 0, v141, vcc
	v_cvt_pk_bf16_f32 v63, v58, v59
	global_store_dwordx4 v[56:57], v[60:63], off
	v_cvt_pk_bf16_f32 v48, v48, v49
	v_cvt_pk_bf16_f32 v49, v50, v51
	v_cvt_pk_bf16_f32 v50, v40, v41
	v_cvt_pk_bf16_f32 v51, v42, v43
	global_store_dwordx4 v[64:65], v[48:51], off offset:256
	v_cvt_pk_bf16_f32 v40, v52, v53
	v_cvt_pk_bf16_f32 v41, v54, v55
	v_cvt_pk_bf16_f32 v42, v44, v45
	v_add_co_u32_e32 v44, vcc, s61, v140
	s_nop 0
	v_lshl_add_u64 v[48:49], v[140:141], 0, s[8:9]
	v_addc_co_u32_e32 v45, vcc, 0, v141, vcc
	v_cvt_pk_bf16_f32 v43, v46, v47
	global_store_dwordx4 v[44:45], v[40:43], off
	v_cvt_pk_bf16_f32 v32, v32, v33
	v_cvt_pk_bf16_f32 v33, v34, v35
	v_cvt_pk_bf16_f32 v34, v24, v25
	v_cvt_pk_bf16_f32 v35, v26, v27
	global_store_dwordx4 v[48:49], v[32:35], off offset:256
	v_cvt_pk_bf16_f32 v24, v36, v37
	v_cvt_pk_bf16_f32 v25, v38, v39
	v_cvt_pk_bf16_f32 v26, v28, v29
	v_add_co_u32_e32 v28, vcc, s62, v140
	s_nop 0
	v_lshl_add_u64 v[32:33], v[140:141], 0, s[30:31]
	v_addc_co_u32_e32 v29, vcc, 0, v141, vcc
	v_cvt_pk_bf16_f32 v27, v30, v31
	global_store_dwordx4 v[28:29], v[24:27], off
	v_cvt_pk_bf16_f32 v16, v16, v17
	v_cvt_pk_bf16_f32 v17, v18, v19
	v_cvt_pk_bf16_f32 v18, v8, v9
	v_cvt_pk_bf16_f32 v19, v10, v11
	global_store_dwordx4 v[32:33], v[16:19], off offset:256
	v_cvt_pk_bf16_f32 v8, v20, v21
	v_cvt_pk_bf16_f32 v9, v22, v23
	v_cvt_pk_bf16_f32 v10, v12, v13
	v_add_co_u32_e32 v12, vcc, s63, v140
	s_nop 0
	v_lshl_add_u64 v[16:17], v[140:141], 0, s[34:35]
	v_addc_co_u32_e32 v13, vcc, 0, v141, vcc
	s_and_b64 vcc, exec, s[38:39]
	v_cvt_pk_bf16_f32 v11, v14, v15
	global_store_dwordx4 v[12:13], v[8:11], off
	v_cvt_pk_bf16_f32 v4, v4, v5
	v_cvt_pk_bf16_f32 v5, v6, v7
	v_cvt_pk_bf16_f32 v6, v0, v1
	v_cvt_pk_bf16_f32 v7, v2, v3
	global_store_dwordx4 v[16:17], v[4:7], off offset:256
	s_cbranch_vccz .LBB0_670
	s_waitcnt vmcnt(0)
	s_cmpk_gt_u32 s10, 0xff
	v_readlane_b32 s62, v232, 20
	v_readlane_b32 s61, v232, 21
	s_cbranch_scc1 .LBB0_677
	s_barrier

; #define PG8_STAGE(bufoff, gbase, voff) do { _Pragma("unroll") for (int _i = 0; _i < 2; ++_i) \
;         __builtin_amdgcn_global_load_lds((const unsigned*)((const char*)(gbase) + (voff)[_i]), (LAS unsigned*)(lds + (bufoff) + ldsw + _i * 8192), 16, 0, 0); } while (0)
; #define PG8_LDA(dst, b, h) do { _Pragma("unroll") for (int m = 0; m < 4; ++m) _Pragma("unroll") for (int k = 0; k < 2; ++k) dst[m][k] = *(const LAS bf16x8*)(lds + PG8_SA(b, h) + aoff + m * 2048 + k * 1024); } while (0)
; #define PG8_LDB(dst, b, h) do { _Pragma("unroll") for (int n = 0; n < 2; ++n) _Pragma("unroll") for (int k = 0; k < 2; ++k) dst[n][k] = *(const LAS bf16x8*)(lds + PG8_SB(b, h) + boff + n * 2048 + k * 1024); } while (0)
; #define PG8_WAIT_V(n) asm volatile("s_waitcnt vmcnt(" #n ")" ::: "memory")
; template <class Epi>
; __device__ __forceinline__ void gemm_phase(LAS unsigned char* lds, const Gemm g, const StaticOrder& S, const Epi& E) {
;     ...
;         for (int t = 0; t < nt; t += 2) {
;             const bool last = (t == nt - 2);
;             const char* a1 = cA + (size_t)(t + 1) * kstep;
;             const char* a2 = last ? nA : cA + (size_t)(t + 2) * kstep; const char* b2 = last ? nB : cB + (size_t)(t + 2) * kstep;
;             const char* a3 = a2 + kstep; const char* b3 = b2 + kstep;
;             PG8_LDB(B0, 0, 0); PG8_SCHED; PG8_LDA(At, 0, 0); PG8_STAGE(PG8_SA(1, 1), a1 + hstep, voffA);
;             PG8_WAIT_L(8); PG8_BAR; PG8_WAIT_L(0); PG8_MMA(0, 0, At, B0); PG8_BAR; PG8_SCHED;
;             PG8_LDB(B1, 0, 1); PG8_STAGE(PG8_SB(0, 0), b2, voffB);
;             PG8_BAR; PG8_WAIT_L(0); PG8_MMA(0, 1, At, B1); PG8_BAR;
;             PG8_LDA(At, 0, 1); PG8_STAGE(PG8_SA(0, 0), a2, voffA);
;             PG8_BAR; PG8_WAIT_L(0); PG8_MMA(1, 0, At, B0); PG8_BAR; PG8_SCHED;
;             PG8_STAGE(PG8_SB(0, 1), b2 + hstep, voffB);
;             PG8_WAIT_V(6); PG8_BAR; PG8_MMA(1, 1, At, B1); PG8_BAR;
;             PG8_LDB(B0, 1, 0); PG8_SCHED; PG8_LDA(At, 1, 0); PG8_STAGE(PG8_SA(0, 1), a2 + hstep, voffA);
;             PG8_WAIT_L(8); PG8_BAR; PG8_WAIT_L(0); PG8_MMA(0, 0, At, B0); PG8_BAR; PG8_SCHED;
;             PG8_LDB(B1, 1, 1); PG8_STAGE(PG8_SB(1, 0), b3, voffB);
;             PG8_BAR; PG8_WAIT_L(0); PG8_MMA(0, 1, At, B1); PG8_BAR;
;             PG8_LDA(At, 1, 1); PG8_STAGE(PG8_SA(1, 0), a3, voffA);
;             PG8_BAR; PG8_WAIT_L(0); PG8_MMA(1, 0, At, B0); PG8_BAR; PG8_SCHED;
.LBB0_796:
	ds_read_b128 v[144:147], v155
	ds_read_b128 v[148:151], v155 offset:1024
	ds_read_b128 v[160:163], v155 offset:2048
	ds_read_b128 v[164:167], v155 offset:3072
	s_add_u32 s42, s40, 0xfff80080
	s_addc_u32 s43, s41, -1
	s_cmp_eq_u32 s58, 28
	s_cselect_b32 s45, s31, s43
	s_cselect_b32 s44, s54, s42
	s_cselect_b32 s43, s9, s57
	s_cselect_b32 s42, s55, s56
	s_add_i32 m0, s27, 0xc000
	ds_read_b128 v[168:171], v156
	ds_read_b128 v[172:175], v156 offset:1024
	ds_read_b128 v[176:179], v156 offset:2048
	ds_read_b128 v[180:183], v156 offset:3072
	ds_read_b128 v[184:187], v156 offset:4096
	ds_read_b128 v[188:191], v156 offset:5120
	ds_read_b128 v[192:195], v156 offset:6144
	ds_read_b128 v[196:199], v156 offset:7168
	global_load_lds_dwordx4 v136, s[40:41]
	s_add_i32 m0, s27, 0xe000
	s_nop 0
	global_load_lds_dwordx4 v138, s[40:41]
	s_waitcnt lgkmcnt(8)
	s_barrier
	s_waitcnt lgkmcnt(0)
	v_mfma_f32_16x16x32_bf16 v[124:127], v[144:147], v[168:171], v[124:127]
	v_mfma_f32_16x16x32_bf16 v[120:123], v[160:163], v[168:171], v[120:123]
	v_mfma_f32_16x16x32_bf16 v[108:111], v[144:147], v[176:179], v[108:111]
	v_mfma_f32_16x16x32_bf16 v[104:107], v[160:163], v[176:179], v[104:107]
	v_mfma_f32_16x16x32_bf16 v[92:95], v[144:147], v[184:187], v[92:95]
	v_mfma_f32_16x16x32_bf16 v[88:91], v[160:163], v[184:187], v[88:91]
	v_mfma_f32_16x16x32_bf16 v[76:79], v[144:147], v[192:195], v[76:79]
	v_mfma_f32_16x16x32_bf16 v[72:75], v[160:163], v[192:195], v[72:75]
	v_mfma_f32_16x16x32_bf16 v[124:127], v[148:151], v[172:175], v[124:127]
	v_mfma_f32_16x16x32_bf16 v[120:123], v[164:167], v[172:175], v[120:123]
	v_mfma_f32_16x16x32_bf16 v[108:111], v[148:151], v[180:183], v[108:111]
	v_mfma_f32_16x16x32_bf16 v[104:107], v[164:167], v[180:183], v[104:107]
	v_mfma_f32_16x16x32_bf16 v[92:95], v[148:151], v[188:191], v[92:95]
	v_mfma_f32_16x16x32_bf16 v[88:91], v[164:167], v[188:191], v[88:91]
	v_mfma_f32_16x16x32_bf16 v[76:79], v[148:151], v[196:199], v[76:79]
	v_mfma_f32_16x16x32_bf16 v[72:75], v[164:167], v[196:199], v[72:75]
	s_barrier
	s_add_i32 s59, s50, s23
	s_add_u32 s98, s42, s2
	s_addc_u32 s99, s43, s3
	s_mov_b32 m0, s59
	ds_read_b128 v[200:203], v157
	ds_read_b128 v[204:207], v157 offset:1024
	ds_read_b128 v[208:211], v157 offset:2048
	ds_read_b128 v[212:215], v157 offset:3072
	global_load_lds_dwordx4 v132, s[42:43]
	s_add_i32 m0, s59, 0x2000
	s_nop 0
	global_load_lds_dwordx4 v128, s[42:43]
	s_barrier
	s_waitcnt lgkmcnt(0)
	v_mfma_f32_16x16x32_bf16 v[116:119], v[200:203], v[168:171], v[116:119]
	v_mfma_f32_16x16x32_bf16 v[112:115], v[208:211], v[168:171], v[112:115]
	v_mfma_f32_16x16x32_bf16 v[100:103], v[200:203], v[176:179], v[100:103]
	v_mfma_f32_16x16x32_bf16 v[96:99], v[208:211], v[176:179], v[96:99]
	v_mfma_f32_16x16x32_bf16 v[84:87], v[200:203], v[184:187], v[84:87]
	v_mfma_f32_16x16x32_bf16 v[80:83], v[208:211], v[184:187], v[80:83]
	v_mfma_f32_16x16x32_bf16 v[68:71], v[200:203], v[192:195], v[68:71]
	v_mfma_f32_16x16x32_bf16 v[64:67], v[208:211], v[192:195], v[64:67]
	v_mfma_f32_16x16x32_bf16 v[116:119], v[204:207], v[172:175], v[116:119]
	v_mfma_f32_16x16x32_bf16 v[112:115], v[212:215], v[172:175], v[112:115]
	v_mfma_f32_16x16x32_bf16 v[100:103], v[204:207], v[180:183], v[100:103]
	v_mfma_f32_16x16x32_bf16 v[96:99], v[212:215], v[180:183], v[96:99]
	v_mfma_f32_16x16x32_bf16 v[84:87], v[204:207], v[188:191], v[84:87]
	v_mfma_f32_16x16x32_bf16 v[80:83], v[212:215], v[188:191], v[80:83]
	v_mfma_f32_16x16x32_bf16 v[68:71], v[204:207], v[196:199], v[68:71]
	v_mfma_f32_16x16x32_bf16 v[64:67], v[212:215], v[196:199], v[64:67]
	s_mov_b32 m0, s27
	s_add_u32 s100, s44, s2
	s_addc_u32 s101, s45, s3
	s_barrier
	ds_read_b128 v[168:171], v156 offset:16384
	ds_read_b128 v[172:175], v156 offset:17408
	ds_read_b128 v[176:179], v156 offset:18432
	ds_read_b128 v[180:183], v156 offset:19456
	ds_read_b128 v[184:187], v156 offset:20480
	ds_read_b128 v[188:191], v156 offset:21504
	ds_read_b128 v[192:195], v156 offset:22528
	ds_read_b128 v[196:199], v156 offset:23552
	global_load_lds_dwordx4 v134, s[44:45]
	s_mov_b32 m0, s28
	s_nop 0
	global_load_lds_dwordx4 v130, s[44:45]
	s_barrier
	s_waitcnt lgkmcnt(0)
	v_mfma_f32_16x16x32_bf16 v[60:63], v[144:147], v[168:171], v[60:63]
	v_mfma_f32_16x16x32_bf16 v[56:59], v[160:163], v[168:171], v[56:59]
	v_mfma_f32_16x16x32_bf16 v[44:47], v[144:147], v[176:179], v[44:47]
	v_mfma_f32_16x16x32_bf16 v[40:43], v[160:163], v[176:179], v[40:43]
	v_mfma_f32_16x16x32_bf16 v[28:31], v[144:147], v[184:187], v[28:31]
	v_mfma_f32_16x16x32_bf16 v[24:27], v[160:163], v[184:187], v[24:27]
	v_mfma_f32_16x16x32_bf16 v[12:15], v[144:147], v[192:195], v[12:15]
	v_mfma_f32_16x16x32_bf16 v[8:11], v[160:163], v[192:195], v[8:11]
	v_mfma_f32_16x16x32_bf16 v[60:63], v[148:151], v[172:175], v[60:63]
	v_mfma_f32_16x16x32_bf16 v[56:59], v[164:167], v[172:175], v[56:59]
	v_mfma_f32_16x16x32_bf16 v[44:47], v[148:151], v[180:183], v[44:47]
	v_mfma_f32_16x16x32_bf16 v[40:43], v[164:167], v[180:183], v[40:43]
	v_mfma_f32_16x16x32_bf16 v[28:31], v[148:151], v[188:191], v[28:31]
	v_mfma_f32_16x16x32_bf16 v[24:27], v[164:167], v[188:191], v[24:27]
	v_mfma_f32_16x16x32_bf16 v[12:15], v[148:151], v[196:199], v[12:15]
	v_mfma_f32_16x16x32_bf16 v[8:11], v[164:167], v[196:199], v[8:11]
	s_barrier
	s_add_u32 s60, s42, 0x80000
	s_addc_u32 s61, s43, 0
	s_add_i32 s59, s51, s23
	s_mov_b32 m0, s59
	s_nop 0
	global_load_lds_dwordx4 v132, s[60:61]
	s_add_i32 m0, s59, 0x2000
	s_nop 0
	global_load_lds_dwordx4 v128, s[60:61]
	s_waitcnt vmcnt(6)
	s_barrier
; #define PG8_STAGE(bufoff, gbase, voff) do { _Pragma("unroll") for (int _i = 0; _i < 2; ++_i) \
;         __builtin_amdgcn_global_load_lds((const unsigned*)((const char*)(gbase) + (voff)[_i]), (LAS unsigned*)(lds + (bufoff) + ldsw + _i * 8192), 16, 0, 0); } while (0)
; #define PG8_LDA(dst, b, h) do { _Pragma("unroll") for (int m = 0; m < 4; ++m) _Pragma("unroll") for (int k = 0; k < 2; ++k) dst[m][k] = *(const LAS bf16x8*)(lds + PG8_SA(b, h) + aoff + m * 2048 + k * 1024); } while (0)
; #define PG8_LDB(dst, b, h) do { _Pragma("unroll") for (int n = 0; n < 2; ++n) _Pragma("unroll") for (int k = 0; k < 2; ++k) dst[n][k] = *(const LAS bf16x8*)(lds + PG8_SB(b, h) + boff + n * 2048 + k * 1024); } while (0)
; #define PG8_MMA(ai, bj, At, Bt) do { __builtin_amdgcn_s_setprio(1); _Pragma("unroll") for (int m = 0; m < 4; ++m) _Pragma("unroll") for (int n = 0; n < 2; ++n) _Pragma("unroll") for (int k = 0; k < 2; ++k) \
;         acc[ai][bj][m][n] = __builtin_amdgcn_mfma_f32_16x16x32_bf16(Bt[n][k], At[m][k], acc[ai][bj][m][n], 0, 0, 0); __builtin_amdgcn_s_setprio(0); } while (0)
; #define PG8_WAIT_V(n) asm volatile("s_waitcnt vmcnt(" #n ")" ::: "memory")
; #define PG8_WAIT_L(n) asm volatile("s_waitcnt lgkmcnt(" #n ")" ::: "memory")
; #define PG8_BAR __builtin_amdgcn_s_barrier()
; #define PG8_SCHED __builtin_amdgcn_sched_barrier(0)
; template <class Epi>
; __device__ __forceinline__ void gemm_phase(LAS unsigned char* lds, const Gemm g, const StaticOrder& S, const Epi& E) {
;     ...
;             PG8_WAIT_V(6); PG8_BAR; PG8_MMA(1, 1, At, B1); PG8_BAR;
;             PG8_LDB(B0, 1, 0); PG8_SCHED; PG8_LDA(At, 1, 0); PG8_STAGE(PG8_SA(0, 1), a2 + hstep, voffA);
;             PG8_WAIT_L(8); PG8_BAR; PG8_WAIT_L(0); PG8_MMA(0, 0, At, B0); PG8_BAR; PG8_SCHED;
;             PG8_LDB(B1, 1, 1); PG8_STAGE(PG8_SB(1, 0), b3, voffB);
;             PG8_BAR; PG8_WAIT_L(0); PG8_MMA(0, 1, At, B1); PG8_BAR;
;             PG8_LDA(At, 1, 1); PG8_STAGE(PG8_SA(1, 0), a3, voffA);
;             PG8_BAR; PG8_WAIT_L(0); PG8_MMA(1, 0, At, B0); PG8_BAR; PG8_SCHED;
	v_mfma_f32_16x16x32_bf16 v[52:55], v[200:203], v[168:171], v[52:55]
	v_mfma_f32_16x16x32_bf16 v[48:51], v[208:211], v[168:171], v[48:51]
	v_mfma_f32_16x16x32_bf16 v[36:39], v[200:203], v[176:179], v[36:39]
	v_mfma_f32_16x16x32_bf16 v[32:35], v[208:211], v[176:179], v[32:35]
	v_mfma_f32_16x16x32_bf16 v[20:23], v[200:203], v[184:187], v[20:23]
	v_mfma_f32_16x16x32_bf16 v[16:19], v[208:211], v[184:187], v[16:19]
	v_mfma_f32_16x16x32_bf16 v[4:7], v[200:203], v[192:195], v[4:7]
	v_mfma_f32_16x16x32_bf16 v[0:3], v[208:211], v[192:195], v[0:3]
	v_mfma_f32_16x16x32_bf16 v[52:55], v[204:207], v[172:175], v[52:55]
	v_mfma_f32_16x16x32_bf16 v[48:51], v[212:215], v[172:175], v[48:51]
	v_mfma_f32_16x16x32_bf16 v[36:39], v[204:207], v[180:183], v[36:39]
	v_mfma_f32_16x16x32_bf16 v[32:35], v[212:215], v[180:183], v[32:35]
	v_mfma_f32_16x16x32_bf16 v[20:23], v[204:207], v[188:191], v[20:23]
	v_mfma_f32_16x16x32_bf16 v[16:19], v[212:215], v[188:191], v[16:19]
	v_mfma_f32_16x16x32_bf16 v[4:7], v[204:207], v[196:199], v[4:7]
	v_mfma_f32_16x16x32_bf16 v[0:3], v[212:215], v[196:199], v[0:3]
	s_add_i32 s59, 0, 0x18000
	v_add_u32_e32 v164, s59, v153
	s_barrier
	ds_read_b128 v[144:147], v164
	ds_read_b128 v[148:151], v164 offset:1024
	ds_read_b128 v[160:163], v164 offset:2048
	ds_read_b128 v[164:167], v164 offset:3072
	s_add_u32 s44, s44, 0x80000
	s_addc_u32 s45, s45, 0
	s_mov_b32 m0, s29
	ds_read_b128 v[168:171], v156 offset:32768
	ds_read_b128 v[172:175], v156 offset:33792
	ds_read_b128 v[176:179], v156 offset:34816
	ds_read_b128 v[180:183], v156 offset:35840
	ds_read_b128 v[184:187], v156 offset:36864
	ds_read_b128 v[188:191], v156 offset:37888
	ds_read_b128 v[192:195], v156 offset:38912
	ds_read_b128 v[196:199], v156 offset:39936
	global_load_lds_dwordx4 v134, s[44:45]
	s_mov_b32 m0, s33
	s_nop 0
	global_load_lds_dwordx4 v130, s[44:45]
	s_waitcnt lgkmcnt(8)
	s_barrier
	s_waitcnt lgkmcnt(0)
	v_mfma_f32_16x16x32_bf16 v[124:127], v[144:147], v[168:171], v[124:127]
	v_mfma_f32_16x16x32_bf16 v[120:123], v[160:163], v[168:171], v[120:123]
	v_mfma_f32_16x16x32_bf16 v[108:111], v[144:147], v[176:179], v[108:111]
	v_mfma_f32_16x16x32_bf16 v[104:107], v[160:163], v[176:179], v[104:107]
	v_mfma_f32_16x16x32_bf16 v[92:95], v[144:147], v[184:187], v[92:95]
	v_mfma_f32_16x16x32_bf16 v[88:91], v[160:163], v[184:187], v[88:91]
	v_mfma_f32_16x16x32_bf16 v[76:79], v[144:147], v[192:195], v[76:79]
	v_mfma_f32_16x16x32_bf16 v[72:75], v[160:163], v[192:195], v[72:75]
	v_mfma_f32_16x16x32_bf16 v[124:127], v[148:151], v[172:175], v[124:127]
	v_mfma_f32_16x16x32_bf16 v[120:123], v[164:167], v[172:175], v[120:123]
	v_mfma_f32_16x16x32_bf16 v[108:111], v[148:151], v[180:183], v[108:111]
	v_mfma_f32_16x16x32_bf16 v[104:107], v[164:167], v[180:183], v[104:107]
	v_mfma_f32_16x16x32_bf16 v[92:95], v[148:151], v[188:191], v[92:95]
	v_mfma_f32_16x16x32_bf16 v[88:91], v[164:167], v[188:191], v[88:91]
	v_mfma_f32_16x16x32_bf16 v[76:79], v[148:151], v[196:199], v[76:79]
	v_mfma_f32_16x16x32_bf16 v[72:75], v[164:167], v[196:199], v[72:75]
	s_barrier
	s_add_i32 s44, 0, 0x1c000
	s_add_i32 s45, s59, s23
	v_add_u32_e32 v212, s44, v153
	s_mov_b32 m0, s45
	ds_read_b128 v[200:203], v212
	ds_read_b128 v[204:207], v212 offset:1024
	ds_read_b128 v[208:211], v212 offset:2048
	ds_read_b128 v[212:215], v212 offset:3072
	global_load_lds_dwordx4 v132, s[98:99]
	s_add_i32 m0, s45, 0x2000
	s_nop 0
	global_load_lds_dwordx4 v128, s[98:99]
	s_barrier
	s_waitcnt lgkmcnt(0)
	v_mfma_f32_16x16x32_bf16 v[116:119], v[200:203], v[168:171], v[116:119]
	v_mfma_f32_16x16x32_bf16 v[112:115], v[208:211], v[168:171], v[112:115]
	v_mfma_f32_16x16x32_bf16 v[100:103], v[200:203], v[176:179], v[100:103]
	v_mfma_f32_16x16x32_bf16 v[96:99], v[208:211], v[176:179], v[96:99]
	v_mfma_f32_16x16x32_bf16 v[84:87], v[200:203], v[184:187], v[84:87]
	v_mfma_f32_16x16x32_bf16 v[80:83], v[208:211], v[184:187], v[80:83]
	v_mfma_f32_16x16x32_bf16 v[68:71], v[200:203], v[192:195], v[68:71]
	v_mfma_f32_16x16x32_bf16 v[64:67], v[208:211], v[192:195], v[64:67]
	v_mfma_f32_16x16x32_bf16 v[116:119], v[204:207], v[172:175], v[116:119]
	v_mfma_f32_16x16x32_bf16 v[112:115], v[212:215], v[172:175], v[112:115]
	v_mfma_f32_16x16x32_bf16 v[100:103], v[204:207], v[180:183], v[100:103]
	v_mfma_f32_16x16x32_bf16 v[96:99], v[212:215], v[180:183], v[96:99]
	v_mfma_f32_16x16x32_bf16 v[84:87], v[204:207], v[188:191], v[84:87]
	v_mfma_f32_16x16x32_bf16 v[80:83], v[212:215], v[188:191], v[80:83]
	v_mfma_f32_16x16x32_bf16 v[68:71], v[204:207], v[196:199], v[68:71]
	v_mfma_f32_16x16x32_bf16 v[64:67], v[212:215], v[196:199], v[64:67]
	s_mov_b32 m0, s46
	s_barrier
	ds_read_b128 v[168:171], v156 offset:49152
	ds_read_b128 v[172:175], v156 offset:50176
	ds_read_b128 v[176:179], v156 offset:51200
	ds_read_b128 v[180:183], v156 offset:52224
	ds_read_b128 v[184:187], v156 offset:53248
	ds_read_b128 v[188:191], v156 offset:54272
	ds_read_b128 v[192:195], v156 offset:55296
	ds_read_b128 v[196:199], v156 offset:56320
	global_load_lds_dwordx4 v134, s[100:101]
	s_mov_b32 m0, s47
	s_nop 0
	global_load_lds_dwordx4 v130, s[100:101]
	s_barrier
; __device__ __forceinline__ float fast_rcp(float x) { return __builtin_amdgcn_rcpf(x); }
; __device__ __forceinline__ float fast_exp2(float x) { return __builtin_amdgcn_exp2f(x); }
; #define PG8_STAGE(bufoff, gbase, voff) do { _Pragma("unroll") for (int _i = 0; _i < 2; ++_i) \
;         __builtin_amdgcn_global_load_lds((const unsigned*)((const char*)(gbase) + (voff)[_i]), (LAS unsigned*)(lds + (bufoff) + ldsw + _i * 8192), 16, 0, 0); } while (0)
; #define PG8_MMA(ai, bj, At, Bt) do { __builtin_amdgcn_s_setprio(1); _Pragma("unroll") for (int m = 0; m < 4; ++m) _Pragma("unroll") for (int n = 0; n < 2; ++n) _Pragma("unroll") for (int k = 0; k < 2; ++k) \
;         acc[ai][bj][m][n] = __builtin_amdgcn_mfma_f32_16x16x32_bf16(Bt[n][k], At[m][k], acc[ai][bj][m][n], 0, 0, 0); __builtin_amdgcn_s_setprio(0); } while (0)
; #define PG8_WAIT_V(n) asm volatile("s_waitcnt vmcnt(" #n ")" ::: "memory")
; #define PG8_WAIT_L(n) asm volatile("s_waitcnt lgkmcnt(" #n ")" ::: "memory")
; #define PG8_BAR __builtin_amdgcn_s_barrier()
; #define PG8_SCHED __builtin_amdgcn_sched_barrier(0)
; template <class Epi>
; __device__ __forceinline__ void gemm_phase(LAS unsigned char* lds, const Gemm g, const StaticOrder& S, const Epi& E) {
;     ...
;             PG8_BAR; PG8_WAIT_L(0); PG8_MMA(1, 0, At, B0); PG8_BAR; PG8_SCHED;
;             PG8_STAGE(PG8_SB(1, 1), b3 + hstep, voffB);
;             PG8_WAIT_V(6); PG8_BAR; PG8_MMA(1, 1, At, B1); PG8_BAR;
;         }
;     __device__ __forceinline__ void operator()(const f32x4 (&acc)[2][2][4][2], const Unit& u, int wr, int wc, int fr, int fq) const {
;         const int row0 = u.pm * BM + wr * 64 + fr, col0 = u.pn * HALF + wc * 32 + 8 * fq;
; #pragma unroll
;         for (int ai = 0; ai < 2; ++ai)
; #pragma unroll
;             for (int m = 0; m < 4; ++m) { bf16_t* rowp = O + (size_t)(row0 + ai * HALF + m * 16) * DFF + col0;
;                 const float r = rs[row0 + ai * HALF + m * 16], r2 = r * r;
;                 f32x4 h0, h1;
; #pragma unroll
;                 for (int j = 0; j < 4; ++j) {
;                     const float g0 = acc[ai][0][m][0][j], g1 = acc[ai][0][m][1][j];
;                     h0[j] = g0 * r2 * fast_rcp(1.0f + fast_exp2(g0 * (-LOG2E * r))) * acc[ai][1][m][0][j];
;                     h1[j] = g1 * r2 * fast_rcp(1.0f + fast_exp2(g1 * (-LOG2E * r))) * acc[ai][1][m][1][j]; }
;                 *(u32x4*)rowp = pack8(h0, h1); }
	s_waitcnt lgkmcnt(0)
	v_mfma_f32_16x16x32_bf16 v[60:63], v[144:147], v[168:171], v[60:63]
	v_mfma_f32_16x16x32_bf16 v[56:59], v[160:163], v[168:171], v[56:59]
	v_mfma_f32_16x16x32_bf16 v[44:47], v[144:147], v[176:179], v[44:47]
	v_mfma_f32_16x16x32_bf16 v[40:43], v[160:163], v[176:179], v[40:43]
	v_mfma_f32_16x16x32_bf16 v[28:31], v[144:147], v[184:187], v[28:31]
	v_mfma_f32_16x16x32_bf16 v[24:27], v[160:163], v[184:187], v[24:27]
	v_mfma_f32_16x16x32_bf16 v[12:15], v[144:147], v[192:195], v[12:15]
	v_mfma_f32_16x16x32_bf16 v[8:11], v[160:163], v[192:195], v[8:11]
	v_mfma_f32_16x16x32_bf16 v[60:63], v[148:151], v[172:175], v[60:63]
	v_mfma_f32_16x16x32_bf16 v[56:59], v[164:167], v[172:175], v[56:59]
	v_mfma_f32_16x16x32_bf16 v[44:47], v[148:151], v[180:183], v[44:47]
	v_mfma_f32_16x16x32_bf16 v[40:43], v[164:167], v[180:183], v[40:43]
	v_mfma_f32_16x16x32_bf16 v[28:31], v[148:151], v[188:191], v[28:31]
	v_mfma_f32_16x16x32_bf16 v[24:27], v[164:167], v[188:191], v[24:27]
	v_mfma_f32_16x16x32_bf16 v[12:15], v[148:151], v[196:199], v[12:15]
	v_mfma_f32_16x16x32_bf16 v[8:11], v[164:167], v[196:199], v[8:11]
	s_barrier
	s_add_u32 s42, s42, 0x80080
	s_addc_u32 s43, s43, 0
	s_add_i32 s44, s44, s23
	s_mov_b32 m0, s44
	s_nop 0
	global_load_lds_dwordx4 v132, s[42:43]
	s_add_i32 m0, s44, 0x2000
	s_nop 0
	global_load_lds_dwordx4 v128, s[42:43]
	s_waitcnt vmcnt(6)
	s_barrier
	v_mfma_f32_16x16x32_bf16 v[52:55], v[200:203], v[168:171], v[52:55]
	v_mfma_f32_16x16x32_bf16 v[48:51], v[208:211], v[168:171], v[48:51]
	v_mfma_f32_16x16x32_bf16 v[36:39], v[200:203], v[176:179], v[36:39]
	v_mfma_f32_16x16x32_bf16 v[32:35], v[208:211], v[176:179], v[32:35]
	v_mfma_f32_16x16x32_bf16 v[20:23], v[200:203], v[184:187], v[20:23]
	v_mfma_f32_16x16x32_bf16 v[16:19], v[208:211], v[184:187], v[16:19]
	v_mfma_f32_16x16x32_bf16 v[4:7], v[200:203], v[192:195], v[4:7]
	v_mfma_f32_16x16x32_bf16 v[0:3], v[208:211], v[192:195], v[0:3]
	v_mfma_f32_16x16x32_bf16 v[52:55], v[204:207], v[172:175], v[52:55]
	v_mfma_f32_16x16x32_bf16 v[48:51], v[212:215], v[172:175], v[48:51]
	v_mfma_f32_16x16x32_bf16 v[36:39], v[204:207], v[180:183], v[36:39]
	v_mfma_f32_16x16x32_bf16 v[32:35], v[212:215], v[180:183], v[32:35]
	v_mfma_f32_16x16x32_bf16 v[20:23], v[204:207], v[188:191], v[20:23]
	v_mfma_f32_16x16x32_bf16 v[16:19], v[212:215], v[188:191], v[16:19]
	v_mfma_f32_16x16x32_bf16 v[4:7], v[204:207], v[196:199], v[4:7]
	v_mfma_f32_16x16x32_bf16 v[0:3], v[212:215], v[196:199], v[0:3]
	s_add_i32 s58, s58, 2
	s_add_u32 s40, s40, 0x100
	s_addc_u32 s41, s41, 0
	s_add_u32 s56, s56, 0x100
	s_addc_u32 s57, s57, 0
	s_cmp_gt_u32 s58, 29
	s_barrier
	s_cbranch_scc0 .LBB0_796
	v_lshl_add_u32 v144, s38, 8, v152
	v_ashrrev_i32_e32 v145, 31, v144
	v_lshl_add_u64 v[150:151], v[144:145], 2, s[14:15]
	v_mov_b32_e32 v145, v224
	v_mov_b32_e32 v204, v225
	v_mov_b32_e32 v205, v226
	v_mov_b32_e32 v206, v227
	v_mov_b32_e32 v207, v228
	v_mov_b32_e32 v208, v229
	v_mov_b32_e32 v209, v230
	v_mov_b32_e32 v210, v231
	v_lshl_or_b32 v148, s53, 7, v154
	v_mov_b64_e32 v[146:147], s[20:21]
	v_ashrrev_i32_e32 v149, 31, v148
	v_mad_i64_i32 v[160:161], s[40:41], v144, s52, v[146:147]
	v_lshlrev_b64 v[148:149], 1, v[148:149]
	v_lshl_add_u64 v[160:161], v[160:161], 0, v[148:149]
	s_and_b64 vcc, exec, s[6:7]
	s_mov_b32 s53, s8
	s_mov_b32 s38, s30
	s_mov_b64 s[42:43], s[36:37]
	v_mul_f32_e32 v162, v145, v145
	v_mul_f32_e32 v145, 0xbfb8aa3b, v145
	v_mul_f32_e32 v163, v124, v162
	v_mul_f32_e32 v164, v120, v162
	v_mul_f32_e32 v120, v120, v145
	v_mul_f32_e32 v165, v125, v162
	v_mul_f32_e32 v125, v125, v145
	v_mul_f32_e32 v166, v121, v162
	v_mul_f32_e32 v121, v121, v145
	v_mul_f32_e32 v167, v126, v162
	v_mul_f32_e32 v126, v126, v145
	v_mul_f32_e32 v168, v122, v162
	v_mul_f32_e32 v122, v122, v145
	v_mul_f32_e32 v169, v127, v162
	v_mul_f32_e32 v127, v127, v145
	v_mul_f32_e32 v162, v123, v162
	v_mul_f32_e32 v123, v123, v145
	v_mul_f32_e32 v124, v124, v145
	v_exp_f32_e32 v120, v120
	v_exp_f32_e32 v125, v125
	v_exp_f32_e32 v121, v121
	v_exp_f32_e32 v126, v126
	v_exp_f32_e32 v122, v122
	v_exp_f32_e32 v127, v127
	v_exp_f32_e32 v123, v123
	v_exp_f32_e32 v124, v124
	v_add_f32_e32 v120, 1.0, v120
	v_add_f32_e32 v125, 1.0, v125
	v_add_f32_e32 v121, 1.0, v121
	v_add_f32_e32 v126, 1.0, v126
	v_add_f32_e32 v122, 1.0, v122
	v_add_f32_e32 v127, 1.0, v127
	v_add_f32_e32 v123, 1.0, v123
	v_add_f32_e32 v124, 1.0, v124
	v_rcp_f32_e32 v120, v120
	v_rcp_f32_e32 v125, v125
	v_rcp_f32_e32 v121, v121
	v_rcp_f32_e32 v126, v126
	v_rcp_f32_e32 v122, v122
	v_rcp_f32_e32 v127, v127
	v_rcp_f32_e32 v123, v123
	v_rcp_f32_e32 v124, v124
	v_mul_f32_e32 v120, v164, v120
	v_mul_f32_e32 v125, v165, v125
	v_mul_f32_e32 v121, v166, v121
	v_mul_f32_e32 v126, v167, v126
	v_mul_f32_e32 v122, v168, v122
	v_mul_f32_e32 v127, v169, v127
	v_mul_f32_e32 v123, v162, v123
	v_mul_f32_e32 v124, v163, v124
	v_mul_f32_e32 v120, v112, v120
	v_mul_f32_e32 v112, v117, v125
	v_mul_f32_e32 v117, v113, v121
	v_mul_f32_e32 v113, v118, v126
	v_mul_f32_e32 v118, v114, v122
	v_mul_f32_e32 v114, v119, v127
	v_mul_f32_e32 v115, v115, v123
	v_mul_f32_e32 v116, v116, v124
	v_cvt_pk_bf16_f32 v112, v116, v112
	v_cvt_pk_bf16_f32 v113, v113, v114
	v_cvt_pk_bf16_f32 v114, v120, v117
	v_cvt_pk_bf16_f32 v115, v118, v115
	global_store_dwordx4 v[160:161], v[112:115], off
	s_nop 1
	v_mov_b32_e32 v114, v204
	s_nop 0
	v_or_b32_e32 v112, 16, v144
	v_mad_i64_i32 v[112:113], s[40:41], v112, s52, v[146:147]
	v_lshl_add_u64 v[112:113], v[112:113], 0, v[148:149]
	v_mul_f32_e32 v115, v114, v114
	v_mul_f32_e32 v114, 0xbfb8aa3b, v114
	v_mul_f32_e32 v116, v108, v115
	v_mul_f32_e32 v117, v104, v115
	v_mul_f32_e32 v104, v104, v114
; __device__ __forceinline__ float fast_rcp(float x) { return __builtin_amdgcn_rcpf(x); }
; __device__ __forceinline__ float fast_exp2(float x) { return __builtin_amdgcn_exp2f(x); }
; __device__ __forceinline__ u32x4 pack8(f32x4 v0, f32x4 v1) { u32x4 w; w.x = cvt_pk_bf16(v0[0], v0[1]); w.y = cvt_pk_bf16(v0[2], v0[3]); w.z = cvt_pk_bf16(v1[0], v1[1]); w.w = cvt_pk_bf16(v1[2], v1[3]); return w; }
;     __device__ __forceinline__ void operator()(const f32x4 (&acc)[2][2][4][2], const Unit& u, int wr, int wc, int fr, int fq) const {
;     ...
;         for (int ai = 0; ai < 2; ++ai)
; #pragma unroll
;             for (int m = 0; m < 4; ++m) { bf16_t* rowp = O + (size_t)(row0 + ai * HALF + m * 16) * DFF + col0;
;                 const float r = rs[row0 + ai * HALF + m * 16], r2 = r * r;
;                 f32x4 h0, h1;
; #pragma unroll
;                 for (int j = 0; j < 4; ++j) {
;                     const float g0 = acc[ai][0][m][0][j], g1 = acc[ai][0][m][1][j];
;                     h0[j] = g0 * r2 * fast_rcp(1.0f + fast_exp2(g0 * (-LOG2E * r))) * acc[ai][1][m][0][j];
;                     h1[j] = g1 * r2 * fast_rcp(1.0f + fast_exp2(g1 * (-LOG2E * r))) * acc[ai][1][m][1][j]; }
;                 *(u32x4*)rowp = pack8(h0, h1); }
	v_mul_f32_e32 v118, v109, v115
	v_mul_f32_e32 v109, v109, v114
	v_mul_f32_e32 v119, v105, v115
	v_mul_f32_e32 v105, v105, v114
	v_mul_f32_e32 v120, v110, v115
	v_mul_f32_e32 v110, v110, v114
	v_mul_f32_e32 v121, v106, v115
	v_mul_f32_e32 v106, v106, v114
	v_mul_f32_e32 v122, v111, v115
	v_mul_f32_e32 v111, v111, v114
	v_mul_f32_e32 v115, v107, v115
	v_mul_f32_e32 v107, v107, v114
	v_mul_f32_e32 v108, v108, v114
	v_exp_f32_e32 v104, v104
	v_exp_f32_e32 v109, v109
	v_exp_f32_e32 v105, v105
	v_exp_f32_e32 v110, v110
	v_exp_f32_e32 v106, v106
	v_exp_f32_e32 v111, v111
	v_exp_f32_e32 v107, v107
	v_exp_f32_e32 v108, v108
	v_add_f32_e32 v104, 1.0, v104
	v_add_f32_e32 v109, 1.0, v109
	v_add_f32_e32 v105, 1.0, v105
	v_add_f32_e32 v110, 1.0, v110
	v_add_f32_e32 v106, 1.0, v106
	v_add_f32_e32 v111, 1.0, v111
	v_add_f32_e32 v107, 1.0, v107
	v_add_f32_e32 v108, 1.0, v108
	v_rcp_f32_e32 v104, v104
	v_rcp_f32_e32 v109, v109
	v_rcp_f32_e32 v105, v105
	v_rcp_f32_e32 v110, v110
	v_rcp_f32_e32 v106, v106
	v_rcp_f32_e32 v111, v111
	v_rcp_f32_e32 v107, v107
	v_rcp_f32_e32 v108, v108
	v_mul_f32_e32 v104, v117, v104
	v_mul_f32_e32 v109, v118, v109
	v_mul_f32_e32 v105, v119, v105
	v_mul_f32_e32 v110, v120, v110
	v_mul_f32_e32 v106, v121, v106
	v_mul_f32_e32 v111, v122, v111
	v_mul_f32_e32 v107, v115, v107
	v_mul_f32_e32 v108, v116, v108
	v_mul_f32_e32 v104, v96, v104
	v_mul_f32_e32 v96, v101, v109
	v_mul_f32_e32 v101, v97, v105
	v_mul_f32_e32 v97, v102, v110
	v_mul_f32_e32 v102, v98, v106
	v_mul_f32_e32 v98, v103, v111
	v_mul_f32_e32 v99, v99, v107
	v_mul_f32_e32 v100, v100, v108
	v_cvt_pk_bf16_f32 v96, v100, v96
	v_cvt_pk_bf16_f32 v97, v97, v98
	v_cvt_pk_bf16_f32 v98, v104, v101
	v_cvt_pk_bf16_f32 v99, v102, v99
	global_store_dwordx4 v[112:113], v[96:99], off
	s_nop 1
	v_mov_b32_e32 v98, v205
	s_nop 0
	v_or_b32_e32 v96, 32, v144
	v_mad_i64_i32 v[96:97], s[40:41], v96, s52, v[146:147]
	v_lshl_add_u64 v[96:97], v[96:97], 0, v[148:149]
	v_mul_f32_e32 v99, v98, v98
	v_mul_f32_e32 v98, 0xbfb8aa3b, v98
	v_mul_f32_e32 v100, v92, v99
	v_mul_f32_e32 v101, v88, v99
	v_mul_f32_e32 v88, v88, v98
	v_mul_f32_e32 v102, v93, v99
	v_mul_f32_e32 v93, v93, v98
	v_mul_f32_e32 v103, v89, v99
	v_mul_f32_e32 v89, v89, v98
	v_mul_f32_e32 v104, v94, v99
	v_mul_f32_e32 v94, v94, v98
	v_mul_f32_e32 v105, v90, v99
	v_mul_f32_e32 v90, v90, v98
	v_mul_f32_e32 v106, v95, v99
	v_mul_f32_e32 v95, v95, v98
	v_mul_f32_e32 v99, v91, v99
	v_mul_f32_e32 v91, v91, v98
	v_mul_f32_e32 v92, v92, v98
	v_exp_f32_e32 v88, v88
	v_exp_f32_e32 v93, v93
	v_exp_f32_e32 v89, v89
	v_exp_f32_e32 v94, v94
	v_exp_f32_e32 v90, v90
	v_exp_f32_e32 v95, v95
	v_exp_f32_e32 v91, v91
	v_exp_f32_e32 v92, v92
	v_add_f32_e32 v88, 1.0, v88
	v_add_f32_e32 v93, 1.0, v93
	v_add_f32_e32 v89, 1.0, v89
	v_add_f32_e32 v94, 1.0, v94
	v_add_f32_e32 v90, 1.0, v90
	v_add_f32_e32 v95, 1.0, v95
	v_add_f32_e32 v91, 1.0, v91
	v_add_f32_e32 v92, 1.0, v92
	v_rcp_f32_e32 v88, v88
	v_rcp_f32_e32 v93, v93
	v_rcp_f32_e32 v89, v89
	v_rcp_f32_e32 v94, v94
	v_rcp_f32_e32 v90, v90
	v_rcp_f32_e32 v95, v95
	v_rcp_f32_e32 v91, v91
	v_rcp_f32_e32 v92, v92
	v_mul_f32_e32 v88, v101, v88
	v_mul_f32_e32 v93, v102, v93
	v_mul_f32_e32 v89, v103, v89
	v_mul_f32_e32 v94, v104, v94
	v_mul_f32_e32 v90, v105, v90
	v_mul_f32_e32 v95, v106, v95
	v_mul_f32_e32 v91, v99, v91
	v_mul_f32_e32 v92, v100, v92
	v_mul_f32_e32 v88, v80, v88
	v_mul_f32_e32 v80, v85, v93
	v_mul_f32_e32 v85, v81, v89
	v_mul_f32_e32 v81, v86, v94
	v_mul_f32_e32 v86, v82, v90
	v_mul_f32_e32 v82, v87, v95
	v_mul_f32_e32 v83, v83, v91
	v_mul_f32_e32 v84, v84, v92
	v_cvt_pk_bf16_f32 v80, v84, v80
	v_cvt_pk_bf16_f32 v81, v81, v82
	v_cvt_pk_bf16_f32 v82, v88, v85
	v_cvt_pk_bf16_f32 v83, v86, v83
	global_store_dwordx4 v[96:97], v[80:83], off
	s_nop 1
	v_mov_b32_e32 v82, v206
	s_nop 0
	v_or_b32_e32 v80, 48, v144
	v_mad_i64_i32 v[80:81], s[40:41], v80, s52, v[146:147]
	v_lshl_add_u64 v[80:81], v[80:81], 0, v[148:149]
	v_mul_f32_e32 v83, v82, v82
	v_mul_f32_e32 v82, 0xbfb8aa3b, v82
	v_mul_f32_e32 v84, v76, v83
	v_mul_f32_e32 v85, v72, v83
	v_mul_f32_e32 v72, v72, v82
	v_mul_f32_e32 v86, v77, v83
	v_mul_f32_e32 v77, v77, v82
	v_mul_f32_e32 v87, v73, v83
	v_mul_f32_e32 v73, v73, v82
	v_mul_f32_e32 v88, v78, v83
	v_mul_f32_e32 v78, v78, v82
	v_mul_f32_e32 v89, v74, v83
	v_mul_f32_e32 v74, v74, v82
	v_mul_f32_e32 v90, v79, v83
	v_mul_f32_e32 v79, v79, v82
	v_mul_f32_e32 v83, v75, v83
	v_mul_f32_e32 v75, v75, v82
	v_mul_f32_e32 v76, v76, v82
	v_exp_f32_e32 v72, v72
	v_exp_f32_e32 v77, v77
	v_exp_f32_e32 v73, v73
	v_exp_f32_e32 v78, v78
	v_exp_f32_e32 v74, v74
	v_exp_f32_e32 v79, v79
	v_exp_f32_e32 v75, v75
	v_exp_f32_e32 v76, v76
	v_add_f32_e32 v72, 1.0, v72
	v_add_f32_e32 v77, 1.0, v77
	v_add_f32_e32 v73, 1.0, v73
	v_add_f32_e32 v78, 1.0, v78
	v_add_f32_e32 v74, 1.0, v74
	v_add_f32_e32 v79, 1.0, v79
	v_add_f32_e32 v75, 1.0, v75
	v_add_f32_e32 v76, 1.0, v76
	v_rcp_f32_e32 v72, v72
	v_rcp_f32_e32 v77, v77
	v_rcp_f32_e32 v73, v73
	v_rcp_f32_e32 v78, v78
	v_rcp_f32_e32 v74, v74
	v_rcp_f32_e32 v79, v79
	v_rcp_f32_e32 v75, v75
	v_rcp_f32_e32 v76, v76
	v_mul_f32_e32 v72, v85, v72
	v_mul_f32_e32 v77, v86, v77
	v_mul_f32_e32 v73, v87, v73
	v_mul_f32_e32 v78, v88, v78
	v_mul_f32_e32 v74, v89, v74
	v_mul_f32_e32 v79, v90, v79
	v_mul_f32_e32 v75, v83, v75
	v_mul_f32_e32 v76, v84, v76
	v_mul_f32_e32 v72, v64, v72
	v_mul_f32_e32 v64, v69, v77
	v_mul_f32_e32 v69, v65, v73
	v_mul_f32_e32 v65, v70, v78
	v_mul_f32_e32 v70, v66, v74
	v_mul_f32_e32 v66, v71, v79
	v_mul_f32_e32 v67, v67, v75
	v_mul_f32_e32 v68, v68, v76
	v_cvt_pk_bf16_f32 v64, v68, v64
	v_cvt_pk_bf16_f32 v65, v65, v66
	v_cvt_pk_bf16_f32 v66, v72, v69
; __device__ __forceinline__ float fast_rcp(float x) { return __builtin_amdgcn_rcpf(x); }
; __device__ __forceinline__ float fast_exp2(float x) { return __builtin_amdgcn_exp2f(x); }
; __device__ __forceinline__ u32x4 pack8(f32x4 v0, f32x4 v1) { u32x4 w; w.x = cvt_pk_bf16(v0[0], v0[1]); w.y = cvt_pk_bf16(v0[2], v0[3]); w.z = cvt_pk_bf16(v1[0], v1[1]); w.w = cvt_pk_bf16(v1[2], v1[3]); return w; }
;     __device__ __forceinline__ void operator()(const f32x4 (&acc)[2][2][4][2], const Unit& u, int wr, int wc, int fr, int fq) const {
;     ...
;         for (int ai = 0; ai < 2; ++ai)
; #pragma unroll
;             for (int m = 0; m < 4; ++m) { bf16_t* rowp = O + (size_t)(row0 + ai * HALF + m * 16) * DFF + col0;
;                 const float r = rs[row0 + ai * HALF + m * 16], r2 = r * r;
;                 f32x4 h0, h1;
; #pragma unroll
;                 for (int j = 0; j < 4; ++j) {
;                     const float g0 = acc[ai][0][m][0][j], g1 = acc[ai][0][m][1][j];
;                     h0[j] = g0 * r2 * fast_rcp(1.0f + fast_exp2(g0 * (-LOG2E * r))) * acc[ai][1][m][0][j];
;                     h1[j] = g1 * r2 * fast_rcp(1.0f + fast_exp2(g1 * (-LOG2E * r))) * acc[ai][1][m][1][j]; }
;                 *(u32x4*)rowp = pack8(h0, h1); }
	v_cvt_pk_bf16_f32 v67, v70, v67
	global_store_dwordx4 v[80:81], v[64:67], off
	s_nop 1
	v_mov_b32_e32 v66, v207
	s_nop 0
	v_add_u32_e32 v64, 0x80, v144
	v_mad_i64_i32 v[64:65], s[40:41], v64, s52, v[146:147]
	v_lshl_add_u64 v[64:65], v[64:65], 0, v[148:149]
	v_mul_f32_e32 v67, v66, v66
	v_mul_f32_e32 v66, 0xbfb8aa3b, v66
	v_mul_f32_e32 v68, v60, v67
	v_mul_f32_e32 v69, v56, v67
	v_mul_f32_e32 v56, v56, v66
	v_mul_f32_e32 v70, v61, v67
	v_mul_f32_e32 v61, v61, v66
	v_mul_f32_e32 v71, v57, v67
	v_mul_f32_e32 v57, v57, v66
	v_mul_f32_e32 v72, v62, v67
	v_mul_f32_e32 v62, v62, v66
	v_mul_f32_e32 v73, v58, v67
	v_mul_f32_e32 v58, v58, v66
	v_mul_f32_e32 v74, v63, v67
	v_mul_f32_e32 v63, v63, v66
	v_mul_f32_e32 v67, v59, v67
	v_mul_f32_e32 v59, v59, v66
	v_mul_f32_e32 v60, v60, v66
	v_exp_f32_e32 v56, v56
	v_exp_f32_e32 v61, v61
	v_exp_f32_e32 v57, v57
	v_exp_f32_e32 v62, v62
	v_exp_f32_e32 v58, v58
	v_exp_f32_e32 v63, v63
	v_exp_f32_e32 v59, v59
	v_exp_f32_e32 v60, v60
	v_add_f32_e32 v56, 1.0, v56
	v_add_f32_e32 v61, 1.0, v61
	v_add_f32_e32 v57, 1.0, v57
	v_add_f32_e32 v62, 1.0, v62
	v_add_f32_e32 v58, 1.0, v58
	v_add_f32_e32 v63, 1.0, v63
	v_add_f32_e32 v59, 1.0, v59
	v_add_f32_e32 v60, 1.0, v60
	v_rcp_f32_e32 v56, v56
	v_rcp_f32_e32 v61, v61
	v_rcp_f32_e32 v57, v57
	v_rcp_f32_e32 v62, v62
	v_rcp_f32_e32 v58, v58
	v_rcp_f32_e32 v63, v63
	v_rcp_f32_e32 v59, v59
	v_rcp_f32_e32 v60, v60
	v_mul_f32_e32 v56, v69, v56
	v_mul_f32_e32 v61, v70, v61
	v_mul_f32_e32 v57, v71, v57
	v_mul_f32_e32 v62, v72, v62
	v_mul_f32_e32 v58, v73, v58
	v_mul_f32_e32 v63, v74, v63
	v_mul_f32_e32 v59, v67, v59
	v_mul_f32_e32 v60, v68, v60
	v_mul_f32_e32 v56, v48, v56
	v_mul_f32_e32 v48, v53, v61
	v_mul_f32_e32 v53, v49, v57
	v_mul_f32_e32 v49, v54, v62
	v_mul_f32_e32 v54, v50, v58
	v_mul_f32_e32 v50, v55, v63
	v_mul_f32_e32 v51, v51, v59
	v_mul_f32_e32 v52, v52, v60
	v_cvt_pk_bf16_f32 v48, v52, v48
	v_cvt_pk_bf16_f32 v49, v49, v50
	v_cvt_pk_bf16_f32 v50, v56, v53
	v_cvt_pk_bf16_f32 v51, v54, v51
	global_store_dwordx4 v[64:65], v[48:51], off
	s_nop 1
	v_mov_b32_e32 v50, v208
	s_nop 0
	v_add_u32_e32 v48, 0x90, v144
	v_mad_i64_i32 v[48:49], s[40:41], v48, s52, v[146:147]
	v_lshl_add_u64 v[48:49], v[48:49], 0, v[148:149]
	v_mul_f32_e32 v51, v50, v50
	v_mul_f32_e32 v50, 0xbfb8aa3b, v50
	v_mul_f32_e32 v52, v44, v51
	v_mul_f32_e32 v53, v40, v51
	v_mul_f32_e32 v40, v40, v50
	v_mul_f32_e32 v54, v45, v51
	v_mul_f32_e32 v45, v45, v50
	v_mul_f32_e32 v55, v41, v51
	v_mul_f32_e32 v41, v41, v50
	v_mul_f32_e32 v56, v46, v51
	v_mul_f32_e32 v46, v46, v50
	v_mul_f32_e32 v57, v42, v51
	v_mul_f32_e32 v42, v42, v50
	v_mul_f32_e32 v58, v47, v51
	v_mul_f32_e32 v47, v47, v50
	v_mul_f32_e32 v51, v43, v51
	v_mul_f32_e32 v43, v43, v50
	v_mul_f32_e32 v44, v44, v50
	v_exp_f32_e32 v40, v40
	v_exp_f32_e32 v45, v45
	v_exp_f32_e32 v41, v41
	v_exp_f32_e32 v46, v46
	v_exp_f32_e32 v42, v42
	v_exp_f32_e32 v47, v47
	v_exp_f32_e32 v43, v43
	v_exp_f32_e32 v44, v44
	v_add_f32_e32 v40, 1.0, v40
	v_add_f32_e32 v45, 1.0, v45
	v_add_f32_e32 v41, 1.0, v41
	v_add_f32_e32 v46, 1.0, v46
	v_add_f32_e32 v42, 1.0, v42
	v_add_f32_e32 v47, 1.0, v47
	v_add_f32_e32 v43, 1.0, v43
	v_add_f32_e32 v44, 1.0, v44
	v_rcp_f32_e32 v40, v40
	v_rcp_f32_e32 v45, v45
	v_rcp_f32_e32 v41, v41
	v_rcp_f32_e32 v46, v46
	v_rcp_f32_e32 v42, v42
	v_rcp_f32_e32 v47, v47
	v_rcp_f32_e32 v43, v43
	v_rcp_f32_e32 v44, v44
	v_mul_f32_e32 v40, v53, v40
	v_mul_f32_e32 v45, v54, v45
	v_mul_f32_e32 v41, v55, v41
	v_mul_f32_e32 v46, v56, v46
	v_mul_f32_e32 v42, v57, v42
	v_mul_f32_e32 v47, v58, v47
	v_mul_f32_e32 v43, v51, v43
	v_mul_f32_e32 v44, v52, v44
	v_mul_f32_e32 v40, v32, v40
	v_mul_f32_e32 v32, v37, v45
	v_mul_f32_e32 v37, v33, v41
	v_mul_f32_e32 v33, v38, v46
	v_mul_f32_e32 v38, v34, v42
	v_mul_f32_e32 v34, v39, v47
	v_mul_f32_e32 v35, v35, v43
	v_mul_f32_e32 v36, v36, v44
	v_cvt_pk_bf16_f32 v32, v36, v32
	v_cvt_pk_bf16_f32 v33, v33, v34
	v_cvt_pk_bf16_f32 v34, v40, v37
	v_cvt_pk_bf16_f32 v35, v38, v35
	global_store_dwordx4 v[48:49], v[32:35], off
; __device__ __forceinline__ float fast_rcp(float x) { return __builtin_amdgcn_rcpf(x); }
; __device__ __forceinline__ float fast_exp2(float x) { return __builtin_amdgcn_exp2f(x); }
; #define PG8_WAIT_V(n) asm volatile("s_waitcnt vmcnt(" #n ")" ::: "memory")
; #define PG8_BAR __builtin_amdgcn_s_barrier()
; __device__ __forceinline__ u32x4 pack8(f32x4 v0, f32x4 v1) { u32x4 w; w.x = cvt_pk_bf16(v0[0], v0[1]); w.y = cvt_pk_bf16(v0[2], v0[3]); w.z = cvt_pk_bf16(v1[0], v1[1]); w.w = cvt_pk_bf16(v1[2], v1[3]); return w; }
; template <class Epi>
; __device__ __forceinline__ void gemm_phase(LAS unsigned char* lds, const Gemm g, const StaticOrder& S, const Epi& E) {
;     ...
;         E(acc, cur, wr, wc, fr, fq);
;         if (!has_next) break;
; #pragma unroll
;         for (int a = 0; a < 2; ++a)
; #pragma unroll
;             for (int b = 0; b < 2; ++b)
; #pragma unroll
;                 for (int m = 0; m < 4; ++m)
; #pragma unroll
;                     for (int n = 0; n < 2; ++n) acc[a][b][m][n] = (f32x4){0.f, 0.f, 0.f, 0.f};
;         cur = nxt; cA = nA; cB = nB; ++ui;
;     }
;     PG8_WAIT_V(0);
;     if (wr == 0) PG8_BAR;
;     __device__ __forceinline__ void operator()(const f32x4 (&acc)[2][2][4][2], const Unit& u, int wr, int wc, int fr, int fq) const {
;     ...
;         for (int ai = 0; ai < 2; ++ai)
; #pragma unroll
;             for (int m = 0; m < 4; ++m) { bf16_t* rowp = O + (size_t)(row0 + ai * HALF + m * 16) * DFF + col0;
;                 const float r = rs[row0 + ai * HALF + m * 16], r2 = r * r;
;                 f32x4 h0, h1;
; #pragma unroll
;                 for (int j = 0; j < 4; ++j) {
;                     const float g0 = acc[ai][0][m][0][j], g1 = acc[ai][0][m][1][j];
;                     h0[j] = g0 * r2 * fast_rcp(1.0f + fast_exp2(g0 * (-LOG2E * r))) * acc[ai][1][m][0][j];
;                     h1[j] = g1 * r2 * fast_rcp(1.0f + fast_exp2(g1 * (-LOG2E * r))) * acc[ai][1][m][1][j]; }
;                 *(u32x4*)rowp = pack8(h0, h1); }
	s_nop 1
	v_mov_b32_e32 v34, v209
	s_nop 0
	v_add_u32_e32 v32, 0xa0, v144
	v_mad_i64_i32 v[32:33], s[40:41], v32, s52, v[146:147]
	v_lshl_add_u64 v[32:33], v[32:33], 0, v[148:149]
	s_mov_b64 s[40:41], s[34:35]
	v_mul_f32_e32 v35, v34, v34
	v_mul_f32_e32 v34, 0xbfb8aa3b, v34
	v_mul_f32_e32 v36, v28, v35
	v_mul_f32_e32 v37, v24, v35
	v_mul_f32_e32 v24, v24, v34
	v_mul_f32_e32 v38, v29, v35
	v_mul_f32_e32 v29, v29, v34
	v_mul_f32_e32 v39, v25, v35
	v_mul_f32_e32 v25, v25, v34
	v_mul_f32_e32 v40, v30, v35
	v_mul_f32_e32 v30, v30, v34
	v_mul_f32_e32 v41, v26, v35
	v_mul_f32_e32 v26, v26, v34
	v_mul_f32_e32 v42, v31, v35
	v_mul_f32_e32 v31, v31, v34
	v_mul_f32_e32 v35, v27, v35
	v_mul_f32_e32 v27, v27, v34
	v_mul_f32_e32 v28, v28, v34
	v_exp_f32_e32 v24, v24
	v_exp_f32_e32 v29, v29
	v_exp_f32_e32 v25, v25
	v_exp_f32_e32 v30, v30
	v_exp_f32_e32 v26, v26
	v_exp_f32_e32 v31, v31
	v_exp_f32_e32 v27, v27
	v_exp_f32_e32 v28, v28
	v_add_f32_e32 v24, 1.0, v24
	v_add_f32_e32 v29, 1.0, v29
	v_add_f32_e32 v25, 1.0, v25
	v_add_f32_e32 v30, 1.0, v30
	v_add_f32_e32 v26, 1.0, v26
	v_add_f32_e32 v31, 1.0, v31
	v_add_f32_e32 v27, 1.0, v27
	v_add_f32_e32 v28, 1.0, v28
	v_rcp_f32_e32 v24, v24
	v_rcp_f32_e32 v29, v29
	v_rcp_f32_e32 v25, v25
	v_rcp_f32_e32 v30, v30
	v_rcp_f32_e32 v26, v26
	v_rcp_f32_e32 v31, v31
	v_rcp_f32_e32 v27, v27
	v_rcp_f32_e32 v28, v28
	v_mul_f32_e32 v24, v37, v24
	v_mul_f32_e32 v29, v38, v29
	v_mul_f32_e32 v25, v39, v25
	v_mul_f32_e32 v30, v40, v30
	v_mul_f32_e32 v26, v41, v26
	v_mul_f32_e32 v31, v42, v31
	v_mul_f32_e32 v27, v35, v27
	v_mul_f32_e32 v28, v36, v28
	v_mul_f32_e32 v24, v16, v24
	v_mul_f32_e32 v16, v21, v29
	v_mul_f32_e32 v21, v17, v25
	v_mul_f32_e32 v17, v22, v30
	v_mul_f32_e32 v22, v18, v26
	v_mul_f32_e32 v18, v23, v31
	v_mul_f32_e32 v19, v19, v27
	v_mul_f32_e32 v20, v20, v28
	v_cvt_pk_bf16_f32 v16, v20, v16
	v_cvt_pk_bf16_f32 v17, v17, v18
	v_cvt_pk_bf16_f32 v18, v24, v21
	v_cvt_pk_bf16_f32 v19, v22, v19
	global_store_dwordx4 v[32:33], v[16:19], off
	s_nop 1
	v_mov_b32_e32 v18, v210
	s_nop 0
	v_add_u32_e32 v16, 0xb0, v144
	v_mad_i64_i32 v[16:17], s[6:7], v16, s52, v[146:147]
	v_lshl_add_u64 v[16:17], v[16:17], 0, v[148:149]
	v_mul_f32_e32 v19, v18, v18
	v_mul_f32_e32 v18, 0xbfb8aa3b, v18
	v_mul_f32_e32 v20, v12, v19
	v_mul_f32_e32 v21, v8, v19
	v_mul_f32_e32 v8, v8, v18
	v_mul_f32_e32 v22, v13, v19
	v_mul_f32_e32 v13, v13, v18
	v_mul_f32_e32 v23, v9, v19
	v_mul_f32_e32 v9, v9, v18
	v_mul_f32_e32 v24, v14, v19
	v_mul_f32_e32 v14, v14, v18
	v_mul_f32_e32 v25, v10, v19
	v_mul_f32_e32 v10, v10, v18
	v_mul_f32_e32 v26, v15, v19
	v_mul_f32_e32 v15, v15, v18
	v_mul_f32_e32 v19, v11, v19
	v_mul_f32_e32 v11, v11, v18
	v_mul_f32_e32 v12, v12, v18
	v_exp_f32_e32 v8, v8
	v_exp_f32_e32 v13, v13
	v_exp_f32_e32 v9, v9
	v_exp_f32_e32 v14, v14
	v_exp_f32_e32 v10, v10
	v_exp_f32_e32 v15, v15
	v_exp_f32_e32 v11, v11
	v_exp_f32_e32 v12, v12
	v_add_f32_e32 v8, 1.0, v8
	v_add_f32_e32 v13, 1.0, v13
	v_add_f32_e32 v9, 1.0, v9
	v_add_f32_e32 v14, 1.0, v14
	v_add_f32_e32 v10, 1.0, v10
	v_add_f32_e32 v15, 1.0, v15
	v_add_f32_e32 v11, 1.0, v11
	v_add_f32_e32 v12, 1.0, v12
	v_rcp_f32_e32 v8, v8
	v_rcp_f32_e32 v13, v13
	v_rcp_f32_e32 v9, v9
	v_rcp_f32_e32 v14, v14
	v_rcp_f32_e32 v10, v10
	v_rcp_f32_e32 v15, v15
	v_rcp_f32_e32 v11, v11
	v_rcp_f32_e32 v12, v12
	v_mul_f32_e32 v8, v21, v8
	v_mul_f32_e32 v13, v22, v13
	v_mul_f32_e32 v9, v23, v9
	v_mul_f32_e32 v14, v24, v14
	v_mul_f32_e32 v10, v25, v10
	v_mul_f32_e32 v15, v26, v15
	v_mul_f32_e32 v11, v19, v11
	v_mul_f32_e32 v12, v20, v12
	v_mul_f32_e32 v8, v0, v8
	v_mul_f32_e32 v0, v5, v13
	v_mul_f32_e32 v5, v1, v9
	v_mul_f32_e32 v1, v6, v14
	v_mul_f32_e32 v6, v2, v10
	v_mul_f32_e32 v2, v7, v15
	v_mul_f32_e32 v3, v3, v11
	v_mul_f32_e32 v4, v4, v12
	v_cvt_pk_bf16_f32 v0, v4, v0
	v_cvt_pk_bf16_f32 v1, v1, v2
	v_cvt_pk_bf16_f32 v2, v8, v5
	v_cvt_pk_bf16_f32 v3, v6, v3
	global_store_dwordx4 v[16:17], v[0:3], off
	s_cbranch_vccz .LBB0_793
	s_waitcnt vmcnt(0)
	s_cmpk_gt_u32 s10, 0xff
	s_cbranch_scc1 .LBB0_800
	s_barrier

; #define PG8_STAGE(bufoff, gbase, voff) do { _Pragma("unroll") for (int _i = 0; _i < 2; ++_i) \
;         __builtin_amdgcn_global_load_lds((const unsigned*)((const char*)(gbase) + (voff)[_i]), (LAS unsigned*)(lds + (bufoff) + ldsw + _i * 8192), 16, 0, 0); } while (0)
; #define PG8_LDA(dst, b, h) do { _Pragma("unroll") for (int m = 0; m < 4; ++m) _Pragma("unroll") for (int k = 0; k < 2; ++k) dst[m][k] = *(const LAS bf16x8*)(lds + PG8_SA(b, h) + aoff + m * 2048 + k * 1024); } while (0)
; #define PG8_LDB(dst, b, h) do { _Pragma("unroll") for (int n = 0; n < 2; ++n) _Pragma("unroll") for (int k = 0; k < 2; ++k) dst[n][k] = *(const LAS bf16x8*)(lds + PG8_SB(b, h) + boff + n * 2048 + k * 1024); } while (0)
; #define PG8_WAIT_V(n) asm volatile("s_waitcnt vmcnt(" #n ")" ::: "memory")
; #define PG8_WAIT_L(n) asm volatile("s_waitcnt lgkmcnt(" #n ")" ::: "memory")
; #define PG8_BAR __builtin_amdgcn_s_barrier()
; #define PG8_SCHED __builtin_amdgcn_sched_barrier(0)
; template <class Epi>
; __device__ __forceinline__ void gemm_phase(LAS unsigned char* lds, const Gemm g, const StaticOrder& S, const Epi& E) {
;     ...
;         for (int t = 0; t < nt; t += 2) {
;             const bool last = (t == nt - 2);
;             const char* a1 = cA + (size_t)(t + 1) * kstep;
;             const char* a2 = last ? nA : cA + (size_t)(t + 2) * kstep; const char* b2 = last ? nB : cB + (size_t)(t + 2) * kstep;
;             const char* a3 = a2 + kstep; const char* b3 = b2 + kstep;
;             PG8_LDB(B0, 0, 0); PG8_SCHED; PG8_LDA(At, 0, 0); PG8_STAGE(PG8_SA(1, 1), a1 + hstep, voffA);
;             PG8_WAIT_L(8); PG8_BAR; PG8_WAIT_L(0); PG8_MMA(0, 0, At, B0); PG8_BAR; PG8_SCHED;
;             PG8_LDB(B1, 0, 1); PG8_STAGE(PG8_SB(0, 0), b2, voffB);
;             PG8_BAR; PG8_WAIT_L(0); PG8_MMA(0, 1, At, B1); PG8_BAR;
;             PG8_LDA(At, 0, 1); PG8_STAGE(PG8_SA(0, 0), a2, voffA);
;             PG8_BAR; PG8_WAIT_L(0); PG8_MMA(1, 0, At, B0); PG8_BAR; PG8_SCHED;
;             PG8_STAGE(PG8_SB(0, 1), b2 + hstep, voffB);
;             PG8_WAIT_V(6); PG8_BAR; PG8_MMA(1, 1, At, B1); PG8_BAR;
;             PG8_LDB(B0, 1, 0); PG8_SCHED; PG8_LDA(At, 1, 0); PG8_STAGE(PG8_SA(0, 1), a2 + hstep, voffA);
;             PG8_WAIT_L(8); PG8_BAR; PG8_WAIT_L(0); PG8_MMA(0, 0, At, B0); PG8_BAR; PG8_SCHED;
.LBB0_864:
	ds_read_b128 v[148:151], v145
	ds_read_b128 v[152:155], v145 offset:1024
	ds_read_b128 v[160:163], v145 offset:2048
	ds_read_b128 v[164:167], v145 offset:3072
	s_add_u32 s44, s42, 0x100
	s_addc_u32 s45, s43, 0
	s_cmpk_eq_i32 s67, 0x54
	s_cselect_b32 s49, s41, s45
	s_cselect_b32 s48, s40, s44
	s_cselect_b32 s47, s7, s66
	s_cselect_b32 s46, s6, s65
	s_add_i32 m0, s28, 0xc000
	ds_read_b128 v[168:171], v146
	ds_read_b128 v[172:175], v146 offset:1024
	ds_read_b128 v[176:179], v146 offset:2048
	ds_read_b128 v[180:183], v146 offset:3072
	ds_read_b128 v[184:187], v146 offset:4096
	ds_read_b128 v[188:191], v146 offset:5120
	ds_read_b128 v[192:195], v146 offset:6144
	ds_read_b128 v[196:199], v146 offset:7168
	global_load_lds_dwordx4 v136, s[42:43]
	s_add_i32 m0, s28, 0xe000
	s_nop 0
	global_load_lds_dwordx4 v138, s[42:43]
	s_waitcnt lgkmcnt(8)
	s_barrier
	s_waitcnt lgkmcnt(0)
	v_mfma_f32_16x16x32_bf16 v[124:127], v[148:151], v[168:171], v[124:127]
	v_mfma_f32_16x16x32_bf16 v[120:123], v[160:163], v[168:171], v[120:123]
	v_mfma_f32_16x16x32_bf16 v[112:115], v[148:151], v[176:179], v[112:115]
	v_mfma_f32_16x16x32_bf16 v[104:107], v[160:163], v[176:179], v[104:107]
	v_mfma_f32_16x16x32_bf16 v[96:99], v[148:151], v[184:187], v[96:99]
	v_mfma_f32_16x16x32_bf16 v[88:91], v[160:163], v[184:187], v[88:91]
	v_mfma_f32_16x16x32_bf16 v[80:83], v[148:151], v[192:195], v[80:83]
	v_mfma_f32_16x16x32_bf16 v[72:75], v[160:163], v[192:195], v[72:75]
	v_mfma_f32_16x16x32_bf16 v[124:127], v[152:155], v[172:175], v[124:127]
	v_mfma_f32_16x16x32_bf16 v[120:123], v[164:167], v[172:175], v[120:123]
	v_mfma_f32_16x16x32_bf16 v[112:115], v[152:155], v[180:183], v[112:115]
	v_mfma_f32_16x16x32_bf16 v[104:107], v[164:167], v[180:183], v[104:107]
	v_mfma_f32_16x16x32_bf16 v[96:99], v[152:155], v[188:191], v[96:99]
	v_mfma_f32_16x16x32_bf16 v[88:91], v[164:167], v[188:191], v[88:91]
	v_mfma_f32_16x16x32_bf16 v[80:83], v[152:155], v[196:199], v[80:83]
	v_mfma_f32_16x16x32_bf16 v[72:75], v[164:167], v[196:199], v[72:75]
	s_barrier
	s_add_i32 s42, s55, s23
	s_add_u32 s98, s46, s2
	s_addc_u32 s99, s47, s3
	s_mov_b32 m0, s42
	ds_read_b128 v[200:203], v147
	ds_read_b128 v[204:207], v147 offset:1024
	ds_read_b128 v[208:211], v147 offset:2048
	ds_read_b128 v[212:215], v147 offset:3072
	global_load_lds_dwordx4 v132, s[46:47]
	s_add_i32 m0, s42, 0x2000
	s_nop 0
	global_load_lds_dwordx4 v128, s[46:47]
	s_barrier
	s_waitcnt lgkmcnt(0)
	v_mfma_f32_16x16x32_bf16 v[116:119], v[200:203], v[168:171], v[116:119]
	v_mfma_f32_16x16x32_bf16 v[108:111], v[208:211], v[168:171], v[108:111]
	v_mfma_f32_16x16x32_bf16 v[100:103], v[200:203], v[176:179], v[100:103]
	v_mfma_f32_16x16x32_bf16 v[92:95], v[208:211], v[176:179], v[92:95]
	v_mfma_f32_16x16x32_bf16 v[84:87], v[200:203], v[184:187], v[84:87]
	v_mfma_f32_16x16x32_bf16 v[76:79], v[208:211], v[184:187], v[76:79]
	v_mfma_f32_16x16x32_bf16 v[68:71], v[200:203], v[192:195], v[68:71]
	v_mfma_f32_16x16x32_bf16 v[64:67], v[208:211], v[192:195], v[64:67]
	v_mfma_f32_16x16x32_bf16 v[116:119], v[204:207], v[172:175], v[116:119]
	v_mfma_f32_16x16x32_bf16 v[108:111], v[212:215], v[172:175], v[108:111]
	v_mfma_f32_16x16x32_bf16 v[100:103], v[204:207], v[180:183], v[100:103]
	v_mfma_f32_16x16x32_bf16 v[92:95], v[212:215], v[180:183], v[92:95]
	v_mfma_f32_16x16x32_bf16 v[84:87], v[204:207], v[188:191], v[84:87]
	v_mfma_f32_16x16x32_bf16 v[76:79], v[212:215], v[188:191], v[76:79]
	v_mfma_f32_16x16x32_bf16 v[68:71], v[204:207], v[196:199], v[68:71]
	v_mfma_f32_16x16x32_bf16 v[64:67], v[212:215], v[196:199], v[64:67]
	s_mov_b32 m0, s28
	s_add_u32 s100, s48, s2
	s_addc_u32 s101, s49, s3
	s_barrier
	ds_read_b128 v[168:171], v146 offset:16384
	ds_read_b128 v[172:175], v146 offset:17408
	ds_read_b128 v[176:179], v146 offset:18432
	ds_read_b128 v[180:183], v146 offset:19456
	ds_read_b128 v[184:187], v146 offset:20480
	ds_read_b128 v[188:191], v146 offset:21504
	ds_read_b128 v[192:195], v146 offset:22528
	ds_read_b128 v[196:199], v146 offset:23552
	global_load_lds_dwordx4 v134, s[48:49]
	s_mov_b32 m0, s29
	s_nop 0
	global_load_lds_dwordx4 v130, s[48:49]
	s_barrier
	s_waitcnt lgkmcnt(0)
	v_mfma_f32_16x16x32_bf16 v[60:63], v[148:151], v[168:171], v[60:63]
	v_mfma_f32_16x16x32_bf16 v[56:59], v[160:163], v[168:171], v[56:59]
	v_mfma_f32_16x16x32_bf16 v[52:55], v[148:151], v[176:179], v[52:55]
	v_mfma_f32_16x16x32_bf16 v[44:47], v[160:163], v[176:179], v[44:47]
	v_mfma_f32_16x16x32_bf16 v[36:39], v[148:151], v[184:187], v[36:39]
	v_mfma_f32_16x16x32_bf16 v[28:31], v[160:163], v[184:187], v[28:31]
	v_mfma_f32_16x16x32_bf16 v[20:23], v[148:151], v[192:195], v[20:23]
	v_mfma_f32_16x16x32_bf16 v[12:15], v[160:163], v[192:195], v[12:15]
	v_mfma_f32_16x16x32_bf16 v[60:63], v[152:155], v[172:175], v[60:63]
	v_mfma_f32_16x16x32_bf16 v[56:59], v[164:167], v[172:175], v[56:59]
	v_mfma_f32_16x16x32_bf16 v[52:55], v[152:155], v[180:183], v[52:55]
	v_mfma_f32_16x16x32_bf16 v[44:47], v[164:167], v[180:183], v[44:47]
	v_mfma_f32_16x16x32_bf16 v[36:39], v[152:155], v[188:191], v[36:39]
	v_mfma_f32_16x16x32_bf16 v[28:31], v[164:167], v[188:191], v[28:31]
	v_mfma_f32_16x16x32_bf16 v[20:23], v[152:155], v[196:199], v[20:23]
	v_mfma_f32_16x16x32_bf16 v[12:15], v[164:167], v[196:199], v[12:15]
	s_barrier
	s_add_u32 s42, s46, 0x160000
	s_addc_u32 s43, s47, 0
	s_add_i32 s68, s56, s23
	s_mov_b32 m0, s68
	s_nop 0
	global_load_lds_dwordx4 v132, s[42:43]
	s_add_i32 m0, s68, 0x2000
	s_nop 0
	global_load_lds_dwordx4 v128, s[42:43]
	s_waitcnt vmcnt(6)
	s_barrier
; #define PG8_STAGE(bufoff, gbase, voff) do { _Pragma("unroll") for (int _i = 0; _i < 2; ++_i) \
;         __builtin_amdgcn_global_load_lds((const unsigned*)((const char*)(gbase) + (voff)[_i]), (LAS unsigned*)(lds + (bufoff) + ldsw + _i * 8192), 16, 0, 0); } while (0)
; #define PG8_LDA(dst, b, h) do { _Pragma("unroll") for (int m = 0; m < 4; ++m) _Pragma("unroll") for (int k = 0; k < 2; ++k) dst[m][k] = *(const LAS bf16x8*)(lds + PG8_SA(b, h) + aoff + m * 2048 + k * 1024); } while (0)
; #define PG8_LDB(dst, b, h) do { _Pragma("unroll") for (int n = 0; n < 2; ++n) _Pragma("unroll") for (int k = 0; k < 2; ++k) dst[n][k] = *(const LAS bf16x8*)(lds + PG8_SB(b, h) + boff + n * 2048 + k * 1024); } while (0)
; #define PG8_MMA(ai, bj, At, Bt) do { __builtin_amdgcn_s_setprio(1); _Pragma("unroll") for (int m = 0; m < 4; ++m) _Pragma("unroll") for (int n = 0; n < 2; ++n) _Pragma("unroll") for (int k = 0; k < 2; ++k) \
;         acc[ai][bj][m][n] = __builtin_amdgcn_mfma_f32_16x16x32_bf16(Bt[n][k], At[m][k], acc[ai][bj][m][n], 0, 0, 0); __builtin_amdgcn_s_setprio(0); } while (0)
; #define PG8_WAIT_V(n) asm volatile("s_waitcnt vmcnt(" #n ")" ::: "memory")
; #define PG8_WAIT_L(n) asm volatile("s_waitcnt lgkmcnt(" #n ")" ::: "memory")
; #define PG8_BAR __builtin_amdgcn_s_barrier()
; #define PG8_SCHED __builtin_amdgcn_sched_barrier(0)
; template <class Epi>
; __device__ __forceinline__ void gemm_phase(LAS unsigned char* lds, const Gemm g, const StaticOrder& S, const Epi& E) {
;     ...
;             PG8_WAIT_V(6); PG8_BAR; PG8_MMA(1, 1, At, B1); PG8_BAR;
;             PG8_LDB(B0, 1, 0); PG8_SCHED; PG8_LDA(At, 1, 0); PG8_STAGE(PG8_SA(0, 1), a2 + hstep, voffA);
;             PG8_WAIT_L(8); PG8_BAR; PG8_WAIT_L(0); PG8_MMA(0, 0, At, B0); PG8_BAR; PG8_SCHED;
;             PG8_LDB(B1, 1, 1); PG8_STAGE(PG8_SB(1, 0), b3, voffB);
;             PG8_BAR; PG8_WAIT_L(0); PG8_MMA(0, 1, At, B1); PG8_BAR;
;             PG8_LDA(At, 1, 1); PG8_STAGE(PG8_SA(1, 0), a3, voffA);
;             PG8_BAR; PG8_WAIT_L(0); PG8_MMA(1, 0, At, B0); PG8_BAR; PG8_SCHED;
	v_mfma_f32_16x16x32_bf16 v[48:51], v[200:203], v[168:171], v[48:51]
	v_mfma_f32_16x16x32_bf16 v[40:43], v[208:211], v[168:171], v[40:43]
	v_mfma_f32_16x16x32_bf16 v[32:35], v[200:203], v[176:179], v[32:35]
	v_mfma_f32_16x16x32_bf16 v[24:27], v[208:211], v[176:179], v[24:27]
	v_mfma_f32_16x16x32_bf16 v[16:19], v[200:203], v[184:187], v[16:19]
	v_mfma_f32_16x16x32_bf16 v[8:11], v[208:211], v[184:187], v[8:11]
	v_mfma_f32_16x16x32_bf16 v[4:7], v[200:203], v[192:195], v[4:7]
	v_mfma_f32_16x16x32_bf16 v[0:3], v[208:211], v[192:195], v[0:3]
	v_mfma_f32_16x16x32_bf16 v[48:51], v[204:207], v[172:175], v[48:51]
	v_mfma_f32_16x16x32_bf16 v[40:43], v[212:215], v[172:175], v[40:43]
	v_mfma_f32_16x16x32_bf16 v[32:35], v[204:207], v[180:183], v[32:35]
	v_mfma_f32_16x16x32_bf16 v[24:27], v[212:215], v[180:183], v[24:27]
	v_mfma_f32_16x16x32_bf16 v[16:19], v[204:207], v[188:191], v[16:19]
	v_mfma_f32_16x16x32_bf16 v[8:11], v[212:215], v[188:191], v[8:11]
	v_mfma_f32_16x16x32_bf16 v[4:7], v[204:207], v[196:199], v[4:7]
	v_mfma_f32_16x16x32_bf16 v[0:3], v[212:215], v[196:199], v[0:3]
	s_add_i32 s68, 0, 0x18000
	v_add_u32_e32 v164, s68, v143
	s_barrier
	ds_read_b128 v[148:151], v164
	ds_read_b128 v[152:155], v164 offset:1024
	ds_read_b128 v[160:163], v164 offset:2048
	ds_read_b128 v[164:167], v164 offset:3072
	s_add_u32 s42, s48, 0x160000
	s_addc_u32 s43, s49, 0
	s_mov_b32 m0, s33
	ds_read_b128 v[168:171], v146 offset:32768
	ds_read_b128 v[172:175], v146 offset:33792
	ds_read_b128 v[176:179], v146 offset:34816
	ds_read_b128 v[180:183], v146 offset:35840
	ds_read_b128 v[184:187], v146 offset:36864
	ds_read_b128 v[188:191], v146 offset:37888
	ds_read_b128 v[192:195], v146 offset:38912
	ds_read_b128 v[196:199], v146 offset:39936
	global_load_lds_dwordx4 v134, s[42:43]
	s_mov_b32 m0, s50
	s_nop 0
	global_load_lds_dwordx4 v130, s[42:43]
	s_waitcnt lgkmcnt(8)
	s_barrier
	s_waitcnt lgkmcnt(0)
	v_mfma_f32_16x16x32_bf16 v[124:127], v[148:151], v[168:171], v[124:127]
	v_mfma_f32_16x16x32_bf16 v[120:123], v[160:163], v[168:171], v[120:123]
	v_mfma_f32_16x16x32_bf16 v[112:115], v[148:151], v[176:179], v[112:115]
	v_mfma_f32_16x16x32_bf16 v[104:107], v[160:163], v[176:179], v[104:107]
	v_mfma_f32_16x16x32_bf16 v[96:99], v[148:151], v[184:187], v[96:99]
	v_mfma_f32_16x16x32_bf16 v[88:91], v[160:163], v[184:187], v[88:91]
	v_mfma_f32_16x16x32_bf16 v[80:83], v[148:151], v[192:195], v[80:83]
	v_mfma_f32_16x16x32_bf16 v[72:75], v[160:163], v[192:195], v[72:75]
	v_mfma_f32_16x16x32_bf16 v[124:127], v[152:155], v[172:175], v[124:127]
	v_mfma_f32_16x16x32_bf16 v[120:123], v[164:167], v[172:175], v[120:123]
	v_mfma_f32_16x16x32_bf16 v[112:115], v[152:155], v[180:183], v[112:115]
	v_mfma_f32_16x16x32_bf16 v[104:107], v[164:167], v[180:183], v[104:107]
	v_mfma_f32_16x16x32_bf16 v[96:99], v[152:155], v[188:191], v[96:99]
	v_mfma_f32_16x16x32_bf16 v[88:91], v[164:167], v[188:191], v[88:91]
	v_mfma_f32_16x16x32_bf16 v[80:83], v[152:155], v[196:199], v[80:83]
	v_mfma_f32_16x16x32_bf16 v[72:75], v[164:167], v[196:199], v[72:75]
	s_barrier
	s_add_i32 s48, 0, 0x1c000
	s_add_i32 s42, s68, s23
	v_add_u32_e32 v212, s48, v143
	s_mov_b32 m0, s42
	ds_read_b128 v[200:203], v212
	ds_read_b128 v[204:207], v212 offset:1024
	ds_read_b128 v[208:211], v212 offset:2048
	ds_read_b128 v[212:215], v212 offset:3072
	global_load_lds_dwordx4 v132, s[98:99]
	s_add_i32 m0, s42, 0x2000
	s_nop 0
	global_load_lds_dwordx4 v128, s[98:99]
	s_barrier
	s_waitcnt lgkmcnt(0)
	v_mfma_f32_16x16x32_bf16 v[116:119], v[200:203], v[168:171], v[116:119]
	v_mfma_f32_16x16x32_bf16 v[108:111], v[208:211], v[168:171], v[108:111]
	v_mfma_f32_16x16x32_bf16 v[100:103], v[200:203], v[176:179], v[100:103]
	v_mfma_f32_16x16x32_bf16 v[92:95], v[208:211], v[176:179], v[92:95]
	v_mfma_f32_16x16x32_bf16 v[84:87], v[200:203], v[184:187], v[84:87]
	v_mfma_f32_16x16x32_bf16 v[76:79], v[208:211], v[184:187], v[76:79]
	v_mfma_f32_16x16x32_bf16 v[68:71], v[200:203], v[192:195], v[68:71]
	v_mfma_f32_16x16x32_bf16 v[64:67], v[208:211], v[192:195], v[64:67]
	v_mfma_f32_16x16x32_bf16 v[116:119], v[204:207], v[172:175], v[116:119]
	v_mfma_f32_16x16x32_bf16 v[108:111], v[212:215], v[172:175], v[108:111]
	v_mfma_f32_16x16x32_bf16 v[100:103], v[204:207], v[180:183], v[100:103]
	v_mfma_f32_16x16x32_bf16 v[92:95], v[212:215], v[180:183], v[92:95]
	v_mfma_f32_16x16x32_bf16 v[84:87], v[204:207], v[188:191], v[84:87]
	v_mfma_f32_16x16x32_bf16 v[76:79], v[212:215], v[188:191], v[76:79]
	v_mfma_f32_16x16x32_bf16 v[68:71], v[204:207], v[196:199], v[68:71]
	v_mfma_f32_16x16x32_bf16 v[64:67], v[212:215], v[196:199], v[64:67]
	s_mov_b32 m0, s52
	s_barrier
	ds_read_b128 v[168:171], v146 offset:49152
	ds_read_b128 v[172:175], v146 offset:50176
	ds_read_b128 v[176:179], v146 offset:51200
	ds_read_b128 v[180:183], v146 offset:52224
	ds_read_b128 v[184:187], v146 offset:53248
	ds_read_b128 v[188:191], v146 offset:54272
	ds_read_b128 v[192:195], v146 offset:55296
	ds_read_b128 v[196:199], v146 offset:56320
	global_load_lds_dwordx4 v134, s[100:101]
	s_mov_b32 m0, s53
	s_nop 0
	global_load_lds_dwordx4 v130, s[100:101]
	s_barrier
; #define PG8_STAGE(bufoff, gbase, voff) do { _Pragma("unroll") for (int _i = 0; _i < 2; ++_i) \
;         __builtin_amdgcn_global_load_lds((const unsigned*)((const char*)(gbase) + (voff)[_i]), (LAS unsigned*)(lds + (bufoff) + ldsw + _i * 8192), 16, 0, 0); } while (0)
; #define PG8_MMA(ai, bj, At, Bt) do { __builtin_amdgcn_s_setprio(1); _Pragma("unroll") for (int m = 0; m < 4; ++m) _Pragma("unroll") for (int n = 0; n < 2; ++n) _Pragma("unroll") for (int k = 0; k < 2; ++k) \
;         acc[ai][bj][m][n] = __builtin_amdgcn_mfma_f32_16x16x32_bf16(Bt[n][k], At[m][k], acc[ai][bj][m][n], 0, 0, 0); __builtin_amdgcn_s_setprio(0); } while (0)
; #define PG8_WAIT_V(n) asm volatile("s_waitcnt vmcnt(" #n ")" ::: "memory")
; #define PG8_WAIT_L(n) asm volatile("s_waitcnt lgkmcnt(" #n ")" ::: "memory")
; #define PG8_BAR __builtin_amdgcn_s_barrier()
; #define PG8_SCHED __builtin_amdgcn_sched_barrier(0)
; template <class Epi>
; __device__ __forceinline__ void gemm_phase(LAS unsigned char* lds, const Gemm g, const StaticOrder& S, const Epi& E) {
;     ...
;             PG8_BAR; PG8_WAIT_L(0); PG8_MMA(1, 0, At, B0); PG8_BAR; PG8_SCHED;
;             PG8_STAGE(PG8_SB(1, 1), b3 + hstep, voffB);
;             PG8_WAIT_V(6); PG8_BAR; PG8_MMA(1, 1, At, B1); PG8_BAR;
;         }
	s_waitcnt lgkmcnt(0)
	v_mfma_f32_16x16x32_bf16 v[60:63], v[148:151], v[168:171], v[60:63]
	v_mfma_f32_16x16x32_bf16 v[56:59], v[160:163], v[168:171], v[56:59]
	v_mfma_f32_16x16x32_bf16 v[52:55], v[148:151], v[176:179], v[52:55]
	v_mfma_f32_16x16x32_bf16 v[44:47], v[160:163], v[176:179], v[44:47]
	v_mfma_f32_16x16x32_bf16 v[36:39], v[148:151], v[184:187], v[36:39]
	v_mfma_f32_16x16x32_bf16 v[28:31], v[160:163], v[184:187], v[28:31]
	v_mfma_f32_16x16x32_bf16 v[20:23], v[148:151], v[192:195], v[20:23]
	v_mfma_f32_16x16x32_bf16 v[12:15], v[160:163], v[192:195], v[12:15]
	v_mfma_f32_16x16x32_bf16 v[60:63], v[152:155], v[172:175], v[60:63]
	v_mfma_f32_16x16x32_bf16 v[56:59], v[164:167], v[172:175], v[56:59]
	v_mfma_f32_16x16x32_bf16 v[52:55], v[152:155], v[180:183], v[52:55]
	v_mfma_f32_16x16x32_bf16 v[44:47], v[164:167], v[180:183], v[44:47]
	v_mfma_f32_16x16x32_bf16 v[36:39], v[152:155], v[188:191], v[36:39]
	v_mfma_f32_16x16x32_bf16 v[28:31], v[164:167], v[188:191], v[28:31]
	v_mfma_f32_16x16x32_bf16 v[20:23], v[152:155], v[196:199], v[20:23]
	v_mfma_f32_16x16x32_bf16 v[12:15], v[164:167], v[196:199], v[12:15]
	s_barrier
	s_add_u32 s42, s46, 0x160080
	s_addc_u32 s43, s47, 0
	s_add_i32 s46, s48, s23
	s_mov_b32 m0, s46
	s_nop 0
	global_load_lds_dwordx4 v132, s[42:43]
	s_add_i32 m0, s46, 0x2000
	s_nop 0
	global_load_lds_dwordx4 v128, s[42:43]
	s_waitcnt vmcnt(6)
	s_barrier
	v_mfma_f32_16x16x32_bf16 v[48:51], v[200:203], v[168:171], v[48:51]
	v_mfma_f32_16x16x32_bf16 v[40:43], v[208:211], v[168:171], v[40:43]
	v_mfma_f32_16x16x32_bf16 v[32:35], v[200:203], v[176:179], v[32:35]
	v_mfma_f32_16x16x32_bf16 v[24:27], v[208:211], v[176:179], v[24:27]
	v_mfma_f32_16x16x32_bf16 v[16:19], v[200:203], v[184:187], v[16:19]
	v_mfma_f32_16x16x32_bf16 v[8:11], v[208:211], v[184:187], v[8:11]
	v_mfma_f32_16x16x32_bf16 v[4:7], v[200:203], v[192:195], v[4:7]
	v_mfma_f32_16x16x32_bf16 v[0:3], v[208:211], v[192:195], v[0:3]
	v_mfma_f32_16x16x32_bf16 v[48:51], v[204:207], v[172:175], v[48:51]
	v_mfma_f32_16x16x32_bf16 v[40:43], v[212:215], v[172:175], v[40:43]
	v_mfma_f32_16x16x32_bf16 v[32:35], v[204:207], v[180:183], v[32:35]
	v_mfma_f32_16x16x32_bf16 v[24:27], v[212:215], v[180:183], v[24:27]
	v_mfma_f32_16x16x32_bf16 v[16:19], v[204:207], v[188:191], v[16:19]
	v_mfma_f32_16x16x32_bf16 v[8:11], v[212:215], v[188:191], v[8:11]
	v_mfma_f32_16x16x32_bf16 v[4:7], v[204:207], v[196:199], v[4:7]
	v_mfma_f32_16x16x32_bf16 v[0:3], v[212:215], v[196:199], v[0:3]
	s_add_i32 s67, s67, 2
	s_add_u32 s65, s65, 0x100
	s_addc_u32 s66, s66, 0
	s_cmpk_gt_u32 s67, 0x55
	s_mov_b64 s[42:43], s[44:45]
	s_barrier
	s_cbranch_scc0 .LBB0_864
; #define PG8_WAIT_V(n) asm volatile("s_waitcnt vmcnt(" #n ")" ::: "memory")
; #define PG8_BAR __builtin_amdgcn_s_barrier()
; __device__ __forceinline__ u32x4 pack8(f32x4 v0, f32x4 v1) { u32x4 w; w.x = cvt_pk_bf16(v0[0], v0[1]); w.y = cvt_pk_bf16(v0[2], v0[3]); w.z = cvt_pk_bf16(v1[0], v1[1]); w.w = cvt_pk_bf16(v1[2], v1[3]); return w; }
; template <class Epi>
; __device__ __forceinline__ void gemm_phase(LAS unsigned char* lds, const Gemm g, const StaticOrder& S, const Epi& E) {
;     ...
;         E(acc, cur, wr, wc, fr, fq);
;         if (!has_next) break;
; #pragma unroll
;         for (int a = 0; a < 2; ++a)
; #pragma unroll
;             for (int b = 0; b < 2; ++b)
; #pragma unroll
;                 for (int m = 0; m < 4; ++m)
; #pragma unroll
;                     for (int n = 0; n < 2; ++n) acc[a][b][m][n] = (f32x4){0.f, 0.f, 0.f, 0.f};
;         cur = nxt; cA = nA; cB = nB; ++ui;
;     }
;     PG8_WAIT_V(0);
;     if (wr == 0) PG8_BAR;
;     __device__ __forceinline__ void operator()(const f32x4 (&acc)[2][2][4][2], const Unit& u, int wr, int wc, int fr, int fq) const {
;         const int row0 = u.pm * BM + wr * 64 + fr, col0 = u.pn * BM + wc * 32 + 8 * fq;
; #pragma unroll
;         for (int ai = 0; ai < 2; ++ai)
; #pragma unroll
;             for (int m = 0; m < 4; ++m) { bf16_t* rowp = O + (size_t)(row0 + ai * HALF + m * 16) * ldc + col0;
; #pragma unroll
;                 for (int bj = 0; bj < 2; ++bj) *(u32x4*)(rowp + bj * HALF) = pack8(acc[ai][bj][m][0], acc[ai][bj][m][1]); }
	v_lshl_add_u32 v148, s63, 8, v142
	v_lshl_or_b32 v140, s64, 8, v144
	v_ashrrev_i32_e32 v149, 31, v148
	v_ashrrev_i32_e32 v141, 31, v140
	v_lshlrev_b64 v[150:151], 12, v[148:149]
	v_lshl_add_u64 v[150:151], s[24:25], 0, v[150:151]
	v_lshlrev_b64 v[152:153], 1, v[140:141]
	v_lshl_add_u64 v[140:141], v[150:151], 0, v[152:153]
	v_cvt_pk_bf16_f32 v124, v124, v125
	v_cvt_pk_bf16_f32 v125, v126, v127
	v_cvt_pk_bf16_f32 v126, v120, v121
	v_cvt_pk_bf16_f32 v127, v122, v123
	global_store_dwordx4 v[140:141], v[124:127], off
	v_cvt_pk_bf16_f32 v116, v116, v117
	v_cvt_pk_bf16_f32 v117, v118, v119
	v_cvt_pk_bf16_f32 v118, v108, v109
	v_or_b32_e32 v108, 16, v148
	v_ashrrev_i32_e32 v109, 31, v108
	v_lshlrev_b64 v[108:109], 12, v[108:109]
	v_lshl_add_u64 v[108:109], s[24:25], 0, v[108:109]
	v_cvt_pk_bf16_f32 v119, v110, v111
	global_store_dwordx4 v[140:141], v[116:119], off offset:256
	s_mov_b32 s64, s61
	s_mov_b32 s63, s62
	v_lshl_add_u64 v[116:117], v[108:109], 0, v[152:153]
	v_cvt_pk_bf16_f32 v108, v112, v113
	v_cvt_pk_bf16_f32 v109, v114, v115
	v_cvt_pk_bf16_f32 v110, v104, v105
	v_cvt_pk_bf16_f32 v111, v106, v107
	global_store_dwordx4 v[116:117], v[108:111], off
	v_cvt_pk_bf16_f32 v100, v100, v101
	v_cvt_pk_bf16_f32 v101, v102, v103
	v_cvt_pk_bf16_f32 v102, v92, v93
	v_or_b32_e32 v92, 32, v148
	v_ashrrev_i32_e32 v93, 31, v92
	v_lshlrev_b64 v[92:93], 12, v[92:93]
	v_lshl_add_u64 v[92:93], s[24:25], 0, v[92:93]
	v_cvt_pk_bf16_f32 v103, v94, v95
	global_store_dwordx4 v[116:117], v[100:103], off offset:256
	s_mov_b64 s[44:45], s[6:7]
	s_mov_b64 s[42:43], s[40:41]
	v_lshl_add_u64 v[100:101], v[92:93], 0, v[152:153]
	v_cvt_pk_bf16_f32 v92, v96, v97
	v_cvt_pk_bf16_f32 v93, v98, v99
	v_cvt_pk_bf16_f32 v94, v88, v89
	v_cvt_pk_bf16_f32 v95, v90, v91
	global_store_dwordx4 v[100:101], v[92:95], off
	v_cvt_pk_bf16_f32 v84, v84, v85
	v_cvt_pk_bf16_f32 v85, v86, v87
	v_cvt_pk_bf16_f32 v86, v76, v77
	v_or_b32_e32 v76, 48, v148
	v_ashrrev_i32_e32 v77, 31, v76
	v_lshlrev_b64 v[76:77], 12, v[76:77]
	v_lshl_add_u64 v[76:77], s[24:25], 0, v[76:77]
	v_cvt_pk_bf16_f32 v87, v78, v79
	global_store_dwordx4 v[100:101], v[84:87], off offset:256
	s_nop 1
	v_lshl_add_u64 v[84:85], v[76:77], 0, v[152:153]
	v_cvt_pk_bf16_f32 v76, v80, v81
	v_cvt_pk_bf16_f32 v77, v82, v83
	v_cvt_pk_bf16_f32 v78, v72, v73
	v_cvt_pk_bf16_f32 v79, v74, v75
	global_store_dwordx4 v[84:85], v[76:79], off
	v_cvt_pk_bf16_f32 v68, v68, v69
	v_cvt_pk_bf16_f32 v69, v70, v71
	v_cvt_pk_bf16_f32 v70, v64, v65
	v_cvt_pk_bf16_f32 v71, v66, v67
	global_store_dwordx4 v[84:85], v[68:71], off offset:256
	v_cvt_pk_bf16_f32 v60, v60, v61
	v_cvt_pk_bf16_f32 v61, v62, v63
	v_cvt_pk_bf16_f32 v62, v56, v57
	v_add_co_u32_e32 v56, vcc, s57, v140
	v_lshl_add_u64 v[64:65], v[140:141], 0, s[8:9]
	s_nop 0
	v_addc_co_u32_e32 v57, vcc, 0, v141, vcc
	v_cvt_pk_bf16_f32 v63, v58, v59
	global_store_dwordx4 v[56:57], v[60:63], off
	v_cvt_pk_bf16_f32 v48, v48, v49
	v_cvt_pk_bf16_f32 v49, v50, v51
	v_cvt_pk_bf16_f32 v50, v40, v41
	v_cvt_pk_bf16_f32 v51, v42, v43
	global_store_dwordx4 v[64:65], v[48:51], off offset:256
	v_cvt_pk_bf16_f32 v40, v52, v53
	v_cvt_pk_bf16_f32 v41, v54, v55
	v_cvt_pk_bf16_f32 v42, v44, v45
	v_add_co_u32_e32 v44, vcc, s58, v140
	s_nop 0
	v_lshl_add_u64 v[48:49], v[140:141], 0, s[30:31]
	v_addc_co_u32_e32 v45, vcc, 0, v141, vcc
	v_cvt_pk_bf16_f32 v43, v46, v47
	global_store_dwordx4 v[44:45], v[40:43], off
	v_cvt_pk_bf16_f32 v32, v32, v33
	v_cvt_pk_bf16_f32 v33, v34, v35
	v_cvt_pk_bf16_f32 v34, v24, v25
	v_cvt_pk_bf16_f32 v35, v26, v27
	global_store_dwordx4 v[48:49], v[32:35], off offset:256
	v_cvt_pk_bf16_f32 v24, v36, v37
	v_cvt_pk_bf16_f32 v25, v38, v39
	v_cvt_pk_bf16_f32 v26, v28, v29
	v_add_co_u32_e32 v28, vcc, s59, v140
	s_nop 0
	v_lshl_add_u64 v[32:33], v[140:141], 0, s[34:35]
	v_addc_co_u32_e32 v29, vcc, 0, v141, vcc
	v_cvt_pk_bf16_f32 v27, v30, v31
	global_store_dwordx4 v[28:29], v[24:27], off
	v_cvt_pk_bf16_f32 v16, v16, v17
	v_cvt_pk_bf16_f32 v17, v18, v19
	v_cvt_pk_bf16_f32 v18, v8, v9
	v_cvt_pk_bf16_f32 v19, v10, v11
	global_store_dwordx4 v[32:33], v[16:19], off offset:256
	v_cvt_pk_bf16_f32 v8, v20, v21
	v_cvt_pk_bf16_f32 v9, v22, v23
	v_cvt_pk_bf16_f32 v10, v12, v13
	v_add_co_u32_e32 v12, vcc, s60, v140
	s_nop 0
	v_lshl_add_u64 v[16:17], v[140:141], 0, s[36:37]
	v_addc_co_u32_e32 v13, vcc, 0, v141, vcc
	s_and_b64 vcc, exec, s[38:39]
	v_cvt_pk_bf16_f32 v11, v14, v15
	global_store_dwordx4 v[12:13], v[8:11], off
	v_cvt_pk_bf16_f32 v4, v4, v5
	v_cvt_pk_bf16_f32 v5, v6, v7
	v_cvt_pk_bf16_f32 v6, v0, v1
	v_cvt_pk_bf16_f32 v7, v2, v3
	global_store_dwordx4 v[16:17], v[4:7], off offset:256
	s_cbranch_vccz .LBB0_857
	s_waitcnt vmcnt(0)
	s_cmpk_gt_u32 s10, 0xff
	v_readlane_b32 s62, v232, 20
	v_readlane_b32 s61, v232, 21
	s_cbranch_scc1 .LBB0_868
	s_barrier

; #define PG8_STAGE(bufoff, gbase, voff) do { _Pragma("unroll") for (int _i = 0; _i < 2; ++_i) \
;         __builtin_amdgcn_global_load_lds((const unsigned*)((const char*)(gbase) + (voff)[_i]), (LAS unsigned*)(lds + (bufoff) + ldsw + _i * 8192), 16, 0, 0); } while (0)
; #define PG8_LDA(dst, b, h) do { _Pragma("unroll") for (int m = 0; m < 4; ++m) _Pragma("unroll") for (int k = 0; k < 2; ++k) dst[m][k] = *(const LAS bf16x8*)(lds + PG8_SA(b, h) + aoff + m * 2048 + k * 1024); } while (0)
; #define PG8_LDB(dst, b, h) do { _Pragma("unroll") for (int n = 0; n < 2; ++n) _Pragma("unroll") for (int k = 0; k < 2; ++k) dst[n][k] = *(const LAS bf16x8*)(lds + PG8_SB(b, h) + boff + n * 2048 + k * 1024); } while (0)
; #define PG8_WAIT_V(n) asm volatile("s_waitcnt vmcnt(" #n ")" ::: "memory")
; #define PG8_WAIT_L(n) asm volatile("s_waitcnt lgkmcnt(" #n ")" ::: "memory")
; #define PG8_BAR __builtin_amdgcn_s_barrier()
; #define PG8_SCHED __builtin_amdgcn_sched_barrier(0)
; template <class Epi>
; __device__ __forceinline__ void gemm_phase(LAS unsigned char* lds, const Gemm g, const StaticOrder& S, const Epi& E) {
;     ...
;         const bool has_next = S.next(ui + 1, nxt);
;         const char* nA = has_next ? (const char*)g.A + (size_t)nxt.pm * tstep : cA; const char* nB = has_next ? (const char*)g.Bt + (size_t)nxt.pn * tstep : cB;
;         for (int t = 0; t < nt; t += 2) {
;             const bool last = (t == nt - 2);
;             const char* a1 = cA + (size_t)(t + 1) * kstep;
;             const char* a2 = last ? nA : cA + (size_t)(t + 2) * kstep; const char* b2 = last ? nB : cB + (size_t)(t + 2) * kstep;
;             const char* a3 = a2 + kstep; const char* b3 = b2 + kstep;
;             PG8_LDB(B0, 0, 0); PG8_SCHED; PG8_LDA(At, 0, 0); PG8_STAGE(PG8_SA(1, 1), a1 + hstep, voffA);
;             PG8_WAIT_L(8); PG8_BAR; PG8_WAIT_L(0); PG8_MMA(0, 0, At, B0); PG8_BAR; PG8_SCHED;
;             PG8_LDB(B1, 0, 1); PG8_STAGE(PG8_SB(0, 0), b2, voffB);
;             PG8_BAR; PG8_WAIT_L(0); PG8_MMA(0, 1, At, B1); PG8_BAR;
;             PG8_LDA(At, 0, 1); PG8_STAGE(PG8_SA(0, 0), a2, voffA);
;             PG8_BAR; PG8_WAIT_L(0); PG8_MMA(1, 0, At, B0); PG8_BAR; PG8_SCHED;
;             PG8_STAGE(PG8_SB(0, 1), b2 + hstep, voffB);
;             PG8_WAIT_V(6); PG8_BAR; PG8_MMA(1, 1, At, B1); PG8_BAR;
.LBB0_987:
	s_add_u32 s53, s46, s52
	s_addc_u32 s61, s47, 0
	s_add_u32 s56, s53, 0x100
	s_addc_u32 s57, s61, 0
	s_and_b64 s[54:55], s[50:51], exec
	s_cselect_b32 s57, s37, s57
	s_cselect_b32 s56, s74, s56
	s_add_u32 s52, s44, s52
	s_addc_u32 s54, s45, 0
	s_add_u32 s52, s52, 0x100
	s_addc_u32 s54, s54, 0
	s_and_b64 s[50:51], s[50:51], exec
	s_cselect_b32 s59, s35, s54
	s_cselect_b32 s58, s75, s52
	s_add_u32 s60, s53, 0x10080
	s_addc_u32 s61, s61, 0
	s_add_i32 s85, s68, s28
	s_add_i32 m0, s33, 0xc000
	s_add_i32 s86, s33, 0xe000
	s_add_i32 s84, s85, 0x2000
	s_add_u32 s54, s58, 0x10000
	s_addc_u32 s55, s59, 0
	s_add_i32 s83, s69, s28
	ds_read_b128 v[144:147], v141
	ds_read_b128 v[148:151], v141 offset:1024
	ds_read_b128 v[152:155], v141 offset:2048
	ds_read_b128 v[160:163], v141 offset:3072
	s_add_i32 s82, s83, 0x2000
	s_add_i32 s81, 0, 0x18000
	s_add_u32 s52, s56, 0x10000
	s_addc_u32 s53, s57, 0
	s_add_i32 s80, s81, s28
	s_add_i32 s79, 0, 0x1c000
	s_add_i32 s78, s80, 0x2000
	s_add_u32 s50, s58, 0x10080
	s_addc_u32 s51, s59, 0
	s_add_i32 s77, s79, s28
	s_add_i32 s76, s77, 0x2000
	v_lshl_add_u64 v[136:137], s[60:61], 0, v[134:135]
	ds_read_b128 v[164:167], v142
	ds_read_b128 v[168:171], v142 offset:1024
	ds_read_b128 v[172:175], v142 offset:2048
	ds_read_b128 v[176:179], v142 offset:3072
	ds_read_b128 v[180:183], v142 offset:4096
	ds_read_b128 v[184:187], v142 offset:5120
	ds_read_b128 v[188:191], v142 offset:6144
	ds_read_b128 v[192:195], v142 offset:7168
	global_load_lds_dwordx4 v[136:137], off
	v_lshl_add_u64 v[136:137], s[60:61], 0, v[130:131]
	s_mov_b32 m0, s86
	s_nop 0
	global_load_lds_dwordx4 v[136:137], off
	s_waitcnt lgkmcnt(8)
	s_barrier
	s_waitcnt lgkmcnt(0)
	s_waitcnt lgkmcnt(0)
	v_mfma_f32_16x16x32_bf16 v[124:127], v[144:147], v[164:167], v[124:127]
	v_mfma_f32_16x16x32_bf16 v[120:123], v[152:155], v[164:167], v[120:123]
	v_mfma_f32_16x16x32_bf16 v[112:115], v[144:147], v[172:175], v[112:115]
	v_mfma_f32_16x16x32_bf16 v[104:107], v[152:155], v[172:175], v[104:107]
	v_mfma_f32_16x16x32_bf16 v[96:99], v[144:147], v[180:183], v[96:99]
	v_mfma_f32_16x16x32_bf16 v[88:91], v[152:155], v[180:183], v[88:91]
	v_mfma_f32_16x16x32_bf16 v[80:83], v[144:147], v[188:191], v[80:83]
	v_mfma_f32_16x16x32_bf16 v[72:75], v[152:155], v[188:191], v[72:75]
	v_mfma_f32_16x16x32_bf16 v[124:127], v[148:151], v[168:171], v[124:127]
	v_mfma_f32_16x16x32_bf16 v[120:123], v[160:163], v[168:171], v[120:123]
	v_mfma_f32_16x16x32_bf16 v[112:115], v[148:151], v[176:179], v[112:115]
	v_mfma_f32_16x16x32_bf16 v[104:107], v[160:163], v[176:179], v[104:107]
	v_mfma_f32_16x16x32_bf16 v[96:99], v[148:151], v[184:187], v[96:99]
	v_mfma_f32_16x16x32_bf16 v[88:91], v[160:163], v[184:187], v[88:91]
	v_mfma_f32_16x16x32_bf16 v[80:83], v[148:151], v[192:195], v[80:83]
	v_mfma_f32_16x16x32_bf16 v[72:75], v[160:163], v[192:195], v[72:75]
	s_barrier
	s_mov_b32 m0, s85
	v_lshl_add_u64 v[136:137], s[58:59], 0, v[132:133]
	ds_read_b128 v[196:199], v143
	ds_read_b128 v[200:203], v143 offset:1024
	ds_read_b128 v[204:207], v143 offset:2048
	ds_read_b128 v[208:211], v143 offset:3072
	global_load_lds_dwordx4 v[136:137], off
	v_lshl_add_u64 v[156:157], s[58:59], 0, v[128:129]
	s_mov_b32 m0, s84
	s_nop 0
	global_load_lds_dwordx4 v[156:157], off
	s_barrier
	s_waitcnt lgkmcnt(0)
	s_waitcnt lgkmcnt(0)
	v_mfma_f32_16x16x32_bf16 v[116:119], v[196:199], v[164:167], v[116:119]
	v_mfma_f32_16x16x32_bf16 v[108:111], v[204:207], v[164:167], v[108:111]
	v_mfma_f32_16x16x32_bf16 v[100:103], v[196:199], v[172:175], v[100:103]
	v_mfma_f32_16x16x32_bf16 v[92:95], v[204:207], v[172:175], v[92:95]
	v_mfma_f32_16x16x32_bf16 v[84:87], v[196:199], v[180:183], v[84:87]
	v_mfma_f32_16x16x32_bf16 v[76:79], v[204:207], v[180:183], v[76:79]
	v_mfma_f32_16x16x32_bf16 v[68:71], v[196:199], v[188:191], v[68:71]
	v_mfma_f32_16x16x32_bf16 v[64:67], v[204:207], v[188:191], v[64:67]
	v_mfma_f32_16x16x32_bf16 v[116:119], v[200:203], v[168:171], v[116:119]
	v_mfma_f32_16x16x32_bf16 v[108:111], v[208:211], v[168:171], v[108:111]
	v_mfma_f32_16x16x32_bf16 v[100:103], v[200:203], v[176:179], v[100:103]
	v_mfma_f32_16x16x32_bf16 v[92:95], v[208:211], v[176:179], v[92:95]
	v_mfma_f32_16x16x32_bf16 v[84:87], v[200:203], v[184:187], v[84:87]
	v_mfma_f32_16x16x32_bf16 v[76:79], v[208:211], v[184:187], v[76:79]
	v_mfma_f32_16x16x32_bf16 v[68:71], v[200:203], v[192:195], v[68:71]
	v_mfma_f32_16x16x32_bf16 v[64:67], v[208:211], v[192:195], v[64:67]
	s_mov_b32 m0, s33
	v_lshl_add_u64 v[212:213], s[56:57], 0, v[134:135]
	s_barrier
	ds_read_b128 v[164:167], v142 offset:16384
	ds_read_b128 v[168:171], v142 offset:17408
	ds_read_b128 v[172:175], v142 offset:18432
	ds_read_b128 v[176:179], v142 offset:19456
	ds_read_b128 v[180:183], v142 offset:20480
	ds_read_b128 v[184:187], v142 offset:21504
	ds_read_b128 v[188:191], v142 offset:22528
	ds_read_b128 v[192:195], v142 offset:23552
	global_load_lds_dwordx4 v[212:213], off
	v_lshl_add_u64 v[214:215], s[56:57], 0, v[130:131]
	s_mov_b32 m0, s43
	s_nop 0
	global_load_lds_dwordx4 v[214:215], off
	s_barrier
	s_waitcnt lgkmcnt(0)
	s_waitcnt lgkmcnt(0)
	v_mfma_f32_16x16x32_bf16 v[60:63], v[144:147], v[164:167], v[60:63]
	v_mfma_f32_16x16x32_bf16 v[56:59], v[152:155], v[164:167], v[56:59]
	v_mfma_f32_16x16x32_bf16 v[52:55], v[144:147], v[172:175], v[52:55]
	v_mfma_f32_16x16x32_bf16 v[44:47], v[152:155], v[172:175], v[44:47]
	v_mfma_f32_16x16x32_bf16 v[36:39], v[144:147], v[180:183], v[36:39]
	v_mfma_f32_16x16x32_bf16 v[28:31], v[152:155], v[180:183], v[28:31]
	v_mfma_f32_16x16x32_bf16 v[20:23], v[144:147], v[188:191], v[20:23]
	v_mfma_f32_16x16x32_bf16 v[12:15], v[152:155], v[188:191], v[12:15]
	v_mfma_f32_16x16x32_bf16 v[60:63], v[148:151], v[168:171], v[60:63]
	v_mfma_f32_16x16x32_bf16 v[56:59], v[160:163], v[168:171], v[56:59]
	v_mfma_f32_16x16x32_bf16 v[52:55], v[148:151], v[176:179], v[52:55]
	v_mfma_f32_16x16x32_bf16 v[44:47], v[160:163], v[176:179], v[44:47]
	v_mfma_f32_16x16x32_bf16 v[36:39], v[148:151], v[184:187], v[36:39]
	v_mfma_f32_16x16x32_bf16 v[28:31], v[160:163], v[184:187], v[28:31]
	v_mfma_f32_16x16x32_bf16 v[20:23], v[148:151], v[192:195], v[20:23]
	v_mfma_f32_16x16x32_bf16 v[12:15], v[160:163], v[192:195], v[12:15]
	s_barrier
; #define PG8_STAGE(bufoff, gbase, voff) do { _Pragma("unroll") for (int _i = 0; _i < 2; ++_i) \
;         __builtin_amdgcn_global_load_lds((const unsigned*)((const char*)(gbase) + (voff)[_i]), (LAS unsigned*)(lds + (bufoff) + ldsw + _i * 8192), 16, 0, 0); } while (0)
; #define PG8_LDA(dst, b, h) do { _Pragma("unroll") for (int m = 0; m < 4; ++m) _Pragma("unroll") for (int k = 0; k < 2; ++k) dst[m][k] = *(const LAS bf16x8*)(lds + PG8_SA(b, h) + aoff + m * 2048 + k * 1024); } while (0)
; #define PG8_LDB(dst, b, h) do { _Pragma("unroll") for (int n = 0; n < 2; ++n) _Pragma("unroll") for (int k = 0; k < 2; ++k) dst[n][k] = *(const LAS bf16x8*)(lds + PG8_SB(b, h) + boff + n * 2048 + k * 1024); } while (0)
; #define PG8_MMA(ai, bj, At, Bt) do { __builtin_amdgcn_s_setprio(1); _Pragma("unroll") for (int m = 0; m < 4; ++m) _Pragma("unroll") for (int n = 0; n < 2; ++n) _Pragma("unroll") for (int k = 0; k < 2; ++k) \
;         acc[ai][bj][m][n] = __builtin_amdgcn_mfma_f32_16x16x32_bf16(Bt[n][k], At[m][k], acc[ai][bj][m][n], 0, 0, 0); __builtin_amdgcn_s_setprio(0); } while (0)
; #define PG8_WAIT_V(n) asm volatile("s_waitcnt vmcnt(" #n ")" ::: "memory")
; #define PG8_WAIT_L(n) asm volatile("s_waitcnt lgkmcnt(" #n ")" ::: "memory")
; #define PG8_BAR __builtin_amdgcn_s_barrier()
; #define PG8_SCHED __builtin_amdgcn_sched_barrier(0)
; template <class Epi>
; __device__ __forceinline__ void gemm_phase(LAS unsigned char* lds, const Gemm g, const StaticOrder& S, const Epi& E) {
;     ...
;             PG8_WAIT_V(6); PG8_BAR; PG8_MMA(1, 1, At, B1); PG8_BAR;
;             PG8_LDB(B0, 1, 0); PG8_SCHED; PG8_LDA(At, 1, 0); PG8_STAGE(PG8_SA(0, 1), a2 + hstep, voffA);
;             PG8_WAIT_L(8); PG8_BAR; PG8_WAIT_L(0); PG8_MMA(0, 0, At, B0); PG8_BAR; PG8_SCHED;
;             PG8_LDB(B1, 1, 1); PG8_STAGE(PG8_SB(1, 0), b3, voffB);
;             PG8_BAR; PG8_WAIT_L(0); PG8_MMA(0, 1, At, B1); PG8_BAR;
;             PG8_LDA(At, 1, 1); PG8_STAGE(PG8_SA(1, 0), a3, voffA);
;             PG8_BAR; PG8_WAIT_L(0); PG8_MMA(1, 0, At, B0); PG8_BAR; PG8_SCHED;
	s_mov_b32 m0, s83
	v_lshl_add_u64 v[144:145], s[54:55], 0, v[132:133]
	global_load_lds_dwordx4 v[144:145], off
	v_lshl_add_u64 v[144:145], s[54:55], 0, v[128:129]
	s_mov_b32 m0, s82
	s_nop 0
	global_load_lds_dwordx4 v[144:145], off
	s_waitcnt vmcnt(6)
	s_barrier
	v_mfma_f32_16x16x32_bf16 v[48:51], v[196:199], v[164:167], v[48:51]
	v_mfma_f32_16x16x32_bf16 v[40:43], v[204:207], v[164:167], v[40:43]
	v_mfma_f32_16x16x32_bf16 v[32:35], v[196:199], v[172:175], v[32:35]
	v_mfma_f32_16x16x32_bf16 v[24:27], v[204:207], v[172:175], v[24:27]
	v_mfma_f32_16x16x32_bf16 v[16:19], v[196:199], v[180:183], v[16:19]
	v_mfma_f32_16x16x32_bf16 v[8:11], v[204:207], v[180:183], v[8:11]
	v_mfma_f32_16x16x32_bf16 v[4:7], v[196:199], v[188:191], v[4:7]
	v_mfma_f32_16x16x32_bf16 v[0:3], v[204:207], v[188:191], v[0:3]
	v_mfma_f32_16x16x32_bf16 v[48:51], v[200:203], v[168:171], v[48:51]
	v_mfma_f32_16x16x32_bf16 v[40:43], v[208:211], v[168:171], v[40:43]
	v_mfma_f32_16x16x32_bf16 v[32:35], v[200:203], v[176:179], v[32:35]
	v_mfma_f32_16x16x32_bf16 v[24:27], v[208:211], v[176:179], v[24:27]
	v_mfma_f32_16x16x32_bf16 v[16:19], v[200:203], v[184:187], v[16:19]
	v_mfma_f32_16x16x32_bf16 v[8:11], v[208:211], v[184:187], v[8:11]
	v_mfma_f32_16x16x32_bf16 v[4:7], v[200:203], v[192:195], v[4:7]
	v_mfma_f32_16x16x32_bf16 v[0:3], v[208:211], v[192:195], v[0:3]
	v_add_u32_e32 v160, s81, v139
	s_barrier
	ds_read_b128 v[144:147], v160
	ds_read_b128 v[148:151], v160 offset:1024
	ds_read_b128 v[152:155], v160 offset:2048
	ds_read_b128 v[160:163], v160 offset:3072
	s_mov_b32 m0, s62
	v_lshl_add_u64 v[196:197], s[52:53], 0, v[134:135]
	ds_read_b128 v[164:167], v142 offset:32768
	ds_read_b128 v[168:171], v142 offset:33792
	ds_read_b128 v[172:175], v142 offset:34816
	ds_read_b128 v[176:179], v142 offset:35840
	ds_read_b128 v[180:183], v142 offset:36864
	ds_read_b128 v[184:187], v142 offset:37888
	ds_read_b128 v[188:191], v142 offset:38912
	ds_read_b128 v[192:195], v142 offset:39936
	global_load_lds_dwordx4 v[196:197], off
	v_lshl_add_u64 v[196:197], s[52:53], 0, v[130:131]
	s_mov_b32 m0, s63
	s_nop 0
	global_load_lds_dwordx4 v[196:197], off
	s_waitcnt lgkmcnt(8)
	s_barrier
	s_waitcnt lgkmcnt(0)
	s_waitcnt lgkmcnt(0)
	v_mfma_f32_16x16x32_bf16 v[124:127], v[144:147], v[164:167], v[124:127]
	v_mfma_f32_16x16x32_bf16 v[120:123], v[152:155], v[164:167], v[120:123]
	v_mfma_f32_16x16x32_bf16 v[112:115], v[144:147], v[172:175], v[112:115]
	v_mfma_f32_16x16x32_bf16 v[104:107], v[152:155], v[172:175], v[104:107]
	v_mfma_f32_16x16x32_bf16 v[96:99], v[144:147], v[180:183], v[96:99]
	v_mfma_f32_16x16x32_bf16 v[88:91], v[152:155], v[180:183], v[88:91]
	v_mfma_f32_16x16x32_bf16 v[80:83], v[144:147], v[188:191], v[80:83]
	v_mfma_f32_16x16x32_bf16 v[72:75], v[152:155], v[188:191], v[72:75]
	v_mfma_f32_16x16x32_bf16 v[124:127], v[148:151], v[168:171], v[124:127]
	v_mfma_f32_16x16x32_bf16 v[120:123], v[160:163], v[168:171], v[120:123]
	v_mfma_f32_16x16x32_bf16 v[112:115], v[148:151], v[176:179], v[112:115]
	v_mfma_f32_16x16x32_bf16 v[104:107], v[160:163], v[176:179], v[104:107]
	v_mfma_f32_16x16x32_bf16 v[96:99], v[148:151], v[184:187], v[96:99]
	v_mfma_f32_16x16x32_bf16 v[88:91], v[160:163], v[184:187], v[88:91]
	v_mfma_f32_16x16x32_bf16 v[80:83], v[148:151], v[192:195], v[80:83]
	v_mfma_f32_16x16x32_bf16 v[72:75], v[160:163], v[192:195], v[72:75]
	s_barrier
	s_mov_b32 m0, s80
	v_add_u32_e32 v208, s79, v139
	v_lshl_add_u64 v[136:137], v[136:137], 0, s[2:3]
	ds_read_b128 v[196:199], v208
	ds_read_b128 v[200:203], v208 offset:1024
	ds_read_b128 v[204:207], v208 offset:2048
	ds_read_b128 v[208:211], v208 offset:3072
	global_load_lds_dwordx4 v[136:137], off
	v_lshl_add_u64 v[136:137], v[156:157], 0, s[2:3]
	s_mov_b32 m0, s78
	s_nop 0
	global_load_lds_dwordx4 v[136:137], off
	s_barrier
	s_waitcnt lgkmcnt(0)
	s_waitcnt lgkmcnt(0)
	v_mfma_f32_16x16x32_bf16 v[116:119], v[196:199], v[164:167], v[116:119]
	v_mfma_f32_16x16x32_bf16 v[108:111], v[204:207], v[164:167], v[108:111]
	v_mfma_f32_16x16x32_bf16 v[100:103], v[196:199], v[172:175], v[100:103]
	v_mfma_f32_16x16x32_bf16 v[92:95], v[204:207], v[172:175], v[92:95]
	v_mfma_f32_16x16x32_bf16 v[84:87], v[196:199], v[180:183], v[84:87]
	v_mfma_f32_16x16x32_bf16 v[76:79], v[204:207], v[180:183], v[76:79]
	v_mfma_f32_16x16x32_bf16 v[68:71], v[196:199], v[188:191], v[68:71]
	v_mfma_f32_16x16x32_bf16 v[64:67], v[204:207], v[188:191], v[64:67]
	v_mfma_f32_16x16x32_bf16 v[116:119], v[200:203], v[168:171], v[116:119]
	v_mfma_f32_16x16x32_bf16 v[108:111], v[208:211], v[168:171], v[108:111]
	v_mfma_f32_16x16x32_bf16 v[100:103], v[200:203], v[176:179], v[100:103]
	v_mfma_f32_16x16x32_bf16 v[92:95], v[208:211], v[176:179], v[92:95]
	v_mfma_f32_16x16x32_bf16 v[84:87], v[200:203], v[184:187], v[84:87]
	v_mfma_f32_16x16x32_bf16 v[76:79], v[208:211], v[184:187], v[76:79]
	v_mfma_f32_16x16x32_bf16 v[68:71], v[200:203], v[192:195], v[68:71]
	v_mfma_f32_16x16x32_bf16 v[64:67], v[208:211], v[192:195], v[64:67]
	s_mov_b32 m0, s65
	v_lshl_add_u64 v[136:137], v[212:213], 0, s[2:3]
	s_barrier
	ds_read_b128 v[164:167], v142 offset:49152
	ds_read_b128 v[168:171], v142 offset:50176
	ds_read_b128 v[172:175], v142 offset:51200
	ds_read_b128 v[176:179], v142 offset:52224
	ds_read_b128 v[180:183], v142 offset:53248
	ds_read_b128 v[184:187], v142 offset:54272
	ds_read_b128 v[188:191], v142 offset:55296
	ds_read_b128 v[192:195], v142 offset:56320
	global_load_lds_dwordx4 v[136:137], off
	v_lshl_add_u64 v[136:137], v[214:215], 0, s[2:3]
	s_mov_b32 m0, s66
	s_nop 0
	global_load_lds_dwordx4 v[136:137], off
	s_barrier
; #define PG8_STAGE(bufoff, gbase, voff) do { _Pragma("unroll") for (int _i = 0; _i < 2; ++_i) \
;         __builtin_amdgcn_global_load_lds((const unsigned*)((const char*)(gbase) + (voff)[_i]), (LAS unsigned*)(lds + (bufoff) + ldsw + _i * 8192), 16, 0, 0); } while (0)
; #define PG8_MMA(ai, bj, At, Bt) do { __builtin_amdgcn_s_setprio(1); _Pragma("unroll") for (int m = 0; m < 4; ++m) _Pragma("unroll") for (int n = 0; n < 2; ++n) _Pragma("unroll") for (int k = 0; k < 2; ++k) \
;         acc[ai][bj][m][n] = __builtin_amdgcn_mfma_f32_16x16x32_bf16(Bt[n][k], At[m][k], acc[ai][bj][m][n], 0, 0, 0); __builtin_amdgcn_s_setprio(0); } while (0)
; #define PG8_WAIT_V(n) asm volatile("s_waitcnt vmcnt(" #n ")" ::: "memory")
; #define PG8_WAIT_L(n) asm volatile("s_waitcnt lgkmcnt(" #n ")" ::: "memory")
; #define PG8_BAR __builtin_amdgcn_s_barrier()
; #define PG8_SCHED __builtin_amdgcn_sched_barrier(0)
; template <class Epi>
; __device__ __forceinline__ void gemm_phase(LAS unsigned char* lds, const Gemm g, const StaticOrder& S, const Epi& E) {
;     ...
;             PG8_BAR; PG8_WAIT_L(0); PG8_MMA(1, 0, At, B0); PG8_BAR; PG8_SCHED;
;             PG8_STAGE(PG8_SB(1, 1), b3 + hstep, voffB);
;             PG8_WAIT_V(6); PG8_BAR; PG8_MMA(1, 1, At, B1); PG8_BAR;
;         }
	s_waitcnt lgkmcnt(0)
	s_waitcnt lgkmcnt(0)
	v_mfma_f32_16x16x32_bf16 v[60:63], v[144:147], v[164:167], v[60:63]
	v_mfma_f32_16x16x32_bf16 v[56:59], v[152:155], v[164:167], v[56:59]
	v_mfma_f32_16x16x32_bf16 v[52:55], v[144:147], v[172:175], v[52:55]
	v_mfma_f32_16x16x32_bf16 v[44:47], v[152:155], v[172:175], v[44:47]
	v_mfma_f32_16x16x32_bf16 v[36:39], v[144:147], v[180:183], v[36:39]
	v_mfma_f32_16x16x32_bf16 v[28:31], v[152:155], v[180:183], v[28:31]
	v_mfma_f32_16x16x32_bf16 v[20:23], v[144:147], v[188:191], v[20:23]
	v_mfma_f32_16x16x32_bf16 v[12:15], v[152:155], v[188:191], v[12:15]
	v_mfma_f32_16x16x32_bf16 v[60:63], v[148:151], v[168:171], v[60:63]
	v_mfma_f32_16x16x32_bf16 v[56:59], v[160:163], v[168:171], v[56:59]
	v_mfma_f32_16x16x32_bf16 v[52:55], v[148:151], v[176:179], v[52:55]
	v_mfma_f32_16x16x32_bf16 v[44:47], v[160:163], v[176:179], v[44:47]
	v_mfma_f32_16x16x32_bf16 v[36:39], v[148:151], v[184:187], v[36:39]
	v_mfma_f32_16x16x32_bf16 v[28:31], v[160:163], v[184:187], v[28:31]
	v_mfma_f32_16x16x32_bf16 v[20:23], v[148:151], v[192:195], v[20:23]
	v_mfma_f32_16x16x32_bf16 v[12:15], v[160:163], v[192:195], v[12:15]
	s_barrier
	s_mov_b32 m0, s77
	v_lshl_add_u64 v[136:137], s[50:51], 0, v[132:133]
	global_load_lds_dwordx4 v[136:137], off
	v_lshl_add_u64 v[136:137], s[50:51], 0, v[128:129]
	s_mov_b32 m0, s76
	s_nop 0
	global_load_lds_dwordx4 v[136:137], off
	s_waitcnt vmcnt(6)
	s_barrier
	v_mfma_f32_16x16x32_bf16 v[48:51], v[196:199], v[164:167], v[48:51]
	v_mfma_f32_16x16x32_bf16 v[40:43], v[204:207], v[164:167], v[40:43]
	v_mfma_f32_16x16x32_bf16 v[32:35], v[196:199], v[172:175], v[32:35]
	v_mfma_f32_16x16x32_bf16 v[24:27], v[204:207], v[172:175], v[24:27]
	v_mfma_f32_16x16x32_bf16 v[16:19], v[196:199], v[180:183], v[16:19]
	v_mfma_f32_16x16x32_bf16 v[8:11], v[204:207], v[180:183], v[8:11]
	v_mfma_f32_16x16x32_bf16 v[4:7], v[196:199], v[188:191], v[4:7]
	v_mfma_f32_16x16x32_bf16 v[0:3], v[204:207], v[188:191], v[0:3]
	v_mfma_f32_16x16x32_bf16 v[48:51], v[200:203], v[168:171], v[48:51]
	v_mfma_f32_16x16x32_bf16 v[40:43], v[208:211], v[168:171], v[40:43]
	v_mfma_f32_16x16x32_bf16 v[32:35], v[200:203], v[176:179], v[32:35]
	v_mfma_f32_16x16x32_bf16 v[24:27], v[208:211], v[176:179], v[24:27]
	v_mfma_f32_16x16x32_bf16 v[16:19], v[200:203], v[184:187], v[16:19]
	v_mfma_f32_16x16x32_bf16 v[8:11], v[208:211], v[184:187], v[8:11]
	v_mfma_f32_16x16x32_bf16 v[4:7], v[200:203], v[192:195], v[4:7]
	v_mfma_f32_16x16x32_bf16 v[0:3], v[208:211], v[192:195], v[0:3]
	s_movk_i32 s52, 0x100
	s_andn2_b64 vcc, exec, s[48:49]
	s_mov_b64 s[50:51], -1
	s_mov_b64 s[48:49], 0
	s_barrier
	s_cbranch_vccz .LBB0_987
; #define PG8_WAIT_V(n) asm volatile("s_waitcnt vmcnt(" #n ")" ::: "memory")
; #define PG8_BAR __builtin_amdgcn_s_barrier()
; __device__ __forceinline__ u32x4 pack8(f32x4 v0, f32x4 v1) { u32x4 w; w.x = cvt_pk_bf16(v0[0], v0[1]); w.y = cvt_pk_bf16(v0[2], v0[3]); w.z = cvt_pk_bf16(v1[0], v1[1]); w.w = cvt_pk_bf16(v1[2], v1[3]); return w; }
; template <class Epi>
; __device__ __forceinline__ void gemm_phase(LAS unsigned char* lds, const Gemm g, const StaticOrder& S, const Epi& E) {
;     ...
;         E(acc, cur, wr, wc, fr, fq);
;         if (!has_next) break;
; #pragma unroll
;         for (int a = 0; a < 2; ++a)
; #pragma unroll
;             for (int b = 0; b < 2; ++b)
; #pragma unroll
;                 for (int m = 0; m < 4; ++m)
; #pragma unroll
;                     for (int n = 0; n < 2; ++n) acc[a][b][m][n] = (f32x4){0.f, 0.f, 0.f, 0.f};
;         cur = nxt; cA = nA; cB = nB; ++ui;
;     }
;     PG8_WAIT_V(0);
;     if (wr == 0) PG8_BAR;
;     __device__ __forceinline__ void operator()(const f32x4 (&acc)[2][2][4][2], const Unit& u, int wr, int wc, int fr, int fq) const {
;         const int row0 = u.pm * BM + wr * 64 + fr, col0 = u.pn * BM + wc * 32 + 8 * fq;
; #pragma unroll
;         for (int ai = 0; ai < 2; ++ai)
; #pragma unroll
;             for (int m = 0; m < 4; ++m) { bf16_t* rowp = O + (size_t)(row0 + ai * HALF + m * 16) * ldc + col0;
; #pragma unroll
;                 for (int bj = 0; bj < 2; ++bj) *(u32x4*)(rowp + bj * HALF) = pack8(acc[ai][bj][m][0], acc[ai][bj][m][1]); }
	v_lshl_add_u32 v144, s42, 8, v138
	v_lshl_or_b32 v136, s73, 8, v140
	v_ashrrev_i32_e32 v145, 31, v144
	v_ashrrev_i32_e32 v137, 31, v136
	v_lshlrev_b64 v[146:147], 12, v[144:145]
	v_lshl_add_u64 v[146:147], s[20:21], 0, v[146:147]
	v_lshlrev_b64 v[148:149], 1, v[136:137]
	v_lshl_add_u64 v[136:137], v[146:147], 0, v[148:149]
	v_cvt_pk_bf16_f32 v124, v124, v125
	v_cvt_pk_bf16_f32 v125, v126, v127
	v_cvt_pk_bf16_f32 v126, v120, v121
	v_cvt_pk_bf16_f32 v127, v122, v123
	global_store_dwordx4 v[136:137], v[124:127], off
	v_cvt_pk_bf16_f32 v116, v116, v117
	v_cvt_pk_bf16_f32 v117, v118, v119
	v_cvt_pk_bf16_f32 v118, v108, v109
	v_or_b32_e32 v108, 16, v144
	v_ashrrev_i32_e32 v109, 31, v108
	v_lshlrev_b64 v[108:109], 12, v[108:109]
	v_lshl_add_u64 v[108:109], s[20:21], 0, v[108:109]
	v_cvt_pk_bf16_f32 v119, v110, v111
	global_store_dwordx4 v[136:137], v[116:119], off offset:256
	s_mov_b32 s35, 0x80000
	s_mov_b64 s[44:45], 0x80000
	v_lshl_add_u64 v[116:117], v[108:109], 0, v[148:149]
	v_cvt_pk_bf16_f32 v108, v112, v113
	v_cvt_pk_bf16_f32 v109, v114, v115
	v_cvt_pk_bf16_f32 v110, v104, v105
	v_cvt_pk_bf16_f32 v111, v106, v107
	global_store_dwordx4 v[116:117], v[108:111], off
	v_cvt_pk_bf16_f32 v100, v100, v101
	v_cvt_pk_bf16_f32 v101, v102, v103
	v_cvt_pk_bf16_f32 v102, v92, v93
	v_or_b32_e32 v92, 32, v144
	v_ashrrev_i32_e32 v93, 31, v92
	v_lshlrev_b64 v[92:93], 12, v[92:93]
	v_lshl_add_u64 v[92:93], s[20:21], 0, v[92:93]
	v_cvt_pk_bf16_f32 v103, v94, v95
	global_store_dwordx4 v[116:117], v[100:103], off offset:256
	s_mov_b32 s73, s34
	s_mov_b32 s42, s36
	v_lshl_add_u64 v[100:101], v[92:93], 0, v[148:149]
	v_cvt_pk_bf16_f32 v92, v96, v97
	v_cvt_pk_bf16_f32 v93, v98, v99
	v_cvt_pk_bf16_f32 v94, v88, v89
	v_cvt_pk_bf16_f32 v95, v90, v91
	global_store_dwordx4 v[100:101], v[92:95], off
	v_cvt_pk_bf16_f32 v84, v84, v85
	v_cvt_pk_bf16_f32 v85, v86, v87
	v_cvt_pk_bf16_f32 v86, v76, v77
	v_or_b32_e32 v76, 48, v144
	v_ashrrev_i32_e32 v77, 31, v76
	v_lshlrev_b64 v[76:77], 12, v[76:77]
	v_lshl_add_u64 v[76:77], s[20:21], 0, v[76:77]
	v_cvt_pk_bf16_f32 v87, v78, v79
	global_store_dwordx4 v[100:101], v[84:87], off offset:256
	s_mov_b64 s[46:47], s[38:39]
	s_nop 0
	v_lshl_add_u64 v[84:85], v[76:77], 0, v[148:149]
	v_cvt_pk_bf16_f32 v76, v80, v81
	v_cvt_pk_bf16_f32 v77, v82, v83
	v_cvt_pk_bf16_f32 v78, v72, v73
	v_cvt_pk_bf16_f32 v79, v74, v75
	global_store_dwordx4 v[84:85], v[76:79], off
	v_cvt_pk_bf16_f32 v68, v68, v69
	v_cvt_pk_bf16_f32 v69, v70, v71
	v_cvt_pk_bf16_f32 v70, v64, v65
	v_cvt_pk_bf16_f32 v71, v66, v67
	global_store_dwordx4 v[84:85], v[68:71], off offset:256
	v_cvt_pk_bf16_f32 v60, v60, v61
	v_cvt_pk_bf16_f32 v61, v62, v63
	v_cvt_pk_bf16_f32 v62, v56, v57
	v_add_co_u32_e32 v56, vcc, s35, v136
	v_lshl_add_u64 v[64:65], v[136:137], 0, s[44:45]
	s_nop 0
	v_addc_co_u32_e32 v57, vcc, 0, v137, vcc
	v_cvt_pk_bf16_f32 v63, v58, v59
	global_store_dwordx4 v[56:57], v[60:63], off
	v_cvt_pk_bf16_f32 v48, v48, v49
	v_cvt_pk_bf16_f32 v49, v50, v51
	v_cvt_pk_bf16_f32 v50, v40, v41
	v_cvt_pk_bf16_f32 v51, v42, v43
	global_store_dwordx4 v[64:65], v[48:51], off offset:256
	s_mov_b64 s[44:45], 0x90000
	v_cvt_pk_bf16_f32 v40, v52, v53
	v_cvt_pk_bf16_f32 v41, v54, v55
	v_cvt_pk_bf16_f32 v42, v44, v45
	v_add_co_u32_e32 v44, vcc, s70, v136
	v_lshl_add_u64 v[48:49], v[136:137], 0, s[44:45]
	s_nop 0
	v_addc_co_u32_e32 v45, vcc, 0, v137, vcc
	v_cvt_pk_bf16_f32 v43, v46, v47
	global_store_dwordx4 v[44:45], v[40:43], off
	v_cvt_pk_bf16_f32 v32, v32, v33
	v_cvt_pk_bf16_f32 v33, v34, v35
	v_cvt_pk_bf16_f32 v34, v24, v25
	v_cvt_pk_bf16_f32 v35, v26, v27
	global_store_dwordx4 v[48:49], v[32:35], off offset:256
	v_cvt_pk_bf16_f32 v24, v36, v37
	v_cvt_pk_bf16_f32 v25, v38, v39
	v_cvt_pk_bf16_f32 v26, v28, v29
	v_add_co_u32_e32 v28, vcc, s71, v136
	s_nop 0
	v_lshl_add_u64 v[32:33], v[136:137], 0, s[6:7]
	v_addc_co_u32_e32 v29, vcc, 0, v137, vcc
	v_cvt_pk_bf16_f32 v27, v30, v31
	global_store_dwordx4 v[28:29], v[24:27], off
	v_cvt_pk_bf16_f32 v16, v16, v17
	v_cvt_pk_bf16_f32 v17, v18, v19
	v_cvt_pk_bf16_f32 v18, v8, v9
	v_cvt_pk_bf16_f32 v19, v10, v11
	global_store_dwordx4 v[32:33], v[16:19], off offset:256
	v_cvt_pk_bf16_f32 v8, v20, v21
	v_cvt_pk_bf16_f32 v9, v22, v23
	v_cvt_pk_bf16_f32 v10, v12, v13
	v_add_co_u32_e32 v12, vcc, s72, v136
	s_nop 0
	v_lshl_add_u64 v[16:17], v[136:137], 0, s[8:9]
	v_addc_co_u32_e32 v13, vcc, 0, v137, vcc
	s_and_b64 vcc, exec, s[30:31]
	s_mov_b64 s[44:45], s[40:41]
	v_cvt_pk_bf16_f32 v11, v14, v15
	global_store_dwordx4 v[12:13], v[8:11], off
	v_cvt_pk_bf16_f32 v4, v4, v5
	v_cvt_pk_bf16_f32 v5, v6, v7
	v_cvt_pk_bf16_f32 v6, v0, v1
	v_cvt_pk_bf16_f32 v7, v2, v3
	global_store_dwordx4 v[16:17], v[4:7], off offset:256
	s_cbranch_vccz .LBB0_984
	s_waitcnt vmcnt(0)
	s_cmpk_gt_u32 s10, 0xff
	s_cbranch_scc1 .LBB0_991
	s_barrier

; #define PG8_STAGE(bufoff, gbase, voff) do { _Pragma("unroll") for (int _i = 0; _i < 2; ++_i) \
;         __builtin_amdgcn_global_load_lds((const unsigned*)((const char*)(gbase) + (voff)[_i]), (LAS unsigned*)(lds + (bufoff) + ldsw + _i * 8192), 16, 0, 0); } while (0)
; #define PG8_LDA(dst, b, h) do { _Pragma("unroll") for (int m = 0; m < 4; ++m) _Pragma("unroll") for (int k = 0; k < 2; ++k) dst[m][k] = *(const LAS bf16x8*)(lds + PG8_SA(b, h) + aoff + m * 2048 + k * 1024); } while (0)
; #define PG8_LDB(dst, b, h) do { _Pragma("unroll") for (int n = 0; n < 2; ++n) _Pragma("unroll") for (int k = 0; k < 2; ++k) dst[n][k] = *(const LAS bf16x8*)(lds + PG8_SB(b, h) + boff + n * 2048 + k * 1024); } while (0)
; #define PG8_WAIT_V(n) asm volatile("s_waitcnt vmcnt(" #n ")" ::: "memory")
; #define PG8_WAIT_L(n) asm volatile("s_waitcnt lgkmcnt(" #n ")" ::: "memory")
; #define PG8_BAR __builtin_amdgcn_s_barrier()
; #define PG8_SCHED __builtin_amdgcn_sched_barrier(0)
; template <class Epi>
; __device__ __forceinline__ void gemm_phase(LAS unsigned char* lds, const Gemm g, const StaticOrder& S, const Epi& E) {
;     ...
;         for (int t = 0; t < nt; t += 2) {
;             const bool last = (t == nt - 2);
;             const char* a1 = cA + (size_t)(t + 1) * kstep;
;             const char* a2 = last ? nA : cA + (size_t)(t + 2) * kstep; const char* b2 = last ? nB : cB + (size_t)(t + 2) * kstep;
;             const char* a3 = a2 + kstep; const char* b3 = b2 + kstep;
;             PG8_LDB(B0, 0, 0); PG8_SCHED; PG8_LDA(At, 0, 0); PG8_STAGE(PG8_SA(1, 1), a1 + hstep, voffA);
;             PG8_WAIT_L(8); PG8_BAR; PG8_WAIT_L(0); PG8_MMA(0, 0, At, B0); PG8_BAR; PG8_SCHED;
;             PG8_LDB(B1, 0, 1); PG8_STAGE(PG8_SB(0, 0), b2, voffB);
;             PG8_BAR; PG8_WAIT_L(0); PG8_MMA(0, 1, At, B1); PG8_BAR;
;             PG8_LDA(At, 0, 1); PG8_STAGE(PG8_SA(0, 0), a2, voffA);
;             PG8_BAR; PG8_WAIT_L(0); PG8_MMA(1, 0, At, B0); PG8_BAR; PG8_SCHED;
;             PG8_STAGE(PG8_SB(0, 1), b2 + hstep, voffB);
;             PG8_WAIT_V(6); PG8_BAR; PG8_MMA(1, 1, At, B1); PG8_BAR;
;             PG8_LDB(B0, 1, 0); PG8_SCHED; PG8_LDA(At, 1, 0); PG8_STAGE(PG8_SA(0, 1), a2 + hstep, voffA);
;             PG8_WAIT_L(8); PG8_BAR; PG8_WAIT_L(0); PG8_MMA(0, 0, At, B0); PG8_BAR; PG8_SCHED;
.LBB0_999:
	ds_read_b128 v[140:143], v151
	ds_read_b128 v[144:147], v151 offset:1024
	ds_read_b128 v[154:157], v151 offset:2048
	ds_read_b128 v[160:163], v151 offset:3072
	s_add_u32 s48, s46, 0xfff80080
	s_addc_u32 s49, s47, -1
	s_cmp_eq_u32 s63, 28
	s_cselect_b32 s51, s37, s49
	s_cselect_b32 s50, s59, s48
	s_cselect_b32 s49, s35, s62
	s_cselect_b32 s48, s60, s61
	s_add_i32 m0, s28, 0xc000
	ds_read_b128 v[164:167], v152
	ds_read_b128 v[168:171], v152 offset:1024
	ds_read_b128 v[172:175], v152 offset:2048
	ds_read_b128 v[176:179], v152 offset:3072
	ds_read_b128 v[180:183], v152 offset:4096
	ds_read_b128 v[184:187], v152 offset:5120
	ds_read_b128 v[188:191], v152 offset:6144
	ds_read_b128 v[192:195], v152 offset:7168
	global_load_lds_dwordx4 v136, s[46:47]
	s_add_i32 m0, s28, 0xe000
	s_nop 0
	global_load_lds_dwordx4 v138, s[46:47]
	s_waitcnt lgkmcnt(8)
	s_barrier
	s_waitcnt lgkmcnt(0)
	v_mfma_f32_16x16x32_bf16 v[124:127], v[140:143], v[164:167], v[124:127]
	v_mfma_f32_16x16x32_bf16 v[120:123], v[154:157], v[164:167], v[120:123]
	v_mfma_f32_16x16x32_bf16 v[108:111], v[140:143], v[172:175], v[108:111]
	v_mfma_f32_16x16x32_bf16 v[104:107], v[154:157], v[172:175], v[104:107]
	v_mfma_f32_16x16x32_bf16 v[92:95], v[140:143], v[180:183], v[92:95]
	v_mfma_f32_16x16x32_bf16 v[88:91], v[154:157], v[180:183], v[88:91]
	v_mfma_f32_16x16x32_bf16 v[76:79], v[140:143], v[188:191], v[76:79]
	v_mfma_f32_16x16x32_bf16 v[72:75], v[154:157], v[188:191], v[72:75]
	v_mfma_f32_16x16x32_bf16 v[124:127], v[144:147], v[168:171], v[124:127]
	v_mfma_f32_16x16x32_bf16 v[120:123], v[160:163], v[168:171], v[120:123]
	v_mfma_f32_16x16x32_bf16 v[108:111], v[144:147], v[176:179], v[108:111]
	v_mfma_f32_16x16x32_bf16 v[104:107], v[160:163], v[176:179], v[104:107]
	v_mfma_f32_16x16x32_bf16 v[92:95], v[144:147], v[184:187], v[92:95]
	v_mfma_f32_16x16x32_bf16 v[88:91], v[160:163], v[184:187], v[88:91]
	v_mfma_f32_16x16x32_bf16 v[76:79], v[144:147], v[192:195], v[76:79]
	v_mfma_f32_16x16x32_bf16 v[72:75], v[160:163], v[192:195], v[72:75]
	s_barrier
	s_add_i32 s64, s56, s23
	s_add_u32 s98, s48, s4
	s_addc_u32 s99, s49, s5
	s_mov_b32 m0, s64
	ds_read_b128 v[196:199], v153
	ds_read_b128 v[200:203], v153 offset:1024
	ds_read_b128 v[204:207], v153 offset:2048
	ds_read_b128 v[208:211], v153 offset:3072
	global_load_lds_dwordx4 v132, s[48:49]
	s_add_i32 m0, s64, 0x2000
	s_nop 0
	global_load_lds_dwordx4 v128, s[48:49]
	s_barrier
	s_waitcnt lgkmcnt(0)
	v_mfma_f32_16x16x32_bf16 v[116:119], v[196:199], v[164:167], v[116:119]
	v_mfma_f32_16x16x32_bf16 v[112:115], v[204:207], v[164:167], v[112:115]
	v_mfma_f32_16x16x32_bf16 v[100:103], v[196:199], v[172:175], v[100:103]
	v_mfma_f32_16x16x32_bf16 v[96:99], v[204:207], v[172:175], v[96:99]
	v_mfma_f32_16x16x32_bf16 v[84:87], v[196:199], v[180:183], v[84:87]
	v_mfma_f32_16x16x32_bf16 v[80:83], v[204:207], v[180:183], v[80:83]
	v_mfma_f32_16x16x32_bf16 v[68:71], v[196:199], v[188:191], v[68:71]
	v_mfma_f32_16x16x32_bf16 v[64:67], v[204:207], v[188:191], v[64:67]
	v_mfma_f32_16x16x32_bf16 v[116:119], v[200:203], v[168:171], v[116:119]
	v_mfma_f32_16x16x32_bf16 v[112:115], v[208:211], v[168:171], v[112:115]
	v_mfma_f32_16x16x32_bf16 v[100:103], v[200:203], v[176:179], v[100:103]
	v_mfma_f32_16x16x32_bf16 v[96:99], v[208:211], v[176:179], v[96:99]
	v_mfma_f32_16x16x32_bf16 v[84:87], v[200:203], v[184:187], v[84:87]
	v_mfma_f32_16x16x32_bf16 v[80:83], v[208:211], v[184:187], v[80:83]
	v_mfma_f32_16x16x32_bf16 v[68:71], v[200:203], v[192:195], v[68:71]
	v_mfma_f32_16x16x32_bf16 v[64:67], v[208:211], v[192:195], v[64:67]
	s_mov_b32 m0, s28
	s_add_u32 s100, s50, s4
	s_addc_u32 s101, s51, s5
	s_barrier
	ds_read_b128 v[164:167], v152 offset:16384
	ds_read_b128 v[168:171], v152 offset:17408
	ds_read_b128 v[172:175], v152 offset:18432
	ds_read_b128 v[176:179], v152 offset:19456
	ds_read_b128 v[180:183], v152 offset:20480
	ds_read_b128 v[184:187], v152 offset:21504
	ds_read_b128 v[188:191], v152 offset:22528
	ds_read_b128 v[192:195], v152 offset:23552
	global_load_lds_dwordx4 v134, s[50:51]
	s_mov_b32 m0, s29
	s_nop 0
	global_load_lds_dwordx4 v130, s[50:51]
	s_barrier
	s_waitcnt lgkmcnt(0)
	v_mfma_f32_16x16x32_bf16 v[60:63], v[140:143], v[164:167], v[60:63]
	v_mfma_f32_16x16x32_bf16 v[56:59], v[154:157], v[164:167], v[56:59]
	v_mfma_f32_16x16x32_bf16 v[44:47], v[140:143], v[172:175], v[44:47]
	v_mfma_f32_16x16x32_bf16 v[40:43], v[154:157], v[172:175], v[40:43]
	v_mfma_f32_16x16x32_bf16 v[28:31], v[140:143], v[180:183], v[28:31]
	v_mfma_f32_16x16x32_bf16 v[24:27], v[154:157], v[180:183], v[24:27]
	v_mfma_f32_16x16x32_bf16 v[12:15], v[140:143], v[188:191], v[12:15]
	v_mfma_f32_16x16x32_bf16 v[8:11], v[154:157], v[188:191], v[8:11]
	v_mfma_f32_16x16x32_bf16 v[60:63], v[144:147], v[168:171], v[60:63]
	v_mfma_f32_16x16x32_bf16 v[56:59], v[160:163], v[168:171], v[56:59]
	v_mfma_f32_16x16x32_bf16 v[44:47], v[144:147], v[176:179], v[44:47]
	v_mfma_f32_16x16x32_bf16 v[40:43], v[160:163], v[176:179], v[40:43]
	v_mfma_f32_16x16x32_bf16 v[28:31], v[144:147], v[184:187], v[28:31]
	v_mfma_f32_16x16x32_bf16 v[24:27], v[160:163], v[184:187], v[24:27]
	v_mfma_f32_16x16x32_bf16 v[12:15], v[144:147], v[192:195], v[12:15]
	v_mfma_f32_16x16x32_bf16 v[8:11], v[160:163], v[192:195], v[8:11]
	s_barrier
	s_add_u32 s64, s48, 0x80000
	s_addc_u32 s65, s49, 0
	s_add_i32 s66, s57, s23
	s_mov_b32 m0, s66
	s_nop 0
	global_load_lds_dwordx4 v132, s[64:65]
	s_add_i32 m0, s66, 0x2000
	s_nop 0
	global_load_lds_dwordx4 v128, s[64:65]
	s_waitcnt vmcnt(6)
	s_barrier
; #define PG8_STAGE(bufoff, gbase, voff) do { _Pragma("unroll") for (int _i = 0; _i < 2; ++_i) \
;         __builtin_amdgcn_global_load_lds((const unsigned*)((const char*)(gbase) + (voff)[_i]), (LAS unsigned*)(lds + (bufoff) + ldsw + _i * 8192), 16, 0, 0); } while (0)
; #define PG8_LDA(dst, b, h) do { _Pragma("unroll") for (int m = 0; m < 4; ++m) _Pragma("unroll") for (int k = 0; k < 2; ++k) dst[m][k] = *(const LAS bf16x8*)(lds + PG8_SA(b, h) + aoff + m * 2048 + k * 1024); } while (0)
; #define PG8_LDB(dst, b, h) do { _Pragma("unroll") for (int n = 0; n < 2; ++n) _Pragma("unroll") for (int k = 0; k < 2; ++k) dst[n][k] = *(const LAS bf16x8*)(lds + PG8_SB(b, h) + boff + n * 2048 + k * 1024); } while (0)
; #define PG8_MMA(ai, bj, At, Bt) do { __builtin_amdgcn_s_setprio(1); _Pragma("unroll") for (int m = 0; m < 4; ++m) _Pragma("unroll") for (int n = 0; n < 2; ++n) _Pragma("unroll") for (int k = 0; k < 2; ++k) \
;         acc[ai][bj][m][n] = __builtin_amdgcn_mfma_f32_16x16x32_bf16(Bt[n][k], At[m][k], acc[ai][bj][m][n], 0, 0, 0); __builtin_amdgcn_s_setprio(0); } while (0)
; #define PG8_WAIT_V(n) asm volatile("s_waitcnt vmcnt(" #n ")" ::: "memory")
; #define PG8_WAIT_L(n) asm volatile("s_waitcnt lgkmcnt(" #n ")" ::: "memory")
; #define PG8_BAR __builtin_amdgcn_s_barrier()
; #define PG8_SCHED __builtin_amdgcn_sched_barrier(0)
; template <class Epi>
; __device__ __forceinline__ void gemm_phase(LAS unsigned char* lds, const Gemm g, const StaticOrder& S, const Epi& E) {
;     ...
;             PG8_WAIT_V(6); PG8_BAR; PG8_MMA(1, 1, At, B1); PG8_BAR;
;             PG8_LDB(B0, 1, 0); PG8_SCHED; PG8_LDA(At, 1, 0); PG8_STAGE(PG8_SA(0, 1), a2 + hstep, voffA);
;             PG8_WAIT_L(8); PG8_BAR; PG8_WAIT_L(0); PG8_MMA(0, 0, At, B0); PG8_BAR; PG8_SCHED;
;             PG8_LDB(B1, 1, 1); PG8_STAGE(PG8_SB(1, 0), b3, voffB);
;             PG8_BAR; PG8_WAIT_L(0); PG8_MMA(0, 1, At, B1); PG8_BAR;
;             PG8_LDA(At, 1, 1); PG8_STAGE(PG8_SA(1, 0), a3, voffA);
;             PG8_BAR; PG8_WAIT_L(0); PG8_MMA(1, 0, At, B0); PG8_BAR; PG8_SCHED;
	v_mfma_f32_16x16x32_bf16 v[52:55], v[196:199], v[164:167], v[52:55]
	v_mfma_f32_16x16x32_bf16 v[48:51], v[204:207], v[164:167], v[48:51]
	v_mfma_f32_16x16x32_bf16 v[36:39], v[196:199], v[172:175], v[36:39]
	v_mfma_f32_16x16x32_bf16 v[32:35], v[204:207], v[172:175], v[32:35]
	v_mfma_f32_16x16x32_bf16 v[20:23], v[196:199], v[180:183], v[20:23]
	v_mfma_f32_16x16x32_bf16 v[16:19], v[204:207], v[180:183], v[16:19]
	v_mfma_f32_16x16x32_bf16 v[4:7], v[196:199], v[188:191], v[4:7]
	v_mfma_f32_16x16x32_bf16 v[0:3], v[204:207], v[188:191], v[0:3]
	v_mfma_f32_16x16x32_bf16 v[52:55], v[200:203], v[168:171], v[52:55]
	v_mfma_f32_16x16x32_bf16 v[48:51], v[208:211], v[168:171], v[48:51]
	v_mfma_f32_16x16x32_bf16 v[36:39], v[200:203], v[176:179], v[36:39]
	v_mfma_f32_16x16x32_bf16 v[32:35], v[208:211], v[176:179], v[32:35]
	v_mfma_f32_16x16x32_bf16 v[20:23], v[200:203], v[184:187], v[20:23]
	v_mfma_f32_16x16x32_bf16 v[16:19], v[208:211], v[184:187], v[16:19]
	v_mfma_f32_16x16x32_bf16 v[4:7], v[200:203], v[192:195], v[4:7]
	v_mfma_f32_16x16x32_bf16 v[0:3], v[208:211], v[192:195], v[0:3]
	s_add_i32 s64, 0, 0x18000
	v_add_u32_e32 v160, s64, v149
	s_barrier
	ds_read_b128 v[140:143], v160
	ds_read_b128 v[144:147], v160 offset:1024
	ds_read_b128 v[154:157], v160 offset:2048
	ds_read_b128 v[160:163], v160 offset:3072
	s_add_u32 s50, s50, 0x80000
	s_addc_u32 s51, s51, 0
	s_mov_b32 m0, s33
	ds_read_b128 v[164:167], v152 offset:32768
	ds_read_b128 v[168:171], v152 offset:33792
	ds_read_b128 v[172:175], v152 offset:34816
	ds_read_b128 v[176:179], v152 offset:35840
	ds_read_b128 v[180:183], v152 offset:36864
	ds_read_b128 v[184:187], v152 offset:37888
	ds_read_b128 v[188:191], v152 offset:38912
	ds_read_b128 v[192:195], v152 offset:39936
	global_load_lds_dwordx4 v134, s[50:51]
	s_mov_b32 m0, s45
	s_nop 0
	global_load_lds_dwordx4 v130, s[50:51]
	s_waitcnt lgkmcnt(8)
	s_barrier
	s_waitcnt lgkmcnt(0)
	v_mfma_f32_16x16x32_bf16 v[124:127], v[140:143], v[164:167], v[124:127]
	v_mfma_f32_16x16x32_bf16 v[120:123], v[154:157], v[164:167], v[120:123]
	v_mfma_f32_16x16x32_bf16 v[108:111], v[140:143], v[172:175], v[108:111]
	v_mfma_f32_16x16x32_bf16 v[104:107], v[154:157], v[172:175], v[104:107]
	v_mfma_f32_16x16x32_bf16 v[92:95], v[140:143], v[180:183], v[92:95]
	v_mfma_f32_16x16x32_bf16 v[88:91], v[154:157], v[180:183], v[88:91]
	v_mfma_f32_16x16x32_bf16 v[76:79], v[140:143], v[188:191], v[76:79]
	v_mfma_f32_16x16x32_bf16 v[72:75], v[154:157], v[188:191], v[72:75]
	v_mfma_f32_16x16x32_bf16 v[124:127], v[144:147], v[168:171], v[124:127]
	v_mfma_f32_16x16x32_bf16 v[120:123], v[160:163], v[168:171], v[120:123]
	v_mfma_f32_16x16x32_bf16 v[108:111], v[144:147], v[176:179], v[108:111]
	v_mfma_f32_16x16x32_bf16 v[104:107], v[160:163], v[176:179], v[104:107]
	v_mfma_f32_16x16x32_bf16 v[92:95], v[144:147], v[184:187], v[92:95]
	v_mfma_f32_16x16x32_bf16 v[88:91], v[160:163], v[184:187], v[88:91]
	v_mfma_f32_16x16x32_bf16 v[76:79], v[144:147], v[192:195], v[76:79]
	v_mfma_f32_16x16x32_bf16 v[72:75], v[160:163], v[192:195], v[72:75]
	s_barrier
	s_add_i32 s50, 0, 0x1c000
	s_add_i32 s51, s64, s23
	v_add_u32_e32 v208, s50, v149
	s_mov_b32 m0, s51
	ds_read_b128 v[196:199], v208
	ds_read_b128 v[200:203], v208 offset:1024
	ds_read_b128 v[204:207], v208 offset:2048
	ds_read_b128 v[208:211], v208 offset:3072
	global_load_lds_dwordx4 v132, s[98:99]
	s_add_i32 m0, s51, 0x2000
	s_nop 0
	global_load_lds_dwordx4 v128, s[98:99]
	s_barrier
	s_waitcnt lgkmcnt(0)
	v_mfma_f32_16x16x32_bf16 v[116:119], v[196:199], v[164:167], v[116:119]
	v_mfma_f32_16x16x32_bf16 v[112:115], v[204:207], v[164:167], v[112:115]
	v_mfma_f32_16x16x32_bf16 v[100:103], v[196:199], v[172:175], v[100:103]
	v_mfma_f32_16x16x32_bf16 v[96:99], v[204:207], v[172:175], v[96:99]
	v_mfma_f32_16x16x32_bf16 v[84:87], v[196:199], v[180:183], v[84:87]
	v_mfma_f32_16x16x32_bf16 v[80:83], v[204:207], v[180:183], v[80:83]
	v_mfma_f32_16x16x32_bf16 v[68:71], v[196:199], v[188:191], v[68:71]
	v_mfma_f32_16x16x32_bf16 v[64:67], v[204:207], v[188:191], v[64:67]
	v_mfma_f32_16x16x32_bf16 v[116:119], v[200:203], v[168:171], v[116:119]
	v_mfma_f32_16x16x32_bf16 v[112:115], v[208:211], v[168:171], v[112:115]
	v_mfma_f32_16x16x32_bf16 v[100:103], v[200:203], v[176:179], v[100:103]
	v_mfma_f32_16x16x32_bf16 v[96:99], v[208:211], v[176:179], v[96:99]
	v_mfma_f32_16x16x32_bf16 v[84:87], v[200:203], v[184:187], v[84:87]
	v_mfma_f32_16x16x32_bf16 v[80:83], v[208:211], v[184:187], v[80:83]
	v_mfma_f32_16x16x32_bf16 v[68:71], v[200:203], v[192:195], v[68:71]
	v_mfma_f32_16x16x32_bf16 v[64:67], v[208:211], v[192:195], v[64:67]
	s_mov_b32 m0, s53
	s_barrier
	ds_read_b128 v[164:167], v152 offset:49152
	ds_read_b128 v[168:171], v152 offset:50176
	ds_read_b128 v[172:175], v152 offset:51200
	ds_read_b128 v[176:179], v152 offset:52224
	ds_read_b128 v[180:183], v152 offset:53248
	ds_read_b128 v[184:187], v152 offset:54272
	ds_read_b128 v[188:191], v152 offset:55296
	ds_read_b128 v[192:195], v152 offset:56320
	global_load_lds_dwordx4 v134, s[100:101]
	s_mov_b32 m0, s54
	s_nop 0
	global_load_lds_dwordx4 v130, s[100:101]
	s_barrier
; __device__ __forceinline__ float bf_lo(unsigned w) { return __uint_as_float(w << 16); }
; __device__ __forceinline__ float bf_hi(unsigned w) { return __uint_as_float(w & 0xffff0000u); }
; __device__ __forceinline__ float fast_rcp(float x) { return __builtin_amdgcn_rcpf(x); }
; __device__ __forceinline__ float fast_exp2(float x) { return __builtin_amdgcn_exp2f(x); }
; #define PG8_STAGE(bufoff, gbase, voff) do { _Pragma("unroll") for (int _i = 0; _i < 2; ++_i) \
;         __builtin_amdgcn_global_load_lds((const unsigned*)((const char*)(gbase) + (voff)[_i]), (LAS unsigned*)(lds + (bufoff) + ldsw + _i * 8192), 16, 0, 0); } while (0)
; #define PG8_WAIT_V(n) asm volatile("s_waitcnt vmcnt(" #n ")" ::: "memory")
; #define PG8_WAIT_L(n) asm volatile("s_waitcnt lgkmcnt(" #n ")" ::: "memory")
; #define PG8_BAR __builtin_amdgcn_s_barrier()
; template <class Epi>
; __device__ __forceinline__ void gemm_phase(LAS unsigned char* lds, const Gemm g, const StaticOrder& S, const Epi& E) {
;     ...
;             PG8_BAR; PG8_WAIT_L(0); PG8_MMA(1, 0, At, B0); PG8_BAR; PG8_SCHED;
;             PG8_STAGE(PG8_SB(1, 1), b3 + hstep, voffB);
;             PG8_WAIT_V(6); PG8_BAR; PG8_MMA(1, 1, At, B1); PG8_BAR;
;         }
;     __device__ __forceinline__ void operator()(const f32x4 (&acc)[2][2][4][2], const Unit& u, int wr, int wc, int fr, int fq) const {
;         const int row0 = u.pm * BM + wr * 64 + fr, col0 = u.pn * BM + wc * 32 + 8 * fq;
; #pragma unroll
;         for (int ai = 0; ai < 2; ++ai)
; #pragma unroll
;             for (int m = 0; m < 4; ++m) { const size_t ro = (size_t)(row0 + ai * HALF + m * 16) * DM + col0; const float nr = -LOG2E * rs[row0 + ai * HALF + m * 16];
; #pragma unroll
;                 for (int bj = 0; bj < 2; ++bj) {
;                     const u32x4 pw = *(const u32x4*)(PP + ro + bj * HALF);
;                     const float pv[8] = {bf_lo(pw.x), bf_hi(pw.x), bf_lo(pw.y), bf_hi(pw.y), bf_lo(pw.z), bf_hi(pw.z), bf_lo(pw.w), bf_hi(pw.w)};
;                     f32x4 t0, t1;
; #pragma unroll
;                     for (int j = 0; j < 4; ++j) {
;                         t0[j] = fast_rcp(1.0f + fast_exp2(acc[ai][bj][m][0][j] * nr)) * pv[j];
;                         t1[j] = fast_rcp(1.0f + fast_exp2(acc[ai][bj][m][1][j] * nr)) * pv[4 + j]; }
;                     *(u32x4*)(O + ro + bj * HALF) = pack8(t0, t1); } }
	s_waitcnt lgkmcnt(0)
	v_mfma_f32_16x16x32_bf16 v[60:63], v[140:143], v[164:167], v[60:63]
	v_mfma_f32_16x16x32_bf16 v[56:59], v[154:157], v[164:167], v[56:59]
	v_mfma_f32_16x16x32_bf16 v[44:47], v[140:143], v[172:175], v[44:47]
	v_mfma_f32_16x16x32_bf16 v[40:43], v[154:157], v[172:175], v[40:43]
	v_mfma_f32_16x16x32_bf16 v[28:31], v[140:143], v[180:183], v[28:31]
	v_mfma_f32_16x16x32_bf16 v[24:27], v[154:157], v[180:183], v[24:27]
	v_mfma_f32_16x16x32_bf16 v[12:15], v[140:143], v[188:191], v[12:15]
	v_mfma_f32_16x16x32_bf16 v[8:11], v[154:157], v[188:191], v[8:11]
	v_mfma_f32_16x16x32_bf16 v[60:63], v[144:147], v[168:171], v[60:63]
	v_mfma_f32_16x16x32_bf16 v[56:59], v[160:163], v[168:171], v[56:59]
	v_mfma_f32_16x16x32_bf16 v[44:47], v[144:147], v[176:179], v[44:47]
	v_mfma_f32_16x16x32_bf16 v[40:43], v[160:163], v[176:179], v[40:43]
	v_mfma_f32_16x16x32_bf16 v[28:31], v[144:147], v[184:187], v[28:31]
	v_mfma_f32_16x16x32_bf16 v[24:27], v[160:163], v[184:187], v[24:27]
	v_mfma_f32_16x16x32_bf16 v[12:15], v[144:147], v[192:195], v[12:15]
	v_mfma_f32_16x16x32_bf16 v[8:11], v[160:163], v[192:195], v[8:11]
	s_barrier
	s_add_u32 s48, s48, 0x80080
	s_addc_u32 s49, s49, 0
	s_add_i32 s50, s50, s23
	s_mov_b32 m0, s50
	s_nop 0
	global_load_lds_dwordx4 v132, s[48:49]
	s_add_i32 m0, s50, 0x2000
	s_nop 0
	global_load_lds_dwordx4 v128, s[48:49]
	s_waitcnt vmcnt(6)
	s_barrier
	v_mfma_f32_16x16x32_bf16 v[52:55], v[196:199], v[164:167], v[52:55]
	v_mfma_f32_16x16x32_bf16 v[48:51], v[204:207], v[164:167], v[48:51]
	v_mfma_f32_16x16x32_bf16 v[36:39], v[196:199], v[172:175], v[36:39]
	v_mfma_f32_16x16x32_bf16 v[32:35], v[204:207], v[172:175], v[32:35]
	v_mfma_f32_16x16x32_bf16 v[20:23], v[196:199], v[180:183], v[20:23]
	v_mfma_f32_16x16x32_bf16 v[16:19], v[204:207], v[180:183], v[16:19]
	v_mfma_f32_16x16x32_bf16 v[4:7], v[196:199], v[188:191], v[4:7]
	v_mfma_f32_16x16x32_bf16 v[0:3], v[204:207], v[188:191], v[0:3]
	v_mfma_f32_16x16x32_bf16 v[52:55], v[200:203], v[168:171], v[52:55]
	v_mfma_f32_16x16x32_bf16 v[48:51], v[208:211], v[168:171], v[48:51]
	v_mfma_f32_16x16x32_bf16 v[36:39], v[200:203], v[176:179], v[36:39]
	v_mfma_f32_16x16x32_bf16 v[32:35], v[208:211], v[176:179], v[32:35]
	v_mfma_f32_16x16x32_bf16 v[20:23], v[200:203], v[184:187], v[20:23]
	v_mfma_f32_16x16x32_bf16 v[16:19], v[208:211], v[184:187], v[16:19]
	v_mfma_f32_16x16x32_bf16 v[4:7], v[200:203], v[192:195], v[4:7]
	v_mfma_f32_16x16x32_bf16 v[0:3], v[208:211], v[192:195], v[0:3]
	s_add_i32 s63, s63, 2
	s_add_u32 s46, s46, 0x100
	s_addc_u32 s47, s47, 0
	s_add_u32 s61, s61, 0x100
	s_addc_u32 s62, s62, 0
	s_cmp_gt_u32 s63, 29
	s_barrier
	s_cbranch_scc0 .LBB0_999
	v_lshl_add_u32 v144, s44, 8, v148
	v_ashrrev_i32_e32 v145, 31, v144
	v_lshl_add_u64 v[140:141], v[144:145], 2, s[14:15]
	global_load_dword v164, v[140:141], off
	v_lshl_or_b32 v146, s58, 8, v150
	v_ashrrev_i32_e32 v147, 31, v146
	v_lshlrev_b64 v[142:143], 11, v[144:145]
	v_lshl_add_u64 v[142:143], v[142:143], 0, v[146:147]
	v_lshlrev_b64 v[142:143], 1, v[142:143]
	v_lshl_add_u64 v[160:161], s[20:21], 0, v[142:143]
	global_load_dwordx4 v[154:157], v[160:161], off
	global_load_dwordx4 v[220:223], v[160:161], off offset:256
	v_lshl_add_u64 v[162:163], s[24:25], 0, v[142:143]
	s_and_b64 vcc, exec, s[38:39]
	s_mov_b32 s58, s34
	s_mov_b32 s44, s36
	s_mov_b64 s[48:49], s[42:43]
	s_mov_b64 s[46:47], s[40:41]
	s_waitcnt vmcnt(0)
	v_mul_f32_e32 v145, 0xbfb8aa3b, v164
	v_mul_f32_e32 v124, v124, v145
	v_mul_f32_e32 v120, v120, v145
	v_mul_f32_e32 v125, v125, v145
	v_mul_f32_e32 v121, v121, v145
	v_mul_f32_e32 v126, v126, v145
	v_mul_f32_e32 v122, v122, v145
	v_mul_f32_e32 v127, v127, v145
	v_mul_f32_e32 v123, v123, v145
	v_exp_f32_e32 v124, v124
	v_exp_f32_e32 v120, v120
	v_exp_f32_e32 v125, v125
	v_exp_f32_e32 v121, v121
	v_exp_f32_e32 v126, v126
	v_exp_f32_e32 v122, v122
	v_exp_f32_e32 v127, v127
	v_exp_f32_e32 v123, v123
	v_add_f32_e32 v124, 1.0, v124
	v_add_f32_e32 v120, 1.0, v120
	v_add_f32_e32 v125, 1.0, v125
	v_add_f32_e32 v121, 1.0, v121
	v_add_f32_e32 v126, 1.0, v126
	v_add_f32_e32 v122, 1.0, v122
	v_add_f32_e32 v127, 1.0, v127
	v_add_f32_e32 v123, 1.0, v123
	v_rcp_f32_e32 v124, v124
	v_rcp_f32_e32 v120, v120
	v_rcp_f32_e32 v125, v125
	v_rcp_f32_e32 v121, v121
	v_rcp_f32_e32 v126, v126
	v_rcp_f32_e32 v122, v122
	v_rcp_f32_e32 v127, v127
	v_rcp_f32_e32 v123, v123
	v_lshlrev_b32_e32 v164, 16, v154
	v_and_b32_e32 v154, 0xffff0000, v154
	v_lshlrev_b32_e32 v165, 16, v155
	v_and_b32_e32 v155, 0xffff0000, v155
	v_lshlrev_b32_e32 v166, 16, v156
	v_and_b32_e32 v156, 0xffff0000, v156
	v_lshlrev_b32_e32 v167, 16, v157
	v_and_b32_e32 v157, 0xffff0000, v157
	v_mul_f32_e32 v124, v124, v164
	v_mul_f32_e32 v164, v120, v166
	v_mul_f32_e32 v120, v125, v154
	v_mul_f32_e32 v125, v121, v156
	v_mul_f32_e32 v121, v126, v165
	v_mul_f32_e32 v126, v122, v167
	v_mul_f32_e32 v122, v127, v155
	v_mul_f32_e32 v123, v123, v157
	v_cvt_pk_bf16_f32 v120, v124, v120
	v_cvt_pk_bf16_f32 v121, v121, v122
	v_cvt_pk_bf16_f32 v122, v164, v125
	v_cvt_pk_bf16_f32 v123, v126, v123
	global_store_dwordx4 v[162:163], v[120:123], off
	v_mul_f32_e32 v116, v116, v145
	v_mul_f32_e32 v112, v112, v145
	v_mul_f32_e32 v117, v117, v145
	v_mul_f32_e32 v113, v113, v145
	v_mul_f32_e32 v118, v118, v145
	v_mul_f32_e32 v114, v114, v145
	v_mul_f32_e32 v119, v119, v145
	v_mul_f32_e32 v115, v115, v145
	v_exp_f32_e32 v116, v116
	v_exp_f32_e32 v112, v112
	v_exp_f32_e32 v117, v117
	v_exp_f32_e32 v113, v113
	v_exp_f32_e32 v118, v118
	v_exp_f32_e32 v114, v114
	v_exp_f32_e32 v119, v119
	v_exp_f32_e32 v115, v115
	v_add_f32_e32 v116, 1.0, v116
	v_add_f32_e32 v112, 1.0, v112
	v_add_f32_e32 v117, 1.0, v117
; __device__ __forceinline__ float bf_lo(unsigned w) { return __uint_as_float(w << 16); }
; __device__ __forceinline__ float bf_hi(unsigned w) { return __uint_as_float(w & 0xffff0000u); }
; __device__ __forceinline__ float fast_rcp(float x) { return __builtin_amdgcn_rcpf(x); }
; __device__ __forceinline__ float fast_exp2(float x) { return __builtin_amdgcn_exp2f(x); }
; __device__ __forceinline__ u32x4 pack8(f32x4 v0, f32x4 v1) { u32x4 w; w.x = cvt_pk_bf16(v0[0], v0[1]); w.y = cvt_pk_bf16(v0[2], v0[3]); w.z = cvt_pk_bf16(v1[0], v1[1]); w.w = cvt_pk_bf16(v1[2], v1[3]); return w; }
;     __device__ __forceinline__ void operator()(const f32x4 (&acc)[2][2][4][2], const Unit& u, int wr, int wc, int fr, int fq) const {
;     ...
;         for (int ai = 0; ai < 2; ++ai)
; #pragma unroll
;             for (int m = 0; m < 4; ++m) { const size_t ro = (size_t)(row0 + ai * HALF + m * 16) * DM + col0; const float nr = -LOG2E * rs[row0 + ai * HALF + m * 16];
; #pragma unroll
;                 for (int bj = 0; bj < 2; ++bj) {
;                     const u32x4 pw = *(const u32x4*)(PP + ro + bj * HALF);
;                     const float pv[8] = {bf_lo(pw.x), bf_hi(pw.x), bf_lo(pw.y), bf_hi(pw.y), bf_lo(pw.z), bf_hi(pw.z), bf_lo(pw.w), bf_hi(pw.w)};
;                     f32x4 t0, t1;
; #pragma unroll
;                     for (int j = 0; j < 4; ++j) {
;                         t0[j] = fast_rcp(1.0f + fast_exp2(acc[ai][bj][m][0][j] * nr)) * pv[j];
;                         t1[j] = fast_rcp(1.0f + fast_exp2(acc[ai][bj][m][1][j] * nr)) * pv[4 + j]; }
;                     *(u32x4*)(O + ro + bj * HALF) = pack8(t0, t1); } }
	v_add_f32_e32 v113, 1.0, v113
	v_add_f32_e32 v118, 1.0, v118
	v_add_f32_e32 v114, 1.0, v114
	v_add_f32_e32 v119, 1.0, v119
	v_add_f32_e32 v115, 1.0, v115
	v_rcp_f32_e32 v116, v116
	v_rcp_f32_e32 v112, v112
	v_rcp_f32_e32 v117, v117
	v_rcp_f32_e32 v113, v113
	v_rcp_f32_e32 v118, v118
	v_rcp_f32_e32 v114, v114
	v_rcp_f32_e32 v119, v119
	v_rcp_f32_e32 v115, v115
	v_or_b32_e32 v124, 16, v144
	v_ashrrev_i32_e32 v125, 31, v124
	v_lshlrev_b64 v[124:125], 11, v[124:125]
	v_lshl_add_u64 v[124:125], v[124:125], 0, v[146:147]
	v_lshlrev_b64 v[124:125], 1, v[124:125]
	v_lshl_add_u64 v[126:127], s[20:21], 0, v[124:125]
	v_lshlrev_b32_e32 v145, 16, v220
	v_and_b32_e32 v120, 0xffff0000, v220
	v_lshlrev_b32_e32 v154, 16, v221
	v_and_b32_e32 v121, 0xffff0000, v221
	v_lshlrev_b32_e32 v155, 16, v222
	v_and_b32_e32 v122, 0xffff0000, v222
	v_lshlrev_b32_e32 v156, 16, v223
	v_and_b32_e32 v123, 0xffff0000, v223
	v_mul_f32_e32 v116, v116, v145
	v_mul_f32_e32 v145, v112, v155
	v_mul_f32_e32 v112, v117, v120
	v_mul_f32_e32 v117, v113, v122
	v_mul_f32_e32 v113, v118, v154
	v_mul_f32_e32 v118, v114, v156
	v_mul_f32_e32 v114, v119, v121
	v_mul_f32_e32 v115, v115, v123
	v_cvt_pk_bf16_f32 v112, v116, v112
	v_cvt_pk_bf16_f32 v113, v113, v114
	v_cvt_pk_bf16_f32 v114, v145, v117
	v_cvt_pk_bf16_f32 v115, v118, v115
	global_store_dwordx4 v[162:163], v[112:115], off offset:256
	global_load_dword v118, v[140:141], off offset:64
	s_nop 0
	global_load_dwordx4 v[112:115], v[126:127], off
	global_load_dwordx4 v[224:227], v[126:127], off offset:256
	v_lshl_add_u64 v[116:117], s[24:25], 0, v[124:125]
	s_waitcnt vmcnt(0)
	v_mul_f32_e32 v118, 0xbfb8aa3b, v118
	v_mul_f32_e32 v108, v108, v118
	v_mul_f32_e32 v104, v104, v118
	v_mul_f32_e32 v109, v109, v118
	v_mul_f32_e32 v105, v105, v118
	v_mul_f32_e32 v110, v110, v118
	v_mul_f32_e32 v106, v106, v118
	v_mul_f32_e32 v111, v111, v118
	v_mul_f32_e32 v107, v107, v118
	v_exp_f32_e32 v108, v108
	v_exp_f32_e32 v104, v104
	v_exp_f32_e32 v109, v109
	v_exp_f32_e32 v105, v105
	v_exp_f32_e32 v110, v110
	v_exp_f32_e32 v106, v106
	v_exp_f32_e32 v111, v111
	v_exp_f32_e32 v107, v107
	v_add_f32_e32 v108, 1.0, v108
	v_add_f32_e32 v104, 1.0, v104
	v_add_f32_e32 v109, 1.0, v109
	v_add_f32_e32 v105, 1.0, v105
	v_add_f32_e32 v110, 1.0, v110
	v_add_f32_e32 v106, 1.0, v106
	v_add_f32_e32 v111, 1.0, v111
	v_add_f32_e32 v107, 1.0, v107
	v_rcp_f32_e32 v108, v108
	v_rcp_f32_e32 v104, v104
	v_rcp_f32_e32 v109, v109
	v_rcp_f32_e32 v105, v105
	v_rcp_f32_e32 v110, v110
	v_rcp_f32_e32 v106, v106
	v_rcp_f32_e32 v111, v111
	v_rcp_f32_e32 v107, v107
	v_lshlrev_b32_e32 v119, 16, v112
	v_and_b32_e32 v112, 0xffff0000, v112
	v_lshlrev_b32_e32 v120, 16, v113
	v_and_b32_e32 v113, 0xffff0000, v113
	v_lshlrev_b32_e32 v121, 16, v114
	v_and_b32_e32 v114, 0xffff0000, v114
	v_lshlrev_b32_e32 v122, 16, v115
	v_and_b32_e32 v115, 0xffff0000, v115
	v_mul_f32_e32 v108, v108, v119
	v_mul_f32_e32 v119, v104, v121
	v_mul_f32_e32 v104, v109, v112
	v_mul_f32_e32 v109, v105, v114
	v_mul_f32_e32 v105, v110, v120
	v_mul_f32_e32 v110, v106, v122
	v_mul_f32_e32 v106, v111, v113
	v_mul_f32_e32 v107, v107, v115
	v_cvt_pk_bf16_f32 v104, v108, v104
	v_cvt_pk_bf16_f32 v105, v105, v106
	v_cvt_pk_bf16_f32 v106, v119, v109
	v_cvt_pk_bf16_f32 v107, v110, v107
	global_store_dwordx4 v[116:117], v[104:107], off
	v_mul_f32_e32 v100, v100, v118
	v_mul_f32_e32 v96, v96, v118
	v_mul_f32_e32 v101, v101, v118
	v_mul_f32_e32 v97, v97, v118
	v_mul_f32_e32 v102, v102, v118
	v_mul_f32_e32 v98, v98, v118
	v_mul_f32_e32 v103, v103, v118
	v_mul_f32_e32 v99, v99, v118
	v_exp_f32_e32 v100, v100
	v_exp_f32_e32 v96, v96
	v_exp_f32_e32 v101, v101
	v_exp_f32_e32 v97, v97
	v_exp_f32_e32 v102, v102
	v_exp_f32_e32 v98, v98
	v_exp_f32_e32 v103, v103
	v_exp_f32_e32 v99, v99
	v_add_f32_e32 v100, 1.0, v100
	v_add_f32_e32 v96, 1.0, v96
	v_add_f32_e32 v101, 1.0, v101
	v_add_f32_e32 v97, 1.0, v97
	v_add_f32_e32 v102, 1.0, v102
	v_add_f32_e32 v98, 1.0, v98
	v_add_f32_e32 v103, 1.0, v103
	v_add_f32_e32 v99, 1.0, v99
	v_rcp_f32_e32 v100, v100
	v_rcp_f32_e32 v96, v96
	v_rcp_f32_e32 v101, v101
	v_rcp_f32_e32 v97, v97
	v_rcp_f32_e32 v102, v102
	v_rcp_f32_e32 v98, v98
	v_rcp_f32_e32 v103, v103
	v_rcp_f32_e32 v99, v99
	v_or_b32_e32 v108, 32, v144
	v_ashrrev_i32_e32 v109, 31, v108
	v_lshlrev_b64 v[108:109], 11, v[108:109]
	v_lshl_add_u64 v[108:109], v[108:109], 0, v[146:147]
	v_lshlrev_b64 v[108:109], 1, v[108:109]
	v_lshl_add_u64 v[110:111], s[20:21], 0, v[108:109]
	v_lshlrev_b32_e32 v112, 16, v224
	v_and_b32_e32 v104, 0xffff0000, v224
	v_lshlrev_b32_e32 v113, 16, v225
	v_and_b32_e32 v105, 0xffff0000, v225
	v_lshlrev_b32_e32 v114, 16, v226
	v_and_b32_e32 v106, 0xffff0000, v226
	v_lshlrev_b32_e32 v115, 16, v227
	v_and_b32_e32 v107, 0xffff0000, v227
	v_mul_f32_e32 v100, v100, v112
	v_mul_f32_e32 v112, v96, v114
	v_mul_f32_e32 v96, v101, v104
	v_mul_f32_e32 v101, v97, v106
	v_mul_f32_e32 v97, v102, v113
	v_mul_f32_e32 v102, v98, v115
	v_mul_f32_e32 v98, v103, v105
	v_mul_f32_e32 v99, v99, v107
	v_cvt_pk_bf16_f32 v96, v100, v96
	v_cvt_pk_bf16_f32 v97, v97, v98
	v_cvt_pk_bf16_f32 v98, v112, v101
	v_cvt_pk_bf16_f32 v99, v102, v99
	global_store_dwordx4 v[116:117], v[96:99], off offset:256
	global_load_dword v102, v[140:141], off offset:128
	s_nop 0
	global_load_dwordx4 v[96:99], v[110:111], off
	global_load_dwordx4 v[220:223], v[110:111], off offset:256
	v_lshl_add_u64 v[100:101], s[24:25], 0, v[108:109]
	s_waitcnt vmcnt(0)
; __device__ __forceinline__ float bf_lo(unsigned w) { return __uint_as_float(w << 16); }
; __device__ __forceinline__ float bf_hi(unsigned w) { return __uint_as_float(w & 0xffff0000u); }
; __device__ __forceinline__ float fast_rcp(float x) { return __builtin_amdgcn_rcpf(x); }
; __device__ __forceinline__ float fast_exp2(float x) { return __builtin_amdgcn_exp2f(x); }
; __device__ __forceinline__ u32x4 pack8(f32x4 v0, f32x4 v1) { u32x4 w; w.x = cvt_pk_bf16(v0[0], v0[1]); w.y = cvt_pk_bf16(v0[2], v0[3]); w.z = cvt_pk_bf16(v1[0], v1[1]); w.w = cvt_pk_bf16(v1[2], v1[3]); return w; }
;     __device__ __forceinline__ void operator()(const f32x4 (&acc)[2][2][4][2], const Unit& u, int wr, int wc, int fr, int fq) const {
;     ...
;         for (int ai = 0; ai < 2; ++ai)
; #pragma unroll
;             for (int m = 0; m < 4; ++m) { const size_t ro = (size_t)(row0 + ai * HALF + m * 16) * DM + col0; const float nr = -LOG2E * rs[row0 + ai * HALF + m * 16];
; #pragma unroll
;                 for (int bj = 0; bj < 2; ++bj) {
;                     const u32x4 pw = *(const u32x4*)(PP + ro + bj * HALF);
;                     const float pv[8] = {bf_lo(pw.x), bf_hi(pw.x), bf_lo(pw.y), bf_hi(pw.y), bf_lo(pw.z), bf_hi(pw.z), bf_lo(pw.w), bf_hi(pw.w)};
;                     f32x4 t0, t1;
; #pragma unroll
;                     for (int j = 0; j < 4; ++j) {
;                         t0[j] = fast_rcp(1.0f + fast_exp2(acc[ai][bj][m][0][j] * nr)) * pv[j];
;                         t1[j] = fast_rcp(1.0f + fast_exp2(acc[ai][bj][m][1][j] * nr)) * pv[4 + j]; }
;                     *(u32x4*)(O + ro + bj * HALF) = pack8(t0, t1); } }
	v_mul_f32_e32 v102, 0xbfb8aa3b, v102
	v_mul_f32_e32 v92, v92, v102
	v_mul_f32_e32 v88, v88, v102
	v_mul_f32_e32 v93, v93, v102
	v_mul_f32_e32 v89, v89, v102
	v_mul_f32_e32 v94, v94, v102
	v_mul_f32_e32 v90, v90, v102
	v_mul_f32_e32 v95, v95, v102
	v_mul_f32_e32 v91, v91, v102
	v_exp_f32_e32 v92, v92
	v_exp_f32_e32 v88, v88
	v_exp_f32_e32 v93, v93
	v_exp_f32_e32 v89, v89
	v_exp_f32_e32 v94, v94
	v_exp_f32_e32 v90, v90
	v_exp_f32_e32 v95, v95
	v_exp_f32_e32 v91, v91
	v_add_f32_e32 v92, 1.0, v92
	v_add_f32_e32 v88, 1.0, v88
	v_add_f32_e32 v93, 1.0, v93
	v_add_f32_e32 v89, 1.0, v89
	v_add_f32_e32 v94, 1.0, v94
	v_add_f32_e32 v90, 1.0, v90
	v_add_f32_e32 v95, 1.0, v95
	v_add_f32_e32 v91, 1.0, v91
	v_rcp_f32_e32 v92, v92
	v_rcp_f32_e32 v88, v88
	v_rcp_f32_e32 v93, v93
	v_rcp_f32_e32 v89, v89
	v_rcp_f32_e32 v94, v94
	v_rcp_f32_e32 v90, v90
	v_rcp_f32_e32 v95, v95
	v_rcp_f32_e32 v91, v91
	v_lshlrev_b32_e32 v103, 16, v96
	v_and_b32_e32 v96, 0xffff0000, v96
	v_lshlrev_b32_e32 v104, 16, v97
	v_and_b32_e32 v97, 0xffff0000, v97
	v_lshlrev_b32_e32 v105, 16, v98
	v_and_b32_e32 v98, 0xffff0000, v98
	v_lshlrev_b32_e32 v106, 16, v99
	v_and_b32_e32 v99, 0xffff0000, v99
	v_mul_f32_e32 v92, v92, v103
	v_mul_f32_e32 v103, v88, v105
	v_mul_f32_e32 v88, v93, v96
	v_mul_f32_e32 v93, v89, v98
	v_mul_f32_e32 v89, v94, v104
	v_mul_f32_e32 v94, v90, v106
	v_mul_f32_e32 v90, v95, v97
	v_mul_f32_e32 v91, v91, v99
	v_cvt_pk_bf16_f32 v88, v92, v88
	v_cvt_pk_bf16_f32 v89, v89, v90
	v_cvt_pk_bf16_f32 v90, v103, v93
	v_cvt_pk_bf16_f32 v91, v94, v91
	global_store_dwordx4 v[100:101], v[88:91], off
	v_mul_f32_e32 v84, v84, v102
	v_mul_f32_e32 v80, v80, v102
	v_mul_f32_e32 v85, v85, v102
	v_mul_f32_e32 v81, v81, v102
	v_mul_f32_e32 v86, v86, v102
	v_mul_f32_e32 v82, v82, v102
	v_mul_f32_e32 v87, v87, v102
	v_mul_f32_e32 v83, v83, v102
	v_exp_f32_e32 v84, v84
	v_exp_f32_e32 v80, v80
	v_exp_f32_e32 v85, v85
	v_exp_f32_e32 v81, v81
	v_exp_f32_e32 v86, v86
	v_exp_f32_e32 v82, v82
	v_exp_f32_e32 v87, v87
	v_exp_f32_e32 v83, v83
	v_add_f32_e32 v84, 1.0, v84
	v_add_f32_e32 v80, 1.0, v80
	v_add_f32_e32 v85, 1.0, v85
	v_add_f32_e32 v81, 1.0, v81
	v_add_f32_e32 v86, 1.0, v86
	v_add_f32_e32 v82, 1.0, v82
	v_add_f32_e32 v87, 1.0, v87
	v_add_f32_e32 v83, 1.0, v83
	v_rcp_f32_e32 v84, v84
	v_rcp_f32_e32 v80, v80
	v_rcp_f32_e32 v85, v85
	v_rcp_f32_e32 v81, v81
	v_rcp_f32_e32 v86, v86
	v_rcp_f32_e32 v82, v82
	v_rcp_f32_e32 v87, v87
	v_rcp_f32_e32 v83, v83
	v_or_b32_e32 v92, 48, v144
	v_ashrrev_i32_e32 v93, 31, v92
	v_lshlrev_b64 v[92:93], 11, v[92:93]
	v_lshl_add_u64 v[92:93], v[92:93], 0, v[146:147]
	v_lshlrev_b64 v[92:93], 1, v[92:93]
	v_lshl_add_u64 v[94:95], s[20:21], 0, v[92:93]
	v_lshlrev_b32_e32 v96, 16, v220
	v_and_b32_e32 v88, 0xffff0000, v220
	v_lshlrev_b32_e32 v97, 16, v221
	v_and_b32_e32 v89, 0xffff0000, v221
	v_lshlrev_b32_e32 v98, 16, v222
	v_and_b32_e32 v90, 0xffff0000, v222
	v_lshlrev_b32_e32 v99, 16, v223
	v_and_b32_e32 v91, 0xffff0000, v223
	v_mul_f32_e32 v84, v84, v96
	v_mul_f32_e32 v96, v80, v98
	v_mul_f32_e32 v80, v85, v88
	v_mul_f32_e32 v85, v81, v90
	v_mul_f32_e32 v81, v86, v97
	v_mul_f32_e32 v86, v82, v99
	v_mul_f32_e32 v82, v87, v89
	v_mul_f32_e32 v83, v83, v91
	v_cvt_pk_bf16_f32 v80, v84, v80
	v_cvt_pk_bf16_f32 v81, v81, v82
	v_cvt_pk_bf16_f32 v82, v96, v85
	v_cvt_pk_bf16_f32 v83, v86, v83
	global_store_dwordx4 v[100:101], v[80:83], off offset:256
	global_load_dword v86, v[140:141], off offset:192
	s_nop 0
	global_load_dwordx4 v[80:83], v[94:95], off
	global_load_dwordx4 v[224:227], v[94:95], off offset:256
	v_lshl_add_u64 v[84:85], s[24:25], 0, v[92:93]
	s_waitcnt vmcnt(0)
	v_mul_f32_e32 v86, 0xbfb8aa3b, v86
	v_mul_f32_e32 v76, v76, v86
	v_mul_f32_e32 v72, v72, v86
	v_mul_f32_e32 v77, v77, v86
	v_mul_f32_e32 v73, v73, v86
	v_mul_f32_e32 v78, v78, v86
	v_mul_f32_e32 v74, v74, v86
	v_mul_f32_e32 v79, v79, v86
	v_mul_f32_e32 v75, v75, v86
	v_exp_f32_e32 v76, v76
	v_exp_f32_e32 v72, v72
	v_exp_f32_e32 v77, v77
	v_exp_f32_e32 v73, v73
	v_exp_f32_e32 v78, v78
	v_exp_f32_e32 v74, v74
	v_exp_f32_e32 v79, v79
	v_exp_f32_e32 v75, v75
	v_add_f32_e32 v76, 1.0, v76
	v_add_f32_e32 v72, 1.0, v72
	v_add_f32_e32 v77, 1.0, v77
	v_add_f32_e32 v73, 1.0, v73
	v_add_f32_e32 v78, 1.0, v78
	v_add_f32_e32 v74, 1.0, v74
	v_add_f32_e32 v79, 1.0, v79
	v_add_f32_e32 v75, 1.0, v75
	v_rcp_f32_e32 v76, v76
	v_rcp_f32_e32 v72, v72
	v_rcp_f32_e32 v77, v77
	v_rcp_f32_e32 v73, v73
	v_rcp_f32_e32 v78, v78
	v_rcp_f32_e32 v74, v74
	v_rcp_f32_e32 v79, v79
	v_rcp_f32_e32 v75, v75
	v_lshlrev_b32_e32 v87, 16, v80
	v_and_b32_e32 v80, 0xffff0000, v80
	v_lshlrev_b32_e32 v88, 16, v81
	v_and_b32_e32 v81, 0xffff0000, v81
	v_lshlrev_b32_e32 v89, 16, v82
	v_and_b32_e32 v82, 0xffff0000, v82
	v_lshlrev_b32_e32 v90, 16, v83
	v_and_b32_e32 v83, 0xffff0000, v83
	v_mul_f32_e32 v76, v76, v87
	v_mul_f32_e32 v87, v72, v89
	v_mul_f32_e32 v72, v77, v80
	v_mul_f32_e32 v77, v73, v82
	v_mul_f32_e32 v73, v78, v88
	v_mul_f32_e32 v78, v74, v90
	v_mul_f32_e32 v74, v79, v81
	v_mul_f32_e32 v75, v75, v83
	v_cvt_pk_bf16_f32 v72, v76, v72
	v_cvt_pk_bf16_f32 v73, v73, v74
	v_cvt_pk_bf16_f32 v74, v87, v77
	v_cvt_pk_bf16_f32 v75, v78, v75
	global_store_dwordx4 v[84:85], v[72:75], off
	v_mul_f32_e32 v68, v68, v86
	v_mul_f32_e32 v64, v64, v86
	v_mul_f32_e32 v69, v69, v86
	v_mul_f32_e32 v65, v65, v86
	v_mul_f32_e32 v70, v70, v86
	v_mul_f32_e32 v66, v66, v86
	v_mul_f32_e32 v71, v71, v86
	v_mul_f32_e32 v67, v67, v86
	v_exp_f32_e32 v68, v68
	v_exp_f32_e32 v64, v64
	v_exp_f32_e32 v69, v69
	v_exp_f32_e32 v65, v65
	v_exp_f32_e32 v70, v70
	v_exp_f32_e32 v66, v66
	v_exp_f32_e32 v71, v71
	v_exp_f32_e32 v67, v67
	v_add_f32_e32 v68, 1.0, v68
; __device__ __forceinline__ float bf_lo(unsigned w) { return __uint_as_float(w << 16); }
; __device__ __forceinline__ float bf_hi(unsigned w) { return __uint_as_float(w & 0xffff0000u); }
; __device__ __forceinline__ float fast_rcp(float x) { return __builtin_amdgcn_rcpf(x); }
; __device__ __forceinline__ float fast_exp2(float x) { return __builtin_amdgcn_exp2f(x); }
; __device__ __forceinline__ u32x4 pack8(f32x4 v0, f32x4 v1) { u32x4 w; w.x = cvt_pk_bf16(v0[0], v0[1]); w.y = cvt_pk_bf16(v0[2], v0[3]); w.z = cvt_pk_bf16(v1[0], v1[1]); w.w = cvt_pk_bf16(v1[2], v1[3]); return w; }
;     __device__ __forceinline__ void operator()(const f32x4 (&acc)[2][2][4][2], const Unit& u, int wr, int wc, int fr, int fq) const {
;     ...
;         for (int ai = 0; ai < 2; ++ai)
; #pragma unroll
;             for (int m = 0; m < 4; ++m) { const size_t ro = (size_t)(row0 + ai * HALF + m * 16) * DM + col0; const float nr = -LOG2E * rs[row0 + ai * HALF + m * 16];
; #pragma unroll
;                 for (int bj = 0; bj < 2; ++bj) {
;                     const u32x4 pw = *(const u32x4*)(PP + ro + bj * HALF);
;                     const float pv[8] = {bf_lo(pw.x), bf_hi(pw.x), bf_lo(pw.y), bf_hi(pw.y), bf_lo(pw.z), bf_hi(pw.z), bf_lo(pw.w), bf_hi(pw.w)};
;                     f32x4 t0, t1;
; #pragma unroll
;                     for (int j = 0; j < 4; ++j) {
;                         t0[j] = fast_rcp(1.0f + fast_exp2(acc[ai][bj][m][0][j] * nr)) * pv[j];
;                         t1[j] = fast_rcp(1.0f + fast_exp2(acc[ai][bj][m][1][j] * nr)) * pv[4 + j]; }
;                     *(u32x4*)(O + ro + bj * HALF) = pack8(t0, t1); } }
	v_add_f32_e32 v64, 1.0, v64
	v_add_f32_e32 v69, 1.0, v69
	v_add_f32_e32 v65, 1.0, v65
	v_add_f32_e32 v70, 1.0, v70
	v_add_f32_e32 v66, 1.0, v66
	v_add_f32_e32 v71, 1.0, v71
	v_add_f32_e32 v67, 1.0, v67
	v_rcp_f32_e32 v68, v68
	v_rcp_f32_e32 v64, v64
	v_rcp_f32_e32 v69, v69
	v_rcp_f32_e32 v65, v65
	v_rcp_f32_e32 v70, v70
	v_rcp_f32_e32 v66, v66
	v_rcp_f32_e32 v71, v71
	v_rcp_f32_e32 v67, v67
	v_lshl_add_u64 v[76:77], v[142:143], 0, s[2:3]
	v_lshl_add_u64 v[78:79], s[20:21], 0, v[76:77]
	v_lshlrev_b32_e32 v80, 16, v224
	v_and_b32_e32 v72, 0xffff0000, v224
	v_lshlrev_b32_e32 v81, 16, v225
	v_and_b32_e32 v73, 0xffff0000, v225
	v_lshlrev_b32_e32 v82, 16, v226
	v_and_b32_e32 v74, 0xffff0000, v226
	v_lshlrev_b32_e32 v83, 16, v227
	v_and_b32_e32 v75, 0xffff0000, v227
	v_mul_f32_e32 v68, v68, v80
	v_mul_f32_e32 v80, v64, v82
	v_mul_f32_e32 v64, v69, v72
	v_mul_f32_e32 v69, v65, v74
	v_mul_f32_e32 v65, v70, v81
	v_mul_f32_e32 v70, v66, v83
	v_mul_f32_e32 v66, v71, v73
	v_mul_f32_e32 v67, v67, v75
	v_cvt_pk_bf16_f32 v64, v68, v64
	v_cvt_pk_bf16_f32 v65, v65, v66
	v_cvt_pk_bf16_f32 v66, v80, v69
	v_cvt_pk_bf16_f32 v67, v70, v67
	global_store_dwordx4 v[84:85], v[64:67], off offset:256
	global_load_dword v70, v[140:141], off offset:512
	s_nop 0
	global_load_dwordx4 v[64:67], v[78:79], off
	global_load_dwordx4 v[220:223], v[78:79], off offset:256
	v_lshl_add_u64 v[68:69], s[24:25], 0, v[76:77]
	s_waitcnt vmcnt(0)
	v_mul_f32_e32 v70, 0xbfb8aa3b, v70
	v_mul_f32_e32 v60, v60, v70
	v_mul_f32_e32 v56, v56, v70
	v_mul_f32_e32 v61, v61, v70
	v_mul_f32_e32 v57, v57, v70
	v_mul_f32_e32 v62, v62, v70
	v_mul_f32_e32 v58, v58, v70
	v_mul_f32_e32 v63, v63, v70
	v_mul_f32_e32 v59, v59, v70
	v_exp_f32_e32 v60, v60
	v_exp_f32_e32 v56, v56
	v_exp_f32_e32 v61, v61
	v_exp_f32_e32 v57, v57
	v_exp_f32_e32 v62, v62
	v_exp_f32_e32 v58, v58
	v_exp_f32_e32 v63, v63
	v_exp_f32_e32 v59, v59
	v_add_f32_e32 v60, 1.0, v60
	v_add_f32_e32 v56, 1.0, v56
	v_add_f32_e32 v61, 1.0, v61
	v_add_f32_e32 v57, 1.0, v57
	v_add_f32_e32 v62, 1.0, v62
	v_add_f32_e32 v58, 1.0, v58
	v_add_f32_e32 v63, 1.0, v63
	v_add_f32_e32 v59, 1.0, v59
	v_rcp_f32_e32 v60, v60
	v_rcp_f32_e32 v56, v56
	v_rcp_f32_e32 v61, v61
	v_rcp_f32_e32 v57, v57
	v_rcp_f32_e32 v62, v62
	v_rcp_f32_e32 v58, v58
	v_rcp_f32_e32 v63, v63
	v_rcp_f32_e32 v59, v59
	v_lshlrev_b32_e32 v71, 16, v64
	v_and_b32_e32 v64, 0xffff0000, v64
	v_lshlrev_b32_e32 v72, 16, v65
	v_and_b32_e32 v65, 0xffff0000, v65
	v_lshlrev_b32_e32 v73, 16, v66
	v_and_b32_e32 v66, 0xffff0000, v66
	v_lshlrev_b32_e32 v74, 16, v67
	v_and_b32_e32 v67, 0xffff0000, v67
	v_mul_f32_e32 v60, v60, v71
	v_mul_f32_e32 v71, v56, v73
	v_mul_f32_e32 v56, v61, v64
	v_mul_f32_e32 v61, v57, v66
	v_mul_f32_e32 v57, v62, v72
	v_mul_f32_e32 v62, v58, v74
	v_mul_f32_e32 v58, v63, v65
	v_mul_f32_e32 v59, v59, v67
	v_cvt_pk_bf16_f32 v56, v60, v56
	v_cvt_pk_bf16_f32 v57, v57, v58
	v_cvt_pk_bf16_f32 v58, v71, v61
	v_cvt_pk_bf16_f32 v59, v62, v59
	global_store_dwordx4 v[68:69], v[56:59], off
	v_mul_f32_e32 v52, v52, v70
	v_mul_f32_e32 v48, v48, v70
	v_mul_f32_e32 v53, v53, v70
	v_mul_f32_e32 v49, v49, v70
	v_mul_f32_e32 v54, v54, v70
	v_mul_f32_e32 v50, v50, v70
	v_mul_f32_e32 v55, v55, v70
	v_mul_f32_e32 v51, v51, v70
	v_exp_f32_e32 v52, v52
	v_exp_f32_e32 v48, v48
	v_exp_f32_e32 v53, v53
	v_exp_f32_e32 v49, v49
	v_exp_f32_e32 v54, v54
	v_exp_f32_e32 v50, v50
	v_exp_f32_e32 v55, v55
	v_exp_f32_e32 v51, v51
	v_add_f32_e32 v52, 1.0, v52
	v_add_f32_e32 v48, 1.0, v48
	v_add_f32_e32 v53, 1.0, v53
	v_add_f32_e32 v49, 1.0, v49
	v_add_f32_e32 v54, 1.0, v54
	v_add_f32_e32 v50, 1.0, v50
	v_add_f32_e32 v55, 1.0, v55
	v_add_f32_e32 v51, 1.0, v51
	v_rcp_f32_e32 v52, v52
	v_rcp_f32_e32 v48, v48
	v_rcp_f32_e32 v53, v53
	v_rcp_f32_e32 v49, v49
	v_rcp_f32_e32 v54, v54
	v_rcp_f32_e32 v50, v50
	v_rcp_f32_e32 v55, v55
	v_rcp_f32_e32 v51, v51
	v_lshl_add_u64 v[60:61], v[142:143], 0, s[6:7]
	v_lshl_add_u64 v[62:63], s[20:21], 0, v[60:61]
	v_lshlrev_b32_e32 v64, 16, v220
	v_and_b32_e32 v56, 0xffff0000, v220
	v_lshlrev_b32_e32 v65, 16, v221
	v_and_b32_e32 v57, 0xffff0000, v221
	v_lshlrev_b32_e32 v66, 16, v222
	v_and_b32_e32 v58, 0xffff0000, v222
	v_lshlrev_b32_e32 v67, 16, v223
	v_and_b32_e32 v59, 0xffff0000, v223
	v_mul_f32_e32 v52, v52, v64
	v_mul_f32_e32 v64, v48, v66
	v_mul_f32_e32 v48, v53, v56
	v_mul_f32_e32 v53, v49, v58
	v_mul_f32_e32 v49, v54, v65
	v_mul_f32_e32 v54, v50, v67
	v_mul_f32_e32 v50, v55, v57
	v_mul_f32_e32 v51, v51, v59
	v_cvt_pk_bf16_f32 v48, v52, v48
	v_cvt_pk_bf16_f32 v49, v49, v50
	v_cvt_pk_bf16_f32 v50, v64, v53
	v_cvt_pk_bf16_f32 v51, v54, v51
	global_store_dwordx4 v[68:69], v[48:51], off offset:256
	global_load_dword v54, v[140:141], off offset:576
	s_nop 0
	global_load_dwordx4 v[48:51], v[62:63], off
	global_load_dwordx4 v[224:227], v[62:63], off offset:256
	v_lshl_add_u64 v[52:53], s[24:25], 0, v[60:61]
	s_waitcnt vmcnt(0)
; __device__ __forceinline__ float bf_lo(unsigned w) { return __uint_as_float(w << 16); }
; __device__ __forceinline__ float bf_hi(unsigned w) { return __uint_as_float(w & 0xffff0000u); }
; __device__ __forceinline__ float fast_rcp(float x) { return __builtin_amdgcn_rcpf(x); }
; __device__ __forceinline__ float fast_exp2(float x) { return __builtin_amdgcn_exp2f(x); }
; __device__ __forceinline__ u32x4 pack8(f32x4 v0, f32x4 v1) { u32x4 w; w.x = cvt_pk_bf16(v0[0], v0[1]); w.y = cvt_pk_bf16(v0[2], v0[3]); w.z = cvt_pk_bf16(v1[0], v1[1]); w.w = cvt_pk_bf16(v1[2], v1[3]); return w; }
;     __device__ __forceinline__ void operator()(const f32x4 (&acc)[2][2][4][2], const Unit& u, int wr, int wc, int fr, int fq) const {
;     ...
;         for (int ai = 0; ai < 2; ++ai)
; #pragma unroll
;             for (int m = 0; m < 4; ++m) { const size_t ro = (size_t)(row0 + ai * HALF + m * 16) * DM + col0; const float nr = -LOG2E * rs[row0 + ai * HALF + m * 16];
; #pragma unroll
;                 for (int bj = 0; bj < 2; ++bj) {
;                     const u32x4 pw = *(const u32x4*)(PP + ro + bj * HALF);
;                     const float pv[8] = {bf_lo(pw.x), bf_hi(pw.x), bf_lo(pw.y), bf_hi(pw.y), bf_lo(pw.z), bf_hi(pw.z), bf_lo(pw.w), bf_hi(pw.w)};
;                     f32x4 t0, t1;
; #pragma unroll
;                     for (int j = 0; j < 4; ++j) {
;                         t0[j] = fast_rcp(1.0f + fast_exp2(acc[ai][bj][m][0][j] * nr)) * pv[j];
;                         t1[j] = fast_rcp(1.0f + fast_exp2(acc[ai][bj][m][1][j] * nr)) * pv[4 + j]; }
;                     *(u32x4*)(O + ro + bj * HALF) = pack8(t0, t1); } }
	v_mul_f32_e32 v54, 0xbfb8aa3b, v54
	v_mul_f32_e32 v44, v44, v54
	v_mul_f32_e32 v40, v40, v54
	v_mul_f32_e32 v45, v45, v54
	v_mul_f32_e32 v41, v41, v54
	v_mul_f32_e32 v46, v46, v54
	v_mul_f32_e32 v42, v42, v54
	v_mul_f32_e32 v47, v47, v54
	v_mul_f32_e32 v43, v43, v54
	v_exp_f32_e32 v44, v44
	v_exp_f32_e32 v40, v40
	v_exp_f32_e32 v45, v45
	v_exp_f32_e32 v41, v41
	v_exp_f32_e32 v46, v46
	v_exp_f32_e32 v42, v42
	v_exp_f32_e32 v47, v47
	v_exp_f32_e32 v43, v43
	v_add_f32_e32 v44, 1.0, v44
	v_add_f32_e32 v40, 1.0, v40
	v_add_f32_e32 v45, 1.0, v45
	v_add_f32_e32 v41, 1.0, v41
	v_add_f32_e32 v46, 1.0, v46
	v_add_f32_e32 v42, 1.0, v42
	v_add_f32_e32 v47, 1.0, v47
	v_add_f32_e32 v43, 1.0, v43
	v_rcp_f32_e32 v44, v44
	v_rcp_f32_e32 v40, v40
	v_rcp_f32_e32 v45, v45
	v_rcp_f32_e32 v41, v41
	v_rcp_f32_e32 v46, v46
	v_rcp_f32_e32 v42, v42
	v_rcp_f32_e32 v47, v47
	v_rcp_f32_e32 v43, v43
	v_lshlrev_b32_e32 v55, 16, v48
	v_and_b32_e32 v48, 0xffff0000, v48
	v_lshlrev_b32_e32 v56, 16, v49
	v_and_b32_e32 v49, 0xffff0000, v49
	v_lshlrev_b32_e32 v57, 16, v50
	v_and_b32_e32 v50, 0xffff0000, v50
	v_lshlrev_b32_e32 v58, 16, v51
	v_and_b32_e32 v51, 0xffff0000, v51
	v_mul_f32_e32 v44, v44, v55
	v_mul_f32_e32 v55, v40, v57
	v_mul_f32_e32 v40, v45, v48
	v_mul_f32_e32 v45, v41, v50
	v_mul_f32_e32 v41, v46, v56
	v_mul_f32_e32 v46, v42, v58
	v_mul_f32_e32 v42, v47, v49
	v_mul_f32_e32 v43, v43, v51
	v_cvt_pk_bf16_f32 v40, v44, v40
	v_cvt_pk_bf16_f32 v41, v41, v42
	v_cvt_pk_bf16_f32 v42, v55, v45
	v_cvt_pk_bf16_f32 v43, v46, v43
	global_store_dwordx4 v[52:53], v[40:43], off
	v_mul_f32_e32 v36, v36, v54
	v_mul_f32_e32 v32, v32, v54
	v_mul_f32_e32 v37, v37, v54
	v_mul_f32_e32 v33, v33, v54
	v_mul_f32_e32 v38, v38, v54
	v_mul_f32_e32 v34, v34, v54
	v_mul_f32_e32 v39, v39, v54
	v_mul_f32_e32 v35, v35, v54
	v_exp_f32_e32 v36, v36
	v_exp_f32_e32 v32, v32
	v_exp_f32_e32 v37, v37
	v_exp_f32_e32 v33, v33
	v_exp_f32_e32 v38, v38
	v_exp_f32_e32 v34, v34
	v_exp_f32_e32 v39, v39
	v_exp_f32_e32 v35, v35
	v_add_f32_e32 v36, 1.0, v36
	v_add_f32_e32 v32, 1.0, v32
	v_add_f32_e32 v37, 1.0, v37
	v_add_f32_e32 v33, 1.0, v33
	v_add_f32_e32 v38, 1.0, v38
	v_add_f32_e32 v34, 1.0, v34
	v_add_f32_e32 v39, 1.0, v39
	v_add_f32_e32 v35, 1.0, v35
	v_rcp_f32_e32 v36, v36
	v_rcp_f32_e32 v32, v32
	v_rcp_f32_e32 v37, v37
	v_rcp_f32_e32 v33, v33
	v_rcp_f32_e32 v38, v38
	v_rcp_f32_e32 v34, v34
	v_rcp_f32_e32 v39, v39
	v_rcp_f32_e32 v35, v35
	v_lshl_add_u64 v[44:45], v[142:143], 0, s[8:9]
	v_lshl_add_u64 v[46:47], s[20:21], 0, v[44:45]
	v_lshlrev_b32_e32 v48, 16, v224
	v_and_b32_e32 v40, 0xffff0000, v224
	v_lshlrev_b32_e32 v49, 16, v225
	v_and_b32_e32 v41, 0xffff0000, v225
	v_lshlrev_b32_e32 v50, 16, v226
	v_and_b32_e32 v42, 0xffff0000, v226
	v_lshlrev_b32_e32 v51, 16, v227
	v_and_b32_e32 v43, 0xffff0000, v227
	v_mul_f32_e32 v36, v36, v48
	v_mul_f32_e32 v48, v32, v50
	v_mul_f32_e32 v32, v37, v40
	v_mul_f32_e32 v37, v33, v42
	v_mul_f32_e32 v33, v38, v49
	v_mul_f32_e32 v38, v34, v51
	v_mul_f32_e32 v34, v39, v41
	v_mul_f32_e32 v35, v35, v43
	v_cvt_pk_bf16_f32 v32, v36, v32
	v_cvt_pk_bf16_f32 v33, v33, v34
	v_cvt_pk_bf16_f32 v34, v48, v37
	v_cvt_pk_bf16_f32 v35, v38, v35
	global_store_dwordx4 v[52:53], v[32:35], off offset:256
	global_load_dword v38, v[140:141], off offset:640
	s_nop 0
	global_load_dwordx4 v[32:35], v[46:47], off
	global_load_dwordx4 v[220:223], v[46:47], off offset:256
	v_lshl_add_u64 v[36:37], s[24:25], 0, v[44:45]
	s_waitcnt vmcnt(0)
; __device__ __forceinline__ float bf_lo(unsigned w) { return __uint_as_float(w << 16); }
; __device__ __forceinline__ float bf_hi(unsigned w) { return __uint_as_float(w & 0xffff0000u); }
; __device__ __forceinline__ float fast_rcp(float x) { return __builtin_amdgcn_rcpf(x); }
; __device__ __forceinline__ float fast_exp2(float x) { return __builtin_amdgcn_exp2f(x); }
; #define PG8_WAIT_V(n) asm volatile("s_waitcnt vmcnt(" #n ")" ::: "memory")
; #define PG8_BAR __builtin_amdgcn_s_barrier()
; __device__ __forceinline__ u32x4 pack8(f32x4 v0, f32x4 v1) { u32x4 w; w.x = cvt_pk_bf16(v0[0], v0[1]); w.y = cvt_pk_bf16(v0[2], v0[3]); w.z = cvt_pk_bf16(v1[0], v1[1]); w.w = cvt_pk_bf16(v1[2], v1[3]); return w; }
; template <class Epi>
; __device__ __forceinline__ void gemm_phase(LAS unsigned char* lds, const Gemm g, const StaticOrder& S, const Epi& E) {
;     ...
;         E(acc, cur, wr, wc, fr, fq);
;         if (!has_next) break;
; #pragma unroll
;         for (int a = 0; a < 2; ++a)
; #pragma unroll
;             for (int b = 0; b < 2; ++b)
; #pragma unroll
;                 for (int m = 0; m < 4; ++m)
; #pragma unroll
;                     for (int n = 0; n < 2; ++n) acc[a][b][m][n] = (f32x4){0.f, 0.f, 0.f, 0.f};
;         cur = nxt; cA = nA; cB = nB; ++ui;
;     }
;     PG8_WAIT_V(0);
;     if (wr == 0) PG8_BAR;
;     __device__ __forceinline__ void operator()(const f32x4 (&acc)[2][2][4][2], const Unit& u, int wr, int wc, int fr, int fq) const {
;     ...
;         for (int ai = 0; ai < 2; ++ai)
; #pragma unroll
;             for (int m = 0; m < 4; ++m) { const size_t ro = (size_t)(row0 + ai * HALF + m * 16) * DM + col0; const float nr = -LOG2E * rs[row0 + ai * HALF + m * 16];
; #pragma unroll
;                 for (int bj = 0; bj < 2; ++bj) {
;                     const u32x4 pw = *(const u32x4*)(PP + ro + bj * HALF);
;                     const float pv[8] = {bf_lo(pw.x), bf_hi(pw.x), bf_lo(pw.y), bf_hi(pw.y), bf_lo(pw.z), bf_hi(pw.z), bf_lo(pw.w), bf_hi(pw.w)};
;                     f32x4 t0, t1;
; #pragma unroll
;                     for (int j = 0; j < 4; ++j) {
;                         t0[j] = fast_rcp(1.0f + fast_exp2(acc[ai][bj][m][0][j] * nr)) * pv[j];
;                         t1[j] = fast_rcp(1.0f + fast_exp2(acc[ai][bj][m][1][j] * nr)) * pv[4 + j]; }
;                     *(u32x4*)(O + ro + bj * HALF) = pack8(t0, t1); } }
	v_mul_f32_e32 v38, 0xbfb8aa3b, v38
	v_mul_f32_e32 v28, v28, v38
	v_mul_f32_e32 v24, v24, v38
	v_mul_f32_e32 v29, v29, v38
	v_mul_f32_e32 v25, v25, v38
	v_mul_f32_e32 v30, v30, v38
	v_mul_f32_e32 v26, v26, v38
	v_mul_f32_e32 v31, v31, v38
	v_mul_f32_e32 v27, v27, v38
	v_exp_f32_e32 v28, v28
	v_exp_f32_e32 v24, v24
	v_exp_f32_e32 v29, v29
	v_exp_f32_e32 v25, v25
	v_exp_f32_e32 v30, v30
	v_exp_f32_e32 v26, v26
	v_exp_f32_e32 v31, v31
	v_exp_f32_e32 v27, v27
	v_add_f32_e32 v28, 1.0, v28
	v_add_f32_e32 v24, 1.0, v24
	v_add_f32_e32 v29, 1.0, v29
	v_add_f32_e32 v25, 1.0, v25
	v_add_f32_e32 v30, 1.0, v30
	v_add_f32_e32 v26, 1.0, v26
	v_add_f32_e32 v31, 1.0, v31
	v_add_f32_e32 v27, 1.0, v27
	v_rcp_f32_e32 v28, v28
	v_rcp_f32_e32 v24, v24
	v_rcp_f32_e32 v29, v29
	v_rcp_f32_e32 v25, v25
	v_rcp_f32_e32 v30, v30
	v_rcp_f32_e32 v26, v26
	v_rcp_f32_e32 v31, v31
	v_rcp_f32_e32 v27, v27
	v_lshlrev_b32_e32 v39, 16, v32
	v_and_b32_e32 v32, 0xffff0000, v32
	v_lshlrev_b32_e32 v40, 16, v33
	v_and_b32_e32 v33, 0xffff0000, v33
	v_lshlrev_b32_e32 v41, 16, v34
	v_and_b32_e32 v34, 0xffff0000, v34
	v_lshlrev_b32_e32 v42, 16, v35
	v_and_b32_e32 v35, 0xffff0000, v35
	v_mul_f32_e32 v28, v28, v39
	v_mul_f32_e32 v39, v24, v41
	v_mul_f32_e32 v24, v29, v32
	v_mul_f32_e32 v29, v25, v34
	v_mul_f32_e32 v25, v30, v40
	v_mul_f32_e32 v30, v26, v42
	v_mul_f32_e32 v26, v31, v33
	v_mul_f32_e32 v27, v27, v35
	v_cvt_pk_bf16_f32 v24, v28, v24
	v_cvt_pk_bf16_f32 v25, v25, v26
	v_cvt_pk_bf16_f32 v26, v39, v29
	v_cvt_pk_bf16_f32 v27, v30, v27
	global_store_dwordx4 v[36:37], v[24:27], off
	v_mul_f32_e32 v20, v20, v38
	v_mul_f32_e32 v16, v16, v38
	v_mul_f32_e32 v21, v21, v38
	v_mul_f32_e32 v17, v17, v38
	v_mul_f32_e32 v22, v22, v38
	v_mul_f32_e32 v18, v18, v38
	v_mul_f32_e32 v23, v23, v38
	v_mul_f32_e32 v19, v19, v38
	v_exp_f32_e32 v20, v20
	v_exp_f32_e32 v16, v16
	v_exp_f32_e32 v21, v21
	v_exp_f32_e32 v17, v17
	v_exp_f32_e32 v22, v22
	v_exp_f32_e32 v18, v18
	v_exp_f32_e32 v23, v23
	v_exp_f32_e32 v19, v19
	v_add_f32_e32 v20, 1.0, v20
	v_add_f32_e32 v16, 1.0, v16
	v_add_f32_e32 v21, 1.0, v21
	v_add_f32_e32 v17, 1.0, v17
	v_add_f32_e32 v22, 1.0, v22
	v_add_f32_e32 v18, 1.0, v18
	v_add_f32_e32 v23, 1.0, v23
	v_add_f32_e32 v19, 1.0, v19
	v_rcp_f32_e32 v20, v20
	v_rcp_f32_e32 v16, v16
	v_rcp_f32_e32 v21, v21
	v_rcp_f32_e32 v17, v17
	v_rcp_f32_e32 v22, v22
	v_rcp_f32_e32 v18, v18
	v_rcp_f32_e32 v23, v23
	v_rcp_f32_e32 v19, v19
	v_lshl_add_u64 v[28:29], v[142:143], 0, s[30:31]
	v_lshl_add_u64 v[30:31], s[20:21], 0, v[28:29]
	v_lshlrev_b32_e32 v32, 16, v220
	v_and_b32_e32 v24, 0xffff0000, v220
	v_lshlrev_b32_e32 v33, 16, v221
	v_and_b32_e32 v25, 0xffff0000, v221
	v_lshlrev_b32_e32 v34, 16, v222
	v_and_b32_e32 v26, 0xffff0000, v222
	v_lshlrev_b32_e32 v35, 16, v223
	v_and_b32_e32 v27, 0xffff0000, v223
	v_mul_f32_e32 v20, v20, v32
	v_mul_f32_e32 v32, v16, v34
	v_mul_f32_e32 v16, v21, v24
	v_mul_f32_e32 v21, v17, v26
	v_mul_f32_e32 v17, v22, v33
	v_mul_f32_e32 v22, v18, v35
	v_mul_f32_e32 v18, v23, v25
	v_mul_f32_e32 v19, v19, v27
	v_cvt_pk_bf16_f32 v16, v20, v16
	v_cvt_pk_bf16_f32 v17, v17, v18
	v_cvt_pk_bf16_f32 v18, v32, v21
	v_cvt_pk_bf16_f32 v19, v22, v19
	global_store_dwordx4 v[36:37], v[16:19], off offset:256
	global_load_dword v22, v[140:141], off offset:704
	s_nop 0
	global_load_dwordx4 v[16:19], v[30:31], off
	global_load_dwordx4 v[224:227], v[30:31], off offset:256
	v_lshl_add_u64 v[20:21], s[24:25], 0, v[28:29]
	s_waitcnt vmcnt(0)
	v_mul_f32_e32 v22, 0xbfb8aa3b, v22
	v_mul_f32_e32 v12, v12, v22
	v_mul_f32_e32 v8, v8, v22
	v_mul_f32_e32 v13, v13, v22
	v_mul_f32_e32 v9, v9, v22
	v_mul_f32_e32 v14, v14, v22
	v_mul_f32_e32 v10, v10, v22
	v_mul_f32_e32 v15, v15, v22
	v_mul_f32_e32 v11, v11, v22
	v_exp_f32_e32 v12, v12
	v_exp_f32_e32 v8, v8
	v_exp_f32_e32 v13, v13
	v_exp_f32_e32 v9, v9
	v_exp_f32_e32 v14, v14
	v_exp_f32_e32 v10, v10
	v_exp_f32_e32 v15, v15
	v_exp_f32_e32 v11, v11
	v_add_f32_e32 v12, 1.0, v12
	v_add_f32_e32 v8, 1.0, v8
	v_add_f32_e32 v13, 1.0, v13
	v_add_f32_e32 v9, 1.0, v9
	v_add_f32_e32 v14, 1.0, v14
	v_add_f32_e32 v10, 1.0, v10
	v_add_f32_e32 v15, 1.0, v15
	v_add_f32_e32 v11, 1.0, v11
	v_rcp_f32_e32 v12, v12
	v_rcp_f32_e32 v8, v8
	v_rcp_f32_e32 v13, v13
	v_rcp_f32_e32 v9, v9
	v_rcp_f32_e32 v14, v14
	v_rcp_f32_e32 v10, v10
	v_rcp_f32_e32 v15, v15
	v_rcp_f32_e32 v11, v11
	v_lshlrev_b32_e32 v23, 16, v16
	v_and_b32_e32 v16, 0xffff0000, v16
	v_lshlrev_b32_e32 v24, 16, v17
	v_and_b32_e32 v17, 0xffff0000, v17
	v_lshlrev_b32_e32 v25, 16, v18
	v_and_b32_e32 v18, 0xffff0000, v18
	v_lshlrev_b32_e32 v26, 16, v19
	v_and_b32_e32 v19, 0xffff0000, v19
	v_mul_f32_e32 v12, v12, v23
	v_mul_f32_e32 v23, v8, v25
	v_mul_f32_e32 v8, v13, v16
	v_mul_f32_e32 v13, v9, v18
	v_mul_f32_e32 v9, v14, v24
	v_mul_f32_e32 v14, v10, v26
	v_mul_f32_e32 v10, v15, v17
	v_mul_f32_e32 v11, v11, v19
	v_cvt_pk_bf16_f32 v8, v12, v8
	v_cvt_pk_bf16_f32 v9, v9, v10
	v_cvt_pk_bf16_f32 v10, v23, v13
	v_cvt_pk_bf16_f32 v11, v14, v11
	global_store_dwordx4 v[20:21], v[8:11], off
	v_mul_f32_e32 v4, v4, v22
	v_mul_f32_e32 v0, v0, v22
	v_mul_f32_e32 v5, v5, v22
	v_mul_f32_e32 v1, v1, v22
	v_mul_f32_e32 v6, v6, v22
	v_mul_f32_e32 v2, v2, v22
	v_mul_f32_e32 v7, v7, v22
	v_mul_f32_e32 v3, v3, v22
	v_exp_f32_e32 v4, v4
	v_exp_f32_e32 v0, v0
	v_exp_f32_e32 v5, v5
	v_exp_f32_e32 v1, v1
	v_exp_f32_e32 v6, v6
	v_exp_f32_e32 v2, v2
	v_exp_f32_e32 v7, v7
	v_exp_f32_e32 v3, v3
	v_add_f32_e32 v4, 1.0, v4
	v_add_f32_e32 v0, 1.0, v0
	v_add_f32_e32 v5, 1.0, v5
	v_add_f32_e32 v1, 1.0, v1
	v_add_f32_e32 v6, 1.0, v6
	v_add_f32_e32 v2, 1.0, v2
	v_add_f32_e32 v7, 1.0, v7
	v_add_f32_e32 v3, 1.0, v3
	v_rcp_f32_e32 v4, v4
	v_rcp_f32_e32 v0, v0
	v_rcp_f32_e32 v5, v5
	v_rcp_f32_e32 v1, v1
	v_rcp_f32_e32 v6, v6
	v_rcp_f32_e32 v2, v2
	v_rcp_f32_e32 v7, v7
	v_rcp_f32_e32 v3, v3
	v_lshlrev_b32_e32 v12, 16, v224
	v_and_b32_e32 v8, 0xffff0000, v224
	v_lshlrev_b32_e32 v13, 16, v225
	v_and_b32_e32 v9, 0xffff0000, v225
	v_lshlrev_b32_e32 v14, 16, v226
	v_and_b32_e32 v10, 0xffff0000, v226
	v_lshlrev_b32_e32 v15, 16, v227
	v_and_b32_e32 v11, 0xffff0000, v227
	v_mul_f32_e32 v4, v4, v12
	v_mul_f32_e32 v12, v0, v14
	v_mul_f32_e32 v0, v5, v8
	v_mul_f32_e32 v5, v1, v10
	v_mul_f32_e32 v1, v6, v13
	v_mul_f32_e32 v6, v2, v15
	v_mul_f32_e32 v2, v7, v9
	v_mul_f32_e32 v3, v3, v11
	v_cvt_pk_bf16_f32 v0, v4, v0
	v_cvt_pk_bf16_f32 v1, v1, v2
	v_cvt_pk_bf16_f32 v2, v12, v5
	v_cvt_pk_bf16_f32 v3, v6, v3
	global_store_dwordx4 v[20:21], v[0:3], off offset:256
	s_cbranch_vccz .LBB0_996
	s_waitcnt vmcnt(0)
	s_cmpk_gt_u32 s10, 0xff
	s_cbranch_scc1 .LBB0_1003
	s_barrier
